# mid-segment s_setprio 0/1 pairs removed from the GEMM MFMA segments (A/B test)
# speedup vs baseline: 1.0086x; 1.0019x over previous
; #define PG8_STAGE(bufoff, gbase, voff) do { _Pragma("unroll") for (int _i = 0; _i < 2; ++_i) \
;         __builtin_amdgcn_global_load_lds((const unsigned*)((const char*)(gbase) + (voff)[_i]), (PG8_LAS unsigned*)(lds + (bufoff) + ldsw + _i * 8192), 16, 0, 0); } while (0)
; #define PG8_LDA(dst, b, h) do { _Pragma("unroll") for (int m = 0; m < 4; ++m) _Pragma("unroll") for (int k = 0; k < 2; ++k) dst[m][k] = *(const PG8_LAS bf16x8*)(lds + PG8_SA(b, h) + aoff + m * 2048 + k * 1024); } while (0)
; #define PG8_LDB(dst, b, h) do { _Pragma("unroll") for (int n = 0; n < 2; ++n) _Pragma("unroll") for (int k = 0; k < 2; ++k) dst[n][k] = *(const PG8_LAS bf16x8*)(lds + PG8_SB(b, h) + boff + n * 2048 + k * 1024); } while (0)
; #define PG8_WAIT_V(n) asm volatile("s_waitcnt vmcnt(" #n ")" ::: "memory")
; #define PG8_WAIT_L(n) asm volatile("s_waitcnt lgkmcnt(" #n ")" ::: "memory")
; #define PG8_BAR __builtin_amdgcn_s_barrier()
; #define PG8_SCHED __builtin_amdgcn_sched_barrier(0)
; template <class Epi, class Sched, bool ALIGN_EPI = false, bool SP2 = false>
; __device__ __forceinline__ void gemm_phase(PG8_LAS unsigned char* lds, const Gemm g, const Sched& S, const Epi& E) {
;     ...
;         const bool has_next = S.next(ui + 1, nxt);
;         const char* nA = has_next ? (const char*)g.A + (size_t)nxt.pm * tstep : cA; const char* nB = has_next ? (const char*)g.Bt + (size_t)nxt.pn * tstep : cB;
;         for (int t = 0; t < nt; t += 2) {
;             const bool last = (t == nt - 2);
;             const char* a1 = cA + (size_t)(t + 1) * kstep;
;             const char* a2 = last ? nA : cA + (size_t)(t + 2) * kstep; const char* b2 = last ? nB : cB + (size_t)(t + 2) * kstep;
;             const char* a3 = a2 + kstep; const char* b3 = b2 + kstep;
;             if (last && has_next) S.a_ready(nxt);
;             if constexpr (SP2) {
;             PG8_LDB(B0, 0, 0); PG8_LDB(B1, 0, 1); PG8_SCHED; PG8_LDA(At, 0, 0); PG8_STAGE(PG8_SA(1, 1), a1 + hstep, voffA);
;             PG8_WAIT_V(8); PG8_WAIT_L(0); PG8_BAR; PG8_MMA(0, 0, At, B0); PG8_MMA(0, 1, At, B1); PG8_BAR; PG8_SCHED;
;             PG8_LDA(At, 0, 1); PG8_STAGE(PG8_SB(0, 0), b2, voffB); PG8_STAGE(PG8_SB(0, 1), b2 + hstep, voffB); PG8_STAGE(PG8_SA(0, 0), a2, voffA);
;             PG8_WAIT_V(8); PG8_WAIT_L(0); PG8_BAR; PG8_MMA(1, 0, At, B0); PG8_MMA(1, 1, At, B1); PG8_BAR; PG8_SCHED;
.LBB0_223:
	s_ashr_i32 s15, s14, 31
	s_lshl_b64 s[16:17], s[14:15], 19
	s_add_u32 s16, s36, s16
	s_addc_u32 s17, s37, s17
	s_and_b64 s[18:19], s[4:5], exec
	s_cselect_b32 s15, s17, s21
	s_cselect_b32 s68, s16, s20
	s_ashr_i32 s13, s12, 31
	s_lshl_b64 s[18:19], s[12:13], 19
	s_add_u32 s18, s53, s18
	s_addc_u32 s19, s54, s19
	s_and_b64 s[46:47], s[4:5], exec
	s_cselect_b32 s13, s19, s43
	s_cselect_b32 s69, s18, s42
	s_add_u32 s20, s20, 0x40080
	s_addc_u32 s21, s21, 0
	s_add_u32 s70, s42, 0x100
	s_addc_u32 s71, s43, 0
	s_mov_b32 s72, -2
	ds_read_b128 v[154:157], v150
	ds_read_b128 v[158:161], v150 offset:1024
	ds_read_b128 v[162:165], v150 offset:2048
	ds_read_b128 v[166:169], v150 offset:3072
	ds_read_b128 v[170:173], v151
	ds_read_b128 v[174:177], v151 offset:1024
	ds_read_b128 v[178:181], v151 offset:2048
	ds_read_b128 v[182:185], v151 offset:3072
	s_add_u32 s42, s20, 0xfffc0080
	s_addc_u32 s43, s21, -1
	s_cmp_eq_u32 s72, 12
	s_cselect_b32 s47, s15, s43
	s_cselect_b32 s46, s68, s42
	s_cselect_b32 s43, s13, s71
	s_cselect_b32 s42, s69, s70
	v_lshl_add_u64 v[144:145], s[20:21], 0, v[136:137]
	s_add_i32 m0, s35, 0xc000
	ds_read_b128 v[186:189], v152
	ds_read_b128 v[190:193], v152 offset:1024
	ds_read_b128 v[198:201], v152 offset:2048
	ds_read_b128 v[202:205], v152 offset:3072
	ds_read_b128 v[206:209], v152 offset:4096
	ds_read_b128 v[210:213], v152 offset:5120
	ds_read_b128 v[214:217], v152 offset:6144
	ds_read_b128 v[218:221], v152 offset:7168
	global_load_lds_dwordx4 v[144:145], off
	v_lshl_add_u64 v[144:145], s[20:21], 0, v[138:139]
	s_add_i32 m0, s35, 0xe000
	s_nop 0
	global_load_lds_dwordx4 v[144:145], off
	s_waitcnt vmcnt(8)
	s_waitcnt lgkmcnt(0)
	s_barrier
	s_setprio 1
	s_waitcnt lgkmcnt(0)
	v_mfma_f32_16x16x32_bf16 v[124:127], v[154:157], v[186:189], 0
	v_mfma_f32_16x16x32_bf16 v[116:119], v[162:165], v[186:189], 0
	v_mfma_f32_16x16x32_bf16 v[108:111], v[154:157], v[198:201], 0
	v_mfma_f32_16x16x32_bf16 v[100:103], v[162:165], v[198:201], 0
	v_mfma_f32_16x16x32_bf16 v[92:95], v[154:157], v[206:209], 0
	v_mfma_f32_16x16x32_bf16 v[84:87], v[162:165], v[206:209], 0
	v_mfma_f32_16x16x32_bf16 v[76:79], v[154:157], v[214:217], 0
	v_mfma_f32_16x16x32_bf16 v[68:71], v[162:165], v[214:217], 0
	v_mfma_f32_16x16x32_bf16 v[124:127], v[158:161], v[190:193], v[124:127]
	v_mfma_f32_16x16x32_bf16 v[116:119], v[166:169], v[190:193], v[116:119]
	v_mfma_f32_16x16x32_bf16 v[108:111], v[158:161], v[202:205], v[108:111]
	v_mfma_f32_16x16x32_bf16 v[100:103], v[166:169], v[202:205], v[100:103]
	v_mfma_f32_16x16x32_bf16 v[92:95], v[158:161], v[210:213], v[92:95]
	v_mfma_f32_16x16x32_bf16 v[84:87], v[166:169], v[210:213], v[84:87]
	v_mfma_f32_16x16x32_bf16 v[76:79], v[158:161], v[218:221], v[76:79]
	v_mfma_f32_16x16x32_bf16 v[68:71], v[166:169], v[218:221], v[68:71]
	v_mfma_f32_16x16x32_bf16 v[120:123], v[170:173], v[186:189], 0
	v_mfma_f32_16x16x32_bf16 v[112:115], v[178:181], v[186:189], 0
	v_mfma_f32_16x16x32_bf16 v[104:107], v[170:173], v[198:201], 0
	v_mfma_f32_16x16x32_bf16 v[96:99], v[178:181], v[198:201], 0
	v_mfma_f32_16x16x32_bf16 v[88:91], v[170:173], v[206:209], 0
	v_mfma_f32_16x16x32_bf16 v[80:83], v[178:181], v[206:209], 0
	v_mfma_f32_16x16x32_bf16 v[72:75], v[170:173], v[214:217], 0
	v_mfma_f32_16x16x32_bf16 v[64:67], v[178:181], v[214:217], 0
	v_mfma_f32_16x16x32_bf16 v[120:123], v[174:177], v[190:193], v[120:123]
	v_mfma_f32_16x16x32_bf16 v[112:115], v[182:185], v[190:193], v[112:115]
	v_mfma_f32_16x16x32_bf16 v[104:107], v[174:177], v[202:205], v[104:107]
	v_mfma_f32_16x16x32_bf16 v[96:99], v[182:185], v[202:205], v[96:99]
	v_mfma_f32_16x16x32_bf16 v[88:91], v[174:177], v[210:213], v[88:91]
	v_mfma_f32_16x16x32_bf16 v[80:83], v[182:185], v[210:213], v[80:83]
	v_mfma_f32_16x16x32_bf16 v[72:75], v[174:177], v[218:221], v[72:75]
	v_mfma_f32_16x16x32_bf16 v[64:67], v[182:185], v[218:221], v[64:67]
	s_setprio 0
	s_barrier
	s_add_i32 s73, s63, s55
	v_lshl_add_u64 v[144:145], s[42:43], 0, v[132:133]
	s_mov_b32 m0, s73
	ds_read_b128 v[186:189], v152 offset:16384
	ds_read_b128 v[190:193], v152 offset:17408
	ds_read_b128 v[198:201], v152 offset:18432
	ds_read_b128 v[202:205], v152 offset:19456
	ds_read_b128 v[206:209], v152 offset:20480
	ds_read_b128 v[210:213], v152 offset:21504
	ds_read_b128 v[214:217], v152 offset:22528
	ds_read_b128 v[218:221], v152 offset:23552
	global_load_lds_dwordx4 v[144:145], off
	s_add_i32 m0, s73, 0x2000
	s_add_u32 s74, s42, 0x40000
	v_lshl_add_u64 v[194:195], s[42:43], 0, v[128:129]
	s_addc_u32 s75, s43, 0
	s_add_i32 s73, s64, s55
	global_load_lds_dwordx4 v[194:195], off
	v_lshl_add_u64 v[222:223], s[74:75], 0, v[132:133]
	s_mov_b32 m0, s73
	v_lshl_add_u64 v[224:225], s[46:47], 0, v[130:131]
	global_load_lds_dwordx4 v[222:223], off
	v_lshl_add_u64 v[222:223], s[74:75], 0, v[128:129]
	s_add_i32 m0, s73, 0x2000
	s_nop 0
	global_load_lds_dwordx4 v[222:223], off
	v_lshl_add_u64 v[222:223], s[46:47], 0, v[134:135]
	s_mov_b32 m0, s35
	s_nop 0
	global_load_lds_dwordx4 v[222:223], off
	s_mov_b32 m0, s57
	s_nop 0
	global_load_lds_dwordx4 v[224:225], off
	s_waitcnt vmcnt(8)
	s_waitcnt lgkmcnt(0)
	s_barrier
; #define PG8_STAGE(bufoff, gbase, voff) do { _Pragma("unroll") for (int _i = 0; _i < 2; ++_i) \
;         __builtin_amdgcn_global_load_lds((const unsigned*)((const char*)(gbase) + (voff)[_i]), (PG8_LAS unsigned*)(lds + (bufoff) + ldsw + _i * 8192), 16, 0, 0); } while (0)
; #define PG8_LDA(dst, b, h) do { _Pragma("unroll") for (int m = 0; m < 4; ++m) _Pragma("unroll") for (int k = 0; k < 2; ++k) dst[m][k] = *(const PG8_LAS bf16x8*)(lds + PG8_SA(b, h) + aoff + m * 2048 + k * 1024); } while (0)
; #define PG8_LDB(dst, b, h) do { _Pragma("unroll") for (int n = 0; n < 2; ++n) _Pragma("unroll") for (int k = 0; k < 2; ++k) dst[n][k] = *(const PG8_LAS bf16x8*)(lds + PG8_SB(b, h) + boff + n * 2048 + k * 1024); } while (0)
; #define PG8_MMA(ai, bj, At, Bt) do { __builtin_amdgcn_s_setprio(1); _Pragma("unroll") for (int m = 0; m < 4; ++m) _Pragma("unroll") for (int n = 0; n < 2; ++n) _Pragma("unroll") for (int k = 0; k < 2; ++k) \
;         acc[ai][bj][m][n] = __builtin_amdgcn_mfma_f32_16x16x32_bf16(Bt[n][k], At[m][k], acc[ai][bj][m][n], 0, 0, 0); __builtin_amdgcn_s_setprio(0); } while (0)
; #define PG8_WAIT_V(n) asm volatile("s_waitcnt vmcnt(" #n ")" ::: "memory")
; #define PG8_WAIT_L(n) asm volatile("s_waitcnt lgkmcnt(" #n ")" ::: "memory")
; #define PG8_BAR __builtin_amdgcn_s_barrier()
; #define PG8_SCHED __builtin_amdgcn_sched_barrier(0)
; template <class Epi, class Sched, bool ALIGN_EPI = false, bool SP2 = false>
; __device__ __forceinline__ void gemm_phase(PG8_LAS unsigned char* lds, const Gemm g, const Sched& S, const Epi& E) {
;     ...
;             PG8_WAIT_V(8); PG8_WAIT_L(0); PG8_BAR; PG8_MMA(1, 0, At, B0); PG8_MMA(1, 1, At, B1); PG8_BAR; PG8_SCHED;
;             PG8_LDB(B0, 1, 0); PG8_LDB(B1, 1, 1); PG8_SCHED; PG8_LDA(At, 1, 0); PG8_STAGE(PG8_SA(0, 1), a2 + hstep, voffA);
;             PG8_WAIT_V(8); PG8_WAIT_L(0); PG8_BAR; PG8_MMA(0, 0, At, B0); PG8_MMA(0, 1, At, B1); PG8_BAR; PG8_SCHED;
	s_setprio 1
	s_waitcnt lgkmcnt(0)
	v_mfma_f32_16x16x32_bf16 v[60:63], v[154:157], v[186:189], 0
	v_mfma_f32_16x16x32_bf16 v[52:55], v[162:165], v[186:189], 0
	v_mfma_f32_16x16x32_bf16 v[44:47], v[154:157], v[198:201], 0
	v_mfma_f32_16x16x32_bf16 v[36:39], v[162:165], v[198:201], 0
	v_mfma_f32_16x16x32_bf16 v[28:31], v[154:157], v[206:209], 0
	v_mfma_f32_16x16x32_bf16 v[20:23], v[162:165], v[206:209], 0
	v_mfma_f32_16x16x32_bf16 v[12:15], v[154:157], v[214:217], 0
	v_mfma_f32_16x16x32_bf16 v[4:7], v[162:165], v[214:217], 0
	v_mfma_f32_16x16x32_bf16 v[60:63], v[158:161], v[190:193], v[60:63]
	v_mfma_f32_16x16x32_bf16 v[52:55], v[166:169], v[190:193], v[52:55]
	v_mfma_f32_16x16x32_bf16 v[44:47], v[158:161], v[202:205], v[44:47]
	v_mfma_f32_16x16x32_bf16 v[36:39], v[166:169], v[202:205], v[36:39]
	v_mfma_f32_16x16x32_bf16 v[28:31], v[158:161], v[210:213], v[28:31]
	v_mfma_f32_16x16x32_bf16 v[20:23], v[166:169], v[210:213], v[20:23]
	v_mfma_f32_16x16x32_bf16 v[12:15], v[158:161], v[218:221], v[12:15]
	v_mfma_f32_16x16x32_bf16 v[4:7], v[166:169], v[218:221], v[4:7]
	v_mfma_f32_16x16x32_bf16 v[56:59], v[170:173], v[186:189], 0
	v_mfma_f32_16x16x32_bf16 v[48:51], v[178:181], v[186:189], 0
	v_mfma_f32_16x16x32_bf16 v[40:43], v[170:173], v[198:201], 0
	v_mfma_f32_16x16x32_bf16 v[32:35], v[178:181], v[198:201], 0
	v_mfma_f32_16x16x32_bf16 v[24:27], v[170:173], v[206:209], 0
	v_mfma_f32_16x16x32_bf16 v[16:19], v[178:181], v[206:209], 0
	v_mfma_f32_16x16x32_bf16 v[8:11], v[170:173], v[214:217], 0
	v_mfma_f32_16x16x32_bf16 v[0:3], v[178:181], v[214:217], 0
	v_mfma_f32_16x16x32_bf16 v[56:59], v[174:177], v[190:193], v[56:59]
	v_mfma_f32_16x16x32_bf16 v[48:51], v[182:185], v[190:193], v[48:51]
	v_mfma_f32_16x16x32_bf16 v[40:43], v[174:177], v[202:205], v[40:43]
	v_mfma_f32_16x16x32_bf16 v[32:35], v[182:185], v[202:205], v[32:35]
	v_mfma_f32_16x16x32_bf16 v[24:27], v[174:177], v[210:213], v[24:27]
	v_mfma_f32_16x16x32_bf16 v[16:19], v[182:185], v[210:213], v[16:19]
	v_mfma_f32_16x16x32_bf16 v[8:11], v[174:177], v[218:221], v[8:11]
	v_mfma_f32_16x16x32_bf16 v[0:3], v[182:185], v[218:221], v[0:3]
	s_setprio 0
	s_barrier
	s_add_i32 s73, 0, 0x18000
	v_add_u32_e32 v153, s73, v147
	s_add_i32 s74, 0, 0x1c000
	ds_read_b128 v[154:157], v153
	ds_read_b128 v[158:161], v153 offset:1024
	ds_read_b128 v[162:165], v153 offset:2048
	ds_read_b128 v[166:169], v153 offset:3072
	v_add_u32_e32 v153, s74, v147
	ds_read_b128 v[170:173], v153
	ds_read_b128 v[174:177], v153 offset:1024
	ds_read_b128 v[178:181], v153 offset:2048
	ds_read_b128 v[182:185], v153 offset:3072
	s_add_u32 s46, s46, 0x40000
	s_addc_u32 s47, s47, 0
	s_mov_b32 m0, s58
	v_lshl_add_u64 v[226:227], s[46:47], 0, v[134:135]
	ds_read_b128 v[186:189], v152 offset:32768
	ds_read_b128 v[190:193], v152 offset:33792
	ds_read_b128 v[198:201], v152 offset:34816
	ds_read_b128 v[202:205], v152 offset:35840
	ds_read_b128 v[206:209], v152 offset:36864
	ds_read_b128 v[210:213], v152 offset:37888
	ds_read_b128 v[214:217], v152 offset:38912
	ds_read_b128 v[218:221], v152 offset:39936
	global_load_lds_dwordx4 v[226:227], off
	v_lshl_add_u64 v[226:227], s[46:47], 0, v[130:131]
	s_mov_b32 m0, s59
	s_nop 0
	global_load_lds_dwordx4 v[226:227], off
	s_waitcnt vmcnt(8)
	s_waitcnt lgkmcnt(0)
	s_barrier
	s_setprio 1
	s_waitcnt lgkmcnt(0)
	v_mfma_f32_16x16x32_bf16 v[124:127], v[154:157], v[186:189], v[124:127]
	v_mfma_f32_16x16x32_bf16 v[116:119], v[162:165], v[186:189], v[116:119]
	v_mfma_f32_16x16x32_bf16 v[108:111], v[154:157], v[198:201], v[108:111]
	v_mfma_f32_16x16x32_bf16 v[100:103], v[162:165], v[198:201], v[100:103]
	v_mfma_f32_16x16x32_bf16 v[92:95], v[154:157], v[206:209], v[92:95]
	v_mfma_f32_16x16x32_bf16 v[84:87], v[162:165], v[206:209], v[84:87]
	v_mfma_f32_16x16x32_bf16 v[76:79], v[154:157], v[214:217], v[76:79]
	v_mfma_f32_16x16x32_bf16 v[68:71], v[162:165], v[214:217], v[68:71]
	v_mfma_f32_16x16x32_bf16 v[124:127], v[158:161], v[190:193], v[124:127]
	v_mfma_f32_16x16x32_bf16 v[116:119], v[166:169], v[190:193], v[116:119]
	v_mfma_f32_16x16x32_bf16 v[108:111], v[158:161], v[202:205], v[108:111]
	v_mfma_f32_16x16x32_bf16 v[100:103], v[166:169], v[202:205], v[100:103]
	v_mfma_f32_16x16x32_bf16 v[92:95], v[158:161], v[210:213], v[92:95]
	v_mfma_f32_16x16x32_bf16 v[84:87], v[166:169], v[210:213], v[84:87]
	v_mfma_f32_16x16x32_bf16 v[76:79], v[158:161], v[218:221], v[76:79]
	v_mfma_f32_16x16x32_bf16 v[68:71], v[166:169], v[218:221], v[68:71]
	v_mfma_f32_16x16x32_bf16 v[120:123], v[170:173], v[186:189], v[120:123]
	v_mfma_f32_16x16x32_bf16 v[112:115], v[178:181], v[186:189], v[112:115]
	v_mfma_f32_16x16x32_bf16 v[104:107], v[170:173], v[198:201], v[104:107]
	v_mfma_f32_16x16x32_bf16 v[96:99], v[178:181], v[198:201], v[96:99]
	v_mfma_f32_16x16x32_bf16 v[88:91], v[170:173], v[206:209], v[88:91]
	v_mfma_f32_16x16x32_bf16 v[80:83], v[178:181], v[206:209], v[80:83]
	v_mfma_f32_16x16x32_bf16 v[72:75], v[170:173], v[214:217], v[72:75]
	v_mfma_f32_16x16x32_bf16 v[64:67], v[178:181], v[214:217], v[64:67]
	v_mfma_f32_16x16x32_bf16 v[120:123], v[174:177], v[190:193], v[120:123]
	v_mfma_f32_16x16x32_bf16 v[112:115], v[182:185], v[190:193], v[112:115]
	v_mfma_f32_16x16x32_bf16 v[104:107], v[174:177], v[202:205], v[104:107]
	v_mfma_f32_16x16x32_bf16 v[96:99], v[182:185], v[202:205], v[96:99]
	v_mfma_f32_16x16x32_bf16 v[88:91], v[174:177], v[210:213], v[88:91]
	v_mfma_f32_16x16x32_bf16 v[80:83], v[182:185], v[210:213], v[80:83]
	v_mfma_f32_16x16x32_bf16 v[72:75], v[174:177], v[218:221], v[72:75]
	v_mfma_f32_16x16x32_bf16 v[64:67], v[182:185], v[218:221], v[64:67]
	s_setprio 0
	s_barrier
; #define PG8_STAGE(bufoff, gbase, voff) do { _Pragma("unroll") for (int _i = 0; _i < 2; ++_i) \
;         __builtin_amdgcn_global_load_lds((const unsigned*)((const char*)(gbase) + (voff)[_i]), (PG8_LAS unsigned*)(lds + (bufoff) + ldsw + _i * 8192), 16, 0, 0); } while (0)
; #define PG8_LDA(dst, b, h) do { _Pragma("unroll") for (int m = 0; m < 4; ++m) _Pragma("unroll") for (int k = 0; k < 2; ++k) dst[m][k] = *(const PG8_LAS bf16x8*)(lds + PG8_SA(b, h) + aoff + m * 2048 + k * 1024); } while (0)
; #define PG8_LDB(dst, b, h) do { _Pragma("unroll") for (int n = 0; n < 2; ++n) _Pragma("unroll") for (int k = 0; k < 2; ++k) dst[n][k] = *(const PG8_LAS bf16x8*)(lds + PG8_SB(b, h) + boff + n * 2048 + k * 1024); } while (0)
; #define PG8_MMA(ai, bj, At, Bt) do { __builtin_amdgcn_s_setprio(1); _Pragma("unroll") for (int m = 0; m < 4; ++m) _Pragma("unroll") for (int n = 0; n < 2; ++n) _Pragma("unroll") for (int k = 0; k < 2; ++k) \
;         acc[ai][bj][m][n] = __builtin_amdgcn_mfma_f32_16x16x32_bf16(Bt[n][k], At[m][k], acc[ai][bj][m][n], 0, 0, 0); __builtin_amdgcn_s_setprio(0); } while (0)
; #define PG8_WAIT_V(n) asm volatile("s_waitcnt vmcnt(" #n ")" ::: "memory")
; template <class Epi, class Sched, bool ALIGN_EPI = false, bool SP2 = false>
; __device__ __forceinline__ void gemm_phase(PG8_LAS unsigned char* lds, const Gemm g, const Sched& S, const Epi& E) {
;     ...
;             PG8_LDB(B0, 0, 0); PG8_LDB(B1, 0, 1); PG8_SCHED; PG8_LDA(At, 0, 0); PG8_STAGE(PG8_SA(1, 1), a1 + hstep, voffA);
;             PG8_WAIT_V(8); PG8_WAIT_L(0); PG8_BAR; PG8_MMA(0, 0, At, B0); PG8_MMA(0, 1, At, B1); PG8_BAR; PG8_SCHED;
;             PG8_LDA(At, 0, 1); PG8_STAGE(PG8_SB(0, 0), b2, voffB); PG8_STAGE(PG8_SB(0, 1), b2 + hstep, voffB); PG8_STAGE(PG8_SA(0, 0), a2, voffA);
;             PG8_WAIT_V(8); PG8_WAIT_L(0); PG8_BAR; PG8_MMA(1, 0, At, B0); PG8_MMA(1, 1, At, B1); PG8_BAR; PG8_SCHED;
;             PG8_LDB(B0, 1, 0); PG8_LDB(B1, 1, 1); PG8_SCHED; PG8_LDA(At, 1, 0); PG8_STAGE(PG8_SA(0, 1), a2 + hstep, voffA);
;             PG8_WAIT_V(8); PG8_WAIT_L(0); PG8_BAR; PG8_MMA(0, 0, At, B0); PG8_MMA(0, 1, At, B1); PG8_BAR; PG8_SCHED;
;             PG8_LDA(At, 1, 1); PG8_STAGE(PG8_SB(1, 0), b3, voffB); PG8_STAGE(PG8_SB(1, 1), b3 + hstep, voffB); PG8_STAGE(PG8_SA(1, 0), a3, voffA);
;             PG8_WAIT_V(8); PG8_WAIT_L(0); PG8_BAR; PG8_MMA(1, 0, At, B0); PG8_MMA(1, 1, At, B1); PG8_BAR; PG8_SCHED;
	s_add_i32 s46, s73, s55
	v_lshl_add_u64 v[144:145], v[144:145], 0, s[8:9]
	s_mov_b32 m0, s46
	ds_read_b128 v[186:189], v152 offset:49152
	ds_read_b128 v[190:193], v152 offset:50176
	ds_read_b128 v[198:201], v152 offset:51200
	ds_read_b128 v[202:205], v152 offset:52224
	ds_read_b128 v[206:209], v152 offset:53248
	ds_read_b128 v[210:213], v152 offset:54272
	ds_read_b128 v[214:217], v152 offset:55296
	ds_read_b128 v[218:221], v152 offset:56320
	global_load_lds_dwordx4 v[144:145], off
	s_add_i32 m0, s46, 0x2000
	s_add_u32 s42, s42, 0x40080
	v_lshl_add_u64 v[144:145], v[194:195], 0, s[8:9]
	s_addc_u32 s43, s43, 0
	s_add_i32 s46, s74, s55
	global_load_lds_dwordx4 v[144:145], off
	v_lshl_add_u64 v[144:145], s[42:43], 0, v[132:133]
	s_mov_b32 m0, s46
	s_nop 0
	global_load_lds_dwordx4 v[144:145], off
	v_lshl_add_u64 v[144:145], s[42:43], 0, v[128:129]
	s_add_i32 m0, s46, 0x2000
	s_nop 0
	global_load_lds_dwordx4 v[144:145], off
	v_lshl_add_u64 v[144:145], v[222:223], 0, s[8:9]
	s_mov_b32 m0, s61
	s_nop 0
	global_load_lds_dwordx4 v[144:145], off
	v_lshl_add_u64 v[144:145], v[224:225], 0, s[8:9]
	s_mov_b32 m0, s62
	s_nop 0
	global_load_lds_dwordx4 v[144:145], off
	s_waitcnt vmcnt(8)
	s_waitcnt lgkmcnt(0)
	s_barrier
	s_setprio 1
	s_waitcnt lgkmcnt(0)
	v_mfma_f32_16x16x32_bf16 v[60:63], v[154:157], v[186:189], v[60:63]
	v_mfma_f32_16x16x32_bf16 v[52:55], v[162:165], v[186:189], v[52:55]
	v_mfma_f32_16x16x32_bf16 v[44:47], v[154:157], v[198:201], v[44:47]
	v_mfma_f32_16x16x32_bf16 v[36:39], v[162:165], v[198:201], v[36:39]
	v_mfma_f32_16x16x32_bf16 v[28:31], v[154:157], v[206:209], v[28:31]
	v_mfma_f32_16x16x32_bf16 v[20:23], v[162:165], v[206:209], v[20:23]
	v_mfma_f32_16x16x32_bf16 v[12:15], v[154:157], v[214:217], v[12:15]
	v_mfma_f32_16x16x32_bf16 v[4:7], v[162:165], v[214:217], v[4:7]
	v_mfma_f32_16x16x32_bf16 v[60:63], v[158:161], v[190:193], v[60:63]
	v_mfma_f32_16x16x32_bf16 v[52:55], v[166:169], v[190:193], v[52:55]
	v_mfma_f32_16x16x32_bf16 v[44:47], v[158:161], v[202:205], v[44:47]
	v_mfma_f32_16x16x32_bf16 v[36:39], v[166:169], v[202:205], v[36:39]
	v_mfma_f32_16x16x32_bf16 v[28:31], v[158:161], v[210:213], v[28:31]
	v_mfma_f32_16x16x32_bf16 v[20:23], v[166:169], v[210:213], v[20:23]
	v_mfma_f32_16x16x32_bf16 v[12:15], v[158:161], v[218:221], v[12:15]
	v_mfma_f32_16x16x32_bf16 v[4:7], v[166:169], v[218:221], v[4:7]
	v_mfma_f32_16x16x32_bf16 v[56:59], v[170:173], v[186:189], v[56:59]
	v_mfma_f32_16x16x32_bf16 v[48:51], v[178:181], v[186:189], v[48:51]
	v_mfma_f32_16x16x32_bf16 v[40:43], v[170:173], v[198:201], v[40:43]
	v_mfma_f32_16x16x32_bf16 v[32:35], v[178:181], v[198:201], v[32:35]
	v_mfma_f32_16x16x32_bf16 v[24:27], v[170:173], v[206:209], v[24:27]
	v_mfma_f32_16x16x32_bf16 v[16:19], v[178:181], v[206:209], v[16:19]
	v_mfma_f32_16x16x32_bf16 v[8:11], v[170:173], v[214:217], v[8:11]
	v_mfma_f32_16x16x32_bf16 v[0:3], v[178:181], v[214:217], v[0:3]
	v_mfma_f32_16x16x32_bf16 v[56:59], v[174:177], v[190:193], v[56:59]
	v_mfma_f32_16x16x32_bf16 v[48:51], v[182:185], v[190:193], v[48:51]
	v_mfma_f32_16x16x32_bf16 v[40:43], v[174:177], v[202:205], v[40:43]
	v_mfma_f32_16x16x32_bf16 v[32:35], v[182:185], v[202:205], v[32:35]
	v_mfma_f32_16x16x32_bf16 v[24:27], v[174:177], v[210:213], v[24:27]
	v_mfma_f32_16x16x32_bf16 v[16:19], v[182:185], v[210:213], v[16:19]
	v_mfma_f32_16x16x32_bf16 v[8:11], v[174:177], v[218:221], v[8:11]
	v_mfma_f32_16x16x32_bf16 v[0:3], v[182:185], v[218:221], v[0:3]
	s_setprio 0
	s_barrier
	s_add_i32 s72, s72, 2
	s_add_u32 s20, s20, 0x100
	s_addc_u32 s21, s21, 0
	s_add_u32 s70, s70, 0x100
	s_addc_u32 s71, s71, 0
	s_cmp_gt_u32 s72, 13
.LBB0_224:
	ds_read_b128 v[154:157], v150
	ds_read_b128 v[158:161], v150 offset:1024
	ds_read_b128 v[162:165], v150 offset:2048
	ds_read_b128 v[166:169], v150 offset:3072
	ds_read_b128 v[170:173], v151
	ds_read_b128 v[174:177], v151 offset:1024
	ds_read_b128 v[178:181], v151 offset:2048
	ds_read_b128 v[182:185], v151 offset:3072
	s_add_u32 s42, s20, 0xfffc0080
	s_addc_u32 s43, s21, -1
	s_cmp_eq_u32 s72, 12
	s_cselect_b32 s47, s15, s43
	s_cselect_b32 s46, s68, s42
	s_cselect_b32 s43, s13, s71
	s_cselect_b32 s42, s69, s70
	v_lshl_add_u64 v[144:145], s[20:21], 0, v[136:137]
	s_add_i32 m0, s35, 0xc000
	ds_read_b128 v[186:189], v152
	ds_read_b128 v[190:193], v152 offset:1024
	ds_read_b128 v[198:201], v152 offset:2048
	ds_read_b128 v[202:205], v152 offset:3072
	ds_read_b128 v[206:209], v152 offset:4096
	ds_read_b128 v[210:213], v152 offset:5120
	ds_read_b128 v[214:217], v152 offset:6144
	ds_read_b128 v[218:221], v152 offset:7168
	global_load_lds_dwordx4 v[144:145], off
	v_lshl_add_u64 v[144:145], s[20:21], 0, v[138:139]
	s_add_i32 m0, s35, 0xe000
	s_nop 0
	global_load_lds_dwordx4 v[144:145], off
	s_waitcnt vmcnt(8)
	s_waitcnt lgkmcnt(0)
	s_barrier
; #define PG8_STAGE(bufoff, gbase, voff) do { _Pragma("unroll") for (int _i = 0; _i < 2; ++_i) \
;         __builtin_amdgcn_global_load_lds((const unsigned*)((const char*)(gbase) + (voff)[_i]), (PG8_LAS unsigned*)(lds + (bufoff) + ldsw + _i * 8192), 16, 0, 0); } while (0)
; #define PG8_LDA(dst, b, h) do { _Pragma("unroll") for (int m = 0; m < 4; ++m) _Pragma("unroll") for (int k = 0; k < 2; ++k) dst[m][k] = *(const PG8_LAS bf16x8*)(lds + PG8_SA(b, h) + aoff + m * 2048 + k * 1024); } while (0)
; #define PG8_MMA(ai, bj, At, Bt) do { __builtin_amdgcn_s_setprio(1); _Pragma("unroll") for (int m = 0; m < 4; ++m) _Pragma("unroll") for (int n = 0; n < 2; ++n) _Pragma("unroll") for (int k = 0; k < 2; ++k) \
;         acc[ai][bj][m][n] = __builtin_amdgcn_mfma_f32_16x16x32_bf16(Bt[n][k], At[m][k], acc[ai][bj][m][n], 0, 0, 0); __builtin_amdgcn_s_setprio(0); } while (0)
; #define PG8_WAIT_V(n) asm volatile("s_waitcnt vmcnt(" #n ")" ::: "memory")
; #define PG8_WAIT_L(n) asm volatile("s_waitcnt lgkmcnt(" #n ")" ::: "memory")
; #define PG8_BAR __builtin_amdgcn_s_barrier()
; #define PG8_SCHED __builtin_amdgcn_sched_barrier(0)
; template <class Epi, class Sched, bool ALIGN_EPI = false, bool SP2 = false>
; __device__ __forceinline__ void gemm_phase(PG8_LAS unsigned char* lds, const Gemm g, const Sched& S, const Epi& E) {
;     ...
;             PG8_WAIT_V(8); PG8_WAIT_L(0); PG8_BAR; PG8_MMA(0, 0, At, B0); PG8_MMA(0, 1, At, B1); PG8_BAR; PG8_SCHED;
;             PG8_LDA(At, 0, 1); PG8_STAGE(PG8_SB(0, 0), b2, voffB); PG8_STAGE(PG8_SB(0, 1), b2 + hstep, voffB); PG8_STAGE(PG8_SA(0, 0), a2, voffA);
;             PG8_WAIT_V(8); PG8_WAIT_L(0); PG8_BAR; PG8_MMA(1, 0, At, B0); PG8_MMA(1, 1, At, B1); PG8_BAR; PG8_SCHED;
	s_setprio 1
	s_waitcnt lgkmcnt(0)
	v_mfma_f32_16x16x32_bf16 v[124:127], v[154:157], v[186:189], v[124:127]
	v_mfma_f32_16x16x32_bf16 v[116:119], v[162:165], v[186:189], v[116:119]
	v_mfma_f32_16x16x32_bf16 v[108:111], v[154:157], v[198:201], v[108:111]
	v_mfma_f32_16x16x32_bf16 v[100:103], v[162:165], v[198:201], v[100:103]
	v_mfma_f32_16x16x32_bf16 v[92:95], v[154:157], v[206:209], v[92:95]
	v_mfma_f32_16x16x32_bf16 v[84:87], v[162:165], v[206:209], v[84:87]
	v_mfma_f32_16x16x32_bf16 v[76:79], v[154:157], v[214:217], v[76:79]
	v_mfma_f32_16x16x32_bf16 v[68:71], v[162:165], v[214:217], v[68:71]
	v_mfma_f32_16x16x32_bf16 v[124:127], v[158:161], v[190:193], v[124:127]
	v_mfma_f32_16x16x32_bf16 v[116:119], v[166:169], v[190:193], v[116:119]
	v_mfma_f32_16x16x32_bf16 v[108:111], v[158:161], v[202:205], v[108:111]
	v_mfma_f32_16x16x32_bf16 v[100:103], v[166:169], v[202:205], v[100:103]
	v_mfma_f32_16x16x32_bf16 v[92:95], v[158:161], v[210:213], v[92:95]
	v_mfma_f32_16x16x32_bf16 v[84:87], v[166:169], v[210:213], v[84:87]
	v_mfma_f32_16x16x32_bf16 v[76:79], v[158:161], v[218:221], v[76:79]
	v_mfma_f32_16x16x32_bf16 v[68:71], v[166:169], v[218:221], v[68:71]
	v_mfma_f32_16x16x32_bf16 v[120:123], v[170:173], v[186:189], v[120:123]
	v_mfma_f32_16x16x32_bf16 v[112:115], v[178:181], v[186:189], v[112:115]
	v_mfma_f32_16x16x32_bf16 v[104:107], v[170:173], v[198:201], v[104:107]
	v_mfma_f32_16x16x32_bf16 v[96:99], v[178:181], v[198:201], v[96:99]
	v_mfma_f32_16x16x32_bf16 v[88:91], v[170:173], v[206:209], v[88:91]
	v_mfma_f32_16x16x32_bf16 v[80:83], v[178:181], v[206:209], v[80:83]
	v_mfma_f32_16x16x32_bf16 v[72:75], v[170:173], v[214:217], v[72:75]
	v_mfma_f32_16x16x32_bf16 v[64:67], v[178:181], v[214:217], v[64:67]
	v_mfma_f32_16x16x32_bf16 v[120:123], v[174:177], v[190:193], v[120:123]
	v_mfma_f32_16x16x32_bf16 v[112:115], v[182:185], v[190:193], v[112:115]
	v_mfma_f32_16x16x32_bf16 v[104:107], v[174:177], v[202:205], v[104:107]
	v_mfma_f32_16x16x32_bf16 v[96:99], v[182:185], v[202:205], v[96:99]
	v_mfma_f32_16x16x32_bf16 v[88:91], v[174:177], v[210:213], v[88:91]
	v_mfma_f32_16x16x32_bf16 v[80:83], v[182:185], v[210:213], v[80:83]
	v_mfma_f32_16x16x32_bf16 v[72:75], v[174:177], v[218:221], v[72:75]
	v_mfma_f32_16x16x32_bf16 v[64:67], v[182:185], v[218:221], v[64:67]
	s_setprio 0
	s_barrier
	s_add_i32 s73, s63, s55
	v_lshl_add_u64 v[144:145], s[42:43], 0, v[132:133]
	s_mov_b32 m0, s73
	ds_read_b128 v[186:189], v152 offset:16384
	ds_read_b128 v[190:193], v152 offset:17408
	ds_read_b128 v[198:201], v152 offset:18432
	ds_read_b128 v[202:205], v152 offset:19456
	ds_read_b128 v[206:209], v152 offset:20480
	ds_read_b128 v[210:213], v152 offset:21504
	ds_read_b128 v[214:217], v152 offset:22528
	ds_read_b128 v[218:221], v152 offset:23552
	global_load_lds_dwordx4 v[144:145], off
	s_add_i32 m0, s73, 0x2000
	s_add_u32 s74, s42, 0x40000
	v_lshl_add_u64 v[194:195], s[42:43], 0, v[128:129]
	s_addc_u32 s75, s43, 0
	s_add_i32 s73, s64, s55
	global_load_lds_dwordx4 v[194:195], off
	v_lshl_add_u64 v[222:223], s[74:75], 0, v[132:133]
	s_mov_b32 m0, s73
	v_lshl_add_u64 v[224:225], s[46:47], 0, v[130:131]
	global_load_lds_dwordx4 v[222:223], off
	v_lshl_add_u64 v[222:223], s[74:75], 0, v[128:129]
	s_add_i32 m0, s73, 0x2000
	s_nop 0
	global_load_lds_dwordx4 v[222:223], off
	v_lshl_add_u64 v[222:223], s[46:47], 0, v[134:135]
	s_mov_b32 m0, s35
	s_nop 0
	global_load_lds_dwordx4 v[222:223], off
	s_mov_b32 m0, s57
	s_nop 0
	global_load_lds_dwordx4 v[224:225], off
	s_waitcnt vmcnt(8)
	s_waitcnt lgkmcnt(0)
	s_barrier
	s_setprio 1
	s_waitcnt lgkmcnt(0)
	v_mfma_f32_16x16x32_bf16 v[60:63], v[154:157], v[186:189], v[60:63]
	v_mfma_f32_16x16x32_bf16 v[52:55], v[162:165], v[186:189], v[52:55]
	v_mfma_f32_16x16x32_bf16 v[44:47], v[154:157], v[198:201], v[44:47]
	v_mfma_f32_16x16x32_bf16 v[36:39], v[162:165], v[198:201], v[36:39]
	v_mfma_f32_16x16x32_bf16 v[28:31], v[154:157], v[206:209], v[28:31]
	v_mfma_f32_16x16x32_bf16 v[20:23], v[162:165], v[206:209], v[20:23]
	v_mfma_f32_16x16x32_bf16 v[12:15], v[154:157], v[214:217], v[12:15]
	v_mfma_f32_16x16x32_bf16 v[4:7], v[162:165], v[214:217], v[4:7]
	v_mfma_f32_16x16x32_bf16 v[60:63], v[158:161], v[190:193], v[60:63]
	v_mfma_f32_16x16x32_bf16 v[52:55], v[166:169], v[190:193], v[52:55]
	v_mfma_f32_16x16x32_bf16 v[44:47], v[158:161], v[202:205], v[44:47]
	v_mfma_f32_16x16x32_bf16 v[36:39], v[166:169], v[202:205], v[36:39]
	v_mfma_f32_16x16x32_bf16 v[28:31], v[158:161], v[210:213], v[28:31]
	v_mfma_f32_16x16x32_bf16 v[20:23], v[166:169], v[210:213], v[20:23]
	v_mfma_f32_16x16x32_bf16 v[12:15], v[158:161], v[218:221], v[12:15]
	v_mfma_f32_16x16x32_bf16 v[4:7], v[166:169], v[218:221], v[4:7]
	v_mfma_f32_16x16x32_bf16 v[56:59], v[170:173], v[186:189], v[56:59]
	v_mfma_f32_16x16x32_bf16 v[48:51], v[178:181], v[186:189], v[48:51]
	v_mfma_f32_16x16x32_bf16 v[40:43], v[170:173], v[198:201], v[40:43]
	v_mfma_f32_16x16x32_bf16 v[32:35], v[178:181], v[198:201], v[32:35]
	v_mfma_f32_16x16x32_bf16 v[24:27], v[170:173], v[206:209], v[24:27]
	v_mfma_f32_16x16x32_bf16 v[16:19], v[178:181], v[206:209], v[16:19]
	v_mfma_f32_16x16x32_bf16 v[8:11], v[170:173], v[214:217], v[8:11]
	v_mfma_f32_16x16x32_bf16 v[0:3], v[178:181], v[214:217], v[0:3]
	v_mfma_f32_16x16x32_bf16 v[56:59], v[174:177], v[190:193], v[56:59]
	v_mfma_f32_16x16x32_bf16 v[48:51], v[182:185], v[190:193], v[48:51]
	v_mfma_f32_16x16x32_bf16 v[40:43], v[174:177], v[202:205], v[40:43]
	v_mfma_f32_16x16x32_bf16 v[32:35], v[182:185], v[202:205], v[32:35]
	v_mfma_f32_16x16x32_bf16 v[24:27], v[174:177], v[210:213], v[24:27]
	v_mfma_f32_16x16x32_bf16 v[16:19], v[182:185], v[210:213], v[16:19]
	v_mfma_f32_16x16x32_bf16 v[8:11], v[174:177], v[218:221], v[8:11]
	v_mfma_f32_16x16x32_bf16 v[0:3], v[182:185], v[218:221], v[0:3]
	s_setprio 0
	s_barrier
; #define PG8_STAGE(bufoff, gbase, voff) do { _Pragma("unroll") for (int _i = 0; _i < 2; ++_i) \
;         __builtin_amdgcn_global_load_lds((const unsigned*)((const char*)(gbase) + (voff)[_i]), (PG8_LAS unsigned*)(lds + (bufoff) + ldsw + _i * 8192), 16, 0, 0); } while (0)
; #define PG8_LDA(dst, b, h) do { _Pragma("unroll") for (int m = 0; m < 4; ++m) _Pragma("unroll") for (int k = 0; k < 2; ++k) dst[m][k] = *(const PG8_LAS bf16x8*)(lds + PG8_SA(b, h) + aoff + m * 2048 + k * 1024); } while (0)
; #define PG8_LDB(dst, b, h) do { _Pragma("unroll") for (int n = 0; n < 2; ++n) _Pragma("unroll") for (int k = 0; k < 2; ++k) dst[n][k] = *(const PG8_LAS bf16x8*)(lds + PG8_SB(b, h) + boff + n * 2048 + k * 1024); } while (0)
; #define PG8_MMA(ai, bj, At, Bt) do { __builtin_amdgcn_s_setprio(1); _Pragma("unroll") for (int m = 0; m < 4; ++m) _Pragma("unroll") for (int n = 0; n < 2; ++n) _Pragma("unroll") for (int k = 0; k < 2; ++k) \
;         acc[ai][bj][m][n] = __builtin_amdgcn_mfma_f32_16x16x32_bf16(Bt[n][k], At[m][k], acc[ai][bj][m][n], 0, 0, 0); __builtin_amdgcn_s_setprio(0); } while (0)
; #define PG8_WAIT_V(n) asm volatile("s_waitcnt vmcnt(" #n ")" ::: "memory")
; #define PG8_WAIT_L(n) asm volatile("s_waitcnt lgkmcnt(" #n ")" ::: "memory")
; #define PG8_BAR __builtin_amdgcn_s_barrier()
; #define PG8_SCHED __builtin_amdgcn_sched_barrier(0)
; template <class Epi, class Sched, bool ALIGN_EPI = false, bool SP2 = false>
; __device__ __forceinline__ void gemm_phase(PG8_LAS unsigned char* lds, const Gemm g, const Sched& S, const Epi& E) {
;     ...
;             PG8_LDB(B0, 1, 0); PG8_LDB(B1, 1, 1); PG8_SCHED; PG8_LDA(At, 1, 0); PG8_STAGE(PG8_SA(0, 1), a2 + hstep, voffA);
;             PG8_WAIT_V(8); PG8_WAIT_L(0); PG8_BAR; PG8_MMA(0, 0, At, B0); PG8_MMA(0, 1, At, B1); PG8_BAR; PG8_SCHED;
	s_add_i32 s73, 0, 0x18000
	v_add_u32_e32 v153, s73, v147
	s_add_i32 s74, 0, 0x1c000
	ds_read_b128 v[154:157], v153
	ds_read_b128 v[158:161], v153 offset:1024
	ds_read_b128 v[162:165], v153 offset:2048
	ds_read_b128 v[166:169], v153 offset:3072
	v_add_u32_e32 v153, s74, v147
	ds_read_b128 v[170:173], v153
	ds_read_b128 v[174:177], v153 offset:1024
	ds_read_b128 v[178:181], v153 offset:2048
	ds_read_b128 v[182:185], v153 offset:3072
	s_add_u32 s46, s46, 0x40000
	s_addc_u32 s47, s47, 0
	s_mov_b32 m0, s58
	v_lshl_add_u64 v[226:227], s[46:47], 0, v[134:135]
	ds_read_b128 v[186:189], v152 offset:32768
	ds_read_b128 v[190:193], v152 offset:33792
	ds_read_b128 v[198:201], v152 offset:34816
	ds_read_b128 v[202:205], v152 offset:35840
	ds_read_b128 v[206:209], v152 offset:36864
	ds_read_b128 v[210:213], v152 offset:37888
	ds_read_b128 v[214:217], v152 offset:38912
	ds_read_b128 v[218:221], v152 offset:39936
	global_load_lds_dwordx4 v[226:227], off
	v_lshl_add_u64 v[226:227], s[46:47], 0, v[130:131]
	s_mov_b32 m0, s59
	s_nop 0
	global_load_lds_dwordx4 v[226:227], off
	s_waitcnt vmcnt(8)
	s_waitcnt lgkmcnt(0)
	s_barrier
	s_setprio 1
	s_waitcnt lgkmcnt(0)
	v_mfma_f32_16x16x32_bf16 v[124:127], v[154:157], v[186:189], v[124:127]
	v_mfma_f32_16x16x32_bf16 v[116:119], v[162:165], v[186:189], v[116:119]
	v_mfma_f32_16x16x32_bf16 v[108:111], v[154:157], v[198:201], v[108:111]
	v_mfma_f32_16x16x32_bf16 v[100:103], v[162:165], v[198:201], v[100:103]
	v_mfma_f32_16x16x32_bf16 v[92:95], v[154:157], v[206:209], v[92:95]
	v_mfma_f32_16x16x32_bf16 v[84:87], v[162:165], v[206:209], v[84:87]
	v_mfma_f32_16x16x32_bf16 v[76:79], v[154:157], v[214:217], v[76:79]
	v_mfma_f32_16x16x32_bf16 v[68:71], v[162:165], v[214:217], v[68:71]
	v_mfma_f32_16x16x32_bf16 v[124:127], v[158:161], v[190:193], v[124:127]
	v_mfma_f32_16x16x32_bf16 v[116:119], v[166:169], v[190:193], v[116:119]
	v_mfma_f32_16x16x32_bf16 v[108:111], v[158:161], v[202:205], v[108:111]
	v_mfma_f32_16x16x32_bf16 v[100:103], v[166:169], v[202:205], v[100:103]
	v_mfma_f32_16x16x32_bf16 v[92:95], v[158:161], v[210:213], v[92:95]
	v_mfma_f32_16x16x32_bf16 v[84:87], v[166:169], v[210:213], v[84:87]
	v_mfma_f32_16x16x32_bf16 v[76:79], v[158:161], v[218:221], v[76:79]
	v_mfma_f32_16x16x32_bf16 v[68:71], v[166:169], v[218:221], v[68:71]
	v_mfma_f32_16x16x32_bf16 v[120:123], v[170:173], v[186:189], v[120:123]
	v_mfma_f32_16x16x32_bf16 v[112:115], v[178:181], v[186:189], v[112:115]
	v_mfma_f32_16x16x32_bf16 v[104:107], v[170:173], v[198:201], v[104:107]
	v_mfma_f32_16x16x32_bf16 v[96:99], v[178:181], v[198:201], v[96:99]
	v_mfma_f32_16x16x32_bf16 v[88:91], v[170:173], v[206:209], v[88:91]
	v_mfma_f32_16x16x32_bf16 v[80:83], v[178:181], v[206:209], v[80:83]
	v_mfma_f32_16x16x32_bf16 v[72:75], v[170:173], v[214:217], v[72:75]
	v_mfma_f32_16x16x32_bf16 v[64:67], v[178:181], v[214:217], v[64:67]
	v_mfma_f32_16x16x32_bf16 v[120:123], v[174:177], v[190:193], v[120:123]
	v_mfma_f32_16x16x32_bf16 v[112:115], v[182:185], v[190:193], v[112:115]
	v_mfma_f32_16x16x32_bf16 v[104:107], v[174:177], v[202:205], v[104:107]
	v_mfma_f32_16x16x32_bf16 v[96:99], v[182:185], v[202:205], v[96:99]
	v_mfma_f32_16x16x32_bf16 v[88:91], v[174:177], v[210:213], v[88:91]
	v_mfma_f32_16x16x32_bf16 v[80:83], v[182:185], v[210:213], v[80:83]
	v_mfma_f32_16x16x32_bf16 v[72:75], v[174:177], v[218:221], v[72:75]
	v_mfma_f32_16x16x32_bf16 v[64:67], v[182:185], v[218:221], v[64:67]
	s_setprio 0
	s_barrier
; #define PG8_STAGE(bufoff, gbase, voff) do { _Pragma("unroll") for (int _i = 0; _i < 2; ++_i) \
;         __builtin_amdgcn_global_load_lds((const unsigned*)((const char*)(gbase) + (voff)[_i]), (PG8_LAS unsigned*)(lds + (bufoff) + ldsw + _i * 8192), 16, 0, 0); } while (0)
; #define PG8_LDA(dst, b, h) do { _Pragma("unroll") for (int m = 0; m < 4; ++m) _Pragma("unroll") for (int k = 0; k < 2; ++k) dst[m][k] = *(const PG8_LAS bf16x8*)(lds + PG8_SA(b, h) + aoff + m * 2048 + k * 1024); } while (0)
; #define PG8_MMA(ai, bj, At, Bt) do { __builtin_amdgcn_s_setprio(1); _Pragma("unroll") for (int m = 0; m < 4; ++m) _Pragma("unroll") for (int n = 0; n < 2; ++n) _Pragma("unroll") for (int k = 0; k < 2; ++k) \
;         acc[ai][bj][m][n] = __builtin_amdgcn_mfma_f32_16x16x32_bf16(Bt[n][k], At[m][k], acc[ai][bj][m][n], 0, 0, 0); __builtin_amdgcn_s_setprio(0); } while (0)
; #define PG8_WAIT_V(n) asm volatile("s_waitcnt vmcnt(" #n ")" ::: "memory")
; #define PG8_WAIT_L(n) asm volatile("s_waitcnt lgkmcnt(" #n ")" ::: "memory")
; #define PG8_BAR __builtin_amdgcn_s_barrier()
; #define PG8_SCHED __builtin_amdgcn_sched_barrier(0)
; template <class Epi, class Sched, bool ALIGN_EPI = false, bool SP2 = false>
; __device__ __forceinline__ void gemm_phase(PG8_LAS unsigned char* lds, const Gemm g, const Sched& S, const Epi& E) {
;     ...
;             PG8_LDA(At, 1, 1); PG8_STAGE(PG8_SB(1, 0), b3, voffB); PG8_STAGE(PG8_SB(1, 1), b3 + hstep, voffB); PG8_STAGE(PG8_SA(1, 0), a3, voffA);
;             PG8_WAIT_V(8); PG8_WAIT_L(0); PG8_BAR; PG8_MMA(1, 0, At, B0); PG8_MMA(1, 1, At, B1); PG8_BAR; PG8_SCHED;
;     ...
;         if constexpr (ALIGN_EPI) { if (wr == 0) PG8_BAR; }
	s_add_i32 s46, s73, s55
	v_lshl_add_u64 v[144:145], v[144:145], 0, s[8:9]
	s_mov_b32 m0, s46
	ds_read_b128 v[186:189], v152 offset:49152
	ds_read_b128 v[190:193], v152 offset:50176
	ds_read_b128 v[198:201], v152 offset:51200
	ds_read_b128 v[202:205], v152 offset:52224
	ds_read_b128 v[206:209], v152 offset:53248
	ds_read_b128 v[210:213], v152 offset:54272
	ds_read_b128 v[214:217], v152 offset:55296
	ds_read_b128 v[218:221], v152 offset:56320
	global_load_lds_dwordx4 v[144:145], off
	s_add_i32 m0, s46, 0x2000
	s_add_u32 s42, s42, 0x40080
	v_lshl_add_u64 v[144:145], v[194:195], 0, s[8:9]
	s_addc_u32 s43, s43, 0
	s_add_i32 s46, s74, s55
	global_load_lds_dwordx4 v[144:145], off
	v_lshl_add_u64 v[144:145], s[42:43], 0, v[132:133]
	s_mov_b32 m0, s46
	s_nop 0
	global_load_lds_dwordx4 v[144:145], off
	v_lshl_add_u64 v[144:145], s[42:43], 0, v[128:129]
	s_add_i32 m0, s46, 0x2000
	s_nop 0
	global_load_lds_dwordx4 v[144:145], off
	v_lshl_add_u64 v[144:145], v[222:223], 0, s[8:9]
	s_mov_b32 m0, s61
	s_nop 0
	global_load_lds_dwordx4 v[144:145], off
	v_lshl_add_u64 v[144:145], v[224:225], 0, s[8:9]
	s_mov_b32 m0, s62
	s_nop 0
	global_load_lds_dwordx4 v[144:145], off
	s_waitcnt vmcnt(8)
	s_waitcnt lgkmcnt(0)
	s_barrier
	s_setprio 1
	s_waitcnt lgkmcnt(0)
	v_mfma_f32_16x16x32_bf16 v[60:63], v[154:157], v[186:189], v[60:63]
	v_mfma_f32_16x16x32_bf16 v[52:55], v[162:165], v[186:189], v[52:55]
	v_mfma_f32_16x16x32_bf16 v[44:47], v[154:157], v[198:201], v[44:47]
	v_mfma_f32_16x16x32_bf16 v[36:39], v[162:165], v[198:201], v[36:39]
	v_mfma_f32_16x16x32_bf16 v[28:31], v[154:157], v[206:209], v[28:31]
	v_mfma_f32_16x16x32_bf16 v[20:23], v[162:165], v[206:209], v[20:23]
	v_mfma_f32_16x16x32_bf16 v[12:15], v[154:157], v[214:217], v[12:15]
	v_mfma_f32_16x16x32_bf16 v[4:7], v[162:165], v[214:217], v[4:7]
	v_mfma_f32_16x16x32_bf16 v[60:63], v[158:161], v[190:193], v[60:63]
	v_mfma_f32_16x16x32_bf16 v[52:55], v[166:169], v[190:193], v[52:55]
	v_mfma_f32_16x16x32_bf16 v[44:47], v[158:161], v[202:205], v[44:47]
	v_mfma_f32_16x16x32_bf16 v[36:39], v[166:169], v[202:205], v[36:39]
	v_mfma_f32_16x16x32_bf16 v[28:31], v[158:161], v[210:213], v[28:31]
	v_mfma_f32_16x16x32_bf16 v[20:23], v[166:169], v[210:213], v[20:23]
	v_mfma_f32_16x16x32_bf16 v[12:15], v[158:161], v[218:221], v[12:15]
	v_mfma_f32_16x16x32_bf16 v[4:7], v[166:169], v[218:221], v[4:7]
	v_mfma_f32_16x16x32_bf16 v[56:59], v[170:173], v[186:189], v[56:59]
	v_mfma_f32_16x16x32_bf16 v[48:51], v[178:181], v[186:189], v[48:51]
	v_mfma_f32_16x16x32_bf16 v[40:43], v[170:173], v[198:201], v[40:43]
	v_mfma_f32_16x16x32_bf16 v[32:35], v[178:181], v[198:201], v[32:35]
	v_mfma_f32_16x16x32_bf16 v[24:27], v[170:173], v[206:209], v[24:27]
	v_mfma_f32_16x16x32_bf16 v[16:19], v[178:181], v[206:209], v[16:19]
	v_mfma_f32_16x16x32_bf16 v[8:11], v[170:173], v[214:217], v[8:11]
	v_mfma_f32_16x16x32_bf16 v[0:3], v[178:181], v[214:217], v[0:3]
	v_mfma_f32_16x16x32_bf16 v[56:59], v[174:177], v[190:193], v[56:59]
	v_mfma_f32_16x16x32_bf16 v[48:51], v[182:185], v[190:193], v[48:51]
	v_mfma_f32_16x16x32_bf16 v[40:43], v[174:177], v[202:205], v[40:43]
	v_mfma_f32_16x16x32_bf16 v[32:35], v[182:185], v[202:205], v[32:35]
	v_mfma_f32_16x16x32_bf16 v[24:27], v[174:177], v[210:213], v[24:27]
	v_mfma_f32_16x16x32_bf16 v[16:19], v[182:185], v[210:213], v[16:19]
	v_mfma_f32_16x16x32_bf16 v[8:11], v[174:177], v[218:221], v[8:11]
	v_mfma_f32_16x16x32_bf16 v[0:3], v[182:185], v[218:221], v[0:3]
	s_setprio 0
	s_barrier
	s_add_i32 s72, s72, 2
	s_add_u32 s20, s20, 0x100
	s_addc_u32 s21, s21, 0
	s_add_u32 s70, s70, 0x100
	s_addc_u32 s71, s71, 0
	s_cmp_gt_u32 s72, 13
	s_cbranch_scc0 .LBB0_224
	s_and_b64 vcc, exec, s[10:11]
	s_cbranch_vccz .LBB0_227
	s_barrier

; #define PG8_STAGE(bufoff, gbase, voff) do { _Pragma("unroll") for (int _i = 0; _i < 2; ++_i) \
;         __builtin_amdgcn_global_load_lds((const unsigned*)((const char*)(gbase) + (voff)[_i]), (PG8_LAS unsigned*)(lds + (bufoff) + ldsw + _i * 8192), 16, 0, 0); } while (0)
; #define PG8_LDA(dst, b, h) do { _Pragma("unroll") for (int m = 0; m < 4; ++m) _Pragma("unroll") for (int k = 0; k < 2; ++k) dst[m][k] = *(const PG8_LAS bf16x8*)(lds + PG8_SA(b, h) + aoff + m * 2048 + k * 1024); } while (0)
; #define PG8_LDB(dst, b, h) do { _Pragma("unroll") for (int n = 0; n < 2; ++n) _Pragma("unroll") for (int k = 0; k < 2; ++k) dst[n][k] = *(const PG8_LAS bf16x8*)(lds + PG8_SB(b, h) + boff + n * 2048 + k * 1024); } while (0)
; #define PG8_MMA(ai, bj, At, Bt) do { __builtin_amdgcn_s_setprio(1); _Pragma("unroll") for (int m = 0; m < 4; ++m) _Pragma("unroll") for (int n = 0; n < 2; ++n) _Pragma("unroll") for (int k = 0; k < 2; ++k) \
;         acc[ai][bj][m][n] = __builtin_amdgcn_mfma_f32_16x16x32_bf16(Bt[n][k], At[m][k], acc[ai][bj][m][n], 0, 0, 0); __builtin_amdgcn_s_setprio(0); } while (0)
; #define PG8_WAIT_V(n) asm volatile("s_waitcnt vmcnt(" #n ")" ::: "memory")
; #define PG8_BAR __builtin_amdgcn_s_barrier()
; template <class Epi, class Sched, bool ALIGN_EPI = false, bool SP2 = false>
; __device__ __forceinline__ void gemm_phase(PG8_LAS unsigned char* lds, const Gemm g, const Sched& S, const Epi& E) {
;     ...
;         for (int t = 0; t < nt; t += 2) {
;             const bool last = (t == nt - 2);
;             const char* a1 = cA + (size_t)(t + 1) * kstep;
;             const char* a2 = last ? nA : cA + (size_t)(t + 2) * kstep; const char* b2 = last ? nB : cB + (size_t)(t + 2) * kstep;
;             const char* a3 = a2 + kstep; const char* b3 = b2 + kstep;
;             if (last && has_next) S.a_ready(nxt);
;             if constexpr (SP2) {
;             PG8_LDB(B0, 0, 0); PG8_LDB(B1, 0, 1); PG8_SCHED; PG8_LDA(At, 0, 0); PG8_STAGE(PG8_SA(1, 1), a1 + hstep, voffA);
;             PG8_WAIT_V(8); PG8_WAIT_L(0); PG8_BAR; PG8_MMA(0, 0, At, B0); PG8_MMA(0, 1, At, B1); PG8_BAR; PG8_SCHED;
;             PG8_LDA(At, 0, 1); PG8_STAGE(PG8_SB(0, 0), b2, voffB); PG8_STAGE(PG8_SB(0, 1), b2 + hstep, voffB); PG8_STAGE(PG8_SA(0, 0), a2, voffA);
;             PG8_WAIT_V(8); PG8_WAIT_L(0); PG8_BAR; PG8_MMA(1, 0, At, B0); PG8_MMA(1, 1, At, B1); PG8_BAR; PG8_SCHED;
.LBB0_308:
	s_add_u32 s20, s20, 0xb0080
	s_addc_u32 s21, s21, 0
	s_add_u32 s73, s34, 0x100
	s_addc_u32 s74, s35, 0
	s_mov_b32 s75, -2
	s_waitcnt lgkmcnt(0)
	s_waitcnt lgkmcnt(0)
	ds_read_b128 v[96:99], v223
	ds_read_b128 v[108:111], v223 offset:1024
	ds_read_b128 v[120:123], v223 offset:2048
	ds_read_b128 v[128:131], v223 offset:3072
	ds_read_b128 v[144:147], v224
	ds_read_b128 v[148:151], v224 offset:1024
	ds_read_b128 v[152:155], v224 offset:2048
	ds_read_b128 v[156:159], v224 offset:3072
	s_add_u32 s34, s20, 0xfff50080
	s_addc_u32 s35, s21, -1
	s_cmp_eq_u32 s75, 40
	s_cselect_b32 s51, s1, s35
	s_cselect_b32 s50, s0, s34
	s_cselect_b32 s35, s49, s74
	s_cselect_b32 s34, s48, s73
	v_lshl_add_u64 v[210:211], s[20:21], 0, v[192:193]
	s_add_i32 m0, s54, 0xc000
	ds_read_b128 v[160:163], v225
	ds_read_b128 v[164:167], v225 offset:1024
	ds_read_b128 v[168:171], v225 offset:2048
	ds_read_b128 v[172:175], v225 offset:3072
	ds_read_b128 v[176:179], v225 offset:4096
	ds_read_b128 v[180:183], v225 offset:5120
	ds_read_b128 v[202:205], v225 offset:6144
	ds_read_b128 v[206:209], v225 offset:7168
	global_load_lds_dwordx4 v[210:211], off
	v_lshl_add_u64 v[210:211], s[20:21], 0, v[194:195]
	s_add_i32 m0, s54, 0xe000
	s_nop 0
	global_load_lds_dwordx4 v[210:211], off
	s_waitcnt vmcnt(8)
	s_waitcnt lgkmcnt(0)
	s_barrier
	s_setprio 1
	s_waitcnt lgkmcnt(0)
	v_mfma_f32_16x16x32_bf16 v[140:143], v[96:99], v[160:163], 0
	v_mfma_f32_16x16x32_bf16 v[136:139], v[120:123], v[160:163], 0
	v_mfma_f32_16x16x32_bf16 v[116:119], v[96:99], v[168:171], 0
	v_mfma_f32_16x16x32_bf16 v[112:115], v[120:123], v[168:171], 0
	v_mfma_f32_16x16x32_bf16 v[92:95], v[96:99], v[176:179], 0
	v_mfma_f32_16x16x32_bf16 v[88:91], v[120:123], v[176:179], 0
	v_mfma_f32_16x16x32_bf16 v[76:79], v[96:99], v[202:205], 0
	v_mfma_f32_16x16x32_bf16 v[72:75], v[120:123], v[202:205], 0
	v_mfma_f32_16x16x32_bf16 v[140:143], v[108:111], v[164:167], v[140:143]
	v_mfma_f32_16x16x32_bf16 v[136:139], v[128:131], v[164:167], v[136:139]
	v_mfma_f32_16x16x32_bf16 v[116:119], v[108:111], v[172:175], v[116:119]
	v_mfma_f32_16x16x32_bf16 v[112:115], v[128:131], v[172:175], v[112:115]
	v_mfma_f32_16x16x32_bf16 v[92:95], v[108:111], v[180:183], v[92:95]
	v_mfma_f32_16x16x32_bf16 v[88:91], v[128:131], v[180:183], v[88:91]
	v_mfma_f32_16x16x32_bf16 v[76:79], v[108:111], v[206:209], v[76:79]
	v_mfma_f32_16x16x32_bf16 v[72:75], v[128:131], v[206:209], v[72:75]
	v_mfma_f32_16x16x32_bf16 v[132:135], v[144:147], v[160:163], 0
	v_mfma_f32_16x16x32_bf16 v[124:127], v[152:155], v[160:163], 0
	v_mfma_f32_16x16x32_bf16 v[104:107], v[144:147], v[168:171], 0
	v_mfma_f32_16x16x32_bf16 v[100:103], v[152:155], v[168:171], 0
	v_mfma_f32_16x16x32_bf16 v[84:87], v[144:147], v[176:179], 0
	v_mfma_f32_16x16x32_bf16 v[80:83], v[152:155], v[176:179], 0
	v_mfma_f32_16x16x32_bf16 v[68:71], v[144:147], v[202:205], 0
	v_mfma_f32_16x16x32_bf16 v[64:67], v[152:155], v[202:205], 0
	v_mfma_f32_16x16x32_bf16 v[132:135], v[148:151], v[164:167], v[132:135]
	v_mfma_f32_16x16x32_bf16 v[124:127], v[156:159], v[164:167], v[124:127]
	v_mfma_f32_16x16x32_bf16 v[104:107], v[148:151], v[172:175], v[104:107]
	v_mfma_f32_16x16x32_bf16 v[100:103], v[156:159], v[172:175], v[100:103]
	v_mfma_f32_16x16x32_bf16 v[84:87], v[148:151], v[180:183], v[84:87]
	v_mfma_f32_16x16x32_bf16 v[80:83], v[156:159], v[180:183], v[80:83]
	v_mfma_f32_16x16x32_bf16 v[68:71], v[148:151], v[206:209], v[68:71]
	v_mfma_f32_16x16x32_bf16 v[64:67], v[156:159], v[206:209], v[64:67]
	s_setprio 0
	s_barrier
	s_add_i32 s76, s67, s53
	v_lshl_add_u64 v[210:211], s[34:35], 0, v[186:187]
	s_mov_b32 m0, s76
	ds_read_b128 v[160:163], v225 offset:16384
	ds_read_b128 v[164:167], v225 offset:17408
	ds_read_b128 v[168:171], v225 offset:18432
	ds_read_b128 v[172:175], v225 offset:19456
	ds_read_b128 v[176:179], v225 offset:20480
	ds_read_b128 v[180:183], v225 offset:21504
	ds_read_b128 v[202:205], v225 offset:22528
	ds_read_b128 v[206:209], v225 offset:23552
	global_load_lds_dwordx4 v[210:211], off
	s_add_i32 m0, s76, 0x2000
	s_add_u32 s76, s34, 0xb0000
	v_lshl_add_u64 v[212:213], s[34:35], 0, v[190:191]
	s_addc_u32 s77, s35, 0
	s_add_i32 s78, s68, s53
	global_load_lds_dwordx4 v[212:213], off
	v_lshl_add_u64 v[214:215], s[76:77], 0, v[186:187]
	s_mov_b32 m0, s78
	v_lshl_add_u64 v[216:217], s[50:51], 0, v[188:189]
	global_load_lds_dwordx4 v[214:215], off
	v_lshl_add_u64 v[214:215], s[76:77], 0, v[190:191]
	s_add_i32 m0, s78, 0x2000
	s_nop 0
	global_load_lds_dwordx4 v[214:215], off
	v_lshl_add_u64 v[214:215], s[50:51], 0, v[184:185]
	s_mov_b32 m0, s54
	s_nop 0
	global_load_lds_dwordx4 v[214:215], off
	s_mov_b32 m0, s55
	s_nop 0
	global_load_lds_dwordx4 v[216:217], off
	s_waitcnt vmcnt(8)
	s_waitcnt lgkmcnt(0)
	s_barrier
; #define PG8_STAGE(bufoff, gbase, voff) do { _Pragma("unroll") for (int _i = 0; _i < 2; ++_i) \
;         __builtin_amdgcn_global_load_lds((const unsigned*)((const char*)(gbase) + (voff)[_i]), (PG8_LAS unsigned*)(lds + (bufoff) + ldsw + _i * 8192), 16, 0, 0); } while (0)
; #define PG8_LDA(dst, b, h) do { _Pragma("unroll") for (int m = 0; m < 4; ++m) _Pragma("unroll") for (int k = 0; k < 2; ++k) dst[m][k] = *(const PG8_LAS bf16x8*)(lds + PG8_SA(b, h) + aoff + m * 2048 + k * 1024); } while (0)
; #define PG8_LDB(dst, b, h) do { _Pragma("unroll") for (int n = 0; n < 2; ++n) _Pragma("unroll") for (int k = 0; k < 2; ++k) dst[n][k] = *(const PG8_LAS bf16x8*)(lds + PG8_SB(b, h) + boff + n * 2048 + k * 1024); } while (0)
; #define PG8_MMA(ai, bj, At, Bt) do { __builtin_amdgcn_s_setprio(1); _Pragma("unroll") for (int m = 0; m < 4; ++m) _Pragma("unroll") for (int n = 0; n < 2; ++n) _Pragma("unroll") for (int k = 0; k < 2; ++k) \
;         acc[ai][bj][m][n] = __builtin_amdgcn_mfma_f32_16x16x32_bf16(Bt[n][k], At[m][k], acc[ai][bj][m][n], 0, 0, 0); __builtin_amdgcn_s_setprio(0); } while (0)
; #define PG8_WAIT_V(n) asm volatile("s_waitcnt vmcnt(" #n ")" ::: "memory")
; #define PG8_WAIT_L(n) asm volatile("s_waitcnt lgkmcnt(" #n ")" ::: "memory")
; #define PG8_BAR __builtin_amdgcn_s_barrier()
; #define PG8_SCHED __builtin_amdgcn_sched_barrier(0)
; template <class Epi, class Sched, bool ALIGN_EPI = false, bool SP2 = false>
; __device__ __forceinline__ void gemm_phase(PG8_LAS unsigned char* lds, const Gemm g, const Sched& S, const Epi& E) {
;     ...
;             PG8_WAIT_V(8); PG8_WAIT_L(0); PG8_BAR; PG8_MMA(1, 0, At, B0); PG8_MMA(1, 1, At, B1); PG8_BAR; PG8_SCHED;
;             PG8_LDB(B0, 1, 0); PG8_LDB(B1, 1, 1); PG8_SCHED; PG8_LDA(At, 1, 0); PG8_STAGE(PG8_SA(0, 1), a2 + hstep, voffA);
;             PG8_WAIT_V(8); PG8_WAIT_L(0); PG8_BAR; PG8_MMA(0, 0, At, B0); PG8_MMA(0, 1, At, B1); PG8_BAR; PG8_SCHED;
	s_setprio 1
	s_waitcnt lgkmcnt(0)
	v_mfma_f32_16x16x32_bf16 v[60:63], v[96:99], v[160:163], 0
	v_mfma_f32_16x16x32_bf16 v[56:59], v[120:123], v[160:163], 0
	v_mfma_f32_16x16x32_bf16 v[44:47], v[96:99], v[168:171], 0
	v_mfma_f32_16x16x32_bf16 v[40:43], v[120:123], v[168:171], 0
	v_mfma_f32_16x16x32_bf16 v[28:31], v[96:99], v[176:179], 0
	v_mfma_f32_16x16x32_bf16 v[24:27], v[120:123], v[176:179], 0
	v_mfma_f32_16x16x32_bf16 v[12:15], v[96:99], v[202:205], 0
	v_mfma_f32_16x16x32_bf16 v[8:11], v[120:123], v[202:205], 0
	v_mfma_f32_16x16x32_bf16 v[60:63], v[108:111], v[164:167], v[60:63]
	v_mfma_f32_16x16x32_bf16 v[56:59], v[128:131], v[164:167], v[56:59]
	v_mfma_f32_16x16x32_bf16 v[44:47], v[108:111], v[172:175], v[44:47]
	v_mfma_f32_16x16x32_bf16 v[40:43], v[128:131], v[172:175], v[40:43]
	v_mfma_f32_16x16x32_bf16 v[28:31], v[108:111], v[180:183], v[28:31]
	v_mfma_f32_16x16x32_bf16 v[24:27], v[128:131], v[180:183], v[24:27]
	v_mfma_f32_16x16x32_bf16 v[12:15], v[108:111], v[206:209], v[12:15]
	v_mfma_f32_16x16x32_bf16 v[8:11], v[128:131], v[206:209], v[8:11]
	v_mfma_f32_16x16x32_bf16 v[52:55], v[144:147], v[160:163], 0
	v_mfma_f32_16x16x32_bf16 v[48:51], v[152:155], v[160:163], 0
	v_mfma_f32_16x16x32_bf16 v[36:39], v[144:147], v[168:171], 0
	v_mfma_f32_16x16x32_bf16 v[32:35], v[152:155], v[168:171], 0
	v_mfma_f32_16x16x32_bf16 v[20:23], v[144:147], v[176:179], 0
	v_mfma_f32_16x16x32_bf16 v[16:19], v[152:155], v[176:179], 0
	v_mfma_f32_16x16x32_bf16 v[4:7], v[144:147], v[202:205], 0
	v_mfma_f32_16x16x32_bf16 v[0:3], v[152:155], v[202:205], 0
	v_mfma_f32_16x16x32_bf16 v[52:55], v[148:151], v[164:167], v[52:55]
	v_mfma_f32_16x16x32_bf16 v[48:51], v[156:159], v[164:167], v[48:51]
	v_mfma_f32_16x16x32_bf16 v[36:39], v[148:151], v[172:175], v[36:39]
	v_mfma_f32_16x16x32_bf16 v[32:35], v[156:159], v[172:175], v[32:35]
	v_mfma_f32_16x16x32_bf16 v[20:23], v[148:151], v[180:183], v[20:23]
	v_mfma_f32_16x16x32_bf16 v[16:19], v[156:159], v[180:183], v[16:19]
	v_mfma_f32_16x16x32_bf16 v[4:7], v[148:151], v[206:209], v[4:7]
	v_mfma_f32_16x16x32_bf16 v[0:3], v[156:159], v[206:209], v[0:3]
	s_setprio 0
	s_barrier
	s_add_i32 s76, 0, 0x18000
	s_add_i32 s77, 0, 0x1c000
	v_add_u32_e32 v128, s76, v221
	v_add_u32_e32 v156, s77, v221
	ds_read_b128 v[96:99], v128
	ds_read_b128 v[108:111], v128 offset:1024
	ds_read_b128 v[120:123], v128 offset:2048
	ds_read_b128 v[128:131], v128 offset:3072
	ds_read_b128 v[144:147], v156
	ds_read_b128 v[148:151], v156 offset:1024
	ds_read_b128 v[152:155], v156 offset:2048
	ds_read_b128 v[156:159], v156 offset:3072
	s_add_u32 s50, s50, 0xb0000
	s_addc_u32 s51, s51, 0
	s_mov_b32 m0, s56
	v_lshl_add_u64 v[218:219], s[50:51], 0, v[184:185]
	ds_read_b128 v[160:163], v225 offset:32768
	ds_read_b128 v[164:167], v225 offset:33792
	ds_read_b128 v[168:171], v225 offset:34816
	ds_read_b128 v[172:175], v225 offset:35840
	ds_read_b128 v[176:179], v225 offset:36864
	ds_read_b128 v[180:183], v225 offset:37888
	ds_read_b128 v[202:205], v225 offset:38912
	ds_read_b128 v[206:209], v225 offset:39936
	global_load_lds_dwordx4 v[218:219], off
	v_lshl_add_u64 v[218:219], s[50:51], 0, v[188:189]
	s_mov_b32 m0, s57
	s_nop 0
	global_load_lds_dwordx4 v[218:219], off
	s_waitcnt vmcnt(8)
	s_waitcnt lgkmcnt(0)
	s_barrier
	s_setprio 1
	s_waitcnt lgkmcnt(0)
	v_mfma_f32_16x16x32_bf16 v[140:143], v[96:99], v[160:163], v[140:143]
	v_mfma_f32_16x16x32_bf16 v[136:139], v[120:123], v[160:163], v[136:139]
	v_mfma_f32_16x16x32_bf16 v[116:119], v[96:99], v[168:171], v[116:119]
	v_mfma_f32_16x16x32_bf16 v[112:115], v[120:123], v[168:171], v[112:115]
	v_mfma_f32_16x16x32_bf16 v[92:95], v[96:99], v[176:179], v[92:95]
	v_mfma_f32_16x16x32_bf16 v[88:91], v[120:123], v[176:179], v[88:91]
	v_mfma_f32_16x16x32_bf16 v[76:79], v[96:99], v[202:205], v[76:79]
	v_mfma_f32_16x16x32_bf16 v[72:75], v[120:123], v[202:205], v[72:75]
	v_mfma_f32_16x16x32_bf16 v[140:143], v[108:111], v[164:167], v[140:143]
	v_mfma_f32_16x16x32_bf16 v[136:139], v[128:131], v[164:167], v[136:139]
	v_mfma_f32_16x16x32_bf16 v[116:119], v[108:111], v[172:175], v[116:119]
	v_mfma_f32_16x16x32_bf16 v[112:115], v[128:131], v[172:175], v[112:115]
	v_mfma_f32_16x16x32_bf16 v[92:95], v[108:111], v[180:183], v[92:95]
	v_mfma_f32_16x16x32_bf16 v[88:91], v[128:131], v[180:183], v[88:91]
	v_mfma_f32_16x16x32_bf16 v[76:79], v[108:111], v[206:209], v[76:79]
	v_mfma_f32_16x16x32_bf16 v[72:75], v[128:131], v[206:209], v[72:75]
	v_mfma_f32_16x16x32_bf16 v[132:135], v[144:147], v[160:163], v[132:135]
	v_mfma_f32_16x16x32_bf16 v[124:127], v[152:155], v[160:163], v[124:127]
	v_mfma_f32_16x16x32_bf16 v[104:107], v[144:147], v[168:171], v[104:107]
	v_mfma_f32_16x16x32_bf16 v[100:103], v[152:155], v[168:171], v[100:103]
	v_mfma_f32_16x16x32_bf16 v[84:87], v[144:147], v[176:179], v[84:87]
	v_mfma_f32_16x16x32_bf16 v[80:83], v[152:155], v[176:179], v[80:83]
	v_mfma_f32_16x16x32_bf16 v[68:71], v[144:147], v[202:205], v[68:71]
	v_mfma_f32_16x16x32_bf16 v[64:67], v[152:155], v[202:205], v[64:67]
	v_mfma_f32_16x16x32_bf16 v[132:135], v[148:151], v[164:167], v[132:135]
	v_mfma_f32_16x16x32_bf16 v[124:127], v[156:159], v[164:167], v[124:127]
	v_mfma_f32_16x16x32_bf16 v[104:107], v[148:151], v[172:175], v[104:107]
	v_mfma_f32_16x16x32_bf16 v[100:103], v[156:159], v[172:175], v[100:103]
	v_mfma_f32_16x16x32_bf16 v[84:87], v[148:151], v[180:183], v[84:87]
	v_mfma_f32_16x16x32_bf16 v[80:83], v[156:159], v[180:183], v[80:83]
	v_mfma_f32_16x16x32_bf16 v[68:71], v[148:151], v[206:209], v[68:71]
	v_mfma_f32_16x16x32_bf16 v[64:67], v[156:159], v[206:209], v[64:67]
	s_setprio 0
	s_barrier
; #define PG8_STAGE(bufoff, gbase, voff) do { _Pragma("unroll") for (int _i = 0; _i < 2; ++_i) \
;         __builtin_amdgcn_global_load_lds((const unsigned*)((const char*)(gbase) + (voff)[_i]), (PG8_LAS unsigned*)(lds + (bufoff) + ldsw + _i * 8192), 16, 0, 0); } while (0)
; #define PG8_LDA(dst, b, h) do { _Pragma("unroll") for (int m = 0; m < 4; ++m) _Pragma("unroll") for (int k = 0; k < 2; ++k) dst[m][k] = *(const PG8_LAS bf16x8*)(lds + PG8_SA(b, h) + aoff + m * 2048 + k * 1024); } while (0)
; #define PG8_LDB(dst, b, h) do { _Pragma("unroll") for (int n = 0; n < 2; ++n) _Pragma("unroll") for (int k = 0; k < 2; ++k) dst[n][k] = *(const PG8_LAS bf16x8*)(lds + PG8_SB(b, h) + boff + n * 2048 + k * 1024); } while (0)
; #define PG8_MMA(ai, bj, At, Bt) do { __builtin_amdgcn_s_setprio(1); _Pragma("unroll") for (int m = 0; m < 4; ++m) _Pragma("unroll") for (int n = 0; n < 2; ++n) _Pragma("unroll") for (int k = 0; k < 2; ++k) \
;         acc[ai][bj][m][n] = __builtin_amdgcn_mfma_f32_16x16x32_bf16(Bt[n][k], At[m][k], acc[ai][bj][m][n], 0, 0, 0); __builtin_amdgcn_s_setprio(0); } while (0)
; #define PG8_WAIT_V(n) asm volatile("s_waitcnt vmcnt(" #n ")" ::: "memory")
; template <class Epi, class Sched, bool ALIGN_EPI = false, bool SP2 = false>
; __device__ __forceinline__ void gemm_phase(PG8_LAS unsigned char* lds, const Gemm g, const Sched& S, const Epi& E) {
;     ...
;             PG8_LDB(B0, 0, 0); PG8_LDB(B1, 0, 1); PG8_SCHED; PG8_LDA(At, 0, 0); PG8_STAGE(PG8_SA(1, 1), a1 + hstep, voffA);
;             PG8_WAIT_V(8); PG8_WAIT_L(0); PG8_BAR; PG8_MMA(0, 0, At, B0); PG8_MMA(0, 1, At, B1); PG8_BAR; PG8_SCHED;
;             PG8_LDA(At, 0, 1); PG8_STAGE(PG8_SB(0, 0), b2, voffB); PG8_STAGE(PG8_SB(0, 1), b2 + hstep, voffB); PG8_STAGE(PG8_SA(0, 0), a2, voffA);
;             PG8_WAIT_V(8); PG8_WAIT_L(0); PG8_BAR; PG8_MMA(1, 0, At, B0); PG8_MMA(1, 1, At, B1); PG8_BAR; PG8_SCHED;
;             PG8_LDB(B0, 1, 0); PG8_LDB(B1, 1, 1); PG8_SCHED; PG8_LDA(At, 1, 0); PG8_STAGE(PG8_SA(0, 1), a2 + hstep, voffA);
;             PG8_WAIT_V(8); PG8_WAIT_L(0); PG8_BAR; PG8_MMA(0, 0, At, B0); PG8_MMA(0, 1, At, B1); PG8_BAR; PG8_SCHED;
;             PG8_LDA(At, 1, 1); PG8_STAGE(PG8_SB(1, 0), b3, voffB); PG8_STAGE(PG8_SB(1, 1), b3 + hstep, voffB); PG8_STAGE(PG8_SA(1, 0), a3, voffA);
;             PG8_WAIT_V(8); PG8_WAIT_L(0); PG8_BAR; PG8_MMA(1, 0, At, B0); PG8_MMA(1, 1, At, B1); PG8_BAR; PG8_SCHED;
	s_add_i32 s50, s76, s53
	v_lshl_add_u64 v[210:211], v[210:211], 0, s[12:13]
	s_mov_b32 m0, s50
	ds_read_b128 v[160:163], v225 offset:49152
	ds_read_b128 v[164:167], v225 offset:50176
	ds_read_b128 v[168:171], v225 offset:51200
	ds_read_b128 v[172:175], v225 offset:52224
	ds_read_b128 v[176:179], v225 offset:53248
	ds_read_b128 v[180:183], v225 offset:54272
	ds_read_b128 v[202:205], v225 offset:55296
	ds_read_b128 v[206:209], v225 offset:56320
	global_load_lds_dwordx4 v[210:211], off
	s_add_i32 m0, s50, 0x2000
	s_add_u32 s34, s34, 0xb0080
	v_lshl_add_u64 v[210:211], v[212:213], 0, s[12:13]
	s_addc_u32 s35, s35, 0
	s_add_i32 s50, s77, s53
	global_load_lds_dwordx4 v[210:211], off
	v_lshl_add_u64 v[210:211], s[34:35], 0, v[186:187]
	s_mov_b32 m0, s50
	s_nop 0
	global_load_lds_dwordx4 v[210:211], off
	v_lshl_add_u64 v[210:211], s[34:35], 0, v[190:191]
	s_add_i32 m0, s50, 0x2000
	s_nop 0
	global_load_lds_dwordx4 v[210:211], off
	v_lshl_add_u64 v[210:211], v[214:215], 0, s[12:13]
	s_mov_b32 m0, s62
	s_nop 0
	global_load_lds_dwordx4 v[210:211], off
	v_lshl_add_u64 v[210:211], v[216:217], 0, s[12:13]
	s_mov_b32 m0, s63
	s_nop 0
	global_load_lds_dwordx4 v[210:211], off
	s_waitcnt vmcnt(8)
	s_waitcnt lgkmcnt(0)
	s_barrier
	s_setprio 1
	s_waitcnt lgkmcnt(0)
	v_mfma_f32_16x16x32_bf16 v[60:63], v[96:99], v[160:163], v[60:63]
	v_mfma_f32_16x16x32_bf16 v[56:59], v[120:123], v[160:163], v[56:59]
	v_mfma_f32_16x16x32_bf16 v[44:47], v[96:99], v[168:171], v[44:47]
	v_mfma_f32_16x16x32_bf16 v[40:43], v[120:123], v[168:171], v[40:43]
	v_mfma_f32_16x16x32_bf16 v[28:31], v[96:99], v[176:179], v[28:31]
	v_mfma_f32_16x16x32_bf16 v[24:27], v[120:123], v[176:179], v[24:27]
	v_mfma_f32_16x16x32_bf16 v[12:15], v[96:99], v[202:205], v[12:15]
	v_mfma_f32_16x16x32_bf16 v[8:11], v[120:123], v[202:205], v[8:11]
	v_mfma_f32_16x16x32_bf16 v[60:63], v[108:111], v[164:167], v[60:63]
	v_mfma_f32_16x16x32_bf16 v[56:59], v[128:131], v[164:167], v[56:59]
	v_mfma_f32_16x16x32_bf16 v[44:47], v[108:111], v[172:175], v[44:47]
	v_mfma_f32_16x16x32_bf16 v[40:43], v[128:131], v[172:175], v[40:43]
	v_mfma_f32_16x16x32_bf16 v[28:31], v[108:111], v[180:183], v[28:31]
	v_mfma_f32_16x16x32_bf16 v[24:27], v[128:131], v[180:183], v[24:27]
	v_mfma_f32_16x16x32_bf16 v[12:15], v[108:111], v[206:209], v[12:15]
	v_mfma_f32_16x16x32_bf16 v[8:11], v[128:131], v[206:209], v[8:11]
	v_mfma_f32_16x16x32_bf16 v[52:55], v[144:147], v[160:163], v[52:55]
	v_mfma_f32_16x16x32_bf16 v[48:51], v[152:155], v[160:163], v[48:51]
	v_mfma_f32_16x16x32_bf16 v[36:39], v[144:147], v[168:171], v[36:39]
	v_mfma_f32_16x16x32_bf16 v[32:35], v[152:155], v[168:171], v[32:35]
	v_mfma_f32_16x16x32_bf16 v[20:23], v[144:147], v[176:179], v[20:23]
	v_mfma_f32_16x16x32_bf16 v[16:19], v[152:155], v[176:179], v[16:19]
	v_mfma_f32_16x16x32_bf16 v[4:7], v[144:147], v[202:205], v[4:7]
	v_mfma_f32_16x16x32_bf16 v[0:3], v[152:155], v[202:205], v[0:3]
	v_mfma_f32_16x16x32_bf16 v[52:55], v[148:151], v[164:167], v[52:55]
	v_mfma_f32_16x16x32_bf16 v[48:51], v[156:159], v[164:167], v[48:51]
	v_mfma_f32_16x16x32_bf16 v[36:39], v[148:151], v[172:175], v[36:39]
	v_mfma_f32_16x16x32_bf16 v[32:35], v[156:159], v[172:175], v[32:35]
	v_mfma_f32_16x16x32_bf16 v[20:23], v[148:151], v[180:183], v[20:23]
	v_mfma_f32_16x16x32_bf16 v[16:19], v[156:159], v[180:183], v[16:19]
	v_mfma_f32_16x16x32_bf16 v[4:7], v[148:151], v[206:209], v[4:7]
	v_mfma_f32_16x16x32_bf16 v[0:3], v[156:159], v[206:209], v[0:3]
	s_setprio 0
	s_barrier
	s_add_i32 s75, s75, 2
	s_add_u32 s20, s20, 0x100
	s_addc_u32 s21, s21, 0
	s_add_u32 s73, s73, 0x100
	s_addc_u32 s74, s74, 0
	s_cmp_gt_u32 s75, 41
.LBB0_309:
	ds_read_b128 v[96:99], v223
	ds_read_b128 v[108:111], v223 offset:1024
	ds_read_b128 v[120:123], v223 offset:2048
	ds_read_b128 v[128:131], v223 offset:3072
	ds_read_b128 v[144:147], v224
	ds_read_b128 v[148:151], v224 offset:1024
	ds_read_b128 v[152:155], v224 offset:2048
	ds_read_b128 v[156:159], v224 offset:3072
	s_add_u32 s34, s20, 0xfff50080
	s_addc_u32 s35, s21, -1
	s_cmp_eq_u32 s75, 40
	s_cselect_b32 s51, s1, s35
	s_cselect_b32 s50, s0, s34
	s_cselect_b32 s35, s49, s74
	s_cselect_b32 s34, s48, s73
	v_lshl_add_u64 v[210:211], s[20:21], 0, v[192:193]
	s_add_i32 m0, s54, 0xc000
	ds_read_b128 v[160:163], v225
	ds_read_b128 v[164:167], v225 offset:1024
	ds_read_b128 v[168:171], v225 offset:2048
	ds_read_b128 v[172:175], v225 offset:3072
	ds_read_b128 v[176:179], v225 offset:4096
	ds_read_b128 v[180:183], v225 offset:5120
	ds_read_b128 v[202:205], v225 offset:6144
	ds_read_b128 v[206:209], v225 offset:7168
	global_load_lds_dwordx4 v[210:211], off
	v_lshl_add_u64 v[210:211], s[20:21], 0, v[194:195]
	s_add_i32 m0, s54, 0xe000
	s_nop 0
	global_load_lds_dwordx4 v[210:211], off
	s_waitcnt vmcnt(8)
	s_waitcnt lgkmcnt(0)
	s_barrier
; #define PG8_STAGE(bufoff, gbase, voff) do { _Pragma("unroll") for (int _i = 0; _i < 2; ++_i) \
;         __builtin_amdgcn_global_load_lds((const unsigned*)((const char*)(gbase) + (voff)[_i]), (PG8_LAS unsigned*)(lds + (bufoff) + ldsw + _i * 8192), 16, 0, 0); } while (0)
; #define PG8_LDA(dst, b, h) do { _Pragma("unroll") for (int m = 0; m < 4; ++m) _Pragma("unroll") for (int k = 0; k < 2; ++k) dst[m][k] = *(const PG8_LAS bf16x8*)(lds + PG8_SA(b, h) + aoff + m * 2048 + k * 1024); } while (0)
; #define PG8_MMA(ai, bj, At, Bt) do { __builtin_amdgcn_s_setprio(1); _Pragma("unroll") for (int m = 0; m < 4; ++m) _Pragma("unroll") for (int n = 0; n < 2; ++n) _Pragma("unroll") for (int k = 0; k < 2; ++k) \
;         acc[ai][bj][m][n] = __builtin_amdgcn_mfma_f32_16x16x32_bf16(Bt[n][k], At[m][k], acc[ai][bj][m][n], 0, 0, 0); __builtin_amdgcn_s_setprio(0); } while (0)
; #define PG8_WAIT_V(n) asm volatile("s_waitcnt vmcnt(" #n ")" ::: "memory")
; #define PG8_WAIT_L(n) asm volatile("s_waitcnt lgkmcnt(" #n ")" ::: "memory")
; #define PG8_BAR __builtin_amdgcn_s_barrier()
; #define PG8_SCHED __builtin_amdgcn_sched_barrier(0)
; template <class Epi, class Sched, bool ALIGN_EPI = false, bool SP2 = false>
; __device__ __forceinline__ void gemm_phase(PG8_LAS unsigned char* lds, const Gemm g, const Sched& S, const Epi& E) {
;     ...
;             PG8_WAIT_V(8); PG8_WAIT_L(0); PG8_BAR; PG8_MMA(0, 0, At, B0); PG8_MMA(0, 1, At, B1); PG8_BAR; PG8_SCHED;
;             PG8_LDA(At, 0, 1); PG8_STAGE(PG8_SB(0, 0), b2, voffB); PG8_STAGE(PG8_SB(0, 1), b2 + hstep, voffB); PG8_STAGE(PG8_SA(0, 0), a2, voffA);
;             PG8_WAIT_V(8); PG8_WAIT_L(0); PG8_BAR; PG8_MMA(1, 0, At, B0); PG8_MMA(1, 1, At, B1); PG8_BAR; PG8_SCHED;
	s_setprio 1
	s_waitcnt lgkmcnt(0)
	v_mfma_f32_16x16x32_bf16 v[140:143], v[96:99], v[160:163], v[140:143]
	v_mfma_f32_16x16x32_bf16 v[136:139], v[120:123], v[160:163], v[136:139]
	v_mfma_f32_16x16x32_bf16 v[116:119], v[96:99], v[168:171], v[116:119]
	v_mfma_f32_16x16x32_bf16 v[112:115], v[120:123], v[168:171], v[112:115]
	v_mfma_f32_16x16x32_bf16 v[92:95], v[96:99], v[176:179], v[92:95]
	v_mfma_f32_16x16x32_bf16 v[88:91], v[120:123], v[176:179], v[88:91]
	v_mfma_f32_16x16x32_bf16 v[76:79], v[96:99], v[202:205], v[76:79]
	v_mfma_f32_16x16x32_bf16 v[72:75], v[120:123], v[202:205], v[72:75]
	v_mfma_f32_16x16x32_bf16 v[140:143], v[108:111], v[164:167], v[140:143]
	v_mfma_f32_16x16x32_bf16 v[136:139], v[128:131], v[164:167], v[136:139]
	v_mfma_f32_16x16x32_bf16 v[116:119], v[108:111], v[172:175], v[116:119]
	v_mfma_f32_16x16x32_bf16 v[112:115], v[128:131], v[172:175], v[112:115]
	v_mfma_f32_16x16x32_bf16 v[92:95], v[108:111], v[180:183], v[92:95]
	v_mfma_f32_16x16x32_bf16 v[88:91], v[128:131], v[180:183], v[88:91]
	v_mfma_f32_16x16x32_bf16 v[76:79], v[108:111], v[206:209], v[76:79]
	v_mfma_f32_16x16x32_bf16 v[72:75], v[128:131], v[206:209], v[72:75]
	v_mfma_f32_16x16x32_bf16 v[132:135], v[144:147], v[160:163], v[132:135]
	v_mfma_f32_16x16x32_bf16 v[124:127], v[152:155], v[160:163], v[124:127]
	v_mfma_f32_16x16x32_bf16 v[104:107], v[144:147], v[168:171], v[104:107]
	v_mfma_f32_16x16x32_bf16 v[100:103], v[152:155], v[168:171], v[100:103]
	v_mfma_f32_16x16x32_bf16 v[84:87], v[144:147], v[176:179], v[84:87]
	v_mfma_f32_16x16x32_bf16 v[80:83], v[152:155], v[176:179], v[80:83]
	v_mfma_f32_16x16x32_bf16 v[68:71], v[144:147], v[202:205], v[68:71]
	v_mfma_f32_16x16x32_bf16 v[64:67], v[152:155], v[202:205], v[64:67]
	v_mfma_f32_16x16x32_bf16 v[132:135], v[148:151], v[164:167], v[132:135]
	v_mfma_f32_16x16x32_bf16 v[124:127], v[156:159], v[164:167], v[124:127]
	v_mfma_f32_16x16x32_bf16 v[104:107], v[148:151], v[172:175], v[104:107]
	v_mfma_f32_16x16x32_bf16 v[100:103], v[156:159], v[172:175], v[100:103]
	v_mfma_f32_16x16x32_bf16 v[84:87], v[148:151], v[180:183], v[84:87]
	v_mfma_f32_16x16x32_bf16 v[80:83], v[156:159], v[180:183], v[80:83]
	v_mfma_f32_16x16x32_bf16 v[68:71], v[148:151], v[206:209], v[68:71]
	v_mfma_f32_16x16x32_bf16 v[64:67], v[156:159], v[206:209], v[64:67]
	s_setprio 0
	s_barrier
	s_add_i32 s76, s67, s53
	v_lshl_add_u64 v[210:211], s[34:35], 0, v[186:187]
	s_mov_b32 m0, s76
	ds_read_b128 v[160:163], v225 offset:16384
	ds_read_b128 v[164:167], v225 offset:17408
	ds_read_b128 v[168:171], v225 offset:18432
	ds_read_b128 v[172:175], v225 offset:19456
	ds_read_b128 v[176:179], v225 offset:20480
	ds_read_b128 v[180:183], v225 offset:21504
	ds_read_b128 v[202:205], v225 offset:22528
	ds_read_b128 v[206:209], v225 offset:23552
	global_load_lds_dwordx4 v[210:211], off
	s_add_i32 m0, s76, 0x2000
	s_add_u32 s76, s34, 0xb0000
	v_lshl_add_u64 v[212:213], s[34:35], 0, v[190:191]
	s_addc_u32 s77, s35, 0
	s_add_i32 s78, s68, s53
	global_load_lds_dwordx4 v[212:213], off
	v_lshl_add_u64 v[214:215], s[76:77], 0, v[186:187]
	s_mov_b32 m0, s78
	v_lshl_add_u64 v[216:217], s[50:51], 0, v[188:189]
	global_load_lds_dwordx4 v[214:215], off
	v_lshl_add_u64 v[214:215], s[76:77], 0, v[190:191]
	s_add_i32 m0, s78, 0x2000
	s_nop 0
	global_load_lds_dwordx4 v[214:215], off
	v_lshl_add_u64 v[214:215], s[50:51], 0, v[184:185]
	s_mov_b32 m0, s54
	s_nop 0
	global_load_lds_dwordx4 v[214:215], off
	s_mov_b32 m0, s55
	s_nop 0
	global_load_lds_dwordx4 v[216:217], off
	s_waitcnt vmcnt(8)
	s_waitcnt lgkmcnt(0)
	s_barrier
	s_setprio 1
	s_waitcnt lgkmcnt(0)
	v_mfma_f32_16x16x32_bf16 v[60:63], v[96:99], v[160:163], v[60:63]
	v_mfma_f32_16x16x32_bf16 v[56:59], v[120:123], v[160:163], v[56:59]
	v_mfma_f32_16x16x32_bf16 v[44:47], v[96:99], v[168:171], v[44:47]
	v_mfma_f32_16x16x32_bf16 v[40:43], v[120:123], v[168:171], v[40:43]
	v_mfma_f32_16x16x32_bf16 v[28:31], v[96:99], v[176:179], v[28:31]
	v_mfma_f32_16x16x32_bf16 v[24:27], v[120:123], v[176:179], v[24:27]
	v_mfma_f32_16x16x32_bf16 v[12:15], v[96:99], v[202:205], v[12:15]
	v_mfma_f32_16x16x32_bf16 v[8:11], v[120:123], v[202:205], v[8:11]
	v_mfma_f32_16x16x32_bf16 v[60:63], v[108:111], v[164:167], v[60:63]
	v_mfma_f32_16x16x32_bf16 v[56:59], v[128:131], v[164:167], v[56:59]
	v_mfma_f32_16x16x32_bf16 v[44:47], v[108:111], v[172:175], v[44:47]
	v_mfma_f32_16x16x32_bf16 v[40:43], v[128:131], v[172:175], v[40:43]
	v_mfma_f32_16x16x32_bf16 v[28:31], v[108:111], v[180:183], v[28:31]
	v_mfma_f32_16x16x32_bf16 v[24:27], v[128:131], v[180:183], v[24:27]
	v_mfma_f32_16x16x32_bf16 v[12:15], v[108:111], v[206:209], v[12:15]
	v_mfma_f32_16x16x32_bf16 v[8:11], v[128:131], v[206:209], v[8:11]
	v_mfma_f32_16x16x32_bf16 v[52:55], v[144:147], v[160:163], v[52:55]
	v_mfma_f32_16x16x32_bf16 v[48:51], v[152:155], v[160:163], v[48:51]
	v_mfma_f32_16x16x32_bf16 v[36:39], v[144:147], v[168:171], v[36:39]
	v_mfma_f32_16x16x32_bf16 v[32:35], v[152:155], v[168:171], v[32:35]
	v_mfma_f32_16x16x32_bf16 v[20:23], v[144:147], v[176:179], v[20:23]
	v_mfma_f32_16x16x32_bf16 v[16:19], v[152:155], v[176:179], v[16:19]
	v_mfma_f32_16x16x32_bf16 v[4:7], v[144:147], v[202:205], v[4:7]
	v_mfma_f32_16x16x32_bf16 v[0:3], v[152:155], v[202:205], v[0:3]
	v_mfma_f32_16x16x32_bf16 v[52:55], v[148:151], v[164:167], v[52:55]
	v_mfma_f32_16x16x32_bf16 v[48:51], v[156:159], v[164:167], v[48:51]
	v_mfma_f32_16x16x32_bf16 v[36:39], v[148:151], v[172:175], v[36:39]
	v_mfma_f32_16x16x32_bf16 v[32:35], v[156:159], v[172:175], v[32:35]
	v_mfma_f32_16x16x32_bf16 v[20:23], v[148:151], v[180:183], v[20:23]
	v_mfma_f32_16x16x32_bf16 v[16:19], v[156:159], v[180:183], v[16:19]
	v_mfma_f32_16x16x32_bf16 v[4:7], v[148:151], v[206:209], v[4:7]
	v_mfma_f32_16x16x32_bf16 v[0:3], v[156:159], v[206:209], v[0:3]
	s_setprio 0
	s_barrier
; #define PG8_STAGE(bufoff, gbase, voff) do { _Pragma("unroll") for (int _i = 0; _i < 2; ++_i) \
;         __builtin_amdgcn_global_load_lds((const unsigned*)((const char*)(gbase) + (voff)[_i]), (PG8_LAS unsigned*)(lds + (bufoff) + ldsw + _i * 8192), 16, 0, 0); } while (0)
; #define PG8_LDA(dst, b, h) do { _Pragma("unroll") for (int m = 0; m < 4; ++m) _Pragma("unroll") for (int k = 0; k < 2; ++k) dst[m][k] = *(const PG8_LAS bf16x8*)(lds + PG8_SA(b, h) + aoff + m * 2048 + k * 1024); } while (0)
; #define PG8_LDB(dst, b, h) do { _Pragma("unroll") for (int n = 0; n < 2; ++n) _Pragma("unroll") for (int k = 0; k < 2; ++k) dst[n][k] = *(const PG8_LAS bf16x8*)(lds + PG8_SB(b, h) + boff + n * 2048 + k * 1024); } while (0)
; #define PG8_MMA(ai, bj, At, Bt) do { __builtin_amdgcn_s_setprio(1); _Pragma("unroll") for (int m = 0; m < 4; ++m) _Pragma("unroll") for (int n = 0; n < 2; ++n) _Pragma("unroll") for (int k = 0; k < 2; ++k) \
;         acc[ai][bj][m][n] = __builtin_amdgcn_mfma_f32_16x16x32_bf16(Bt[n][k], At[m][k], acc[ai][bj][m][n], 0, 0, 0); __builtin_amdgcn_s_setprio(0); } while (0)
; #define PG8_WAIT_V(n) asm volatile("s_waitcnt vmcnt(" #n ")" ::: "memory")
; #define PG8_WAIT_L(n) asm volatile("s_waitcnt lgkmcnt(" #n ")" ::: "memory")
; #define PG8_BAR __builtin_amdgcn_s_barrier()
; #define PG8_SCHED __builtin_amdgcn_sched_barrier(0)
; template <class Epi, class Sched, bool ALIGN_EPI = false, bool SP2 = false>
; __device__ __forceinline__ void gemm_phase(PG8_LAS unsigned char* lds, const Gemm g, const Sched& S, const Epi& E) {
;     ...
;             PG8_LDB(B0, 1, 0); PG8_LDB(B1, 1, 1); PG8_SCHED; PG8_LDA(At, 1, 0); PG8_STAGE(PG8_SA(0, 1), a2 + hstep, voffA);
;             PG8_WAIT_V(8); PG8_WAIT_L(0); PG8_BAR; PG8_MMA(0, 0, At, B0); PG8_MMA(0, 1, At, B1); PG8_BAR; PG8_SCHED;
	s_add_i32 s76, 0, 0x18000
	s_add_i32 s77, 0, 0x1c000
	v_add_u32_e32 v128, s76, v221
	v_add_u32_e32 v156, s77, v221
	ds_read_b128 v[96:99], v128
	ds_read_b128 v[108:111], v128 offset:1024
	ds_read_b128 v[120:123], v128 offset:2048
	ds_read_b128 v[128:131], v128 offset:3072
	ds_read_b128 v[144:147], v156
	ds_read_b128 v[148:151], v156 offset:1024
	ds_read_b128 v[152:155], v156 offset:2048
	ds_read_b128 v[156:159], v156 offset:3072
	s_add_u32 s50, s50, 0xb0000
	s_addc_u32 s51, s51, 0
	s_mov_b32 m0, s56
	v_lshl_add_u64 v[218:219], s[50:51], 0, v[184:185]
	ds_read_b128 v[160:163], v225 offset:32768
	ds_read_b128 v[164:167], v225 offset:33792
	ds_read_b128 v[168:171], v225 offset:34816
	ds_read_b128 v[172:175], v225 offset:35840
	ds_read_b128 v[176:179], v225 offset:36864
	ds_read_b128 v[180:183], v225 offset:37888
	ds_read_b128 v[202:205], v225 offset:38912
	ds_read_b128 v[206:209], v225 offset:39936
	global_load_lds_dwordx4 v[218:219], off
	v_lshl_add_u64 v[218:219], s[50:51], 0, v[188:189]
	s_mov_b32 m0, s57
	s_nop 0
	global_load_lds_dwordx4 v[218:219], off
	s_waitcnt vmcnt(8)
	s_waitcnt lgkmcnt(0)
	s_barrier
	s_setprio 1
	s_waitcnt lgkmcnt(0)
	v_mfma_f32_16x16x32_bf16 v[140:143], v[96:99], v[160:163], v[140:143]
	v_mfma_f32_16x16x32_bf16 v[136:139], v[120:123], v[160:163], v[136:139]
	v_mfma_f32_16x16x32_bf16 v[116:119], v[96:99], v[168:171], v[116:119]
	v_mfma_f32_16x16x32_bf16 v[112:115], v[120:123], v[168:171], v[112:115]
	v_mfma_f32_16x16x32_bf16 v[92:95], v[96:99], v[176:179], v[92:95]
	v_mfma_f32_16x16x32_bf16 v[88:91], v[120:123], v[176:179], v[88:91]
	v_mfma_f32_16x16x32_bf16 v[76:79], v[96:99], v[202:205], v[76:79]
	v_mfma_f32_16x16x32_bf16 v[72:75], v[120:123], v[202:205], v[72:75]
	v_mfma_f32_16x16x32_bf16 v[140:143], v[108:111], v[164:167], v[140:143]
	v_mfma_f32_16x16x32_bf16 v[136:139], v[128:131], v[164:167], v[136:139]
	v_mfma_f32_16x16x32_bf16 v[116:119], v[108:111], v[172:175], v[116:119]
	v_mfma_f32_16x16x32_bf16 v[112:115], v[128:131], v[172:175], v[112:115]
	v_mfma_f32_16x16x32_bf16 v[92:95], v[108:111], v[180:183], v[92:95]
	v_mfma_f32_16x16x32_bf16 v[88:91], v[128:131], v[180:183], v[88:91]
	v_mfma_f32_16x16x32_bf16 v[76:79], v[108:111], v[206:209], v[76:79]
	v_mfma_f32_16x16x32_bf16 v[72:75], v[128:131], v[206:209], v[72:75]
	v_mfma_f32_16x16x32_bf16 v[132:135], v[144:147], v[160:163], v[132:135]
	v_mfma_f32_16x16x32_bf16 v[124:127], v[152:155], v[160:163], v[124:127]
	v_mfma_f32_16x16x32_bf16 v[104:107], v[144:147], v[168:171], v[104:107]
	v_mfma_f32_16x16x32_bf16 v[100:103], v[152:155], v[168:171], v[100:103]
	v_mfma_f32_16x16x32_bf16 v[84:87], v[144:147], v[176:179], v[84:87]
	v_mfma_f32_16x16x32_bf16 v[80:83], v[152:155], v[176:179], v[80:83]
	v_mfma_f32_16x16x32_bf16 v[68:71], v[144:147], v[202:205], v[68:71]
	v_mfma_f32_16x16x32_bf16 v[64:67], v[152:155], v[202:205], v[64:67]
	v_mfma_f32_16x16x32_bf16 v[132:135], v[148:151], v[164:167], v[132:135]
	v_mfma_f32_16x16x32_bf16 v[124:127], v[156:159], v[164:167], v[124:127]
	v_mfma_f32_16x16x32_bf16 v[104:107], v[148:151], v[172:175], v[104:107]
	v_mfma_f32_16x16x32_bf16 v[100:103], v[156:159], v[172:175], v[100:103]
	v_mfma_f32_16x16x32_bf16 v[84:87], v[148:151], v[180:183], v[84:87]
	v_mfma_f32_16x16x32_bf16 v[80:83], v[156:159], v[180:183], v[80:83]
	v_mfma_f32_16x16x32_bf16 v[68:71], v[148:151], v[206:209], v[68:71]
	v_mfma_f32_16x16x32_bf16 v[64:67], v[156:159], v[206:209], v[64:67]
	s_setprio 0
	s_barrier
; #define PG8_STAGE(bufoff, gbase, voff) do { _Pragma("unroll") for (int _i = 0; _i < 2; ++_i) \
;         __builtin_amdgcn_global_load_lds((const unsigned*)((const char*)(gbase) + (voff)[_i]), (PG8_LAS unsigned*)(lds + (bufoff) + ldsw + _i * 8192), 16, 0, 0); } while (0)
; #define PG8_LDA(dst, b, h) do { _Pragma("unroll") for (int m = 0; m < 4; ++m) _Pragma("unroll") for (int k = 0; k < 2; ++k) dst[m][k] = *(const PG8_LAS bf16x8*)(lds + PG8_SA(b, h) + aoff + m * 2048 + k * 1024); } while (0)
; #define PG8_MMA(ai, bj, At, Bt) do { __builtin_amdgcn_s_setprio(1); _Pragma("unroll") for (int m = 0; m < 4; ++m) _Pragma("unroll") for (int n = 0; n < 2; ++n) _Pragma("unroll") for (int k = 0; k < 2; ++k) \
;         acc[ai][bj][m][n] = __builtin_amdgcn_mfma_f32_16x16x32_bf16(Bt[n][k], At[m][k], acc[ai][bj][m][n], 0, 0, 0); __builtin_amdgcn_s_setprio(0); } while (0)
; #define PG8_WAIT_V(n) asm volatile("s_waitcnt vmcnt(" #n ")" ::: "memory")
; #define PG8_WAIT_L(n) asm volatile("s_waitcnt lgkmcnt(" #n ")" ::: "memory")
; #define PG8_BAR __builtin_amdgcn_s_barrier()
; #define PG8_SCHED __builtin_amdgcn_sched_barrier(0)
; template <class Epi, class Sched, bool ALIGN_EPI = false, bool SP2 = false>
; __device__ __forceinline__ void gemm_phase(PG8_LAS unsigned char* lds, const Gemm g, const Sched& S, const Epi& E) {
;     ...
;             PG8_LDA(At, 1, 1); PG8_STAGE(PG8_SB(1, 0), b3, voffB); PG8_STAGE(PG8_SB(1, 1), b3 + hstep, voffB); PG8_STAGE(PG8_SA(1, 0), a3, voffA);
;             PG8_WAIT_V(8); PG8_WAIT_L(0); PG8_BAR; PG8_MMA(1, 0, At, B0); PG8_MMA(1, 1, At, B1); PG8_BAR; PG8_SCHED;
;     ...
;         if constexpr (ALIGN_EPI) { if (wr == 0) PG8_BAR; }
	s_add_i32 s50, s76, s53
	v_lshl_add_u64 v[210:211], v[210:211], 0, s[12:13]
	s_mov_b32 m0, s50
	ds_read_b128 v[160:163], v225 offset:49152
	ds_read_b128 v[164:167], v225 offset:50176
	ds_read_b128 v[168:171], v225 offset:51200
	ds_read_b128 v[172:175], v225 offset:52224
	ds_read_b128 v[176:179], v225 offset:53248
	ds_read_b128 v[180:183], v225 offset:54272
	ds_read_b128 v[202:205], v225 offset:55296
	ds_read_b128 v[206:209], v225 offset:56320
	global_load_lds_dwordx4 v[210:211], off
	s_add_i32 m0, s50, 0x2000
	s_add_u32 s34, s34, 0xb0080
	v_lshl_add_u64 v[210:211], v[212:213], 0, s[12:13]
	s_addc_u32 s35, s35, 0
	s_add_i32 s50, s77, s53
	global_load_lds_dwordx4 v[210:211], off
	v_lshl_add_u64 v[210:211], s[34:35], 0, v[186:187]
	s_mov_b32 m0, s50
	s_nop 0
	global_load_lds_dwordx4 v[210:211], off
	v_lshl_add_u64 v[210:211], s[34:35], 0, v[190:191]
	s_add_i32 m0, s50, 0x2000
	s_nop 0
	global_load_lds_dwordx4 v[210:211], off
	v_lshl_add_u64 v[210:211], v[214:215], 0, s[12:13]
	s_mov_b32 m0, s62
	s_nop 0
	global_load_lds_dwordx4 v[210:211], off
	v_lshl_add_u64 v[210:211], v[216:217], 0, s[12:13]
	s_mov_b32 m0, s63
	s_nop 0
	global_load_lds_dwordx4 v[210:211], off
	s_waitcnt vmcnt(8)
	s_waitcnt lgkmcnt(0)
	s_barrier
	s_setprio 1
	s_waitcnt lgkmcnt(0)
	v_mfma_f32_16x16x32_bf16 v[60:63], v[96:99], v[160:163], v[60:63]
	v_mfma_f32_16x16x32_bf16 v[56:59], v[120:123], v[160:163], v[56:59]
	v_mfma_f32_16x16x32_bf16 v[44:47], v[96:99], v[168:171], v[44:47]
	v_mfma_f32_16x16x32_bf16 v[40:43], v[120:123], v[168:171], v[40:43]
	v_mfma_f32_16x16x32_bf16 v[28:31], v[96:99], v[176:179], v[28:31]
	v_mfma_f32_16x16x32_bf16 v[24:27], v[120:123], v[176:179], v[24:27]
	v_mfma_f32_16x16x32_bf16 v[12:15], v[96:99], v[202:205], v[12:15]
	v_mfma_f32_16x16x32_bf16 v[8:11], v[120:123], v[202:205], v[8:11]
	v_mfma_f32_16x16x32_bf16 v[60:63], v[108:111], v[164:167], v[60:63]
	v_mfma_f32_16x16x32_bf16 v[56:59], v[128:131], v[164:167], v[56:59]
	v_mfma_f32_16x16x32_bf16 v[44:47], v[108:111], v[172:175], v[44:47]
	v_mfma_f32_16x16x32_bf16 v[40:43], v[128:131], v[172:175], v[40:43]
	v_mfma_f32_16x16x32_bf16 v[28:31], v[108:111], v[180:183], v[28:31]
	v_mfma_f32_16x16x32_bf16 v[24:27], v[128:131], v[180:183], v[24:27]
	v_mfma_f32_16x16x32_bf16 v[12:15], v[108:111], v[206:209], v[12:15]
	v_mfma_f32_16x16x32_bf16 v[8:11], v[128:131], v[206:209], v[8:11]
	v_mfma_f32_16x16x32_bf16 v[52:55], v[144:147], v[160:163], v[52:55]
	v_mfma_f32_16x16x32_bf16 v[48:51], v[152:155], v[160:163], v[48:51]
	v_mfma_f32_16x16x32_bf16 v[36:39], v[144:147], v[168:171], v[36:39]
	v_mfma_f32_16x16x32_bf16 v[32:35], v[152:155], v[168:171], v[32:35]
	v_mfma_f32_16x16x32_bf16 v[20:23], v[144:147], v[176:179], v[20:23]
	v_mfma_f32_16x16x32_bf16 v[16:19], v[152:155], v[176:179], v[16:19]
	v_mfma_f32_16x16x32_bf16 v[4:7], v[144:147], v[202:205], v[4:7]
	v_mfma_f32_16x16x32_bf16 v[0:3], v[152:155], v[202:205], v[0:3]
	v_mfma_f32_16x16x32_bf16 v[52:55], v[148:151], v[164:167], v[52:55]
	v_mfma_f32_16x16x32_bf16 v[48:51], v[156:159], v[164:167], v[48:51]
	v_mfma_f32_16x16x32_bf16 v[36:39], v[148:151], v[172:175], v[36:39]
	v_mfma_f32_16x16x32_bf16 v[32:35], v[156:159], v[172:175], v[32:35]
	v_mfma_f32_16x16x32_bf16 v[20:23], v[148:151], v[180:183], v[20:23]
	v_mfma_f32_16x16x32_bf16 v[16:19], v[156:159], v[180:183], v[16:19]
	v_mfma_f32_16x16x32_bf16 v[4:7], v[148:151], v[206:209], v[4:7]
	v_mfma_f32_16x16x32_bf16 v[0:3], v[156:159], v[206:209], v[0:3]
	s_setprio 0
	s_barrier
	s_add_i32 s75, s75, 2
	s_add_u32 s20, s20, 0x100
	s_addc_u32 s21, s21, 0
	s_add_u32 s73, s73, 0x100
	s_addc_u32 s74, s74, 0
	s_cmp_gt_u32 s75, 41
	s_cbranch_scc0 .LBB0_309
	s_and_b64 vcc, exec, s[14:15]
	s_cbranch_vccz .LBB0_312
	s_barrier

; #define PG8_STAGE(bufoff, gbase, voff) do { _Pragma("unroll") for (int _i = 0; _i < 2; ++_i) \
;         __builtin_amdgcn_global_load_lds((const unsigned*)((const char*)(gbase) + (voff)[_i]), (PG8_LAS unsigned*)(lds + (bufoff) + ldsw + _i * 8192), 16, 0, 0); } while (0)
; #define PG8_LDA(dst, b, h) do { _Pragma("unroll") for (int m = 0; m < 4; ++m) _Pragma("unroll") for (int k = 0; k < 2; ++k) dst[m][k] = *(const PG8_LAS bf16x8*)(lds + PG8_SA(b, h) + aoff + m * 2048 + k * 1024); } while (0)
; #define PG8_LDB(dst, b, h) do { _Pragma("unroll") for (int n = 0; n < 2; ++n) _Pragma("unroll") for (int k = 0; k < 2; ++k) dst[n][k] = *(const PG8_LAS bf16x8*)(lds + PG8_SB(b, h) + boff + n * 2048 + k * 1024); } while (0)
; #define PG8_WAIT_V(n) asm volatile("s_waitcnt vmcnt(" #n ")" ::: "memory")
; #define PG8_WAIT_L(n) asm volatile("s_waitcnt lgkmcnt(" #n ")" ::: "memory")
; #define PG8_BAR __builtin_amdgcn_s_barrier()
; #define PG8_SCHED __builtin_amdgcn_sched_barrier(0)
; template <class Epi, class Sched, bool ALIGN_EPI = false, bool SP2 = false>
; __device__ __forceinline__ void gemm_phase(PG8_LAS unsigned char* lds, const Gemm g, const Sched& S, const Epi& E) {
;     ...
;         const bool has_next = S.next(ui + 1, nxt);
;         const char* nA = has_next ? (const char*)g.A + (size_t)nxt.pm * tstep : cA; const char* nB = has_next ? (const char*)g.Bt + (size_t)nxt.pn * tstep : cB;
;         for (int t = 0; t < nt; t += 2) {
;             const bool last = (t == nt - 2);
;             const char* a1 = cA + (size_t)(t + 1) * kstep;
;             const char* a2 = last ? nA : cA + (size_t)(t + 2) * kstep; const char* b2 = last ? nB : cB + (size_t)(t + 2) * kstep;
;             const char* a3 = a2 + kstep; const char* b3 = b2 + kstep;
;             if (last && has_next) S.a_ready(nxt);
;             if constexpr (SP2) {
;             PG8_LDB(B0, 0, 0); PG8_LDB(B1, 0, 1); PG8_SCHED; PG8_LDA(At, 0, 0); PG8_STAGE(PG8_SA(1, 1), a1 + hstep, voffA);
;             PG8_WAIT_V(8); PG8_WAIT_L(0); PG8_BAR; PG8_MMA(0, 0, At, B0); PG8_MMA(0, 1, At, B1); PG8_BAR; PG8_SCHED;
;             PG8_LDA(At, 0, 1); PG8_STAGE(PG8_SB(0, 0), b2, voffB); PG8_STAGE(PG8_SB(0, 1), b2 + hstep, voffB); PG8_STAGE(PG8_SA(0, 0), a2, voffA);
;             PG8_WAIT_V(8); PG8_WAIT_L(0); PG8_BAR; PG8_MMA(1, 0, At, B0); PG8_MMA(1, 1, At, B1); PG8_BAR; PG8_SCHED;
.LBB0_413:
	s_ashr_i32 s43, s42, 31
	s_lshl_b64 s[48:49], s[42:43], 19
	s_add_u32 s48, s36, s48
	s_addc_u32 s49, s37, s49
	s_and_b64 s[50:51], s[4:5], exec
	s_cselect_b32 s43, s49, s21
	s_cselect_b32 s78, s48, s20
	s_ashr_i32 s19, s18, 31
	s_lshl_b64 s[50:51], s[18:19], 19
	s_add_u32 s50, s61, s50
	s_addc_u32 s51, s62, s51
	s_and_b64 s[54:55], s[4:5], exec
	s_cselect_b32 s19, s51, s53
	s_cselect_b32 s79, s50, s52
	s_add_u32 s20, s20, 0x40080
	s_addc_u32 s21, s21, 0
	s_add_u32 s80, s52, 0x100
	s_addc_u32 s81, s53, 0
	s_mov_b32 s84, -2
	ds_read_b128 v[146:149], v165
	ds_read_b128 v[150:153], v165 offset:1024
	ds_read_b128 v[154:157], v165 offset:2048
	ds_read_b128 v[168:171], v165 offset:3072
	ds_read_b128 v[172:175], v166
	ds_read_b128 v[176:179], v166 offset:1024
	ds_read_b128 v[180:183], v166 offset:2048
	ds_read_b128 v[184:187], v166 offset:3072
	s_add_u32 s52, s20, 0xfffc0080
	s_addc_u32 s53, s21, -1
	s_cmp_eq_u32 s84, 12
	s_cselect_b32 s55, s43, s53
	s_cselect_b32 s54, s78, s52
	s_cselect_b32 s53, s19, s81
	s_cselect_b32 s52, s79, s80
	v_lshl_add_u64 v[158:159], s[20:21], 0, v[138:139]
	s_add_i32 m0, s35, 0xc000
	ds_read_b128 v[188:191], v167
	ds_read_b128 v[192:195], v167 offset:1024
	ds_read_b128 v[198:201], v167 offset:2048
	ds_read_b128 v[202:205], v167 offset:3072
	ds_read_b128 v[206:209], v167 offset:4096
	ds_read_b128 v[210:213], v167 offset:5120
	ds_read_b128 v[214:217], v167 offset:6144
	ds_read_b128 v[218:221], v167 offset:7168
	global_load_lds_dwordx4 v[158:159], off
	v_lshl_add_u64 v[158:159], s[20:21], 0, v[140:141]
	s_add_i32 m0, s35, 0xe000
	s_nop 0
	global_load_lds_dwordx4 v[158:159], off
	s_waitcnt vmcnt(8)
	s_waitcnt lgkmcnt(0)
	s_barrier
	s_setprio 1
	s_waitcnt lgkmcnt(0)
	v_mfma_f32_16x16x32_bf16 v[124:127], v[146:149], v[188:191], 0
	v_mfma_f32_16x16x32_bf16 v[120:123], v[154:157], v[188:191], 0
	v_mfma_f32_16x16x32_bf16 v[108:111], v[146:149], v[198:201], 0
	v_mfma_f32_16x16x32_bf16 v[104:107], v[154:157], v[198:201], 0
	v_mfma_f32_16x16x32_bf16 v[92:95], v[146:149], v[206:209], 0
	v_mfma_f32_16x16x32_bf16 v[88:91], v[154:157], v[206:209], 0
	v_mfma_f32_16x16x32_bf16 v[76:79], v[146:149], v[214:217], 0
	v_mfma_f32_16x16x32_bf16 v[72:75], v[154:157], v[214:217], 0
	v_mfma_f32_16x16x32_bf16 v[124:127], v[150:153], v[192:195], v[124:127]
	v_mfma_f32_16x16x32_bf16 v[120:123], v[168:171], v[192:195], v[120:123]
	v_mfma_f32_16x16x32_bf16 v[108:111], v[150:153], v[202:205], v[108:111]
	v_mfma_f32_16x16x32_bf16 v[104:107], v[168:171], v[202:205], v[104:107]
	v_mfma_f32_16x16x32_bf16 v[92:95], v[150:153], v[210:213], v[92:95]
	v_mfma_f32_16x16x32_bf16 v[88:91], v[168:171], v[210:213], v[88:91]
	v_mfma_f32_16x16x32_bf16 v[76:79], v[150:153], v[218:221], v[76:79]
	v_mfma_f32_16x16x32_bf16 v[72:75], v[168:171], v[218:221], v[72:75]
	v_mfma_f32_16x16x32_bf16 v[116:119], v[172:175], v[188:191], 0
	v_mfma_f32_16x16x32_bf16 v[112:115], v[180:183], v[188:191], 0
	v_mfma_f32_16x16x32_bf16 v[100:103], v[172:175], v[198:201], 0
	v_mfma_f32_16x16x32_bf16 v[96:99], v[180:183], v[198:201], 0
	v_mfma_f32_16x16x32_bf16 v[84:87], v[172:175], v[206:209], 0
	v_mfma_f32_16x16x32_bf16 v[80:83], v[180:183], v[206:209], 0
	v_mfma_f32_16x16x32_bf16 v[68:71], v[172:175], v[214:217], 0
	v_mfma_f32_16x16x32_bf16 v[64:67], v[180:183], v[214:217], 0
	v_mfma_f32_16x16x32_bf16 v[116:119], v[176:179], v[192:195], v[116:119]
	v_mfma_f32_16x16x32_bf16 v[112:115], v[184:187], v[192:195], v[112:115]
	v_mfma_f32_16x16x32_bf16 v[100:103], v[176:179], v[202:205], v[100:103]
	v_mfma_f32_16x16x32_bf16 v[96:99], v[184:187], v[202:205], v[96:99]
	v_mfma_f32_16x16x32_bf16 v[84:87], v[176:179], v[210:213], v[84:87]
	v_mfma_f32_16x16x32_bf16 v[80:83], v[184:187], v[210:213], v[80:83]
	v_mfma_f32_16x16x32_bf16 v[68:71], v[176:179], v[218:221], v[68:71]
	v_mfma_f32_16x16x32_bf16 v[64:67], v[184:187], v[218:221], v[64:67]
	s_setprio 0
	s_barrier
	s_add_i32 s85, s72, s63
	v_lshl_add_u64 v[158:159], s[52:53], 0, v[132:133]
	s_mov_b32 m0, s85
	ds_read_b128 v[188:191], v167 offset:16384
	ds_read_b128 v[192:195], v167 offset:17408
	ds_read_b128 v[198:201], v167 offset:18432
	ds_read_b128 v[202:205], v167 offset:19456
	ds_read_b128 v[206:209], v167 offset:20480
	ds_read_b128 v[210:213], v167 offset:21504
	ds_read_b128 v[214:217], v167 offset:22528
	ds_read_b128 v[218:221], v167 offset:23552
	global_load_lds_dwordx4 v[158:159], off
	s_add_i32 m0, s85, 0x2000
	s_add_u32 s86, s52, 0x40000
	v_lshl_add_u64 v[222:223], s[52:53], 0, v[128:129]
	s_addc_u32 s87, s53, 0
	s_add_i32 s85, s73, s63
	global_load_lds_dwordx4 v[222:223], off
	v_lshl_add_u64 v[224:225], s[86:87], 0, v[132:133]
	s_mov_b32 m0, s85
	v_lshl_add_u64 v[226:227], s[54:55], 0, v[130:131]
	global_load_lds_dwordx4 v[224:225], off
	v_lshl_add_u64 v[224:225], s[86:87], 0, v[128:129]
	s_add_i32 m0, s85, 0x2000
	s_nop 0
	global_load_lds_dwordx4 v[224:225], off
	v_lshl_add_u64 v[224:225], s[54:55], 0, v[134:135]
	s_mov_b32 m0, s35
	s_nop 0
	global_load_lds_dwordx4 v[224:225], off
	s_mov_b32 m0, s65
	s_nop 0
	global_load_lds_dwordx4 v[226:227], off
	s_waitcnt vmcnt(8)
	s_waitcnt lgkmcnt(0)
	s_barrier
; #define PG8_STAGE(bufoff, gbase, voff) do { _Pragma("unroll") for (int _i = 0; _i < 2; ++_i) \
;         __builtin_amdgcn_global_load_lds((const unsigned*)((const char*)(gbase) + (voff)[_i]), (PG8_LAS unsigned*)(lds + (bufoff) + ldsw + _i * 8192), 16, 0, 0); } while (0)
; #define PG8_LDA(dst, b, h) do { _Pragma("unroll") for (int m = 0; m < 4; ++m) _Pragma("unroll") for (int k = 0; k < 2; ++k) dst[m][k] = *(const PG8_LAS bf16x8*)(lds + PG8_SA(b, h) + aoff + m * 2048 + k * 1024); } while (0)
; #define PG8_LDB(dst, b, h) do { _Pragma("unroll") for (int n = 0; n < 2; ++n) _Pragma("unroll") for (int k = 0; k < 2; ++k) dst[n][k] = *(const PG8_LAS bf16x8*)(lds + PG8_SB(b, h) + boff + n * 2048 + k * 1024); } while (0)
; #define PG8_MMA(ai, bj, At, Bt) do { __builtin_amdgcn_s_setprio(1); _Pragma("unroll") for (int m = 0; m < 4; ++m) _Pragma("unroll") for (int n = 0; n < 2; ++n) _Pragma("unroll") for (int k = 0; k < 2; ++k) \
;         acc[ai][bj][m][n] = __builtin_amdgcn_mfma_f32_16x16x32_bf16(Bt[n][k], At[m][k], acc[ai][bj][m][n], 0, 0, 0); __builtin_amdgcn_s_setprio(0); } while (0)
; #define PG8_WAIT_V(n) asm volatile("s_waitcnt vmcnt(" #n ")" ::: "memory")
; #define PG8_WAIT_L(n) asm volatile("s_waitcnt lgkmcnt(" #n ")" ::: "memory")
; #define PG8_BAR __builtin_amdgcn_s_barrier()
; #define PG8_SCHED __builtin_amdgcn_sched_barrier(0)
; template <class Epi, class Sched, bool ALIGN_EPI = false, bool SP2 = false>
; __device__ __forceinline__ void gemm_phase(PG8_LAS unsigned char* lds, const Gemm g, const Sched& S, const Epi& E) {
;     ...
;             PG8_WAIT_V(8); PG8_WAIT_L(0); PG8_BAR; PG8_MMA(1, 0, At, B0); PG8_MMA(1, 1, At, B1); PG8_BAR; PG8_SCHED;
;             PG8_LDB(B0, 1, 0); PG8_LDB(B1, 1, 1); PG8_SCHED; PG8_LDA(At, 1, 0); PG8_STAGE(PG8_SA(0, 1), a2 + hstep, voffA);
;             PG8_WAIT_V(8); PG8_WAIT_L(0); PG8_BAR; PG8_MMA(0, 0, At, B0); PG8_MMA(0, 1, At, B1); PG8_BAR; PG8_SCHED;
	s_setprio 1
	s_waitcnt lgkmcnt(0)
	v_mfma_f32_16x16x32_bf16 v[60:63], v[146:149], v[188:191], 0
	v_mfma_f32_16x16x32_bf16 v[56:59], v[154:157], v[188:191], 0
	v_mfma_f32_16x16x32_bf16 v[44:47], v[146:149], v[198:201], 0
	v_mfma_f32_16x16x32_bf16 v[40:43], v[154:157], v[198:201], 0
	v_mfma_f32_16x16x32_bf16 v[28:31], v[146:149], v[206:209], 0
	v_mfma_f32_16x16x32_bf16 v[24:27], v[154:157], v[206:209], 0
	v_mfma_f32_16x16x32_bf16 v[12:15], v[146:149], v[214:217], 0
	v_mfma_f32_16x16x32_bf16 v[8:11], v[154:157], v[214:217], 0
	v_mfma_f32_16x16x32_bf16 v[60:63], v[150:153], v[192:195], v[60:63]
	v_mfma_f32_16x16x32_bf16 v[56:59], v[168:171], v[192:195], v[56:59]
	v_mfma_f32_16x16x32_bf16 v[44:47], v[150:153], v[202:205], v[44:47]
	v_mfma_f32_16x16x32_bf16 v[40:43], v[168:171], v[202:205], v[40:43]
	v_mfma_f32_16x16x32_bf16 v[28:31], v[150:153], v[210:213], v[28:31]
	v_mfma_f32_16x16x32_bf16 v[24:27], v[168:171], v[210:213], v[24:27]
	v_mfma_f32_16x16x32_bf16 v[12:15], v[150:153], v[218:221], v[12:15]
	v_mfma_f32_16x16x32_bf16 v[8:11], v[168:171], v[218:221], v[8:11]
	v_mfma_f32_16x16x32_bf16 v[52:55], v[172:175], v[188:191], 0
	v_mfma_f32_16x16x32_bf16 v[48:51], v[180:183], v[188:191], 0
	v_mfma_f32_16x16x32_bf16 v[36:39], v[172:175], v[198:201], 0
	v_mfma_f32_16x16x32_bf16 v[32:35], v[180:183], v[198:201], 0
	v_mfma_f32_16x16x32_bf16 v[20:23], v[172:175], v[206:209], 0
	v_mfma_f32_16x16x32_bf16 v[16:19], v[180:183], v[206:209], 0
	v_mfma_f32_16x16x32_bf16 v[4:7], v[172:175], v[214:217], 0
	v_mfma_f32_16x16x32_bf16 v[0:3], v[180:183], v[214:217], 0
	v_mfma_f32_16x16x32_bf16 v[52:55], v[176:179], v[192:195], v[52:55]
	v_mfma_f32_16x16x32_bf16 v[48:51], v[184:187], v[192:195], v[48:51]
	v_mfma_f32_16x16x32_bf16 v[36:39], v[176:179], v[202:205], v[36:39]
	v_mfma_f32_16x16x32_bf16 v[32:35], v[184:187], v[202:205], v[32:35]
	v_mfma_f32_16x16x32_bf16 v[20:23], v[176:179], v[210:213], v[20:23]
	v_mfma_f32_16x16x32_bf16 v[16:19], v[184:187], v[210:213], v[16:19]
	v_mfma_f32_16x16x32_bf16 v[4:7], v[176:179], v[218:221], v[4:7]
	v_mfma_f32_16x16x32_bf16 v[0:3], v[184:187], v[218:221], v[0:3]
	s_setprio 0
	s_barrier
	s_add_i32 s85, 0, 0x18000
	v_add_u32_e32 v136, s85, v161
	s_add_i32 s86, 0, 0x1c000
	ds_read_b128 v[146:149], v136
	ds_read_b128 v[150:153], v136 offset:1024
	ds_read_b128 v[154:157], v136 offset:2048
	ds_read_b128 v[168:171], v136 offset:3072
	v_add_u32_e32 v136, s86, v161
	ds_read_b128 v[172:175], v136
	ds_read_b128 v[176:179], v136 offset:1024
	ds_read_b128 v[180:183], v136 offset:2048
	ds_read_b128 v[184:187], v136 offset:3072
	s_add_u32 s54, s54, 0x40000
	s_addc_u32 s55, s55, 0
	s_mov_b32 m0, s66
	v_lshl_add_u64 v[228:229], s[54:55], 0, v[134:135]
	ds_read_b128 v[188:191], v167 offset:32768
	ds_read_b128 v[192:195], v167 offset:33792
	ds_read_b128 v[198:201], v167 offset:34816
	ds_read_b128 v[202:205], v167 offset:35840
	ds_read_b128 v[206:209], v167 offset:36864
	ds_read_b128 v[210:213], v167 offset:37888
	ds_read_b128 v[214:217], v167 offset:38912
	ds_read_b128 v[218:221], v167 offset:39936
	global_load_lds_dwordx4 v[228:229], off
	v_lshl_add_u64 v[228:229], s[54:55], 0, v[130:131]
	s_mov_b32 m0, s67
	s_nop 0
	global_load_lds_dwordx4 v[228:229], off
	s_waitcnt vmcnt(8)
	s_waitcnt lgkmcnt(0)
	s_barrier
	s_setprio 1
	s_waitcnt lgkmcnt(0)
	v_mfma_f32_16x16x32_bf16 v[124:127], v[146:149], v[188:191], v[124:127]
	v_mfma_f32_16x16x32_bf16 v[120:123], v[154:157], v[188:191], v[120:123]
	v_mfma_f32_16x16x32_bf16 v[108:111], v[146:149], v[198:201], v[108:111]
	v_mfma_f32_16x16x32_bf16 v[104:107], v[154:157], v[198:201], v[104:107]
	v_mfma_f32_16x16x32_bf16 v[92:95], v[146:149], v[206:209], v[92:95]
	v_mfma_f32_16x16x32_bf16 v[88:91], v[154:157], v[206:209], v[88:91]
	v_mfma_f32_16x16x32_bf16 v[76:79], v[146:149], v[214:217], v[76:79]
	v_mfma_f32_16x16x32_bf16 v[72:75], v[154:157], v[214:217], v[72:75]
	v_mfma_f32_16x16x32_bf16 v[124:127], v[150:153], v[192:195], v[124:127]
	v_mfma_f32_16x16x32_bf16 v[120:123], v[168:171], v[192:195], v[120:123]
	v_mfma_f32_16x16x32_bf16 v[108:111], v[150:153], v[202:205], v[108:111]
	v_mfma_f32_16x16x32_bf16 v[104:107], v[168:171], v[202:205], v[104:107]
	v_mfma_f32_16x16x32_bf16 v[92:95], v[150:153], v[210:213], v[92:95]
	v_mfma_f32_16x16x32_bf16 v[88:91], v[168:171], v[210:213], v[88:91]
	v_mfma_f32_16x16x32_bf16 v[76:79], v[150:153], v[218:221], v[76:79]
	v_mfma_f32_16x16x32_bf16 v[72:75], v[168:171], v[218:221], v[72:75]
	v_mfma_f32_16x16x32_bf16 v[116:119], v[172:175], v[188:191], v[116:119]
	v_mfma_f32_16x16x32_bf16 v[112:115], v[180:183], v[188:191], v[112:115]
	v_mfma_f32_16x16x32_bf16 v[100:103], v[172:175], v[198:201], v[100:103]
	v_mfma_f32_16x16x32_bf16 v[96:99], v[180:183], v[198:201], v[96:99]
	v_mfma_f32_16x16x32_bf16 v[84:87], v[172:175], v[206:209], v[84:87]
	v_mfma_f32_16x16x32_bf16 v[80:83], v[180:183], v[206:209], v[80:83]
	v_mfma_f32_16x16x32_bf16 v[68:71], v[172:175], v[214:217], v[68:71]
	v_mfma_f32_16x16x32_bf16 v[64:67], v[180:183], v[214:217], v[64:67]
	v_mfma_f32_16x16x32_bf16 v[116:119], v[176:179], v[192:195], v[116:119]
	v_mfma_f32_16x16x32_bf16 v[112:115], v[184:187], v[192:195], v[112:115]
	v_mfma_f32_16x16x32_bf16 v[100:103], v[176:179], v[202:205], v[100:103]
	v_mfma_f32_16x16x32_bf16 v[96:99], v[184:187], v[202:205], v[96:99]
	v_mfma_f32_16x16x32_bf16 v[84:87], v[176:179], v[210:213], v[84:87]
	v_mfma_f32_16x16x32_bf16 v[80:83], v[184:187], v[210:213], v[80:83]
	v_mfma_f32_16x16x32_bf16 v[68:71], v[176:179], v[218:221], v[68:71]
	v_mfma_f32_16x16x32_bf16 v[64:67], v[184:187], v[218:221], v[64:67]
	s_setprio 0
	s_barrier
; #define PG8_STAGE(bufoff, gbase, voff) do { _Pragma("unroll") for (int _i = 0; _i < 2; ++_i) \
;         __builtin_amdgcn_global_load_lds((const unsigned*)((const char*)(gbase) + (voff)[_i]), (PG8_LAS unsigned*)(lds + (bufoff) + ldsw + _i * 8192), 16, 0, 0); } while (0)
; #define PG8_LDA(dst, b, h) do { _Pragma("unroll") for (int m = 0; m < 4; ++m) _Pragma("unroll") for (int k = 0; k < 2; ++k) dst[m][k] = *(const PG8_LAS bf16x8*)(lds + PG8_SA(b, h) + aoff + m * 2048 + k * 1024); } while (0)
; #define PG8_LDB(dst, b, h) do { _Pragma("unroll") for (int n = 0; n < 2; ++n) _Pragma("unroll") for (int k = 0; k < 2; ++k) dst[n][k] = *(const PG8_LAS bf16x8*)(lds + PG8_SB(b, h) + boff + n * 2048 + k * 1024); } while (0)
; #define PG8_MMA(ai, bj, At, Bt) do { __builtin_amdgcn_s_setprio(1); _Pragma("unroll") for (int m = 0; m < 4; ++m) _Pragma("unroll") for (int n = 0; n < 2; ++n) _Pragma("unroll") for (int k = 0; k < 2; ++k) \
;         acc[ai][bj][m][n] = __builtin_amdgcn_mfma_f32_16x16x32_bf16(Bt[n][k], At[m][k], acc[ai][bj][m][n], 0, 0, 0); __builtin_amdgcn_s_setprio(0); } while (0)
; #define PG8_WAIT_V(n) asm volatile("s_waitcnt vmcnt(" #n ")" ::: "memory")
; template <class Epi, class Sched, bool ALIGN_EPI = false, bool SP2 = false>
; __device__ __forceinline__ void gemm_phase(PG8_LAS unsigned char* lds, const Gemm g, const Sched& S, const Epi& E) {
;     ...
;             PG8_LDB(B0, 0, 0); PG8_LDB(B1, 0, 1); PG8_SCHED; PG8_LDA(At, 0, 0); PG8_STAGE(PG8_SA(1, 1), a1 + hstep, voffA);
;             PG8_WAIT_V(8); PG8_WAIT_L(0); PG8_BAR; PG8_MMA(0, 0, At, B0); PG8_MMA(0, 1, At, B1); PG8_BAR; PG8_SCHED;
;             PG8_LDA(At, 0, 1); PG8_STAGE(PG8_SB(0, 0), b2, voffB); PG8_STAGE(PG8_SB(0, 1), b2 + hstep, voffB); PG8_STAGE(PG8_SA(0, 0), a2, voffA);
;             PG8_WAIT_V(8); PG8_WAIT_L(0); PG8_BAR; PG8_MMA(1, 0, At, B0); PG8_MMA(1, 1, At, B1); PG8_BAR; PG8_SCHED;
;             PG8_LDB(B0, 1, 0); PG8_LDB(B1, 1, 1); PG8_SCHED; PG8_LDA(At, 1, 0); PG8_STAGE(PG8_SA(0, 1), a2 + hstep, voffA);
;             PG8_WAIT_V(8); PG8_WAIT_L(0); PG8_BAR; PG8_MMA(0, 0, At, B0); PG8_MMA(0, 1, At, B1); PG8_BAR; PG8_SCHED;
;             PG8_LDA(At, 1, 1); PG8_STAGE(PG8_SB(1, 0), b3, voffB); PG8_STAGE(PG8_SB(1, 1), b3 + hstep, voffB); PG8_STAGE(PG8_SA(1, 0), a3, voffA);
;             PG8_WAIT_V(8); PG8_WAIT_L(0); PG8_BAR; PG8_MMA(1, 0, At, B0); PG8_MMA(1, 1, At, B1); PG8_BAR; PG8_SCHED;
	s_add_i32 s54, s85, s63
	v_lshl_add_u64 v[158:159], v[158:159], 0, s[8:9]
	s_mov_b32 m0, s54
	ds_read_b128 v[188:191], v167 offset:49152
	ds_read_b128 v[192:195], v167 offset:50176
	ds_read_b128 v[198:201], v167 offset:51200
	ds_read_b128 v[202:205], v167 offset:52224
	ds_read_b128 v[206:209], v167 offset:53248
	ds_read_b128 v[210:213], v167 offset:54272
	ds_read_b128 v[214:217], v167 offset:55296
	ds_read_b128 v[218:221], v167 offset:56320
	global_load_lds_dwordx4 v[158:159], off
	s_add_i32 m0, s54, 0x2000
	s_add_u32 s52, s52, 0x40080
	v_lshl_add_u64 v[158:159], v[222:223], 0, s[8:9]
	s_addc_u32 s53, s53, 0
	s_add_i32 s54, s86, s63
	global_load_lds_dwordx4 v[158:159], off
	v_lshl_add_u64 v[158:159], s[52:53], 0, v[132:133]
	s_mov_b32 m0, s54
	s_nop 0
	global_load_lds_dwordx4 v[158:159], off
	v_lshl_add_u64 v[158:159], s[52:53], 0, v[128:129]
	s_add_i32 m0, s54, 0x2000
	s_nop 0
	global_load_lds_dwordx4 v[158:159], off
	v_lshl_add_u64 v[158:159], v[224:225], 0, s[8:9]
	s_mov_b32 m0, s69
	s_nop 0
	global_load_lds_dwordx4 v[158:159], off
	v_lshl_add_u64 v[158:159], v[226:227], 0, s[8:9]
	s_mov_b32 m0, s70
	s_nop 0
	global_load_lds_dwordx4 v[158:159], off
	s_waitcnt vmcnt(8)
	s_waitcnt lgkmcnt(0)
	s_barrier
	s_setprio 1
	s_waitcnt lgkmcnt(0)
	v_mfma_f32_16x16x32_bf16 v[60:63], v[146:149], v[188:191], v[60:63]
	v_mfma_f32_16x16x32_bf16 v[56:59], v[154:157], v[188:191], v[56:59]
	v_mfma_f32_16x16x32_bf16 v[44:47], v[146:149], v[198:201], v[44:47]
	v_mfma_f32_16x16x32_bf16 v[40:43], v[154:157], v[198:201], v[40:43]
	v_mfma_f32_16x16x32_bf16 v[28:31], v[146:149], v[206:209], v[28:31]
	v_mfma_f32_16x16x32_bf16 v[24:27], v[154:157], v[206:209], v[24:27]
	v_mfma_f32_16x16x32_bf16 v[12:15], v[146:149], v[214:217], v[12:15]
	v_mfma_f32_16x16x32_bf16 v[8:11], v[154:157], v[214:217], v[8:11]
	v_mfma_f32_16x16x32_bf16 v[60:63], v[150:153], v[192:195], v[60:63]
	v_mfma_f32_16x16x32_bf16 v[56:59], v[168:171], v[192:195], v[56:59]
	v_mfma_f32_16x16x32_bf16 v[44:47], v[150:153], v[202:205], v[44:47]
	v_mfma_f32_16x16x32_bf16 v[40:43], v[168:171], v[202:205], v[40:43]
	v_mfma_f32_16x16x32_bf16 v[28:31], v[150:153], v[210:213], v[28:31]
	v_mfma_f32_16x16x32_bf16 v[24:27], v[168:171], v[210:213], v[24:27]
	v_mfma_f32_16x16x32_bf16 v[12:15], v[150:153], v[218:221], v[12:15]
	v_mfma_f32_16x16x32_bf16 v[8:11], v[168:171], v[218:221], v[8:11]
	v_mfma_f32_16x16x32_bf16 v[52:55], v[172:175], v[188:191], v[52:55]
	v_mfma_f32_16x16x32_bf16 v[48:51], v[180:183], v[188:191], v[48:51]
	v_mfma_f32_16x16x32_bf16 v[36:39], v[172:175], v[198:201], v[36:39]
	v_mfma_f32_16x16x32_bf16 v[32:35], v[180:183], v[198:201], v[32:35]
	v_mfma_f32_16x16x32_bf16 v[20:23], v[172:175], v[206:209], v[20:23]
	v_mfma_f32_16x16x32_bf16 v[16:19], v[180:183], v[206:209], v[16:19]
	v_mfma_f32_16x16x32_bf16 v[4:7], v[172:175], v[214:217], v[4:7]
	v_mfma_f32_16x16x32_bf16 v[0:3], v[180:183], v[214:217], v[0:3]
	v_mfma_f32_16x16x32_bf16 v[52:55], v[176:179], v[192:195], v[52:55]
	v_mfma_f32_16x16x32_bf16 v[48:51], v[184:187], v[192:195], v[48:51]
	v_mfma_f32_16x16x32_bf16 v[36:39], v[176:179], v[202:205], v[36:39]
	v_mfma_f32_16x16x32_bf16 v[32:35], v[184:187], v[202:205], v[32:35]
	v_mfma_f32_16x16x32_bf16 v[20:23], v[176:179], v[210:213], v[20:23]
	v_mfma_f32_16x16x32_bf16 v[16:19], v[184:187], v[210:213], v[16:19]
	v_mfma_f32_16x16x32_bf16 v[4:7], v[176:179], v[218:221], v[4:7]
	v_mfma_f32_16x16x32_bf16 v[0:3], v[184:187], v[218:221], v[0:3]
	s_setprio 0
	s_barrier
	s_add_i32 s84, s84, 2
	s_add_u32 s20, s20, 0x100
	s_addc_u32 s21, s21, 0
	s_add_u32 s80, s80, 0x100
	s_addc_u32 s81, s81, 0
	s_cmp_gt_u32 s84, 13
.LBB0_414:
	ds_read_b128 v[146:149], v165
	ds_read_b128 v[150:153], v165 offset:1024
	ds_read_b128 v[154:157], v165 offset:2048
	ds_read_b128 v[168:171], v165 offset:3072
	ds_read_b128 v[172:175], v166
	ds_read_b128 v[176:179], v166 offset:1024
	ds_read_b128 v[180:183], v166 offset:2048
	ds_read_b128 v[184:187], v166 offset:3072
	s_add_u32 s52, s20, 0xfffc0080
	s_addc_u32 s53, s21, -1
	s_cmp_eq_u32 s84, 12
	s_cselect_b32 s55, s43, s53
	s_cselect_b32 s54, s78, s52
	s_cselect_b32 s53, s19, s81
	s_cselect_b32 s52, s79, s80
	v_lshl_add_u64 v[158:159], s[20:21], 0, v[138:139]
	s_add_i32 m0, s35, 0xc000
	ds_read_b128 v[188:191], v167
	ds_read_b128 v[192:195], v167 offset:1024
	ds_read_b128 v[198:201], v167 offset:2048
	ds_read_b128 v[202:205], v167 offset:3072
	ds_read_b128 v[206:209], v167 offset:4096
	ds_read_b128 v[210:213], v167 offset:5120
	ds_read_b128 v[214:217], v167 offset:6144
	ds_read_b128 v[218:221], v167 offset:7168
	global_load_lds_dwordx4 v[158:159], off
	v_lshl_add_u64 v[158:159], s[20:21], 0, v[140:141]
	s_add_i32 m0, s35, 0xe000
	s_nop 0
	global_load_lds_dwordx4 v[158:159], off
	s_waitcnt vmcnt(8)
	s_waitcnt lgkmcnt(0)
	s_barrier
; #define PG8_STAGE(bufoff, gbase, voff) do { _Pragma("unroll") for (int _i = 0; _i < 2; ++_i) \
;         __builtin_amdgcn_global_load_lds((const unsigned*)((const char*)(gbase) + (voff)[_i]), (PG8_LAS unsigned*)(lds + (bufoff) + ldsw + _i * 8192), 16, 0, 0); } while (0)
; #define PG8_LDA(dst, b, h) do { _Pragma("unroll") for (int m = 0; m < 4; ++m) _Pragma("unroll") for (int k = 0; k < 2; ++k) dst[m][k] = *(const PG8_LAS bf16x8*)(lds + PG8_SA(b, h) + aoff + m * 2048 + k * 1024); } while (0)
; #define PG8_MMA(ai, bj, At, Bt) do { __builtin_amdgcn_s_setprio(1); _Pragma("unroll") for (int m = 0; m < 4; ++m) _Pragma("unroll") for (int n = 0; n < 2; ++n) _Pragma("unroll") for (int k = 0; k < 2; ++k) \
;         acc[ai][bj][m][n] = __builtin_amdgcn_mfma_f32_16x16x32_bf16(Bt[n][k], At[m][k], acc[ai][bj][m][n], 0, 0, 0); __builtin_amdgcn_s_setprio(0); } while (0)
; #define PG8_WAIT_V(n) asm volatile("s_waitcnt vmcnt(" #n ")" ::: "memory")
; #define PG8_WAIT_L(n) asm volatile("s_waitcnt lgkmcnt(" #n ")" ::: "memory")
; #define PG8_BAR __builtin_amdgcn_s_barrier()
; #define PG8_SCHED __builtin_amdgcn_sched_barrier(0)
; template <class Epi, class Sched, bool ALIGN_EPI = false, bool SP2 = false>
; __device__ __forceinline__ void gemm_phase(PG8_LAS unsigned char* lds, const Gemm g, const Sched& S, const Epi& E) {
;     ...
;             PG8_WAIT_V(8); PG8_WAIT_L(0); PG8_BAR; PG8_MMA(0, 0, At, B0); PG8_MMA(0, 1, At, B1); PG8_BAR; PG8_SCHED;
;             PG8_LDA(At, 0, 1); PG8_STAGE(PG8_SB(0, 0), b2, voffB); PG8_STAGE(PG8_SB(0, 1), b2 + hstep, voffB); PG8_STAGE(PG8_SA(0, 0), a2, voffA);
;             PG8_WAIT_V(8); PG8_WAIT_L(0); PG8_BAR; PG8_MMA(1, 0, At, B0); PG8_MMA(1, 1, At, B1); PG8_BAR; PG8_SCHED;
	s_setprio 1
	s_waitcnt lgkmcnt(0)
	v_mfma_f32_16x16x32_bf16 v[124:127], v[146:149], v[188:191], v[124:127]
	v_mfma_f32_16x16x32_bf16 v[120:123], v[154:157], v[188:191], v[120:123]
	v_mfma_f32_16x16x32_bf16 v[108:111], v[146:149], v[198:201], v[108:111]
	v_mfma_f32_16x16x32_bf16 v[104:107], v[154:157], v[198:201], v[104:107]
	v_mfma_f32_16x16x32_bf16 v[92:95], v[146:149], v[206:209], v[92:95]
	v_mfma_f32_16x16x32_bf16 v[88:91], v[154:157], v[206:209], v[88:91]
	v_mfma_f32_16x16x32_bf16 v[76:79], v[146:149], v[214:217], v[76:79]
	v_mfma_f32_16x16x32_bf16 v[72:75], v[154:157], v[214:217], v[72:75]
	v_mfma_f32_16x16x32_bf16 v[124:127], v[150:153], v[192:195], v[124:127]
	v_mfma_f32_16x16x32_bf16 v[120:123], v[168:171], v[192:195], v[120:123]
	v_mfma_f32_16x16x32_bf16 v[108:111], v[150:153], v[202:205], v[108:111]
	v_mfma_f32_16x16x32_bf16 v[104:107], v[168:171], v[202:205], v[104:107]
	v_mfma_f32_16x16x32_bf16 v[92:95], v[150:153], v[210:213], v[92:95]
	v_mfma_f32_16x16x32_bf16 v[88:91], v[168:171], v[210:213], v[88:91]
	v_mfma_f32_16x16x32_bf16 v[76:79], v[150:153], v[218:221], v[76:79]
	v_mfma_f32_16x16x32_bf16 v[72:75], v[168:171], v[218:221], v[72:75]
	v_mfma_f32_16x16x32_bf16 v[116:119], v[172:175], v[188:191], v[116:119]
	v_mfma_f32_16x16x32_bf16 v[112:115], v[180:183], v[188:191], v[112:115]
	v_mfma_f32_16x16x32_bf16 v[100:103], v[172:175], v[198:201], v[100:103]
	v_mfma_f32_16x16x32_bf16 v[96:99], v[180:183], v[198:201], v[96:99]
	v_mfma_f32_16x16x32_bf16 v[84:87], v[172:175], v[206:209], v[84:87]
	v_mfma_f32_16x16x32_bf16 v[80:83], v[180:183], v[206:209], v[80:83]
	v_mfma_f32_16x16x32_bf16 v[68:71], v[172:175], v[214:217], v[68:71]
	v_mfma_f32_16x16x32_bf16 v[64:67], v[180:183], v[214:217], v[64:67]
	v_mfma_f32_16x16x32_bf16 v[116:119], v[176:179], v[192:195], v[116:119]
	v_mfma_f32_16x16x32_bf16 v[112:115], v[184:187], v[192:195], v[112:115]
	v_mfma_f32_16x16x32_bf16 v[100:103], v[176:179], v[202:205], v[100:103]
	v_mfma_f32_16x16x32_bf16 v[96:99], v[184:187], v[202:205], v[96:99]
	v_mfma_f32_16x16x32_bf16 v[84:87], v[176:179], v[210:213], v[84:87]
	v_mfma_f32_16x16x32_bf16 v[80:83], v[184:187], v[210:213], v[80:83]
	v_mfma_f32_16x16x32_bf16 v[68:71], v[176:179], v[218:221], v[68:71]
	v_mfma_f32_16x16x32_bf16 v[64:67], v[184:187], v[218:221], v[64:67]
	s_setprio 0
	s_barrier
	s_add_i32 s85, s72, s63
	v_lshl_add_u64 v[158:159], s[52:53], 0, v[132:133]
	s_mov_b32 m0, s85
	ds_read_b128 v[188:191], v167 offset:16384
	ds_read_b128 v[192:195], v167 offset:17408
	ds_read_b128 v[198:201], v167 offset:18432
	ds_read_b128 v[202:205], v167 offset:19456
	ds_read_b128 v[206:209], v167 offset:20480
	ds_read_b128 v[210:213], v167 offset:21504
	ds_read_b128 v[214:217], v167 offset:22528
	ds_read_b128 v[218:221], v167 offset:23552
	global_load_lds_dwordx4 v[158:159], off
	s_add_i32 m0, s85, 0x2000
	s_add_u32 s86, s52, 0x40000
	v_lshl_add_u64 v[222:223], s[52:53], 0, v[128:129]
	s_addc_u32 s87, s53, 0
	s_add_i32 s85, s73, s63
	global_load_lds_dwordx4 v[222:223], off
	v_lshl_add_u64 v[224:225], s[86:87], 0, v[132:133]
	s_mov_b32 m0, s85
	v_lshl_add_u64 v[226:227], s[54:55], 0, v[130:131]
	global_load_lds_dwordx4 v[224:225], off
	v_lshl_add_u64 v[224:225], s[86:87], 0, v[128:129]
	s_add_i32 m0, s85, 0x2000
	s_nop 0
	global_load_lds_dwordx4 v[224:225], off
	v_lshl_add_u64 v[224:225], s[54:55], 0, v[134:135]
	s_mov_b32 m0, s35
	s_nop 0
	global_load_lds_dwordx4 v[224:225], off
	s_mov_b32 m0, s65
	s_nop 0
	global_load_lds_dwordx4 v[226:227], off
	s_waitcnt vmcnt(8)
	s_waitcnt lgkmcnt(0)
	s_barrier
	s_setprio 1
	s_waitcnt lgkmcnt(0)
	v_mfma_f32_16x16x32_bf16 v[60:63], v[146:149], v[188:191], v[60:63]
	v_mfma_f32_16x16x32_bf16 v[56:59], v[154:157], v[188:191], v[56:59]
	v_mfma_f32_16x16x32_bf16 v[44:47], v[146:149], v[198:201], v[44:47]
	v_mfma_f32_16x16x32_bf16 v[40:43], v[154:157], v[198:201], v[40:43]
	v_mfma_f32_16x16x32_bf16 v[28:31], v[146:149], v[206:209], v[28:31]
	v_mfma_f32_16x16x32_bf16 v[24:27], v[154:157], v[206:209], v[24:27]
	v_mfma_f32_16x16x32_bf16 v[12:15], v[146:149], v[214:217], v[12:15]
	v_mfma_f32_16x16x32_bf16 v[8:11], v[154:157], v[214:217], v[8:11]
	v_mfma_f32_16x16x32_bf16 v[60:63], v[150:153], v[192:195], v[60:63]
	v_mfma_f32_16x16x32_bf16 v[56:59], v[168:171], v[192:195], v[56:59]
	v_mfma_f32_16x16x32_bf16 v[44:47], v[150:153], v[202:205], v[44:47]
	v_mfma_f32_16x16x32_bf16 v[40:43], v[168:171], v[202:205], v[40:43]
	v_mfma_f32_16x16x32_bf16 v[28:31], v[150:153], v[210:213], v[28:31]
	v_mfma_f32_16x16x32_bf16 v[24:27], v[168:171], v[210:213], v[24:27]
	v_mfma_f32_16x16x32_bf16 v[12:15], v[150:153], v[218:221], v[12:15]
	v_mfma_f32_16x16x32_bf16 v[8:11], v[168:171], v[218:221], v[8:11]
	v_mfma_f32_16x16x32_bf16 v[52:55], v[172:175], v[188:191], v[52:55]
	v_mfma_f32_16x16x32_bf16 v[48:51], v[180:183], v[188:191], v[48:51]
	v_mfma_f32_16x16x32_bf16 v[36:39], v[172:175], v[198:201], v[36:39]
	v_mfma_f32_16x16x32_bf16 v[32:35], v[180:183], v[198:201], v[32:35]
	v_mfma_f32_16x16x32_bf16 v[20:23], v[172:175], v[206:209], v[20:23]
	v_mfma_f32_16x16x32_bf16 v[16:19], v[180:183], v[206:209], v[16:19]
	v_mfma_f32_16x16x32_bf16 v[4:7], v[172:175], v[214:217], v[4:7]
	v_mfma_f32_16x16x32_bf16 v[0:3], v[180:183], v[214:217], v[0:3]
	v_mfma_f32_16x16x32_bf16 v[52:55], v[176:179], v[192:195], v[52:55]
	v_mfma_f32_16x16x32_bf16 v[48:51], v[184:187], v[192:195], v[48:51]
	v_mfma_f32_16x16x32_bf16 v[36:39], v[176:179], v[202:205], v[36:39]
	v_mfma_f32_16x16x32_bf16 v[32:35], v[184:187], v[202:205], v[32:35]
	v_mfma_f32_16x16x32_bf16 v[20:23], v[176:179], v[210:213], v[20:23]
	v_mfma_f32_16x16x32_bf16 v[16:19], v[184:187], v[210:213], v[16:19]
	v_mfma_f32_16x16x32_bf16 v[4:7], v[176:179], v[218:221], v[4:7]
	v_mfma_f32_16x16x32_bf16 v[0:3], v[184:187], v[218:221], v[0:3]
	s_setprio 0
	s_barrier
; #define PG8_STAGE(bufoff, gbase, voff) do { _Pragma("unroll") for (int _i = 0; _i < 2; ++_i) \
;         __builtin_amdgcn_global_load_lds((const unsigned*)((const char*)(gbase) + (voff)[_i]), (PG8_LAS unsigned*)(lds + (bufoff) + ldsw + _i * 8192), 16, 0, 0); } while (0)
; #define PG8_LDA(dst, b, h) do { _Pragma("unroll") for (int m = 0; m < 4; ++m) _Pragma("unroll") for (int k = 0; k < 2; ++k) dst[m][k] = *(const PG8_LAS bf16x8*)(lds + PG8_SA(b, h) + aoff + m * 2048 + k * 1024); } while (0)
; #define PG8_LDB(dst, b, h) do { _Pragma("unroll") for (int n = 0; n < 2; ++n) _Pragma("unroll") for (int k = 0; k < 2; ++k) dst[n][k] = *(const PG8_LAS bf16x8*)(lds + PG8_SB(b, h) + boff + n * 2048 + k * 1024); } while (0)
; #define PG8_MMA(ai, bj, At, Bt) do { __builtin_amdgcn_s_setprio(1); _Pragma("unroll") for (int m = 0; m < 4; ++m) _Pragma("unroll") for (int n = 0; n < 2; ++n) _Pragma("unroll") for (int k = 0; k < 2; ++k) \
;         acc[ai][bj][m][n] = __builtin_amdgcn_mfma_f32_16x16x32_bf16(Bt[n][k], At[m][k], acc[ai][bj][m][n], 0, 0, 0); __builtin_amdgcn_s_setprio(0); } while (0)
; #define PG8_WAIT_V(n) asm volatile("s_waitcnt vmcnt(" #n ")" ::: "memory")
; #define PG8_WAIT_L(n) asm volatile("s_waitcnt lgkmcnt(" #n ")" ::: "memory")
; #define PG8_BAR __builtin_amdgcn_s_barrier()
; #define PG8_SCHED __builtin_amdgcn_sched_barrier(0)
; template <class Epi, class Sched, bool ALIGN_EPI = false, bool SP2 = false>
; __device__ __forceinline__ void gemm_phase(PG8_LAS unsigned char* lds, const Gemm g, const Sched& S, const Epi& E) {
;     ...
;             PG8_LDB(B0, 1, 0); PG8_LDB(B1, 1, 1); PG8_SCHED; PG8_LDA(At, 1, 0); PG8_STAGE(PG8_SA(0, 1), a2 + hstep, voffA);
;             PG8_WAIT_V(8); PG8_WAIT_L(0); PG8_BAR; PG8_MMA(0, 0, At, B0); PG8_MMA(0, 1, At, B1); PG8_BAR; PG8_SCHED;
	s_add_i32 s85, 0, 0x18000
	v_add_u32_e32 v136, s85, v161
	s_add_i32 s86, 0, 0x1c000
	ds_read_b128 v[146:149], v136
	ds_read_b128 v[150:153], v136 offset:1024
	ds_read_b128 v[154:157], v136 offset:2048
	ds_read_b128 v[168:171], v136 offset:3072
	v_add_u32_e32 v136, s86, v161
	ds_read_b128 v[172:175], v136
	ds_read_b128 v[176:179], v136 offset:1024
	ds_read_b128 v[180:183], v136 offset:2048
	ds_read_b128 v[184:187], v136 offset:3072
	s_add_u32 s54, s54, 0x40000
	s_addc_u32 s55, s55, 0
	s_mov_b32 m0, s66
	v_lshl_add_u64 v[228:229], s[54:55], 0, v[134:135]
	ds_read_b128 v[188:191], v167 offset:32768
	ds_read_b128 v[192:195], v167 offset:33792
	ds_read_b128 v[198:201], v167 offset:34816
	ds_read_b128 v[202:205], v167 offset:35840
	ds_read_b128 v[206:209], v167 offset:36864
	ds_read_b128 v[210:213], v167 offset:37888
	ds_read_b128 v[214:217], v167 offset:38912
	ds_read_b128 v[218:221], v167 offset:39936
	global_load_lds_dwordx4 v[228:229], off
	v_lshl_add_u64 v[228:229], s[54:55], 0, v[130:131]
	s_mov_b32 m0, s67
	s_nop 0
	global_load_lds_dwordx4 v[228:229], off
	s_waitcnt vmcnt(8)
	s_waitcnt lgkmcnt(0)
	s_barrier
	s_setprio 1
	s_waitcnt lgkmcnt(0)
	v_mfma_f32_16x16x32_bf16 v[124:127], v[146:149], v[188:191], v[124:127]
	v_mfma_f32_16x16x32_bf16 v[120:123], v[154:157], v[188:191], v[120:123]
	v_mfma_f32_16x16x32_bf16 v[108:111], v[146:149], v[198:201], v[108:111]
	v_mfma_f32_16x16x32_bf16 v[104:107], v[154:157], v[198:201], v[104:107]
	v_mfma_f32_16x16x32_bf16 v[92:95], v[146:149], v[206:209], v[92:95]
	v_mfma_f32_16x16x32_bf16 v[88:91], v[154:157], v[206:209], v[88:91]
	v_mfma_f32_16x16x32_bf16 v[76:79], v[146:149], v[214:217], v[76:79]
	v_mfma_f32_16x16x32_bf16 v[72:75], v[154:157], v[214:217], v[72:75]
	v_mfma_f32_16x16x32_bf16 v[124:127], v[150:153], v[192:195], v[124:127]
	v_mfma_f32_16x16x32_bf16 v[120:123], v[168:171], v[192:195], v[120:123]
	v_mfma_f32_16x16x32_bf16 v[108:111], v[150:153], v[202:205], v[108:111]
	v_mfma_f32_16x16x32_bf16 v[104:107], v[168:171], v[202:205], v[104:107]
	v_mfma_f32_16x16x32_bf16 v[92:95], v[150:153], v[210:213], v[92:95]
	v_mfma_f32_16x16x32_bf16 v[88:91], v[168:171], v[210:213], v[88:91]
	v_mfma_f32_16x16x32_bf16 v[76:79], v[150:153], v[218:221], v[76:79]
	v_mfma_f32_16x16x32_bf16 v[72:75], v[168:171], v[218:221], v[72:75]
	v_mfma_f32_16x16x32_bf16 v[116:119], v[172:175], v[188:191], v[116:119]
	v_mfma_f32_16x16x32_bf16 v[112:115], v[180:183], v[188:191], v[112:115]
	v_mfma_f32_16x16x32_bf16 v[100:103], v[172:175], v[198:201], v[100:103]
	v_mfma_f32_16x16x32_bf16 v[96:99], v[180:183], v[198:201], v[96:99]
	v_mfma_f32_16x16x32_bf16 v[84:87], v[172:175], v[206:209], v[84:87]
	v_mfma_f32_16x16x32_bf16 v[80:83], v[180:183], v[206:209], v[80:83]
	v_mfma_f32_16x16x32_bf16 v[68:71], v[172:175], v[214:217], v[68:71]
	v_mfma_f32_16x16x32_bf16 v[64:67], v[180:183], v[214:217], v[64:67]
	v_mfma_f32_16x16x32_bf16 v[116:119], v[176:179], v[192:195], v[116:119]
	v_mfma_f32_16x16x32_bf16 v[112:115], v[184:187], v[192:195], v[112:115]
	v_mfma_f32_16x16x32_bf16 v[100:103], v[176:179], v[202:205], v[100:103]
	v_mfma_f32_16x16x32_bf16 v[96:99], v[184:187], v[202:205], v[96:99]
	v_mfma_f32_16x16x32_bf16 v[84:87], v[176:179], v[210:213], v[84:87]
	v_mfma_f32_16x16x32_bf16 v[80:83], v[184:187], v[210:213], v[80:83]
	v_mfma_f32_16x16x32_bf16 v[68:71], v[176:179], v[218:221], v[68:71]
	v_mfma_f32_16x16x32_bf16 v[64:67], v[184:187], v[218:221], v[64:67]
	s_setprio 0
	s_barrier
; #define PG8_STAGE(bufoff, gbase, voff) do { _Pragma("unroll") for (int _i = 0; _i < 2; ++_i) \
;         __builtin_amdgcn_global_load_lds((const unsigned*)((const char*)(gbase) + (voff)[_i]), (PG8_LAS unsigned*)(lds + (bufoff) + ldsw + _i * 8192), 16, 0, 0); } while (0)
; #define PG8_LDA(dst, b, h) do { _Pragma("unroll") for (int m = 0; m < 4; ++m) _Pragma("unroll") for (int k = 0; k < 2; ++k) dst[m][k] = *(const PG8_LAS bf16x8*)(lds + PG8_SA(b, h) + aoff + m * 2048 + k * 1024); } while (0)
; #define PG8_MMA(ai, bj, At, Bt) do { __builtin_amdgcn_s_setprio(1); _Pragma("unroll") for (int m = 0; m < 4; ++m) _Pragma("unroll") for (int n = 0; n < 2; ++n) _Pragma("unroll") for (int k = 0; k < 2; ++k) \
;         acc[ai][bj][m][n] = __builtin_amdgcn_mfma_f32_16x16x32_bf16(Bt[n][k], At[m][k], acc[ai][bj][m][n], 0, 0, 0); __builtin_amdgcn_s_setprio(0); } while (0)
; #define PG8_WAIT_V(n) asm volatile("s_waitcnt vmcnt(" #n ")" ::: "memory")
; #define PG8_WAIT_L(n) asm volatile("s_waitcnt lgkmcnt(" #n ")" ::: "memory")
; #define PG8_BAR __builtin_amdgcn_s_barrier()
; #define PG8_SCHED __builtin_amdgcn_sched_barrier(0)
; template <class Epi, class Sched, bool ALIGN_EPI = false, bool SP2 = false>
; __device__ __forceinline__ void gemm_phase(PG8_LAS unsigned char* lds, const Gemm g, const Sched& S, const Epi& E) {
;     ...
;             PG8_LDA(At, 1, 1); PG8_STAGE(PG8_SB(1, 0), b3, voffB); PG8_STAGE(PG8_SB(1, 1), b3 + hstep, voffB); PG8_STAGE(PG8_SA(1, 0), a3, voffA);
;             PG8_WAIT_V(8); PG8_WAIT_L(0); PG8_BAR; PG8_MMA(1, 0, At, B0); PG8_MMA(1, 1, At, B1); PG8_BAR; PG8_SCHED;
;     ...
;         if constexpr (ALIGN_EPI) { if (wr == 0) PG8_BAR; }
	s_add_i32 s54, s85, s63
	v_lshl_add_u64 v[158:159], v[158:159], 0, s[8:9]
	s_mov_b32 m0, s54
	ds_read_b128 v[188:191], v167 offset:49152
	ds_read_b128 v[192:195], v167 offset:50176
	ds_read_b128 v[198:201], v167 offset:51200
	ds_read_b128 v[202:205], v167 offset:52224
	ds_read_b128 v[206:209], v167 offset:53248
	ds_read_b128 v[210:213], v167 offset:54272
	ds_read_b128 v[214:217], v167 offset:55296
	ds_read_b128 v[218:221], v167 offset:56320
	global_load_lds_dwordx4 v[158:159], off
	s_add_i32 m0, s54, 0x2000
	s_add_u32 s52, s52, 0x40080
	v_lshl_add_u64 v[158:159], v[222:223], 0, s[8:9]
	s_addc_u32 s53, s53, 0
	s_add_i32 s54, s86, s63
	global_load_lds_dwordx4 v[158:159], off
	v_lshl_add_u64 v[158:159], s[52:53], 0, v[132:133]
	s_mov_b32 m0, s54
	s_nop 0
	global_load_lds_dwordx4 v[158:159], off
	v_lshl_add_u64 v[158:159], s[52:53], 0, v[128:129]
	s_add_i32 m0, s54, 0x2000
	s_nop 0
	global_load_lds_dwordx4 v[158:159], off
	v_lshl_add_u64 v[158:159], v[224:225], 0, s[8:9]
	s_mov_b32 m0, s69
	s_nop 0
	global_load_lds_dwordx4 v[158:159], off
	v_lshl_add_u64 v[158:159], v[226:227], 0, s[8:9]
	s_mov_b32 m0, s70
	s_nop 0
	global_load_lds_dwordx4 v[158:159], off
	s_waitcnt vmcnt(8)
	s_waitcnt lgkmcnt(0)
	s_barrier
	s_setprio 1
	s_waitcnt lgkmcnt(0)
	v_mfma_f32_16x16x32_bf16 v[60:63], v[146:149], v[188:191], v[60:63]
	v_mfma_f32_16x16x32_bf16 v[56:59], v[154:157], v[188:191], v[56:59]
	v_mfma_f32_16x16x32_bf16 v[44:47], v[146:149], v[198:201], v[44:47]
	v_mfma_f32_16x16x32_bf16 v[40:43], v[154:157], v[198:201], v[40:43]
	v_mfma_f32_16x16x32_bf16 v[28:31], v[146:149], v[206:209], v[28:31]
	v_mfma_f32_16x16x32_bf16 v[24:27], v[154:157], v[206:209], v[24:27]
	v_mfma_f32_16x16x32_bf16 v[12:15], v[146:149], v[214:217], v[12:15]
	v_mfma_f32_16x16x32_bf16 v[8:11], v[154:157], v[214:217], v[8:11]
	v_mfma_f32_16x16x32_bf16 v[60:63], v[150:153], v[192:195], v[60:63]
	v_mfma_f32_16x16x32_bf16 v[56:59], v[168:171], v[192:195], v[56:59]
	v_mfma_f32_16x16x32_bf16 v[44:47], v[150:153], v[202:205], v[44:47]
	v_mfma_f32_16x16x32_bf16 v[40:43], v[168:171], v[202:205], v[40:43]
	v_mfma_f32_16x16x32_bf16 v[28:31], v[150:153], v[210:213], v[28:31]
	v_mfma_f32_16x16x32_bf16 v[24:27], v[168:171], v[210:213], v[24:27]
	v_mfma_f32_16x16x32_bf16 v[12:15], v[150:153], v[218:221], v[12:15]
	v_mfma_f32_16x16x32_bf16 v[8:11], v[168:171], v[218:221], v[8:11]
	v_mfma_f32_16x16x32_bf16 v[52:55], v[172:175], v[188:191], v[52:55]
	v_mfma_f32_16x16x32_bf16 v[48:51], v[180:183], v[188:191], v[48:51]
	v_mfma_f32_16x16x32_bf16 v[36:39], v[172:175], v[198:201], v[36:39]
	v_mfma_f32_16x16x32_bf16 v[32:35], v[180:183], v[198:201], v[32:35]
	v_mfma_f32_16x16x32_bf16 v[20:23], v[172:175], v[206:209], v[20:23]
	v_mfma_f32_16x16x32_bf16 v[16:19], v[180:183], v[206:209], v[16:19]
	v_mfma_f32_16x16x32_bf16 v[4:7], v[172:175], v[214:217], v[4:7]
	v_mfma_f32_16x16x32_bf16 v[0:3], v[180:183], v[214:217], v[0:3]
	v_mfma_f32_16x16x32_bf16 v[52:55], v[176:179], v[192:195], v[52:55]
	v_mfma_f32_16x16x32_bf16 v[48:51], v[184:187], v[192:195], v[48:51]
	v_mfma_f32_16x16x32_bf16 v[36:39], v[176:179], v[202:205], v[36:39]
	v_mfma_f32_16x16x32_bf16 v[32:35], v[184:187], v[202:205], v[32:35]
	v_mfma_f32_16x16x32_bf16 v[20:23], v[176:179], v[210:213], v[20:23]
	v_mfma_f32_16x16x32_bf16 v[16:19], v[184:187], v[210:213], v[16:19]
	v_mfma_f32_16x16x32_bf16 v[4:7], v[176:179], v[218:221], v[4:7]
	v_mfma_f32_16x16x32_bf16 v[0:3], v[184:187], v[218:221], v[0:3]
	s_setprio 0
	s_barrier
	s_add_i32 s84, s84, 2
	s_add_u32 s20, s20, 0x100
	s_addc_u32 s21, s21, 0
	s_add_u32 s80, s80, 0x100
	s_addc_u32 s81, s81, 0
	s_cmp_gt_u32 s84, 13
	s_cbranch_scc0 .LBB0_414
	s_and_b64 vcc, exec, s[10:11]
	s_cbranch_vccz .LBB0_417
	s_barrier

; #define PG8_STAGE(bufoff, gbase, voff) do { _Pragma("unroll") for (int _i = 0; _i < 2; ++_i) \
;         __builtin_amdgcn_global_load_lds((const unsigned*)((const char*)(gbase) + (voff)[_i]), (PG8_LAS unsigned*)(lds + (bufoff) + ldsw + _i * 8192), 16, 0, 0); } while (0)
; #define PG8_LDA(dst, b, h) do { _Pragma("unroll") for (int m = 0; m < 4; ++m) _Pragma("unroll") for (int k = 0; k < 2; ++k) dst[m][k] = *(const PG8_LAS bf16x8*)(lds + PG8_SA(b, h) + aoff + m * 2048 + k * 1024); } while (0)
; #define PG8_LDB(dst, b, h) do { _Pragma("unroll") for (int n = 0; n < 2; ++n) _Pragma("unroll") for (int k = 0; k < 2; ++k) dst[n][k] = *(const PG8_LAS bf16x8*)(lds + PG8_SB(b, h) + boff + n * 2048 + k * 1024); } while (0)
; #define PG8_WAIT_V(n) asm volatile("s_waitcnt vmcnt(" #n ")" ::: "memory")
; #define PG8_WAIT_L(n) asm volatile("s_waitcnt lgkmcnt(" #n ")" ::: "memory")
; #define PG8_BAR __builtin_amdgcn_s_barrier()
; #define PG8_SCHED __builtin_amdgcn_sched_barrier(0)
; template <class Epi, class Sched, bool ALIGN_EPI = false, bool SP2 = false>
; __device__ __forceinline__ void gemm_phase(PG8_LAS unsigned char* lds, const Gemm g, const Sched& S, const Epi& E) {
;     ...
;         const bool has_next = S.next(ui + 1, nxt);
;         const char* nA = has_next ? (const char*)g.A + (size_t)nxt.pm * tstep : cA; const char* nB = has_next ? (const char*)g.Bt + (size_t)nxt.pn * tstep : cB;
;         for (int t = 0; t < nt; t += 2) {
;             const bool last = (t == nt - 2);
;             const char* a1 = cA + (size_t)(t + 1) * kstep;
;             const char* a2 = last ? nA : cA + (size_t)(t + 2) * kstep; const char* b2 = last ? nB : cB + (size_t)(t + 2) * kstep;
;             const char* a3 = a2 + kstep; const char* b3 = b2 + kstep;
;             if (last && has_next) S.a_ready(nxt);
;             if constexpr (SP2) {
;             PG8_LDB(B0, 0, 0); PG8_LDB(B1, 0, 1); PG8_SCHED; PG8_LDA(At, 0, 0); PG8_STAGE(PG8_SA(1, 1), a1 + hstep, voffA);
;             PG8_WAIT_V(8); PG8_WAIT_L(0); PG8_BAR; PG8_MMA(0, 0, At, B0); PG8_MMA(0, 1, At, B1); PG8_BAR; PG8_SCHED;
;             PG8_LDA(At, 0, 1); PG8_STAGE(PG8_SB(0, 0), b2, voffB); PG8_STAGE(PG8_SB(0, 1), b2 + hstep, voffB); PG8_STAGE(PG8_SA(0, 0), a2, voffA);
;             PG8_WAIT_V(8); PG8_WAIT_L(0); PG8_BAR; PG8_MMA(1, 0, At, B0); PG8_MMA(1, 1, At, B1); PG8_BAR; PG8_SCHED;
.LBB0_623:
	s_ashr_i32 s17, s16, 31
	s_lshl_b64 s[18:19], s[16:17], 18
	s_add_u32 s18, s0, s18
	s_addc_u32 s19, s1, s19
	s_and_b64 s[38:39], s[4:5], exec
	s_cselect_b32 s17, s19, s21
	s_cselect_b32 s63, s18, s20
	s_ashr_i32 s15, s14, 31
	s_lshl_b64 s[38:39], s[14:15], 18
	s_add_u32 s38, s33, s38
	s_addc_u32 s39, s50, s39
	s_and_b64 s[48:49], s[4:5], exec
	s_cselect_b32 s15, s39, s47
	s_cselect_b32 s64, s38, s46
	s_add_u32 s20, s20, 0x20080
	s_addc_u32 s21, s21, 0
	s_add_u32 s65, s46, 0x100
	s_addc_u32 s66, s47, 0
	s_mov_b32 s67, -2
	ds_read_b128 v[112:115], v167
	ds_read_b128 v[116:119], v167 offset:1024
	ds_read_b128 v[152:155], v167 offset:2048
	ds_read_b128 v[156:159], v167 offset:3072
	ds_read_b128 v[160:163], v168
	ds_read_b128 v[170:173], v168 offset:1024
	ds_read_b128 v[174:177], v168 offset:2048
	ds_read_b128 v[178:181], v168 offset:3072
	s_add_u32 s46, s20, 0xfffe0080
	s_addc_u32 s47, s21, -1
	s_cmp_eq_u32 s67, 4
	s_cselect_b32 s49, s17, s47
	s_cselect_b32 s48, s63, s46
	s_cselect_b32 s47, s15, s66
	s_cselect_b32 s46, s64, s65
	v_lshl_add_u64 v[194:195], s[20:21], 0, v[144:145]
	s_add_i32 m0, s35, 0xc000
	ds_read_b128 v[182:185], v169
	ds_read_b128 v[186:189], v169 offset:1024
	ds_read_b128 v[190:193], v169 offset:2048
	ds_read_b128 v[198:201], v169 offset:3072
	ds_read_b128 v[202:205], v169 offset:4096
	ds_read_b128 v[206:209], v169 offset:5120
	ds_read_b128 v[210:213], v169 offset:6144
	ds_read_b128 v[214:217], v169 offset:7168
	global_load_lds_dwordx4 v[194:195], off
	v_lshl_add_u64 v[194:195], s[20:21], 0, v[146:147]
	s_add_i32 m0, s35, 0xe000
	s_nop 0
	global_load_lds_dwordx4 v[194:195], off
	s_waitcnt vmcnt(8)
	s_waitcnt lgkmcnt(0)
	s_barrier
	s_setprio 1
	s_waitcnt lgkmcnt(0)
	v_mfma_f32_16x16x32_bf16 v[132:135], v[112:115], v[182:185], 0
	v_mfma_f32_16x16x32_bf16 v[128:131], v[152:155], v[182:185], 0
	v_mfma_f32_16x16x32_bf16 v[124:127], v[112:115], v[190:193], 0
	v_mfma_f32_16x16x32_bf16 v[120:123], v[152:155], v[190:193], 0
	v_mfma_f32_16x16x32_bf16 v[108:111], v[112:115], v[202:205], 0
	v_mfma_f32_16x16x32_bf16 v[104:107], v[152:155], v[202:205], 0
	v_mfma_f32_16x16x32_bf16 v[100:103], v[112:115], v[210:213], 0
	v_mfma_f32_16x16x32_bf16 v[96:99], v[152:155], v[210:213], 0
	v_mfma_f32_16x16x32_bf16 v[132:135], v[116:119], v[186:189], v[132:135]
	v_mfma_f32_16x16x32_bf16 v[128:131], v[156:159], v[186:189], v[128:131]
	v_mfma_f32_16x16x32_bf16 v[124:127], v[116:119], v[198:201], v[124:127]
	v_mfma_f32_16x16x32_bf16 v[120:123], v[156:159], v[198:201], v[120:123]
	v_mfma_f32_16x16x32_bf16 v[108:111], v[116:119], v[206:209], v[108:111]
	v_mfma_f32_16x16x32_bf16 v[104:107], v[156:159], v[206:209], v[104:107]
	v_mfma_f32_16x16x32_bf16 v[100:103], v[116:119], v[214:217], v[100:103]
	v_mfma_f32_16x16x32_bf16 v[96:99], v[156:159], v[214:217], v[96:99]
	v_mfma_f32_16x16x32_bf16 v[60:63], v[160:163], v[182:185], 0
	v_mfma_f32_16x16x32_bf16 v[56:59], v[174:177], v[182:185], 0
	v_mfma_f32_16x16x32_bf16 v[52:55], v[160:163], v[190:193], 0
	v_mfma_f32_16x16x32_bf16 v[48:51], v[174:177], v[190:193], 0
	v_mfma_f32_16x16x32_bf16 v[44:47], v[160:163], v[202:205], 0
	v_mfma_f32_16x16x32_bf16 v[40:43], v[174:177], v[202:205], 0
	v_mfma_f32_16x16x32_bf16 v[36:39], v[160:163], v[210:213], 0
	v_mfma_f32_16x16x32_bf16 v[32:35], v[174:177], v[210:213], 0
	v_mfma_f32_16x16x32_bf16 v[60:63], v[170:173], v[186:189], v[60:63]
	v_mfma_f32_16x16x32_bf16 v[56:59], v[178:181], v[186:189], v[56:59]
	v_mfma_f32_16x16x32_bf16 v[52:55], v[170:173], v[198:201], v[52:55]
	v_mfma_f32_16x16x32_bf16 v[48:51], v[178:181], v[198:201], v[48:51]
	v_mfma_f32_16x16x32_bf16 v[44:47], v[170:173], v[206:209], v[44:47]
	v_mfma_f32_16x16x32_bf16 v[40:43], v[178:181], v[206:209], v[40:43]
	v_mfma_f32_16x16x32_bf16 v[36:39], v[170:173], v[214:217], v[36:39]
	v_mfma_f32_16x16x32_bf16 v[32:35], v[178:181], v[214:217], v[32:35]
	s_setprio 0
	s_barrier
	s_add_i32 s68, s60, s51
	v_lshl_add_u64 v[194:195], s[46:47], 0, v[138:139]
	s_mov_b32 m0, s68
	ds_read_b128 v[182:185], v169 offset:16384
	ds_read_b128 v[186:189], v169 offset:17408
	ds_read_b128 v[190:193], v169 offset:18432
	ds_read_b128 v[198:201], v169 offset:19456
	ds_read_b128 v[202:205], v169 offset:20480
	ds_read_b128 v[206:209], v169 offset:21504
	ds_read_b128 v[210:213], v169 offset:22528
	ds_read_b128 v[214:217], v169 offset:23552
	global_load_lds_dwordx4 v[194:195], off
	s_add_i32 m0, s68, 0x2000
	s_add_u32 s68, s46, 0x20000
	v_lshl_add_u64 v[218:219], s[46:47], 0, v[142:143]
	s_addc_u32 s69, s47, 0
	s_add_i32 s70, s61, s51
	global_load_lds_dwordx4 v[218:219], off
	v_lshl_add_u64 v[220:221], s[68:69], 0, v[138:139]
	s_mov_b32 m0, s70
	v_lshl_add_u64 v[222:223], s[48:49], 0, v[140:141]
	global_load_lds_dwordx4 v[220:221], off
	v_lshl_add_u64 v[220:221], s[68:69], 0, v[142:143]
	s_add_i32 m0, s70, 0x2000
	s_nop 0
	global_load_lds_dwordx4 v[220:221], off
	v_lshl_add_u64 v[220:221], s[48:49], 0, v[136:137]
	s_mov_b32 m0, s35
	s_nop 0
	global_load_lds_dwordx4 v[220:221], off
	s_mov_b32 m0, s52
	s_nop 0
	global_load_lds_dwordx4 v[222:223], off
	s_waitcnt vmcnt(8)
	s_waitcnt lgkmcnt(0)
	s_barrier
; #define PG8_STAGE(bufoff, gbase, voff) do { _Pragma("unroll") for (int _i = 0; _i < 2; ++_i) \
;         __builtin_amdgcn_global_load_lds((const unsigned*)((const char*)(gbase) + (voff)[_i]), (PG8_LAS unsigned*)(lds + (bufoff) + ldsw + _i * 8192), 16, 0, 0); } while (0)
; #define PG8_LDA(dst, b, h) do { _Pragma("unroll") for (int m = 0; m < 4; ++m) _Pragma("unroll") for (int k = 0; k < 2; ++k) dst[m][k] = *(const PG8_LAS bf16x8*)(lds + PG8_SA(b, h) + aoff + m * 2048 + k * 1024); } while (0)
; #define PG8_LDB(dst, b, h) do { _Pragma("unroll") for (int n = 0; n < 2; ++n) _Pragma("unroll") for (int k = 0; k < 2; ++k) dst[n][k] = *(const PG8_LAS bf16x8*)(lds + PG8_SB(b, h) + boff + n * 2048 + k * 1024); } while (0)
; #define PG8_MMA(ai, bj, At, Bt) do { __builtin_amdgcn_s_setprio(1); _Pragma("unroll") for (int m = 0; m < 4; ++m) _Pragma("unroll") for (int n = 0; n < 2; ++n) _Pragma("unroll") for (int k = 0; k < 2; ++k) \
;         acc[ai][bj][m][n] = __builtin_amdgcn_mfma_f32_16x16x32_bf16(Bt[n][k], At[m][k], acc[ai][bj][m][n], 0, 0, 0); __builtin_amdgcn_s_setprio(0); } while (0)
; #define PG8_WAIT_V(n) asm volatile("s_waitcnt vmcnt(" #n ")" ::: "memory")
; #define PG8_WAIT_L(n) asm volatile("s_waitcnt lgkmcnt(" #n ")" ::: "memory")
; #define PG8_BAR __builtin_amdgcn_s_barrier()
; #define PG8_SCHED __builtin_amdgcn_sched_barrier(0)
; template <class Epi, class Sched, bool ALIGN_EPI = false, bool SP2 = false>
; __device__ __forceinline__ void gemm_phase(PG8_LAS unsigned char* lds, const Gemm g, const Sched& S, const Epi& E) {
;     ...
;             PG8_WAIT_V(8); PG8_WAIT_L(0); PG8_BAR; PG8_MMA(1, 0, At, B0); PG8_MMA(1, 1, At, B1); PG8_BAR; PG8_SCHED;
;             PG8_LDB(B0, 1, 0); PG8_LDB(B1, 1, 1); PG8_SCHED; PG8_LDA(At, 1, 0); PG8_STAGE(PG8_SA(0, 1), a2 + hstep, voffA);
;             PG8_WAIT_V(8); PG8_WAIT_L(0); PG8_BAR; PG8_MMA(0, 0, At, B0); PG8_MMA(0, 1, At, B1); PG8_BAR; PG8_SCHED;
	s_setprio 1
	s_waitcnt lgkmcnt(0)
	v_mfma_f32_16x16x32_bf16 v[92:95], v[112:115], v[182:185], 0
	v_mfma_f32_16x16x32_bf16 v[88:91], v[152:155], v[182:185], 0
	v_mfma_f32_16x16x32_bf16 v[84:87], v[112:115], v[190:193], 0
	v_mfma_f32_16x16x32_bf16 v[80:83], v[152:155], v[190:193], 0
	v_mfma_f32_16x16x32_bf16 v[76:79], v[112:115], v[202:205], 0
	v_mfma_f32_16x16x32_bf16 v[72:75], v[152:155], v[202:205], 0
	v_mfma_f32_16x16x32_bf16 v[68:71], v[112:115], v[210:213], 0
	v_mfma_f32_16x16x32_bf16 v[64:67], v[152:155], v[210:213], 0
	v_mfma_f32_16x16x32_bf16 v[92:95], v[116:119], v[186:189], v[92:95]
	v_mfma_f32_16x16x32_bf16 v[88:91], v[156:159], v[186:189], v[88:91]
	v_mfma_f32_16x16x32_bf16 v[84:87], v[116:119], v[198:201], v[84:87]
	v_mfma_f32_16x16x32_bf16 v[80:83], v[156:159], v[198:201], v[80:83]
	v_mfma_f32_16x16x32_bf16 v[76:79], v[116:119], v[206:209], v[76:79]
	v_mfma_f32_16x16x32_bf16 v[72:75], v[156:159], v[206:209], v[72:75]
	v_mfma_f32_16x16x32_bf16 v[68:71], v[116:119], v[214:217], v[68:71]
	v_mfma_f32_16x16x32_bf16 v[64:67], v[156:159], v[214:217], v[64:67]
	v_mfma_f32_16x16x32_bf16 v[28:31], v[160:163], v[182:185], 0
	v_mfma_f32_16x16x32_bf16 v[24:27], v[174:177], v[182:185], 0
	v_mfma_f32_16x16x32_bf16 v[20:23], v[160:163], v[190:193], 0
	v_mfma_f32_16x16x32_bf16 v[16:19], v[174:177], v[190:193], 0
	v_mfma_f32_16x16x32_bf16 v[12:15], v[160:163], v[202:205], 0
	v_mfma_f32_16x16x32_bf16 v[8:11], v[174:177], v[202:205], 0
	v_mfma_f32_16x16x32_bf16 v[4:7], v[160:163], v[210:213], 0
	v_mfma_f32_16x16x32_bf16 v[0:3], v[174:177], v[210:213], 0
	v_mfma_f32_16x16x32_bf16 v[28:31], v[170:173], v[186:189], v[28:31]
	v_mfma_f32_16x16x32_bf16 v[24:27], v[178:181], v[186:189], v[24:27]
	v_mfma_f32_16x16x32_bf16 v[20:23], v[170:173], v[198:201], v[20:23]
	v_mfma_f32_16x16x32_bf16 v[16:19], v[178:181], v[198:201], v[16:19]
	v_mfma_f32_16x16x32_bf16 v[12:15], v[170:173], v[206:209], v[12:15]
	v_mfma_f32_16x16x32_bf16 v[8:11], v[178:181], v[206:209], v[8:11]
	v_mfma_f32_16x16x32_bf16 v[4:7], v[170:173], v[214:217], v[4:7]
	v_mfma_f32_16x16x32_bf16 v[0:3], v[178:181], v[214:217], v[0:3]
	s_setprio 0
	s_barrier
	s_add_i32 s68, 0, 0x18000
	s_add_i32 s69, 0, 0x1c000
	v_add_u32_e32 v156, s68, v165
	v_add_u32_e32 v178, s69, v165
	ds_read_b128 v[112:115], v156
	ds_read_b128 v[116:119], v156 offset:1024
	ds_read_b128 v[152:155], v156 offset:2048
	ds_read_b128 v[156:159], v156 offset:3072
	ds_read_b128 v[160:163], v178
	ds_read_b128 v[170:173], v178 offset:1024
	ds_read_b128 v[174:177], v178 offset:2048
	ds_read_b128 v[178:181], v178 offset:3072
	s_add_u32 s48, s48, 0x20000
	s_addc_u32 s49, s49, 0
	s_mov_b32 m0, s53
	v_lshl_add_u64 v[224:225], s[48:49], 0, v[136:137]
	ds_read_b128 v[182:185], v169 offset:32768
	ds_read_b128 v[186:189], v169 offset:33792
	ds_read_b128 v[190:193], v169 offset:34816
	ds_read_b128 v[198:201], v169 offset:35840
	ds_read_b128 v[202:205], v169 offset:36864
	ds_read_b128 v[206:209], v169 offset:37888
	ds_read_b128 v[210:213], v169 offset:38912
	ds_read_b128 v[214:217], v169 offset:39936
	global_load_lds_dwordx4 v[224:225], off
	v_lshl_add_u64 v[224:225], s[48:49], 0, v[140:141]
	s_mov_b32 m0, s54
	s_nop 0
	global_load_lds_dwordx4 v[224:225], off
	s_waitcnt vmcnt(8)
	s_waitcnt lgkmcnt(0)
	s_barrier
	s_setprio 1
	s_waitcnt lgkmcnt(0)
	v_mfma_f32_16x16x32_bf16 v[132:135], v[112:115], v[182:185], v[132:135]
	v_mfma_f32_16x16x32_bf16 v[128:131], v[152:155], v[182:185], v[128:131]
	v_mfma_f32_16x16x32_bf16 v[124:127], v[112:115], v[190:193], v[124:127]
	v_mfma_f32_16x16x32_bf16 v[120:123], v[152:155], v[190:193], v[120:123]
	v_mfma_f32_16x16x32_bf16 v[108:111], v[112:115], v[202:205], v[108:111]
	v_mfma_f32_16x16x32_bf16 v[104:107], v[152:155], v[202:205], v[104:107]
	v_mfma_f32_16x16x32_bf16 v[100:103], v[112:115], v[210:213], v[100:103]
	v_mfma_f32_16x16x32_bf16 v[96:99], v[152:155], v[210:213], v[96:99]
	v_mfma_f32_16x16x32_bf16 v[132:135], v[116:119], v[186:189], v[132:135]
	v_mfma_f32_16x16x32_bf16 v[128:131], v[156:159], v[186:189], v[128:131]
	v_mfma_f32_16x16x32_bf16 v[124:127], v[116:119], v[198:201], v[124:127]
	v_mfma_f32_16x16x32_bf16 v[120:123], v[156:159], v[198:201], v[120:123]
	v_mfma_f32_16x16x32_bf16 v[108:111], v[116:119], v[206:209], v[108:111]
	v_mfma_f32_16x16x32_bf16 v[104:107], v[156:159], v[206:209], v[104:107]
	v_mfma_f32_16x16x32_bf16 v[100:103], v[116:119], v[214:217], v[100:103]
	v_mfma_f32_16x16x32_bf16 v[96:99], v[156:159], v[214:217], v[96:99]
	v_mfma_f32_16x16x32_bf16 v[60:63], v[160:163], v[182:185], v[60:63]
	v_mfma_f32_16x16x32_bf16 v[56:59], v[174:177], v[182:185], v[56:59]
	v_mfma_f32_16x16x32_bf16 v[52:55], v[160:163], v[190:193], v[52:55]
	v_mfma_f32_16x16x32_bf16 v[48:51], v[174:177], v[190:193], v[48:51]
	v_mfma_f32_16x16x32_bf16 v[44:47], v[160:163], v[202:205], v[44:47]
	v_mfma_f32_16x16x32_bf16 v[40:43], v[174:177], v[202:205], v[40:43]
	v_mfma_f32_16x16x32_bf16 v[36:39], v[160:163], v[210:213], v[36:39]
	v_mfma_f32_16x16x32_bf16 v[32:35], v[174:177], v[210:213], v[32:35]
	v_mfma_f32_16x16x32_bf16 v[60:63], v[170:173], v[186:189], v[60:63]
	v_mfma_f32_16x16x32_bf16 v[56:59], v[178:181], v[186:189], v[56:59]
	v_mfma_f32_16x16x32_bf16 v[52:55], v[170:173], v[198:201], v[52:55]
	v_mfma_f32_16x16x32_bf16 v[48:51], v[178:181], v[198:201], v[48:51]
	v_mfma_f32_16x16x32_bf16 v[44:47], v[170:173], v[206:209], v[44:47]
	v_mfma_f32_16x16x32_bf16 v[40:43], v[178:181], v[206:209], v[40:43]
	v_mfma_f32_16x16x32_bf16 v[36:39], v[170:173], v[214:217], v[36:39]
	v_mfma_f32_16x16x32_bf16 v[32:35], v[178:181], v[214:217], v[32:35]
	s_setprio 0
	s_barrier
; #define PG8_STAGE(bufoff, gbase, voff) do { _Pragma("unroll") for (int _i = 0; _i < 2; ++_i) \
;         __builtin_amdgcn_global_load_lds((const unsigned*)((const char*)(gbase) + (voff)[_i]), (PG8_LAS unsigned*)(lds + (bufoff) + ldsw + _i * 8192), 16, 0, 0); } while (0)
; #define PG8_LDA(dst, b, h) do { _Pragma("unroll") for (int m = 0; m < 4; ++m) _Pragma("unroll") for (int k = 0; k < 2; ++k) dst[m][k] = *(const PG8_LAS bf16x8*)(lds + PG8_SA(b, h) + aoff + m * 2048 + k * 1024); } while (0)
; #define PG8_LDB(dst, b, h) do { _Pragma("unroll") for (int n = 0; n < 2; ++n) _Pragma("unroll") for (int k = 0; k < 2; ++k) dst[n][k] = *(const PG8_LAS bf16x8*)(lds + PG8_SB(b, h) + boff + n * 2048 + k * 1024); } while (0)
; #define PG8_MMA(ai, bj, At, Bt) do { __builtin_amdgcn_s_setprio(1); _Pragma("unroll") for (int m = 0; m < 4; ++m) _Pragma("unroll") for (int n = 0; n < 2; ++n) _Pragma("unroll") for (int k = 0; k < 2; ++k) \
;         acc[ai][bj][m][n] = __builtin_amdgcn_mfma_f32_16x16x32_bf16(Bt[n][k], At[m][k], acc[ai][bj][m][n], 0, 0, 0); __builtin_amdgcn_s_setprio(0); } while (0)
; #define PG8_WAIT_V(n) asm volatile("s_waitcnt vmcnt(" #n ")" ::: "memory")
; template <class Epi, class Sched, bool ALIGN_EPI = false, bool SP2 = false>
; __device__ __forceinline__ void gemm_phase(PG8_LAS unsigned char* lds, const Gemm g, const Sched& S, const Epi& E) {
;     ...
;             PG8_LDB(B0, 0, 0); PG8_LDB(B1, 0, 1); PG8_SCHED; PG8_LDA(At, 0, 0); PG8_STAGE(PG8_SA(1, 1), a1 + hstep, voffA);
;             PG8_WAIT_V(8); PG8_WAIT_L(0); PG8_BAR; PG8_MMA(0, 0, At, B0); PG8_MMA(0, 1, At, B1); PG8_BAR; PG8_SCHED;
;             PG8_LDA(At, 0, 1); PG8_STAGE(PG8_SB(0, 0), b2, voffB); PG8_STAGE(PG8_SB(0, 1), b2 + hstep, voffB); PG8_STAGE(PG8_SA(0, 0), a2, voffA);
;             PG8_WAIT_V(8); PG8_WAIT_L(0); PG8_BAR; PG8_MMA(1, 0, At, B0); PG8_MMA(1, 1, At, B1); PG8_BAR; PG8_SCHED;
;             PG8_LDB(B0, 1, 0); PG8_LDB(B1, 1, 1); PG8_SCHED; PG8_LDA(At, 1, 0); PG8_STAGE(PG8_SA(0, 1), a2 + hstep, voffA);
;             PG8_WAIT_V(8); PG8_WAIT_L(0); PG8_BAR; PG8_MMA(0, 0, At, B0); PG8_MMA(0, 1, At, B1); PG8_BAR; PG8_SCHED;
;             PG8_LDA(At, 1, 1); PG8_STAGE(PG8_SB(1, 0), b3, voffB); PG8_STAGE(PG8_SB(1, 1), b3 + hstep, voffB); PG8_STAGE(PG8_SA(1, 0), a3, voffA);
;             PG8_WAIT_V(8); PG8_WAIT_L(0); PG8_BAR; PG8_MMA(1, 0, At, B0); PG8_MMA(1, 1, At, B1); PG8_BAR; PG8_SCHED;
	s_add_i32 s48, s68, s51
	v_lshl_add_u64 v[194:195], v[194:195], 0, s[10:11]
	s_mov_b32 m0, s48
	ds_read_b128 v[182:185], v169 offset:49152
	ds_read_b128 v[186:189], v169 offset:50176
	ds_read_b128 v[190:193], v169 offset:51200
	ds_read_b128 v[198:201], v169 offset:52224
	ds_read_b128 v[202:205], v169 offset:53248
	ds_read_b128 v[206:209], v169 offset:54272
	ds_read_b128 v[210:213], v169 offset:55296
	ds_read_b128 v[214:217], v169 offset:56320
	global_load_lds_dwordx4 v[194:195], off
	s_add_i32 m0, s48, 0x2000
	s_add_u32 s46, s46, 0x20080
	v_lshl_add_u64 v[194:195], v[218:219], 0, s[10:11]
	s_addc_u32 s47, s47, 0
	s_add_i32 s48, s69, s51
	global_load_lds_dwordx4 v[194:195], off
	v_lshl_add_u64 v[194:195], s[46:47], 0, v[138:139]
	s_mov_b32 m0, s48
	s_nop 0
	global_load_lds_dwordx4 v[194:195], off
	v_lshl_add_u64 v[194:195], s[46:47], 0, v[142:143]
	s_add_i32 m0, s48, 0x2000
	s_nop 0
	global_load_lds_dwordx4 v[194:195], off
	v_lshl_add_u64 v[194:195], v[220:221], 0, s[10:11]
	s_mov_b32 m0, s56
	s_nop 0
	global_load_lds_dwordx4 v[194:195], off
	v_lshl_add_u64 v[194:195], v[222:223], 0, s[10:11]
	s_mov_b32 m0, s57
	s_nop 0
	global_load_lds_dwordx4 v[194:195], off
	s_waitcnt vmcnt(8)
	s_waitcnt lgkmcnt(0)
	s_barrier
	s_setprio 1
	s_waitcnt lgkmcnt(0)
	v_mfma_f32_16x16x32_bf16 v[92:95], v[112:115], v[182:185], v[92:95]
	v_mfma_f32_16x16x32_bf16 v[88:91], v[152:155], v[182:185], v[88:91]
	v_mfma_f32_16x16x32_bf16 v[84:87], v[112:115], v[190:193], v[84:87]
	v_mfma_f32_16x16x32_bf16 v[80:83], v[152:155], v[190:193], v[80:83]
	v_mfma_f32_16x16x32_bf16 v[76:79], v[112:115], v[202:205], v[76:79]
	v_mfma_f32_16x16x32_bf16 v[72:75], v[152:155], v[202:205], v[72:75]
	v_mfma_f32_16x16x32_bf16 v[68:71], v[112:115], v[210:213], v[68:71]
	v_mfma_f32_16x16x32_bf16 v[64:67], v[152:155], v[210:213], v[64:67]
	v_mfma_f32_16x16x32_bf16 v[92:95], v[116:119], v[186:189], v[92:95]
	v_mfma_f32_16x16x32_bf16 v[88:91], v[156:159], v[186:189], v[88:91]
	v_mfma_f32_16x16x32_bf16 v[84:87], v[116:119], v[198:201], v[84:87]
	v_mfma_f32_16x16x32_bf16 v[80:83], v[156:159], v[198:201], v[80:83]
	v_mfma_f32_16x16x32_bf16 v[76:79], v[116:119], v[206:209], v[76:79]
	v_mfma_f32_16x16x32_bf16 v[72:75], v[156:159], v[206:209], v[72:75]
	v_mfma_f32_16x16x32_bf16 v[68:71], v[116:119], v[214:217], v[68:71]
	v_mfma_f32_16x16x32_bf16 v[64:67], v[156:159], v[214:217], v[64:67]
	v_mfma_f32_16x16x32_bf16 v[28:31], v[160:163], v[182:185], v[28:31]
	v_mfma_f32_16x16x32_bf16 v[24:27], v[174:177], v[182:185], v[24:27]
	v_mfma_f32_16x16x32_bf16 v[20:23], v[160:163], v[190:193], v[20:23]
	v_mfma_f32_16x16x32_bf16 v[16:19], v[174:177], v[190:193], v[16:19]
	v_mfma_f32_16x16x32_bf16 v[12:15], v[160:163], v[202:205], v[12:15]
	v_mfma_f32_16x16x32_bf16 v[8:11], v[174:177], v[202:205], v[8:11]
	v_mfma_f32_16x16x32_bf16 v[4:7], v[160:163], v[210:213], v[4:7]
	v_mfma_f32_16x16x32_bf16 v[0:3], v[174:177], v[210:213], v[0:3]
	v_mfma_f32_16x16x32_bf16 v[28:31], v[170:173], v[186:189], v[28:31]
	v_mfma_f32_16x16x32_bf16 v[24:27], v[178:181], v[186:189], v[24:27]
	v_mfma_f32_16x16x32_bf16 v[20:23], v[170:173], v[198:201], v[20:23]
	v_mfma_f32_16x16x32_bf16 v[16:19], v[178:181], v[198:201], v[16:19]
	v_mfma_f32_16x16x32_bf16 v[12:15], v[170:173], v[206:209], v[12:15]
	v_mfma_f32_16x16x32_bf16 v[8:11], v[178:181], v[206:209], v[8:11]
	v_mfma_f32_16x16x32_bf16 v[4:7], v[170:173], v[214:217], v[4:7]
	v_mfma_f32_16x16x32_bf16 v[0:3], v[178:181], v[214:217], v[0:3]
	s_setprio 0
	s_barrier
	s_add_i32 s67, s67, 2
	s_add_u32 s20, s20, 0x100
	s_addc_u32 s21, s21, 0
	s_add_u32 s65, s65, 0x100
	s_addc_u32 s66, s66, 0
	s_cmp_gt_u32 s67, 5
.LBB0_624:
	ds_read_b128 v[112:115], v167
	ds_read_b128 v[116:119], v167 offset:1024
	ds_read_b128 v[152:155], v167 offset:2048
	ds_read_b128 v[156:159], v167 offset:3072
	ds_read_b128 v[160:163], v168
	ds_read_b128 v[170:173], v168 offset:1024
	ds_read_b128 v[174:177], v168 offset:2048
	ds_read_b128 v[178:181], v168 offset:3072
	s_add_u32 s46, s20, 0xfffe0080
	s_addc_u32 s47, s21, -1
	s_cmp_eq_u32 s67, 4
	s_cselect_b32 s49, s17, s47
	s_cselect_b32 s48, s63, s46
	s_cselect_b32 s47, s15, s66
	s_cselect_b32 s46, s64, s65
	v_lshl_add_u64 v[194:195], s[20:21], 0, v[144:145]
	s_add_i32 m0, s35, 0xc000
	ds_read_b128 v[182:185], v169
	ds_read_b128 v[186:189], v169 offset:1024
	ds_read_b128 v[190:193], v169 offset:2048
	ds_read_b128 v[198:201], v169 offset:3072
	ds_read_b128 v[202:205], v169 offset:4096
	ds_read_b128 v[206:209], v169 offset:5120
	ds_read_b128 v[210:213], v169 offset:6144
	ds_read_b128 v[214:217], v169 offset:7168
	global_load_lds_dwordx4 v[194:195], off
	v_lshl_add_u64 v[194:195], s[20:21], 0, v[146:147]
	s_add_i32 m0, s35, 0xe000
	s_nop 0
	global_load_lds_dwordx4 v[194:195], off
	s_waitcnt vmcnt(8)
	s_waitcnt lgkmcnt(0)
	s_barrier
; #define PG8_STAGE(bufoff, gbase, voff) do { _Pragma("unroll") for (int _i = 0; _i < 2; ++_i) \
;         __builtin_amdgcn_global_load_lds((const unsigned*)((const char*)(gbase) + (voff)[_i]), (PG8_LAS unsigned*)(lds + (bufoff) + ldsw + _i * 8192), 16, 0, 0); } while (0)
; #define PG8_LDA(dst, b, h) do { _Pragma("unroll") for (int m = 0; m < 4; ++m) _Pragma("unroll") for (int k = 0; k < 2; ++k) dst[m][k] = *(const PG8_LAS bf16x8*)(lds + PG8_SA(b, h) + aoff + m * 2048 + k * 1024); } while (0)
; #define PG8_MMA(ai, bj, At, Bt) do { __builtin_amdgcn_s_setprio(1); _Pragma("unroll") for (int m = 0; m < 4; ++m) _Pragma("unroll") for (int n = 0; n < 2; ++n) _Pragma("unroll") for (int k = 0; k < 2; ++k) \
;         acc[ai][bj][m][n] = __builtin_amdgcn_mfma_f32_16x16x32_bf16(Bt[n][k], At[m][k], acc[ai][bj][m][n], 0, 0, 0); __builtin_amdgcn_s_setprio(0); } while (0)
; #define PG8_WAIT_V(n) asm volatile("s_waitcnt vmcnt(" #n ")" ::: "memory")
; #define PG8_WAIT_L(n) asm volatile("s_waitcnt lgkmcnt(" #n ")" ::: "memory")
; #define PG8_BAR __builtin_amdgcn_s_barrier()
; #define PG8_SCHED __builtin_amdgcn_sched_barrier(0)
; template <class Epi, class Sched, bool ALIGN_EPI = false, bool SP2 = false>
; __device__ __forceinline__ void gemm_phase(PG8_LAS unsigned char* lds, const Gemm g, const Sched& S, const Epi& E) {
;     ...
;             PG8_WAIT_V(8); PG8_WAIT_L(0); PG8_BAR; PG8_MMA(0, 0, At, B0); PG8_MMA(0, 1, At, B1); PG8_BAR; PG8_SCHED;
;             PG8_LDA(At, 0, 1); PG8_STAGE(PG8_SB(0, 0), b2, voffB); PG8_STAGE(PG8_SB(0, 1), b2 + hstep, voffB); PG8_STAGE(PG8_SA(0, 0), a2, voffA);
;             PG8_WAIT_V(8); PG8_WAIT_L(0); PG8_BAR; PG8_MMA(1, 0, At, B0); PG8_MMA(1, 1, At, B1); PG8_BAR; PG8_SCHED;
	s_setprio 1
	s_waitcnt lgkmcnt(0)
	v_mfma_f32_16x16x32_bf16 v[132:135], v[112:115], v[182:185], v[132:135]
	v_mfma_f32_16x16x32_bf16 v[128:131], v[152:155], v[182:185], v[128:131]
	v_mfma_f32_16x16x32_bf16 v[124:127], v[112:115], v[190:193], v[124:127]
	v_mfma_f32_16x16x32_bf16 v[120:123], v[152:155], v[190:193], v[120:123]
	v_mfma_f32_16x16x32_bf16 v[108:111], v[112:115], v[202:205], v[108:111]
	v_mfma_f32_16x16x32_bf16 v[104:107], v[152:155], v[202:205], v[104:107]
	v_mfma_f32_16x16x32_bf16 v[100:103], v[112:115], v[210:213], v[100:103]
	v_mfma_f32_16x16x32_bf16 v[96:99], v[152:155], v[210:213], v[96:99]
	v_mfma_f32_16x16x32_bf16 v[132:135], v[116:119], v[186:189], v[132:135]
	v_mfma_f32_16x16x32_bf16 v[128:131], v[156:159], v[186:189], v[128:131]
	v_mfma_f32_16x16x32_bf16 v[124:127], v[116:119], v[198:201], v[124:127]
	v_mfma_f32_16x16x32_bf16 v[120:123], v[156:159], v[198:201], v[120:123]
	v_mfma_f32_16x16x32_bf16 v[108:111], v[116:119], v[206:209], v[108:111]
	v_mfma_f32_16x16x32_bf16 v[104:107], v[156:159], v[206:209], v[104:107]
	v_mfma_f32_16x16x32_bf16 v[100:103], v[116:119], v[214:217], v[100:103]
	v_mfma_f32_16x16x32_bf16 v[96:99], v[156:159], v[214:217], v[96:99]
	v_mfma_f32_16x16x32_bf16 v[60:63], v[160:163], v[182:185], v[60:63]
	v_mfma_f32_16x16x32_bf16 v[56:59], v[174:177], v[182:185], v[56:59]
	v_mfma_f32_16x16x32_bf16 v[52:55], v[160:163], v[190:193], v[52:55]
	v_mfma_f32_16x16x32_bf16 v[48:51], v[174:177], v[190:193], v[48:51]
	v_mfma_f32_16x16x32_bf16 v[44:47], v[160:163], v[202:205], v[44:47]
	v_mfma_f32_16x16x32_bf16 v[40:43], v[174:177], v[202:205], v[40:43]
	v_mfma_f32_16x16x32_bf16 v[36:39], v[160:163], v[210:213], v[36:39]
	v_mfma_f32_16x16x32_bf16 v[32:35], v[174:177], v[210:213], v[32:35]
	v_mfma_f32_16x16x32_bf16 v[60:63], v[170:173], v[186:189], v[60:63]
	v_mfma_f32_16x16x32_bf16 v[56:59], v[178:181], v[186:189], v[56:59]
	v_mfma_f32_16x16x32_bf16 v[52:55], v[170:173], v[198:201], v[52:55]
	v_mfma_f32_16x16x32_bf16 v[48:51], v[178:181], v[198:201], v[48:51]
	v_mfma_f32_16x16x32_bf16 v[44:47], v[170:173], v[206:209], v[44:47]
	v_mfma_f32_16x16x32_bf16 v[40:43], v[178:181], v[206:209], v[40:43]
	v_mfma_f32_16x16x32_bf16 v[36:39], v[170:173], v[214:217], v[36:39]
	v_mfma_f32_16x16x32_bf16 v[32:35], v[178:181], v[214:217], v[32:35]
	s_setprio 0
	s_barrier
	s_add_i32 s68, s60, s51
	v_lshl_add_u64 v[194:195], s[46:47], 0, v[138:139]
	s_mov_b32 m0, s68
	ds_read_b128 v[182:185], v169 offset:16384
	ds_read_b128 v[186:189], v169 offset:17408
	ds_read_b128 v[190:193], v169 offset:18432
	ds_read_b128 v[198:201], v169 offset:19456
	ds_read_b128 v[202:205], v169 offset:20480
	ds_read_b128 v[206:209], v169 offset:21504
	ds_read_b128 v[210:213], v169 offset:22528
	ds_read_b128 v[214:217], v169 offset:23552
	global_load_lds_dwordx4 v[194:195], off
	s_add_i32 m0, s68, 0x2000
	s_add_u32 s68, s46, 0x20000
	v_lshl_add_u64 v[218:219], s[46:47], 0, v[142:143]
	s_addc_u32 s69, s47, 0
	s_add_i32 s70, s61, s51
	global_load_lds_dwordx4 v[218:219], off
	v_lshl_add_u64 v[220:221], s[68:69], 0, v[138:139]
	s_mov_b32 m0, s70
	v_lshl_add_u64 v[222:223], s[48:49], 0, v[140:141]
	global_load_lds_dwordx4 v[220:221], off
	v_lshl_add_u64 v[220:221], s[68:69], 0, v[142:143]
	s_add_i32 m0, s70, 0x2000
	s_nop 0
	global_load_lds_dwordx4 v[220:221], off
	v_lshl_add_u64 v[220:221], s[48:49], 0, v[136:137]
	s_mov_b32 m0, s35
	s_nop 0
	global_load_lds_dwordx4 v[220:221], off
	s_mov_b32 m0, s52
	s_nop 0
	global_load_lds_dwordx4 v[222:223], off
	s_waitcnt vmcnt(8)
	s_waitcnt lgkmcnt(0)
	s_barrier
	s_setprio 1
	s_waitcnt lgkmcnt(0)
	v_mfma_f32_16x16x32_bf16 v[92:95], v[112:115], v[182:185], v[92:95]
	v_mfma_f32_16x16x32_bf16 v[88:91], v[152:155], v[182:185], v[88:91]
	v_mfma_f32_16x16x32_bf16 v[84:87], v[112:115], v[190:193], v[84:87]
	v_mfma_f32_16x16x32_bf16 v[80:83], v[152:155], v[190:193], v[80:83]
	v_mfma_f32_16x16x32_bf16 v[76:79], v[112:115], v[202:205], v[76:79]
	v_mfma_f32_16x16x32_bf16 v[72:75], v[152:155], v[202:205], v[72:75]
	v_mfma_f32_16x16x32_bf16 v[68:71], v[112:115], v[210:213], v[68:71]
	v_mfma_f32_16x16x32_bf16 v[64:67], v[152:155], v[210:213], v[64:67]
	v_mfma_f32_16x16x32_bf16 v[92:95], v[116:119], v[186:189], v[92:95]
	v_mfma_f32_16x16x32_bf16 v[88:91], v[156:159], v[186:189], v[88:91]
	v_mfma_f32_16x16x32_bf16 v[84:87], v[116:119], v[198:201], v[84:87]
	v_mfma_f32_16x16x32_bf16 v[80:83], v[156:159], v[198:201], v[80:83]
	v_mfma_f32_16x16x32_bf16 v[76:79], v[116:119], v[206:209], v[76:79]
	v_mfma_f32_16x16x32_bf16 v[72:75], v[156:159], v[206:209], v[72:75]
	v_mfma_f32_16x16x32_bf16 v[68:71], v[116:119], v[214:217], v[68:71]
	v_mfma_f32_16x16x32_bf16 v[64:67], v[156:159], v[214:217], v[64:67]
	v_mfma_f32_16x16x32_bf16 v[28:31], v[160:163], v[182:185], v[28:31]
	v_mfma_f32_16x16x32_bf16 v[24:27], v[174:177], v[182:185], v[24:27]
	v_mfma_f32_16x16x32_bf16 v[20:23], v[160:163], v[190:193], v[20:23]
	v_mfma_f32_16x16x32_bf16 v[16:19], v[174:177], v[190:193], v[16:19]
	v_mfma_f32_16x16x32_bf16 v[12:15], v[160:163], v[202:205], v[12:15]
	v_mfma_f32_16x16x32_bf16 v[8:11], v[174:177], v[202:205], v[8:11]
	v_mfma_f32_16x16x32_bf16 v[4:7], v[160:163], v[210:213], v[4:7]
	v_mfma_f32_16x16x32_bf16 v[0:3], v[174:177], v[210:213], v[0:3]
	v_mfma_f32_16x16x32_bf16 v[28:31], v[170:173], v[186:189], v[28:31]
	v_mfma_f32_16x16x32_bf16 v[24:27], v[178:181], v[186:189], v[24:27]
	v_mfma_f32_16x16x32_bf16 v[20:23], v[170:173], v[198:201], v[20:23]
	v_mfma_f32_16x16x32_bf16 v[16:19], v[178:181], v[198:201], v[16:19]
	v_mfma_f32_16x16x32_bf16 v[12:15], v[170:173], v[206:209], v[12:15]
	v_mfma_f32_16x16x32_bf16 v[8:11], v[178:181], v[206:209], v[8:11]
	v_mfma_f32_16x16x32_bf16 v[4:7], v[170:173], v[214:217], v[4:7]
	v_mfma_f32_16x16x32_bf16 v[0:3], v[178:181], v[214:217], v[0:3]
	s_setprio 0
	s_barrier
; #define PG8_STAGE(bufoff, gbase, voff) do { _Pragma("unroll") for (int _i = 0; _i < 2; ++_i) \
;         __builtin_amdgcn_global_load_lds((const unsigned*)((const char*)(gbase) + (voff)[_i]), (PG8_LAS unsigned*)(lds + (bufoff) + ldsw + _i * 8192), 16, 0, 0); } while (0)
; #define PG8_LDA(dst, b, h) do { _Pragma("unroll") for (int m = 0; m < 4; ++m) _Pragma("unroll") for (int k = 0; k < 2; ++k) dst[m][k] = *(const PG8_LAS bf16x8*)(lds + PG8_SA(b, h) + aoff + m * 2048 + k * 1024); } while (0)
; #define PG8_LDB(dst, b, h) do { _Pragma("unroll") for (int n = 0; n < 2; ++n) _Pragma("unroll") for (int k = 0; k < 2; ++k) dst[n][k] = *(const PG8_LAS bf16x8*)(lds + PG8_SB(b, h) + boff + n * 2048 + k * 1024); } while (0)
; #define PG8_MMA(ai, bj, At, Bt) do { __builtin_amdgcn_s_setprio(1); _Pragma("unroll") for (int m = 0; m < 4; ++m) _Pragma("unroll") for (int n = 0; n < 2; ++n) _Pragma("unroll") for (int k = 0; k < 2; ++k) \
;         acc[ai][bj][m][n] = __builtin_amdgcn_mfma_f32_16x16x32_bf16(Bt[n][k], At[m][k], acc[ai][bj][m][n], 0, 0, 0); __builtin_amdgcn_s_setprio(0); } while (0)
; #define PG8_WAIT_V(n) asm volatile("s_waitcnt vmcnt(" #n ")" ::: "memory")
; #define PG8_WAIT_L(n) asm volatile("s_waitcnt lgkmcnt(" #n ")" ::: "memory")
; #define PG8_BAR __builtin_amdgcn_s_barrier()
; #define PG8_SCHED __builtin_amdgcn_sched_barrier(0)
; template <class Epi, class Sched, bool ALIGN_EPI = false, bool SP2 = false>
; __device__ __forceinline__ void gemm_phase(PG8_LAS unsigned char* lds, const Gemm g, const Sched& S, const Epi& E) {
;     ...
;             PG8_LDB(B0, 1, 0); PG8_LDB(B1, 1, 1); PG8_SCHED; PG8_LDA(At, 1, 0); PG8_STAGE(PG8_SA(0, 1), a2 + hstep, voffA);
;             PG8_WAIT_V(8); PG8_WAIT_L(0); PG8_BAR; PG8_MMA(0, 0, At, B0); PG8_MMA(0, 1, At, B1); PG8_BAR; PG8_SCHED;
	s_add_i32 s68, 0, 0x18000
	s_add_i32 s69, 0, 0x1c000
	v_add_u32_e32 v156, s68, v165
	v_add_u32_e32 v178, s69, v165
	ds_read_b128 v[112:115], v156
	ds_read_b128 v[116:119], v156 offset:1024
	ds_read_b128 v[152:155], v156 offset:2048
	ds_read_b128 v[156:159], v156 offset:3072
	ds_read_b128 v[160:163], v178
	ds_read_b128 v[170:173], v178 offset:1024
	ds_read_b128 v[174:177], v178 offset:2048
	ds_read_b128 v[178:181], v178 offset:3072
	s_add_u32 s48, s48, 0x20000
	s_addc_u32 s49, s49, 0
	s_mov_b32 m0, s53
	v_lshl_add_u64 v[224:225], s[48:49], 0, v[136:137]
	ds_read_b128 v[182:185], v169 offset:32768
	ds_read_b128 v[186:189], v169 offset:33792
	ds_read_b128 v[190:193], v169 offset:34816
	ds_read_b128 v[198:201], v169 offset:35840
	ds_read_b128 v[202:205], v169 offset:36864
	ds_read_b128 v[206:209], v169 offset:37888
	ds_read_b128 v[210:213], v169 offset:38912
	ds_read_b128 v[214:217], v169 offset:39936
	global_load_lds_dwordx4 v[224:225], off
	v_lshl_add_u64 v[224:225], s[48:49], 0, v[140:141]
	s_mov_b32 m0, s54
	s_nop 0
	global_load_lds_dwordx4 v[224:225], off
	s_waitcnt vmcnt(8)
	s_waitcnt lgkmcnt(0)
	s_barrier
	s_setprio 1
	s_waitcnt lgkmcnt(0)
	v_mfma_f32_16x16x32_bf16 v[132:135], v[112:115], v[182:185], v[132:135]
	v_mfma_f32_16x16x32_bf16 v[128:131], v[152:155], v[182:185], v[128:131]
	v_mfma_f32_16x16x32_bf16 v[124:127], v[112:115], v[190:193], v[124:127]
	v_mfma_f32_16x16x32_bf16 v[120:123], v[152:155], v[190:193], v[120:123]
	v_mfma_f32_16x16x32_bf16 v[108:111], v[112:115], v[202:205], v[108:111]
	v_mfma_f32_16x16x32_bf16 v[104:107], v[152:155], v[202:205], v[104:107]
	v_mfma_f32_16x16x32_bf16 v[100:103], v[112:115], v[210:213], v[100:103]
	v_mfma_f32_16x16x32_bf16 v[96:99], v[152:155], v[210:213], v[96:99]
	v_mfma_f32_16x16x32_bf16 v[132:135], v[116:119], v[186:189], v[132:135]
	v_mfma_f32_16x16x32_bf16 v[128:131], v[156:159], v[186:189], v[128:131]
	v_mfma_f32_16x16x32_bf16 v[124:127], v[116:119], v[198:201], v[124:127]
	v_mfma_f32_16x16x32_bf16 v[120:123], v[156:159], v[198:201], v[120:123]
	v_mfma_f32_16x16x32_bf16 v[108:111], v[116:119], v[206:209], v[108:111]
	v_mfma_f32_16x16x32_bf16 v[104:107], v[156:159], v[206:209], v[104:107]
	v_mfma_f32_16x16x32_bf16 v[100:103], v[116:119], v[214:217], v[100:103]
	v_mfma_f32_16x16x32_bf16 v[96:99], v[156:159], v[214:217], v[96:99]
	v_mfma_f32_16x16x32_bf16 v[60:63], v[160:163], v[182:185], v[60:63]
	v_mfma_f32_16x16x32_bf16 v[56:59], v[174:177], v[182:185], v[56:59]
	v_mfma_f32_16x16x32_bf16 v[52:55], v[160:163], v[190:193], v[52:55]
	v_mfma_f32_16x16x32_bf16 v[48:51], v[174:177], v[190:193], v[48:51]
	v_mfma_f32_16x16x32_bf16 v[44:47], v[160:163], v[202:205], v[44:47]
	v_mfma_f32_16x16x32_bf16 v[40:43], v[174:177], v[202:205], v[40:43]
	v_mfma_f32_16x16x32_bf16 v[36:39], v[160:163], v[210:213], v[36:39]
	v_mfma_f32_16x16x32_bf16 v[32:35], v[174:177], v[210:213], v[32:35]
	v_mfma_f32_16x16x32_bf16 v[60:63], v[170:173], v[186:189], v[60:63]
	v_mfma_f32_16x16x32_bf16 v[56:59], v[178:181], v[186:189], v[56:59]
	v_mfma_f32_16x16x32_bf16 v[52:55], v[170:173], v[198:201], v[52:55]
	v_mfma_f32_16x16x32_bf16 v[48:51], v[178:181], v[198:201], v[48:51]
	v_mfma_f32_16x16x32_bf16 v[44:47], v[170:173], v[206:209], v[44:47]
	v_mfma_f32_16x16x32_bf16 v[40:43], v[178:181], v[206:209], v[40:43]
	v_mfma_f32_16x16x32_bf16 v[36:39], v[170:173], v[214:217], v[36:39]
	v_mfma_f32_16x16x32_bf16 v[32:35], v[178:181], v[214:217], v[32:35]
	s_setprio 0
	s_barrier
; #define PG8_STAGE(bufoff, gbase, voff) do { _Pragma("unroll") for (int _i = 0; _i < 2; ++_i) \
;         __builtin_amdgcn_global_load_lds((const unsigned*)((const char*)(gbase) + (voff)[_i]), (PG8_LAS unsigned*)(lds + (bufoff) + ldsw + _i * 8192), 16, 0, 0); } while (0)
; #define PG8_LDA(dst, b, h) do { _Pragma("unroll") for (int m = 0; m < 4; ++m) _Pragma("unroll") for (int k = 0; k < 2; ++k) dst[m][k] = *(const PG8_LAS bf16x8*)(lds + PG8_SA(b, h) + aoff + m * 2048 + k * 1024); } while (0)
; #define PG8_MMA(ai, bj, At, Bt) do { __builtin_amdgcn_s_setprio(1); _Pragma("unroll") for (int m = 0; m < 4; ++m) _Pragma("unroll") for (int n = 0; n < 2; ++n) _Pragma("unroll") for (int k = 0; k < 2; ++k) \
;         acc[ai][bj][m][n] = __builtin_amdgcn_mfma_f32_16x16x32_bf16(Bt[n][k], At[m][k], acc[ai][bj][m][n], 0, 0, 0); __builtin_amdgcn_s_setprio(0); } while (0)
; #define PG8_WAIT_V(n) asm volatile("s_waitcnt vmcnt(" #n ")" ::: "memory")
; #define PG8_WAIT_L(n) asm volatile("s_waitcnt lgkmcnt(" #n ")" ::: "memory")
; #define PG8_BAR __builtin_amdgcn_s_barrier()
; #define PG8_SCHED __builtin_amdgcn_sched_barrier(0)
; template <class Epi, class Sched, bool ALIGN_EPI = false, bool SP2 = false>
; __device__ __forceinline__ void gemm_phase(PG8_LAS unsigned char* lds, const Gemm g, const Sched& S, const Epi& E) {
;     ...
;             PG8_LDA(At, 1, 1); PG8_STAGE(PG8_SB(1, 0), b3, voffB); PG8_STAGE(PG8_SB(1, 1), b3 + hstep, voffB); PG8_STAGE(PG8_SA(1, 0), a3, voffA);
;             PG8_WAIT_V(8); PG8_WAIT_L(0); PG8_BAR; PG8_MMA(1, 0, At, B0); PG8_MMA(1, 1, At, B1); PG8_BAR; PG8_SCHED;
;     ...
;         if constexpr (ALIGN_EPI) { if (wr == 0) PG8_BAR; }
	s_add_i32 s48, s68, s51
	v_lshl_add_u64 v[194:195], v[194:195], 0, s[10:11]
	s_mov_b32 m0, s48
	ds_read_b128 v[182:185], v169 offset:49152
	ds_read_b128 v[186:189], v169 offset:50176
	ds_read_b128 v[190:193], v169 offset:51200
	ds_read_b128 v[198:201], v169 offset:52224
	ds_read_b128 v[202:205], v169 offset:53248
	ds_read_b128 v[206:209], v169 offset:54272
	ds_read_b128 v[210:213], v169 offset:55296
	ds_read_b128 v[214:217], v169 offset:56320
	global_load_lds_dwordx4 v[194:195], off
	s_add_i32 m0, s48, 0x2000
	s_add_u32 s46, s46, 0x20080
	v_lshl_add_u64 v[194:195], v[218:219], 0, s[10:11]
	s_addc_u32 s47, s47, 0
	s_add_i32 s48, s69, s51
	global_load_lds_dwordx4 v[194:195], off
	v_lshl_add_u64 v[194:195], s[46:47], 0, v[138:139]
	s_mov_b32 m0, s48
	s_nop 0
	global_load_lds_dwordx4 v[194:195], off
	v_lshl_add_u64 v[194:195], s[46:47], 0, v[142:143]
	s_add_i32 m0, s48, 0x2000
	s_nop 0
	global_load_lds_dwordx4 v[194:195], off
	v_lshl_add_u64 v[194:195], v[220:221], 0, s[10:11]
	s_mov_b32 m0, s56
	s_nop 0
	global_load_lds_dwordx4 v[194:195], off
	v_lshl_add_u64 v[194:195], v[222:223], 0, s[10:11]
	s_mov_b32 m0, s57
	s_nop 0
	global_load_lds_dwordx4 v[194:195], off
	s_waitcnt vmcnt(8)
	s_waitcnt lgkmcnt(0)
	s_barrier
	s_setprio 1
	s_waitcnt lgkmcnt(0)
	v_mfma_f32_16x16x32_bf16 v[92:95], v[112:115], v[182:185], v[92:95]
	v_mfma_f32_16x16x32_bf16 v[88:91], v[152:155], v[182:185], v[88:91]
	v_mfma_f32_16x16x32_bf16 v[84:87], v[112:115], v[190:193], v[84:87]
	v_mfma_f32_16x16x32_bf16 v[80:83], v[152:155], v[190:193], v[80:83]
	v_mfma_f32_16x16x32_bf16 v[76:79], v[112:115], v[202:205], v[76:79]
	v_mfma_f32_16x16x32_bf16 v[72:75], v[152:155], v[202:205], v[72:75]
	v_mfma_f32_16x16x32_bf16 v[68:71], v[112:115], v[210:213], v[68:71]
	v_mfma_f32_16x16x32_bf16 v[64:67], v[152:155], v[210:213], v[64:67]
	v_mfma_f32_16x16x32_bf16 v[92:95], v[116:119], v[186:189], v[92:95]
	v_mfma_f32_16x16x32_bf16 v[88:91], v[156:159], v[186:189], v[88:91]
	v_mfma_f32_16x16x32_bf16 v[84:87], v[116:119], v[198:201], v[84:87]
	v_mfma_f32_16x16x32_bf16 v[80:83], v[156:159], v[198:201], v[80:83]
	v_mfma_f32_16x16x32_bf16 v[76:79], v[116:119], v[206:209], v[76:79]
	v_mfma_f32_16x16x32_bf16 v[72:75], v[156:159], v[206:209], v[72:75]
	v_mfma_f32_16x16x32_bf16 v[68:71], v[116:119], v[214:217], v[68:71]
	v_mfma_f32_16x16x32_bf16 v[64:67], v[156:159], v[214:217], v[64:67]
	v_mfma_f32_16x16x32_bf16 v[28:31], v[160:163], v[182:185], v[28:31]
	v_mfma_f32_16x16x32_bf16 v[24:27], v[174:177], v[182:185], v[24:27]
	v_mfma_f32_16x16x32_bf16 v[20:23], v[160:163], v[190:193], v[20:23]
	v_mfma_f32_16x16x32_bf16 v[16:19], v[174:177], v[190:193], v[16:19]
	v_mfma_f32_16x16x32_bf16 v[12:15], v[160:163], v[202:205], v[12:15]
	v_mfma_f32_16x16x32_bf16 v[8:11], v[174:177], v[202:205], v[8:11]
	v_mfma_f32_16x16x32_bf16 v[4:7], v[160:163], v[210:213], v[4:7]
	v_mfma_f32_16x16x32_bf16 v[0:3], v[174:177], v[210:213], v[0:3]
	v_mfma_f32_16x16x32_bf16 v[28:31], v[170:173], v[186:189], v[28:31]
	v_mfma_f32_16x16x32_bf16 v[24:27], v[178:181], v[186:189], v[24:27]
	v_mfma_f32_16x16x32_bf16 v[20:23], v[170:173], v[198:201], v[20:23]
	v_mfma_f32_16x16x32_bf16 v[16:19], v[178:181], v[198:201], v[16:19]
	v_mfma_f32_16x16x32_bf16 v[12:15], v[170:173], v[206:209], v[12:15]
	v_mfma_f32_16x16x32_bf16 v[8:11], v[178:181], v[206:209], v[8:11]
	v_mfma_f32_16x16x32_bf16 v[4:7], v[170:173], v[214:217], v[4:7]
	v_mfma_f32_16x16x32_bf16 v[0:3], v[178:181], v[214:217], v[0:3]
	s_setprio 0
	s_barrier
	s_add_i32 s67, s67, 2
	s_add_u32 s20, s20, 0x100
	s_addc_u32 s21, s21, 0
	s_add_u32 s65, s65, 0x100
	s_addc_u32 s66, s66, 0
	s_cmp_gt_u32 s67, 5
	s_cbranch_scc0 .LBB0_624
	s_and_b64 vcc, exec, s[12:13]
	s_cbranch_vccz .LBB0_627
	s_barrier

; #define PG8_STAGE(bufoff, gbase, voff) do { _Pragma("unroll") for (int _i = 0; _i < 2; ++_i) \
;         __builtin_amdgcn_global_load_lds((const unsigned*)((const char*)(gbase) + (voff)[_i]), (PG8_LAS unsigned*)(lds + (bufoff) + ldsw + _i * 8192), 16, 0, 0); } while (0)
; #define PG8_LDA(dst, b, h) do { _Pragma("unroll") for (int m = 0; m < 4; ++m) _Pragma("unroll") for (int k = 0; k < 2; ++k) dst[m][k] = *(const PG8_LAS bf16x8*)(lds + PG8_SA(b, h) + aoff + m * 2048 + k * 1024); } while (0)
; #define PG8_LDB(dst, b, h) do { _Pragma("unroll") for (int n = 0; n < 2; ++n) _Pragma("unroll") for (int k = 0; k < 2; ++k) dst[n][k] = *(const PG8_LAS bf16x8*)(lds + PG8_SB(b, h) + boff + n * 2048 + k * 1024); } while (0)
; #define PG8_WAIT_V(n) asm volatile("s_waitcnt vmcnt(" #n ")" ::: "memory")
; #define PG8_WAIT_L(n) asm volatile("s_waitcnt lgkmcnt(" #n ")" ::: "memory")
; #define PG8_BAR __builtin_amdgcn_s_barrier()
; #define PG8_SCHED __builtin_amdgcn_sched_barrier(0)
; template <class Epi, class Sched, bool ALIGN_EPI = false, bool SP2 = false>
; __device__ __forceinline__ void gemm_phase(PG8_LAS unsigned char* lds, const Gemm g, const Sched& S, const Epi& E) {
;     ...
;         const bool has_next = S.next(ui + 1, nxt);
;         const char* nA = has_next ? (const char*)g.A + (size_t)nxt.pm * tstep : cA; const char* nB = has_next ? (const char*)g.Bt + (size_t)nxt.pn * tstep : cB;
;         for (int t = 0; t < nt; t += 2) {
;             const bool last = (t == nt - 2);
;             const char* a1 = cA + (size_t)(t + 1) * kstep;
;             const char* a2 = last ? nA : cA + (size_t)(t + 2) * kstep; const char* b2 = last ? nB : cB + (size_t)(t + 2) * kstep;
;             const char* a3 = a2 + kstep; const char* b3 = b2 + kstep;
;             if (last && has_next) S.a_ready(nxt);
;             if constexpr (SP2) {
;             PG8_LDB(B0, 0, 0); PG8_LDB(B1, 0, 1); PG8_SCHED; PG8_LDA(At, 0, 0); PG8_STAGE(PG8_SA(1, 1), a1 + hstep, voffA);
;             PG8_WAIT_V(8); PG8_WAIT_L(0); PG8_BAR; PG8_MMA(0, 0, At, B0); PG8_MMA(0, 1, At, B1); PG8_BAR; PG8_SCHED;
;             PG8_LDA(At, 0, 1); PG8_STAGE(PG8_SB(0, 0), b2, voffB); PG8_STAGE(PG8_SB(0, 1), b2 + hstep, voffB); PG8_STAGE(PG8_SA(0, 0), a2, voffA);
;             PG8_WAIT_V(8); PG8_WAIT_L(0); PG8_BAR; PG8_MMA(1, 0, At, B0); PG8_MMA(1, 1, At, B1); PG8_BAR; PG8_SCHED;
.LBB0_704:
	s_ashr_i32 s47, s46, 31
	s_lshl_b64 s[48:49], s[46:47], 19
	s_add_u32 s48, s42, s48
	s_addc_u32 s49, s43, s49
	s_and_b64 s[50:51], s[6:7], exec
	s_cselect_b32 s35, s49, s21
	s_cselect_b32 s47, s48, s20
	s_ashr_i32 s45, s44, 31
	s_lshl_b64 s[50:51], s[44:45], 19
	s_add_u32 s50, s3, s50
	s_addc_u32 s51, s33, s51
	s_and_b64 s[56:57], s[6:7], exec
	s_cselect_b32 s45, s51, s55
	s_cselect_b32 s73, s50, s54
	s_add_u32 s20, s20, 0x40080
	s_addc_u32 s21, s21, 0
	s_add_u32 s74, s54, 0x100
	s_addc_u32 s75, s55, 0
	s_mov_b32 s76, -2
	s_waitcnt lgkmcnt(0)
	ds_read_b128 v[96:99], v223
	ds_read_b128 v[108:111], v223 offset:1024
	ds_read_b128 v[120:123], v223 offset:2048
	ds_read_b128 v[128:131], v223 offset:3072
	ds_read_b128 v[144:147], v224
	ds_read_b128 v[148:151], v224 offset:1024
	ds_read_b128 v[152:155], v224 offset:2048
	ds_read_b128 v[156:159], v224 offset:3072
	s_add_u32 s54, s20, 0xfffc0080
	s_addc_u32 s55, s21, -1
	s_cmp_eq_u32 s76, 12
	s_cselect_b32 s57, s35, s55
	s_cselect_b32 s56, s47, s54
	s_cselect_b32 s55, s45, s75
	s_cselect_b32 s54, s73, s74
	v_lshl_add_u64 v[210:211], s[20:21], 0, v[192:193]
	s_add_i32 m0, s53, 0xc000
	ds_read_b128 v[160:163], v225
	ds_read_b128 v[164:167], v225 offset:1024
	ds_read_b128 v[168:171], v225 offset:2048
	ds_read_b128 v[172:175], v225 offset:3072
	ds_read_b128 v[176:179], v225 offset:4096
	ds_read_b128 v[180:183], v225 offset:5120
	ds_read_b128 v[202:205], v225 offset:6144
	ds_read_b128 v[206:209], v225 offset:7168
	global_load_lds_dwordx4 v[210:211], off
	v_lshl_add_u64 v[210:211], s[20:21], 0, v[194:195]
	s_add_i32 m0, s53, 0xe000
	s_nop 0
	global_load_lds_dwordx4 v[210:211], off
	s_waitcnt vmcnt(8)
	s_waitcnt lgkmcnt(0)
	s_barrier
	s_setprio 1
	s_waitcnt lgkmcnt(0)
	v_mfma_f32_16x16x32_bf16 v[140:143], v[96:99], v[160:163], 0
	v_mfma_f32_16x16x32_bf16 v[136:139], v[120:123], v[160:163], 0
	v_mfma_f32_16x16x32_bf16 v[116:119], v[96:99], v[168:171], 0
	v_mfma_f32_16x16x32_bf16 v[112:115], v[120:123], v[168:171], 0
	v_mfma_f32_16x16x32_bf16 v[92:95], v[96:99], v[176:179], 0
	v_mfma_f32_16x16x32_bf16 v[88:91], v[120:123], v[176:179], 0
	v_mfma_f32_16x16x32_bf16 v[76:79], v[96:99], v[202:205], 0
	v_mfma_f32_16x16x32_bf16 v[72:75], v[120:123], v[202:205], 0
	v_mfma_f32_16x16x32_bf16 v[140:143], v[108:111], v[164:167], v[140:143]
	v_mfma_f32_16x16x32_bf16 v[136:139], v[128:131], v[164:167], v[136:139]
	v_mfma_f32_16x16x32_bf16 v[116:119], v[108:111], v[172:175], v[116:119]
	v_mfma_f32_16x16x32_bf16 v[112:115], v[128:131], v[172:175], v[112:115]
	v_mfma_f32_16x16x32_bf16 v[92:95], v[108:111], v[180:183], v[92:95]
	v_mfma_f32_16x16x32_bf16 v[88:91], v[128:131], v[180:183], v[88:91]
	v_mfma_f32_16x16x32_bf16 v[76:79], v[108:111], v[206:209], v[76:79]
	v_mfma_f32_16x16x32_bf16 v[72:75], v[128:131], v[206:209], v[72:75]
	v_mfma_f32_16x16x32_bf16 v[132:135], v[144:147], v[160:163], 0
	v_mfma_f32_16x16x32_bf16 v[124:127], v[152:155], v[160:163], 0
	v_mfma_f32_16x16x32_bf16 v[104:107], v[144:147], v[168:171], 0
	v_mfma_f32_16x16x32_bf16 v[100:103], v[152:155], v[168:171], 0
	v_mfma_f32_16x16x32_bf16 v[84:87], v[144:147], v[176:179], 0
	v_mfma_f32_16x16x32_bf16 v[80:83], v[152:155], v[176:179], 0
	v_mfma_f32_16x16x32_bf16 v[68:71], v[144:147], v[202:205], 0
	v_mfma_f32_16x16x32_bf16 v[64:67], v[152:155], v[202:205], 0
	v_mfma_f32_16x16x32_bf16 v[132:135], v[148:151], v[164:167], v[132:135]
	v_mfma_f32_16x16x32_bf16 v[124:127], v[156:159], v[164:167], v[124:127]
	v_mfma_f32_16x16x32_bf16 v[104:107], v[148:151], v[172:175], v[104:107]
	v_mfma_f32_16x16x32_bf16 v[100:103], v[156:159], v[172:175], v[100:103]
	v_mfma_f32_16x16x32_bf16 v[84:87], v[148:151], v[180:183], v[84:87]
	v_mfma_f32_16x16x32_bf16 v[80:83], v[156:159], v[180:183], v[80:83]
	v_mfma_f32_16x16x32_bf16 v[68:71], v[148:151], v[206:209], v[68:71]
	v_mfma_f32_16x16x32_bf16 v[64:67], v[156:159], v[206:209], v[64:67]
	s_setprio 0
	s_barrier
	s_add_i32 s77, s71, s58
	v_lshl_add_u64 v[210:211], s[54:55], 0, v[186:187]
	s_mov_b32 m0, s77
	ds_read_b128 v[160:163], v225 offset:16384
	ds_read_b128 v[164:167], v225 offset:17408
	ds_read_b128 v[168:171], v225 offset:18432
	ds_read_b128 v[172:175], v225 offset:19456
	ds_read_b128 v[176:179], v225 offset:20480
	ds_read_b128 v[180:183], v225 offset:21504
	ds_read_b128 v[202:205], v225 offset:22528
	ds_read_b128 v[206:209], v225 offset:23552
	global_load_lds_dwordx4 v[210:211], off
	s_add_i32 m0, s77, 0x2000
	s_add_u32 s78, s54, 0x40000
	v_lshl_add_u64 v[212:213], s[54:55], 0, v[190:191]
	s_addc_u32 s79, s55, 0
	s_add_i32 s77, s72, s58
	global_load_lds_dwordx4 v[212:213], off
	v_lshl_add_u64 v[214:215], s[78:79], 0, v[186:187]
	s_mov_b32 m0, s77
	v_lshl_add_u64 v[216:217], s[56:57], 0, v[188:189]
	global_load_lds_dwordx4 v[214:215], off
	v_lshl_add_u64 v[214:215], s[78:79], 0, v[190:191]
	s_add_i32 m0, s77, 0x2000
	s_nop 0
	global_load_lds_dwordx4 v[214:215], off
	v_lshl_add_u64 v[214:215], s[56:57], 0, v[184:185]
	s_mov_b32 m0, s53
	s_nop 0
	global_load_lds_dwordx4 v[214:215], off
	s_mov_b32 m0, s59
	s_nop 0
	global_load_lds_dwordx4 v[216:217], off
	s_waitcnt vmcnt(8)
	s_waitcnt lgkmcnt(0)
	s_barrier
; #define PG8_STAGE(bufoff, gbase, voff) do { _Pragma("unroll") for (int _i = 0; _i < 2; ++_i) \
;         __builtin_amdgcn_global_load_lds((const unsigned*)((const char*)(gbase) + (voff)[_i]), (PG8_LAS unsigned*)(lds + (bufoff) + ldsw + _i * 8192), 16, 0, 0); } while (0)
; #define PG8_LDA(dst, b, h) do { _Pragma("unroll") for (int m = 0; m < 4; ++m) _Pragma("unroll") for (int k = 0; k < 2; ++k) dst[m][k] = *(const PG8_LAS bf16x8*)(lds + PG8_SA(b, h) + aoff + m * 2048 + k * 1024); } while (0)
; #define PG8_LDB(dst, b, h) do { _Pragma("unroll") for (int n = 0; n < 2; ++n) _Pragma("unroll") for (int k = 0; k < 2; ++k) dst[n][k] = *(const PG8_LAS bf16x8*)(lds + PG8_SB(b, h) + boff + n * 2048 + k * 1024); } while (0)
; #define PG8_MMA(ai, bj, At, Bt) do { __builtin_amdgcn_s_setprio(1); _Pragma("unroll") for (int m = 0; m < 4; ++m) _Pragma("unroll") for (int n = 0; n < 2; ++n) _Pragma("unroll") for (int k = 0; k < 2; ++k) \
;         acc[ai][bj][m][n] = __builtin_amdgcn_mfma_f32_16x16x32_bf16(Bt[n][k], At[m][k], acc[ai][bj][m][n], 0, 0, 0); __builtin_amdgcn_s_setprio(0); } while (0)
; #define PG8_WAIT_V(n) asm volatile("s_waitcnt vmcnt(" #n ")" ::: "memory")
; #define PG8_WAIT_L(n) asm volatile("s_waitcnt lgkmcnt(" #n ")" ::: "memory")
; #define PG8_BAR __builtin_amdgcn_s_barrier()
; #define PG8_SCHED __builtin_amdgcn_sched_barrier(0)
; template <class Epi, class Sched, bool ALIGN_EPI = false, bool SP2 = false>
; __device__ __forceinline__ void gemm_phase(PG8_LAS unsigned char* lds, const Gemm g, const Sched& S, const Epi& E) {
;     ...
;             PG8_WAIT_V(8); PG8_WAIT_L(0); PG8_BAR; PG8_MMA(1, 0, At, B0); PG8_MMA(1, 1, At, B1); PG8_BAR; PG8_SCHED;
;             PG8_LDB(B0, 1, 0); PG8_LDB(B1, 1, 1); PG8_SCHED; PG8_LDA(At, 1, 0); PG8_STAGE(PG8_SA(0, 1), a2 + hstep, voffA);
;             PG8_WAIT_V(8); PG8_WAIT_L(0); PG8_BAR; PG8_MMA(0, 0, At, B0); PG8_MMA(0, 1, At, B1); PG8_BAR; PG8_SCHED;
	s_setprio 1
	s_waitcnt lgkmcnt(0)
	v_mfma_f32_16x16x32_bf16 v[60:63], v[96:99], v[160:163], 0
	v_mfma_f32_16x16x32_bf16 v[56:59], v[120:123], v[160:163], 0
	v_mfma_f32_16x16x32_bf16 v[44:47], v[96:99], v[168:171], 0
	v_mfma_f32_16x16x32_bf16 v[40:43], v[120:123], v[168:171], 0
	v_mfma_f32_16x16x32_bf16 v[28:31], v[96:99], v[176:179], 0
	v_mfma_f32_16x16x32_bf16 v[24:27], v[120:123], v[176:179], 0
	v_mfma_f32_16x16x32_bf16 v[12:15], v[96:99], v[202:205], 0
	v_mfma_f32_16x16x32_bf16 v[8:11], v[120:123], v[202:205], 0
	v_mfma_f32_16x16x32_bf16 v[60:63], v[108:111], v[164:167], v[60:63]
	v_mfma_f32_16x16x32_bf16 v[56:59], v[128:131], v[164:167], v[56:59]
	v_mfma_f32_16x16x32_bf16 v[44:47], v[108:111], v[172:175], v[44:47]
	v_mfma_f32_16x16x32_bf16 v[40:43], v[128:131], v[172:175], v[40:43]
	v_mfma_f32_16x16x32_bf16 v[28:31], v[108:111], v[180:183], v[28:31]
	v_mfma_f32_16x16x32_bf16 v[24:27], v[128:131], v[180:183], v[24:27]
	v_mfma_f32_16x16x32_bf16 v[12:15], v[108:111], v[206:209], v[12:15]
	v_mfma_f32_16x16x32_bf16 v[8:11], v[128:131], v[206:209], v[8:11]
	v_mfma_f32_16x16x32_bf16 v[52:55], v[144:147], v[160:163], 0
	v_mfma_f32_16x16x32_bf16 v[48:51], v[152:155], v[160:163], 0
	v_mfma_f32_16x16x32_bf16 v[36:39], v[144:147], v[168:171], 0
	v_mfma_f32_16x16x32_bf16 v[32:35], v[152:155], v[168:171], 0
	v_mfma_f32_16x16x32_bf16 v[20:23], v[144:147], v[176:179], 0
	v_mfma_f32_16x16x32_bf16 v[16:19], v[152:155], v[176:179], 0
	v_mfma_f32_16x16x32_bf16 v[4:7], v[144:147], v[202:205], 0
	v_mfma_f32_16x16x32_bf16 v[0:3], v[152:155], v[202:205], 0
	v_mfma_f32_16x16x32_bf16 v[52:55], v[148:151], v[164:167], v[52:55]
	v_mfma_f32_16x16x32_bf16 v[48:51], v[156:159], v[164:167], v[48:51]
	v_mfma_f32_16x16x32_bf16 v[36:39], v[148:151], v[172:175], v[36:39]
	v_mfma_f32_16x16x32_bf16 v[32:35], v[156:159], v[172:175], v[32:35]
	v_mfma_f32_16x16x32_bf16 v[20:23], v[148:151], v[180:183], v[20:23]
	v_mfma_f32_16x16x32_bf16 v[16:19], v[156:159], v[180:183], v[16:19]
	v_mfma_f32_16x16x32_bf16 v[4:7], v[148:151], v[206:209], v[4:7]
	v_mfma_f32_16x16x32_bf16 v[0:3], v[156:159], v[206:209], v[0:3]
	s_setprio 0
	s_barrier
	s_add_i32 s77, 0, 0x18000
	s_add_i32 s78, 0, 0x1c000
	v_add_u32_e32 v128, s77, v221
	v_add_u32_e32 v156, s78, v221
	ds_read_b128 v[96:99], v128
	ds_read_b128 v[108:111], v128 offset:1024
	ds_read_b128 v[120:123], v128 offset:2048
	ds_read_b128 v[128:131], v128 offset:3072
	ds_read_b128 v[144:147], v156
	ds_read_b128 v[148:151], v156 offset:1024
	ds_read_b128 v[152:155], v156 offset:2048
	ds_read_b128 v[156:159], v156 offset:3072
	s_add_u32 s56, s56, 0x40000
	s_addc_u32 s57, s57, 0
	s_mov_b32 m0, s60
	v_lshl_add_u64 v[218:219], s[56:57], 0, v[184:185]
	ds_read_b128 v[160:163], v225 offset:32768
	ds_read_b128 v[164:167], v225 offset:33792
	ds_read_b128 v[168:171], v225 offset:34816
	ds_read_b128 v[172:175], v225 offset:35840
	ds_read_b128 v[176:179], v225 offset:36864
	ds_read_b128 v[180:183], v225 offset:37888
	ds_read_b128 v[202:205], v225 offset:38912
	ds_read_b128 v[206:209], v225 offset:39936
	global_load_lds_dwordx4 v[218:219], off
	v_lshl_add_u64 v[218:219], s[56:57], 0, v[188:189]
	s_mov_b32 m0, s61
	s_nop 0
	global_load_lds_dwordx4 v[218:219], off
	s_waitcnt vmcnt(8)
	s_waitcnt lgkmcnt(0)
	s_barrier
	s_setprio 1
	s_waitcnt lgkmcnt(0)
	v_mfma_f32_16x16x32_bf16 v[140:143], v[96:99], v[160:163], v[140:143]
	v_mfma_f32_16x16x32_bf16 v[136:139], v[120:123], v[160:163], v[136:139]
	v_mfma_f32_16x16x32_bf16 v[116:119], v[96:99], v[168:171], v[116:119]
	v_mfma_f32_16x16x32_bf16 v[112:115], v[120:123], v[168:171], v[112:115]
	v_mfma_f32_16x16x32_bf16 v[92:95], v[96:99], v[176:179], v[92:95]
	v_mfma_f32_16x16x32_bf16 v[88:91], v[120:123], v[176:179], v[88:91]
	v_mfma_f32_16x16x32_bf16 v[76:79], v[96:99], v[202:205], v[76:79]
	v_mfma_f32_16x16x32_bf16 v[72:75], v[120:123], v[202:205], v[72:75]
	v_mfma_f32_16x16x32_bf16 v[140:143], v[108:111], v[164:167], v[140:143]
	v_mfma_f32_16x16x32_bf16 v[136:139], v[128:131], v[164:167], v[136:139]
	v_mfma_f32_16x16x32_bf16 v[116:119], v[108:111], v[172:175], v[116:119]
	v_mfma_f32_16x16x32_bf16 v[112:115], v[128:131], v[172:175], v[112:115]
	v_mfma_f32_16x16x32_bf16 v[92:95], v[108:111], v[180:183], v[92:95]
	v_mfma_f32_16x16x32_bf16 v[88:91], v[128:131], v[180:183], v[88:91]
	v_mfma_f32_16x16x32_bf16 v[76:79], v[108:111], v[206:209], v[76:79]
	v_mfma_f32_16x16x32_bf16 v[72:75], v[128:131], v[206:209], v[72:75]
	v_mfma_f32_16x16x32_bf16 v[132:135], v[144:147], v[160:163], v[132:135]
	v_mfma_f32_16x16x32_bf16 v[124:127], v[152:155], v[160:163], v[124:127]
	v_mfma_f32_16x16x32_bf16 v[104:107], v[144:147], v[168:171], v[104:107]
	v_mfma_f32_16x16x32_bf16 v[100:103], v[152:155], v[168:171], v[100:103]
	v_mfma_f32_16x16x32_bf16 v[84:87], v[144:147], v[176:179], v[84:87]
	v_mfma_f32_16x16x32_bf16 v[80:83], v[152:155], v[176:179], v[80:83]
	v_mfma_f32_16x16x32_bf16 v[68:71], v[144:147], v[202:205], v[68:71]
	v_mfma_f32_16x16x32_bf16 v[64:67], v[152:155], v[202:205], v[64:67]
	v_mfma_f32_16x16x32_bf16 v[132:135], v[148:151], v[164:167], v[132:135]
	v_mfma_f32_16x16x32_bf16 v[124:127], v[156:159], v[164:167], v[124:127]
	v_mfma_f32_16x16x32_bf16 v[104:107], v[148:151], v[172:175], v[104:107]
	v_mfma_f32_16x16x32_bf16 v[100:103], v[156:159], v[172:175], v[100:103]
	v_mfma_f32_16x16x32_bf16 v[84:87], v[148:151], v[180:183], v[84:87]
	v_mfma_f32_16x16x32_bf16 v[80:83], v[156:159], v[180:183], v[80:83]
	v_mfma_f32_16x16x32_bf16 v[68:71], v[148:151], v[206:209], v[68:71]
	v_mfma_f32_16x16x32_bf16 v[64:67], v[156:159], v[206:209], v[64:67]
	s_setprio 0
	s_barrier
; #define PG8_STAGE(bufoff, gbase, voff) do { _Pragma("unroll") for (int _i = 0; _i < 2; ++_i) \
;         __builtin_amdgcn_global_load_lds((const unsigned*)((const char*)(gbase) + (voff)[_i]), (PG8_LAS unsigned*)(lds + (bufoff) + ldsw + _i * 8192), 16, 0, 0); } while (0)
; #define PG8_LDA(dst, b, h) do { _Pragma("unroll") for (int m = 0; m < 4; ++m) _Pragma("unroll") for (int k = 0; k < 2; ++k) dst[m][k] = *(const PG8_LAS bf16x8*)(lds + PG8_SA(b, h) + aoff + m * 2048 + k * 1024); } while (0)
; #define PG8_LDB(dst, b, h) do { _Pragma("unroll") for (int n = 0; n < 2; ++n) _Pragma("unroll") for (int k = 0; k < 2; ++k) dst[n][k] = *(const PG8_LAS bf16x8*)(lds + PG8_SB(b, h) + boff + n * 2048 + k * 1024); } while (0)
; #define PG8_MMA(ai, bj, At, Bt) do { __builtin_amdgcn_s_setprio(1); _Pragma("unroll") for (int m = 0; m < 4; ++m) _Pragma("unroll") for (int n = 0; n < 2; ++n) _Pragma("unroll") for (int k = 0; k < 2; ++k) \
;         acc[ai][bj][m][n] = __builtin_amdgcn_mfma_f32_16x16x32_bf16(Bt[n][k], At[m][k], acc[ai][bj][m][n], 0, 0, 0); __builtin_amdgcn_s_setprio(0); } while (0)
; #define PG8_WAIT_V(n) asm volatile("s_waitcnt vmcnt(" #n ")" ::: "memory")
; template <class Epi, class Sched, bool ALIGN_EPI = false, bool SP2 = false>
; __device__ __forceinline__ void gemm_phase(PG8_LAS unsigned char* lds, const Gemm g, const Sched& S, const Epi& E) {
;     ...
;             PG8_LDB(B0, 0, 0); PG8_LDB(B1, 0, 1); PG8_SCHED; PG8_LDA(At, 0, 0); PG8_STAGE(PG8_SA(1, 1), a1 + hstep, voffA);
;             PG8_WAIT_V(8); PG8_WAIT_L(0); PG8_BAR; PG8_MMA(0, 0, At, B0); PG8_MMA(0, 1, At, B1); PG8_BAR; PG8_SCHED;
;             PG8_LDA(At, 0, 1); PG8_STAGE(PG8_SB(0, 0), b2, voffB); PG8_STAGE(PG8_SB(0, 1), b2 + hstep, voffB); PG8_STAGE(PG8_SA(0, 0), a2, voffA);
;             PG8_WAIT_V(8); PG8_WAIT_L(0); PG8_BAR; PG8_MMA(1, 0, At, B0); PG8_MMA(1, 1, At, B1); PG8_BAR; PG8_SCHED;
;             PG8_LDB(B0, 1, 0); PG8_LDB(B1, 1, 1); PG8_SCHED; PG8_LDA(At, 1, 0); PG8_STAGE(PG8_SA(0, 1), a2 + hstep, voffA);
;             PG8_WAIT_V(8); PG8_WAIT_L(0); PG8_BAR; PG8_MMA(0, 0, At, B0); PG8_MMA(0, 1, At, B1); PG8_BAR; PG8_SCHED;
;             PG8_LDA(At, 1, 1); PG8_STAGE(PG8_SB(1, 0), b3, voffB); PG8_STAGE(PG8_SB(1, 1), b3 + hstep, voffB); PG8_STAGE(PG8_SA(1, 0), a3, voffA);
;             PG8_WAIT_V(8); PG8_WAIT_L(0); PG8_BAR; PG8_MMA(1, 0, At, B0); PG8_MMA(1, 1, At, B1); PG8_BAR; PG8_SCHED;
	s_add_i32 s56, s77, s58
	v_lshl_add_u64 v[210:211], v[210:211], 0, s[12:13]
	s_mov_b32 m0, s56
	ds_read_b128 v[160:163], v225 offset:49152
	ds_read_b128 v[164:167], v225 offset:50176
	ds_read_b128 v[168:171], v225 offset:51200
	ds_read_b128 v[172:175], v225 offset:52224
	ds_read_b128 v[176:179], v225 offset:53248
	ds_read_b128 v[180:183], v225 offset:54272
	ds_read_b128 v[202:205], v225 offset:55296
	ds_read_b128 v[206:209], v225 offset:56320
	global_load_lds_dwordx4 v[210:211], off
	s_add_i32 m0, s56, 0x2000
	s_add_u32 s54, s54, 0x40080
	v_lshl_add_u64 v[210:211], v[212:213], 0, s[12:13]
	s_addc_u32 s55, s55, 0
	s_add_i32 s56, s78, s58
	global_load_lds_dwordx4 v[210:211], off
	v_lshl_add_u64 v[210:211], s[54:55], 0, v[186:187]
	s_mov_b32 m0, s56
	s_nop 0
	global_load_lds_dwordx4 v[210:211], off
	v_lshl_add_u64 v[210:211], s[54:55], 0, v[190:191]
	s_add_i32 m0, s56, 0x2000
	s_nop 0
	global_load_lds_dwordx4 v[210:211], off
	v_lshl_add_u64 v[210:211], v[214:215], 0, s[12:13]
	s_mov_b32 m0, s66
	s_nop 0
	global_load_lds_dwordx4 v[210:211], off
	v_lshl_add_u64 v[210:211], v[216:217], 0, s[12:13]
	s_mov_b32 m0, s67
	s_nop 0
	global_load_lds_dwordx4 v[210:211], off
	s_waitcnt vmcnt(8)
	s_waitcnt lgkmcnt(0)
	s_barrier
	s_setprio 1
	s_waitcnt lgkmcnt(0)
	v_mfma_f32_16x16x32_bf16 v[60:63], v[96:99], v[160:163], v[60:63]
	v_mfma_f32_16x16x32_bf16 v[56:59], v[120:123], v[160:163], v[56:59]
	v_mfma_f32_16x16x32_bf16 v[44:47], v[96:99], v[168:171], v[44:47]
	v_mfma_f32_16x16x32_bf16 v[40:43], v[120:123], v[168:171], v[40:43]
	v_mfma_f32_16x16x32_bf16 v[28:31], v[96:99], v[176:179], v[28:31]
	v_mfma_f32_16x16x32_bf16 v[24:27], v[120:123], v[176:179], v[24:27]
	v_mfma_f32_16x16x32_bf16 v[12:15], v[96:99], v[202:205], v[12:15]
	v_mfma_f32_16x16x32_bf16 v[8:11], v[120:123], v[202:205], v[8:11]
	v_mfma_f32_16x16x32_bf16 v[60:63], v[108:111], v[164:167], v[60:63]
	v_mfma_f32_16x16x32_bf16 v[56:59], v[128:131], v[164:167], v[56:59]
	v_mfma_f32_16x16x32_bf16 v[44:47], v[108:111], v[172:175], v[44:47]
	v_mfma_f32_16x16x32_bf16 v[40:43], v[128:131], v[172:175], v[40:43]
	v_mfma_f32_16x16x32_bf16 v[28:31], v[108:111], v[180:183], v[28:31]
	v_mfma_f32_16x16x32_bf16 v[24:27], v[128:131], v[180:183], v[24:27]
	v_mfma_f32_16x16x32_bf16 v[12:15], v[108:111], v[206:209], v[12:15]
	v_mfma_f32_16x16x32_bf16 v[8:11], v[128:131], v[206:209], v[8:11]
	v_mfma_f32_16x16x32_bf16 v[52:55], v[144:147], v[160:163], v[52:55]
	v_mfma_f32_16x16x32_bf16 v[48:51], v[152:155], v[160:163], v[48:51]
	v_mfma_f32_16x16x32_bf16 v[36:39], v[144:147], v[168:171], v[36:39]
	v_mfma_f32_16x16x32_bf16 v[32:35], v[152:155], v[168:171], v[32:35]
	v_mfma_f32_16x16x32_bf16 v[20:23], v[144:147], v[176:179], v[20:23]
	v_mfma_f32_16x16x32_bf16 v[16:19], v[152:155], v[176:179], v[16:19]
	v_mfma_f32_16x16x32_bf16 v[4:7], v[144:147], v[202:205], v[4:7]
	v_mfma_f32_16x16x32_bf16 v[0:3], v[152:155], v[202:205], v[0:3]
	v_mfma_f32_16x16x32_bf16 v[52:55], v[148:151], v[164:167], v[52:55]
	v_mfma_f32_16x16x32_bf16 v[48:51], v[156:159], v[164:167], v[48:51]
	v_mfma_f32_16x16x32_bf16 v[36:39], v[148:151], v[172:175], v[36:39]
	v_mfma_f32_16x16x32_bf16 v[32:35], v[156:159], v[172:175], v[32:35]
	v_mfma_f32_16x16x32_bf16 v[20:23], v[148:151], v[180:183], v[20:23]
	v_mfma_f32_16x16x32_bf16 v[16:19], v[156:159], v[180:183], v[16:19]
	v_mfma_f32_16x16x32_bf16 v[4:7], v[148:151], v[206:209], v[4:7]
	v_mfma_f32_16x16x32_bf16 v[0:3], v[156:159], v[206:209], v[0:3]
	s_setprio 0
	s_barrier
	s_add_i32 s76, s76, 2
	s_add_u32 s20, s20, 0x100
	s_addc_u32 s21, s21, 0
	s_add_u32 s74, s74, 0x100
	s_addc_u32 s75, s75, 0
	s_cmp_gt_u32 s76, 13
.LBB0_705:
	ds_read_b128 v[96:99], v223
	ds_read_b128 v[108:111], v223 offset:1024
	ds_read_b128 v[120:123], v223 offset:2048
	ds_read_b128 v[128:131], v223 offset:3072
	ds_read_b128 v[144:147], v224
	ds_read_b128 v[148:151], v224 offset:1024
	ds_read_b128 v[152:155], v224 offset:2048
	ds_read_b128 v[156:159], v224 offset:3072
	s_add_u32 s54, s20, 0xfffc0080
	s_addc_u32 s55, s21, -1
	s_cmp_eq_u32 s76, 12
	s_cselect_b32 s57, s35, s55
	s_cselect_b32 s56, s47, s54
	s_cselect_b32 s55, s45, s75
	s_cselect_b32 s54, s73, s74
	v_lshl_add_u64 v[210:211], s[20:21], 0, v[192:193]
	s_add_i32 m0, s53, 0xc000
	ds_read_b128 v[160:163], v225
	ds_read_b128 v[164:167], v225 offset:1024
	ds_read_b128 v[168:171], v225 offset:2048
	ds_read_b128 v[172:175], v225 offset:3072
	ds_read_b128 v[176:179], v225 offset:4096
	ds_read_b128 v[180:183], v225 offset:5120
	ds_read_b128 v[202:205], v225 offset:6144
	ds_read_b128 v[206:209], v225 offset:7168
	global_load_lds_dwordx4 v[210:211], off
	v_lshl_add_u64 v[210:211], s[20:21], 0, v[194:195]
	s_add_i32 m0, s53, 0xe000
	s_nop 0
	global_load_lds_dwordx4 v[210:211], off
	s_waitcnt vmcnt(8)
	s_waitcnt lgkmcnt(0)
	s_barrier
; #define PG8_STAGE(bufoff, gbase, voff) do { _Pragma("unroll") for (int _i = 0; _i < 2; ++_i) \
;         __builtin_amdgcn_global_load_lds((const unsigned*)((const char*)(gbase) + (voff)[_i]), (PG8_LAS unsigned*)(lds + (bufoff) + ldsw + _i * 8192), 16, 0, 0); } while (0)
; #define PG8_LDA(dst, b, h) do { _Pragma("unroll") for (int m = 0; m < 4; ++m) _Pragma("unroll") for (int k = 0; k < 2; ++k) dst[m][k] = *(const PG8_LAS bf16x8*)(lds + PG8_SA(b, h) + aoff + m * 2048 + k * 1024); } while (0)
; #define PG8_MMA(ai, bj, At, Bt) do { __builtin_amdgcn_s_setprio(1); _Pragma("unroll") for (int m = 0; m < 4; ++m) _Pragma("unroll") for (int n = 0; n < 2; ++n) _Pragma("unroll") for (int k = 0; k < 2; ++k) \
;         acc[ai][bj][m][n] = __builtin_amdgcn_mfma_f32_16x16x32_bf16(Bt[n][k], At[m][k], acc[ai][bj][m][n], 0, 0, 0); __builtin_amdgcn_s_setprio(0); } while (0)
; #define PG8_WAIT_V(n) asm volatile("s_waitcnt vmcnt(" #n ")" ::: "memory")
; #define PG8_WAIT_L(n) asm volatile("s_waitcnt lgkmcnt(" #n ")" ::: "memory")
; #define PG8_BAR __builtin_amdgcn_s_barrier()
; #define PG8_SCHED __builtin_amdgcn_sched_barrier(0)
; template <class Epi, class Sched, bool ALIGN_EPI = false, bool SP2 = false>
; __device__ __forceinline__ void gemm_phase(PG8_LAS unsigned char* lds, const Gemm g, const Sched& S, const Epi& E) {
;     ...
;             PG8_WAIT_V(8); PG8_WAIT_L(0); PG8_BAR; PG8_MMA(0, 0, At, B0); PG8_MMA(0, 1, At, B1); PG8_BAR; PG8_SCHED;
;             PG8_LDA(At, 0, 1); PG8_STAGE(PG8_SB(0, 0), b2, voffB); PG8_STAGE(PG8_SB(0, 1), b2 + hstep, voffB); PG8_STAGE(PG8_SA(0, 0), a2, voffA);
;             PG8_WAIT_V(8); PG8_WAIT_L(0); PG8_BAR; PG8_MMA(1, 0, At, B0); PG8_MMA(1, 1, At, B1); PG8_BAR; PG8_SCHED;
	s_setprio 1
	s_waitcnt lgkmcnt(0)
	v_mfma_f32_16x16x32_bf16 v[140:143], v[96:99], v[160:163], v[140:143]
	v_mfma_f32_16x16x32_bf16 v[136:139], v[120:123], v[160:163], v[136:139]
	v_mfma_f32_16x16x32_bf16 v[116:119], v[96:99], v[168:171], v[116:119]
	v_mfma_f32_16x16x32_bf16 v[112:115], v[120:123], v[168:171], v[112:115]
	v_mfma_f32_16x16x32_bf16 v[92:95], v[96:99], v[176:179], v[92:95]
	v_mfma_f32_16x16x32_bf16 v[88:91], v[120:123], v[176:179], v[88:91]
	v_mfma_f32_16x16x32_bf16 v[76:79], v[96:99], v[202:205], v[76:79]
	v_mfma_f32_16x16x32_bf16 v[72:75], v[120:123], v[202:205], v[72:75]
	v_mfma_f32_16x16x32_bf16 v[140:143], v[108:111], v[164:167], v[140:143]
	v_mfma_f32_16x16x32_bf16 v[136:139], v[128:131], v[164:167], v[136:139]
	v_mfma_f32_16x16x32_bf16 v[116:119], v[108:111], v[172:175], v[116:119]
	v_mfma_f32_16x16x32_bf16 v[112:115], v[128:131], v[172:175], v[112:115]
	v_mfma_f32_16x16x32_bf16 v[92:95], v[108:111], v[180:183], v[92:95]
	v_mfma_f32_16x16x32_bf16 v[88:91], v[128:131], v[180:183], v[88:91]
	v_mfma_f32_16x16x32_bf16 v[76:79], v[108:111], v[206:209], v[76:79]
	v_mfma_f32_16x16x32_bf16 v[72:75], v[128:131], v[206:209], v[72:75]
	v_mfma_f32_16x16x32_bf16 v[132:135], v[144:147], v[160:163], v[132:135]
	v_mfma_f32_16x16x32_bf16 v[124:127], v[152:155], v[160:163], v[124:127]
	v_mfma_f32_16x16x32_bf16 v[104:107], v[144:147], v[168:171], v[104:107]
	v_mfma_f32_16x16x32_bf16 v[100:103], v[152:155], v[168:171], v[100:103]
	v_mfma_f32_16x16x32_bf16 v[84:87], v[144:147], v[176:179], v[84:87]
	v_mfma_f32_16x16x32_bf16 v[80:83], v[152:155], v[176:179], v[80:83]
	v_mfma_f32_16x16x32_bf16 v[68:71], v[144:147], v[202:205], v[68:71]
	v_mfma_f32_16x16x32_bf16 v[64:67], v[152:155], v[202:205], v[64:67]
	v_mfma_f32_16x16x32_bf16 v[132:135], v[148:151], v[164:167], v[132:135]
	v_mfma_f32_16x16x32_bf16 v[124:127], v[156:159], v[164:167], v[124:127]
	v_mfma_f32_16x16x32_bf16 v[104:107], v[148:151], v[172:175], v[104:107]
	v_mfma_f32_16x16x32_bf16 v[100:103], v[156:159], v[172:175], v[100:103]
	v_mfma_f32_16x16x32_bf16 v[84:87], v[148:151], v[180:183], v[84:87]
	v_mfma_f32_16x16x32_bf16 v[80:83], v[156:159], v[180:183], v[80:83]
	v_mfma_f32_16x16x32_bf16 v[68:71], v[148:151], v[206:209], v[68:71]
	v_mfma_f32_16x16x32_bf16 v[64:67], v[156:159], v[206:209], v[64:67]
	s_setprio 0
	s_barrier
	s_add_i32 s77, s71, s58
	v_lshl_add_u64 v[210:211], s[54:55], 0, v[186:187]
	s_mov_b32 m0, s77
	ds_read_b128 v[160:163], v225 offset:16384
	ds_read_b128 v[164:167], v225 offset:17408
	ds_read_b128 v[168:171], v225 offset:18432
	ds_read_b128 v[172:175], v225 offset:19456
	ds_read_b128 v[176:179], v225 offset:20480
	ds_read_b128 v[180:183], v225 offset:21504
	ds_read_b128 v[202:205], v225 offset:22528
	ds_read_b128 v[206:209], v225 offset:23552
	global_load_lds_dwordx4 v[210:211], off
	s_add_i32 m0, s77, 0x2000
	s_add_u32 s78, s54, 0x40000
	v_lshl_add_u64 v[212:213], s[54:55], 0, v[190:191]
	s_addc_u32 s79, s55, 0
	s_add_i32 s77, s72, s58
	global_load_lds_dwordx4 v[212:213], off
	v_lshl_add_u64 v[214:215], s[78:79], 0, v[186:187]
	s_mov_b32 m0, s77
	v_lshl_add_u64 v[216:217], s[56:57], 0, v[188:189]
	global_load_lds_dwordx4 v[214:215], off
	v_lshl_add_u64 v[214:215], s[78:79], 0, v[190:191]
	s_add_i32 m0, s77, 0x2000
	s_nop 0
	global_load_lds_dwordx4 v[214:215], off
	v_lshl_add_u64 v[214:215], s[56:57], 0, v[184:185]
	s_mov_b32 m0, s53
	s_nop 0
	global_load_lds_dwordx4 v[214:215], off
	s_mov_b32 m0, s59
	s_nop 0
	global_load_lds_dwordx4 v[216:217], off
	s_waitcnt vmcnt(8)
	s_waitcnt lgkmcnt(0)
	s_barrier
	s_setprio 1
	s_waitcnt lgkmcnt(0)
	v_mfma_f32_16x16x32_bf16 v[60:63], v[96:99], v[160:163], v[60:63]
	v_mfma_f32_16x16x32_bf16 v[56:59], v[120:123], v[160:163], v[56:59]
	v_mfma_f32_16x16x32_bf16 v[44:47], v[96:99], v[168:171], v[44:47]
	v_mfma_f32_16x16x32_bf16 v[40:43], v[120:123], v[168:171], v[40:43]
	v_mfma_f32_16x16x32_bf16 v[28:31], v[96:99], v[176:179], v[28:31]
	v_mfma_f32_16x16x32_bf16 v[24:27], v[120:123], v[176:179], v[24:27]
	v_mfma_f32_16x16x32_bf16 v[12:15], v[96:99], v[202:205], v[12:15]
	v_mfma_f32_16x16x32_bf16 v[8:11], v[120:123], v[202:205], v[8:11]
	v_mfma_f32_16x16x32_bf16 v[60:63], v[108:111], v[164:167], v[60:63]
	v_mfma_f32_16x16x32_bf16 v[56:59], v[128:131], v[164:167], v[56:59]
	v_mfma_f32_16x16x32_bf16 v[44:47], v[108:111], v[172:175], v[44:47]
	v_mfma_f32_16x16x32_bf16 v[40:43], v[128:131], v[172:175], v[40:43]
	v_mfma_f32_16x16x32_bf16 v[28:31], v[108:111], v[180:183], v[28:31]
	v_mfma_f32_16x16x32_bf16 v[24:27], v[128:131], v[180:183], v[24:27]
	v_mfma_f32_16x16x32_bf16 v[12:15], v[108:111], v[206:209], v[12:15]
	v_mfma_f32_16x16x32_bf16 v[8:11], v[128:131], v[206:209], v[8:11]
	v_mfma_f32_16x16x32_bf16 v[52:55], v[144:147], v[160:163], v[52:55]
	v_mfma_f32_16x16x32_bf16 v[48:51], v[152:155], v[160:163], v[48:51]
	v_mfma_f32_16x16x32_bf16 v[36:39], v[144:147], v[168:171], v[36:39]
	v_mfma_f32_16x16x32_bf16 v[32:35], v[152:155], v[168:171], v[32:35]
	v_mfma_f32_16x16x32_bf16 v[20:23], v[144:147], v[176:179], v[20:23]
	v_mfma_f32_16x16x32_bf16 v[16:19], v[152:155], v[176:179], v[16:19]
	v_mfma_f32_16x16x32_bf16 v[4:7], v[144:147], v[202:205], v[4:7]
	v_mfma_f32_16x16x32_bf16 v[0:3], v[152:155], v[202:205], v[0:3]
	v_mfma_f32_16x16x32_bf16 v[52:55], v[148:151], v[164:167], v[52:55]
	v_mfma_f32_16x16x32_bf16 v[48:51], v[156:159], v[164:167], v[48:51]
	v_mfma_f32_16x16x32_bf16 v[36:39], v[148:151], v[172:175], v[36:39]
	v_mfma_f32_16x16x32_bf16 v[32:35], v[156:159], v[172:175], v[32:35]
	v_mfma_f32_16x16x32_bf16 v[20:23], v[148:151], v[180:183], v[20:23]
	v_mfma_f32_16x16x32_bf16 v[16:19], v[156:159], v[180:183], v[16:19]
	v_mfma_f32_16x16x32_bf16 v[4:7], v[148:151], v[206:209], v[4:7]
	v_mfma_f32_16x16x32_bf16 v[0:3], v[156:159], v[206:209], v[0:3]
	s_setprio 0
	s_barrier
; #define PG8_STAGE(bufoff, gbase, voff) do { _Pragma("unroll") for (int _i = 0; _i < 2; ++_i) \
;         __builtin_amdgcn_global_load_lds((const unsigned*)((const char*)(gbase) + (voff)[_i]), (PG8_LAS unsigned*)(lds + (bufoff) + ldsw + _i * 8192), 16, 0, 0); } while (0)
; #define PG8_LDA(dst, b, h) do { _Pragma("unroll") for (int m = 0; m < 4; ++m) _Pragma("unroll") for (int k = 0; k < 2; ++k) dst[m][k] = *(const PG8_LAS bf16x8*)(lds + PG8_SA(b, h) + aoff + m * 2048 + k * 1024); } while (0)
; #define PG8_LDB(dst, b, h) do { _Pragma("unroll") for (int n = 0; n < 2; ++n) _Pragma("unroll") for (int k = 0; k < 2; ++k) dst[n][k] = *(const PG8_LAS bf16x8*)(lds + PG8_SB(b, h) + boff + n * 2048 + k * 1024); } while (0)
; #define PG8_MMA(ai, bj, At, Bt) do { __builtin_amdgcn_s_setprio(1); _Pragma("unroll") for (int m = 0; m < 4; ++m) _Pragma("unroll") for (int n = 0; n < 2; ++n) _Pragma("unroll") for (int k = 0; k < 2; ++k) \
;         acc[ai][bj][m][n] = __builtin_amdgcn_mfma_f32_16x16x32_bf16(Bt[n][k], At[m][k], acc[ai][bj][m][n], 0, 0, 0); __builtin_amdgcn_s_setprio(0); } while (0)
; #define PG8_WAIT_V(n) asm volatile("s_waitcnt vmcnt(" #n ")" ::: "memory")
; #define PG8_WAIT_L(n) asm volatile("s_waitcnt lgkmcnt(" #n ")" ::: "memory")
; #define PG8_BAR __builtin_amdgcn_s_barrier()
; #define PG8_SCHED __builtin_amdgcn_sched_barrier(0)
; template <class Epi, class Sched, bool ALIGN_EPI = false, bool SP2 = false>
; __device__ __forceinline__ void gemm_phase(PG8_LAS unsigned char* lds, const Gemm g, const Sched& S, const Epi& E) {
;     ...
;             PG8_LDB(B0, 1, 0); PG8_LDB(B1, 1, 1); PG8_SCHED; PG8_LDA(At, 1, 0); PG8_STAGE(PG8_SA(0, 1), a2 + hstep, voffA);
;             PG8_WAIT_V(8); PG8_WAIT_L(0); PG8_BAR; PG8_MMA(0, 0, At, B0); PG8_MMA(0, 1, At, B1); PG8_BAR; PG8_SCHED;
	s_add_i32 s77, 0, 0x18000
	s_add_i32 s78, 0, 0x1c000
	v_add_u32_e32 v128, s77, v221
	v_add_u32_e32 v156, s78, v221
	ds_read_b128 v[96:99], v128
	ds_read_b128 v[108:111], v128 offset:1024
	ds_read_b128 v[120:123], v128 offset:2048
	ds_read_b128 v[128:131], v128 offset:3072
	ds_read_b128 v[144:147], v156
	ds_read_b128 v[148:151], v156 offset:1024
	ds_read_b128 v[152:155], v156 offset:2048
	ds_read_b128 v[156:159], v156 offset:3072
	s_add_u32 s56, s56, 0x40000
	s_addc_u32 s57, s57, 0
	s_mov_b32 m0, s60
	v_lshl_add_u64 v[218:219], s[56:57], 0, v[184:185]
	ds_read_b128 v[160:163], v225 offset:32768
	ds_read_b128 v[164:167], v225 offset:33792
	ds_read_b128 v[168:171], v225 offset:34816
	ds_read_b128 v[172:175], v225 offset:35840
	ds_read_b128 v[176:179], v225 offset:36864
	ds_read_b128 v[180:183], v225 offset:37888
	ds_read_b128 v[202:205], v225 offset:38912
	ds_read_b128 v[206:209], v225 offset:39936
	global_load_lds_dwordx4 v[218:219], off
	v_lshl_add_u64 v[218:219], s[56:57], 0, v[188:189]
	s_mov_b32 m0, s61
	s_nop 0
	global_load_lds_dwordx4 v[218:219], off
	s_waitcnt vmcnt(8)
	s_waitcnt lgkmcnt(0)
	s_barrier
	s_setprio 1
	s_waitcnt lgkmcnt(0)
	v_mfma_f32_16x16x32_bf16 v[140:143], v[96:99], v[160:163], v[140:143]
	v_mfma_f32_16x16x32_bf16 v[136:139], v[120:123], v[160:163], v[136:139]
	v_mfma_f32_16x16x32_bf16 v[116:119], v[96:99], v[168:171], v[116:119]
	v_mfma_f32_16x16x32_bf16 v[112:115], v[120:123], v[168:171], v[112:115]
	v_mfma_f32_16x16x32_bf16 v[92:95], v[96:99], v[176:179], v[92:95]
	v_mfma_f32_16x16x32_bf16 v[88:91], v[120:123], v[176:179], v[88:91]
	v_mfma_f32_16x16x32_bf16 v[76:79], v[96:99], v[202:205], v[76:79]
	v_mfma_f32_16x16x32_bf16 v[72:75], v[120:123], v[202:205], v[72:75]
	v_mfma_f32_16x16x32_bf16 v[140:143], v[108:111], v[164:167], v[140:143]
	v_mfma_f32_16x16x32_bf16 v[136:139], v[128:131], v[164:167], v[136:139]
	v_mfma_f32_16x16x32_bf16 v[116:119], v[108:111], v[172:175], v[116:119]
	v_mfma_f32_16x16x32_bf16 v[112:115], v[128:131], v[172:175], v[112:115]
	v_mfma_f32_16x16x32_bf16 v[92:95], v[108:111], v[180:183], v[92:95]
	v_mfma_f32_16x16x32_bf16 v[88:91], v[128:131], v[180:183], v[88:91]
	v_mfma_f32_16x16x32_bf16 v[76:79], v[108:111], v[206:209], v[76:79]
	v_mfma_f32_16x16x32_bf16 v[72:75], v[128:131], v[206:209], v[72:75]
	v_mfma_f32_16x16x32_bf16 v[132:135], v[144:147], v[160:163], v[132:135]
	v_mfma_f32_16x16x32_bf16 v[124:127], v[152:155], v[160:163], v[124:127]
	v_mfma_f32_16x16x32_bf16 v[104:107], v[144:147], v[168:171], v[104:107]
	v_mfma_f32_16x16x32_bf16 v[100:103], v[152:155], v[168:171], v[100:103]
	v_mfma_f32_16x16x32_bf16 v[84:87], v[144:147], v[176:179], v[84:87]
	v_mfma_f32_16x16x32_bf16 v[80:83], v[152:155], v[176:179], v[80:83]
	v_mfma_f32_16x16x32_bf16 v[68:71], v[144:147], v[202:205], v[68:71]
	v_mfma_f32_16x16x32_bf16 v[64:67], v[152:155], v[202:205], v[64:67]
	v_mfma_f32_16x16x32_bf16 v[132:135], v[148:151], v[164:167], v[132:135]
	v_mfma_f32_16x16x32_bf16 v[124:127], v[156:159], v[164:167], v[124:127]
	v_mfma_f32_16x16x32_bf16 v[104:107], v[148:151], v[172:175], v[104:107]
	v_mfma_f32_16x16x32_bf16 v[100:103], v[156:159], v[172:175], v[100:103]
	v_mfma_f32_16x16x32_bf16 v[84:87], v[148:151], v[180:183], v[84:87]
	v_mfma_f32_16x16x32_bf16 v[80:83], v[156:159], v[180:183], v[80:83]
	v_mfma_f32_16x16x32_bf16 v[68:71], v[148:151], v[206:209], v[68:71]
	v_mfma_f32_16x16x32_bf16 v[64:67], v[156:159], v[206:209], v[64:67]
	s_setprio 0
	s_barrier
; #define PG8_STAGE(bufoff, gbase, voff) do { _Pragma("unroll") for (int _i = 0; _i < 2; ++_i) \
;         __builtin_amdgcn_global_load_lds((const unsigned*)((const char*)(gbase) + (voff)[_i]), (PG8_LAS unsigned*)(lds + (bufoff) + ldsw + _i * 8192), 16, 0, 0); } while (0)
; #define PG8_LDA(dst, b, h) do { _Pragma("unroll") for (int m = 0; m < 4; ++m) _Pragma("unroll") for (int k = 0; k < 2; ++k) dst[m][k] = *(const PG8_LAS bf16x8*)(lds + PG8_SA(b, h) + aoff + m * 2048 + k * 1024); } while (0)
; #define PG8_MMA(ai, bj, At, Bt) do { __builtin_amdgcn_s_setprio(1); _Pragma("unroll") for (int m = 0; m < 4; ++m) _Pragma("unroll") for (int n = 0; n < 2; ++n) _Pragma("unroll") for (int k = 0; k < 2; ++k) \
;         acc[ai][bj][m][n] = __builtin_amdgcn_mfma_f32_16x16x32_bf16(Bt[n][k], At[m][k], acc[ai][bj][m][n], 0, 0, 0); __builtin_amdgcn_s_setprio(0); } while (0)
; #define PG8_WAIT_V(n) asm volatile("s_waitcnt vmcnt(" #n ")" ::: "memory")
; #define PG8_WAIT_L(n) asm volatile("s_waitcnt lgkmcnt(" #n ")" ::: "memory")
; #define PG8_BAR __builtin_amdgcn_s_barrier()
; #define PG8_SCHED __builtin_amdgcn_sched_barrier(0)
; template <class Epi, class Sched, bool ALIGN_EPI = false, bool SP2 = false>
; __device__ __forceinline__ void gemm_phase(PG8_LAS unsigned char* lds, const Gemm g, const Sched& S, const Epi& E) {
;     ...
;             PG8_LDA(At, 1, 1); PG8_STAGE(PG8_SB(1, 0), b3, voffB); PG8_STAGE(PG8_SB(1, 1), b3 + hstep, voffB); PG8_STAGE(PG8_SA(1, 0), a3, voffA);
;             PG8_WAIT_V(8); PG8_WAIT_L(0); PG8_BAR; PG8_MMA(1, 0, At, B0); PG8_MMA(1, 1, At, B1); PG8_BAR; PG8_SCHED;
;     ...
;         if constexpr (ALIGN_EPI) { if (wr == 0) PG8_BAR; }
	s_add_i32 s56, s77, s58
	v_lshl_add_u64 v[210:211], v[210:211], 0, s[12:13]
	s_mov_b32 m0, s56
	ds_read_b128 v[160:163], v225 offset:49152
	ds_read_b128 v[164:167], v225 offset:50176
	ds_read_b128 v[168:171], v225 offset:51200
	ds_read_b128 v[172:175], v225 offset:52224
	ds_read_b128 v[176:179], v225 offset:53248
	ds_read_b128 v[180:183], v225 offset:54272
	ds_read_b128 v[202:205], v225 offset:55296
	ds_read_b128 v[206:209], v225 offset:56320
	global_load_lds_dwordx4 v[210:211], off
	s_add_i32 m0, s56, 0x2000
	s_add_u32 s54, s54, 0x40080
	v_lshl_add_u64 v[210:211], v[212:213], 0, s[12:13]
	s_addc_u32 s55, s55, 0
	s_add_i32 s56, s78, s58
	global_load_lds_dwordx4 v[210:211], off
	v_lshl_add_u64 v[210:211], s[54:55], 0, v[186:187]
	s_mov_b32 m0, s56
	s_nop 0
	global_load_lds_dwordx4 v[210:211], off
	v_lshl_add_u64 v[210:211], s[54:55], 0, v[190:191]
	s_add_i32 m0, s56, 0x2000
	s_nop 0
	global_load_lds_dwordx4 v[210:211], off
	v_lshl_add_u64 v[210:211], v[214:215], 0, s[12:13]
	s_mov_b32 m0, s66
	s_nop 0
	global_load_lds_dwordx4 v[210:211], off
	v_lshl_add_u64 v[210:211], v[216:217], 0, s[12:13]
	s_mov_b32 m0, s67
	s_nop 0
	global_load_lds_dwordx4 v[210:211], off
	s_waitcnt vmcnt(8)
	s_waitcnt lgkmcnt(0)
	s_barrier
	s_setprio 1
	s_waitcnt lgkmcnt(0)
	v_mfma_f32_16x16x32_bf16 v[60:63], v[96:99], v[160:163], v[60:63]
	v_mfma_f32_16x16x32_bf16 v[56:59], v[120:123], v[160:163], v[56:59]
	v_mfma_f32_16x16x32_bf16 v[44:47], v[96:99], v[168:171], v[44:47]
	v_mfma_f32_16x16x32_bf16 v[40:43], v[120:123], v[168:171], v[40:43]
	v_mfma_f32_16x16x32_bf16 v[28:31], v[96:99], v[176:179], v[28:31]
	v_mfma_f32_16x16x32_bf16 v[24:27], v[120:123], v[176:179], v[24:27]
	v_mfma_f32_16x16x32_bf16 v[12:15], v[96:99], v[202:205], v[12:15]
	v_mfma_f32_16x16x32_bf16 v[8:11], v[120:123], v[202:205], v[8:11]
	v_mfma_f32_16x16x32_bf16 v[60:63], v[108:111], v[164:167], v[60:63]
	v_mfma_f32_16x16x32_bf16 v[56:59], v[128:131], v[164:167], v[56:59]
	v_mfma_f32_16x16x32_bf16 v[44:47], v[108:111], v[172:175], v[44:47]
	v_mfma_f32_16x16x32_bf16 v[40:43], v[128:131], v[172:175], v[40:43]
	v_mfma_f32_16x16x32_bf16 v[28:31], v[108:111], v[180:183], v[28:31]
	v_mfma_f32_16x16x32_bf16 v[24:27], v[128:131], v[180:183], v[24:27]
	v_mfma_f32_16x16x32_bf16 v[12:15], v[108:111], v[206:209], v[12:15]
	v_mfma_f32_16x16x32_bf16 v[8:11], v[128:131], v[206:209], v[8:11]
	v_mfma_f32_16x16x32_bf16 v[52:55], v[144:147], v[160:163], v[52:55]
	v_mfma_f32_16x16x32_bf16 v[48:51], v[152:155], v[160:163], v[48:51]
	v_mfma_f32_16x16x32_bf16 v[36:39], v[144:147], v[168:171], v[36:39]
	v_mfma_f32_16x16x32_bf16 v[32:35], v[152:155], v[168:171], v[32:35]
	v_mfma_f32_16x16x32_bf16 v[20:23], v[144:147], v[176:179], v[20:23]
	v_mfma_f32_16x16x32_bf16 v[16:19], v[152:155], v[176:179], v[16:19]
	v_mfma_f32_16x16x32_bf16 v[4:7], v[144:147], v[202:205], v[4:7]
	v_mfma_f32_16x16x32_bf16 v[0:3], v[152:155], v[202:205], v[0:3]
	v_mfma_f32_16x16x32_bf16 v[52:55], v[148:151], v[164:167], v[52:55]
	v_mfma_f32_16x16x32_bf16 v[48:51], v[156:159], v[164:167], v[48:51]
	v_mfma_f32_16x16x32_bf16 v[36:39], v[148:151], v[172:175], v[36:39]
	v_mfma_f32_16x16x32_bf16 v[32:35], v[156:159], v[172:175], v[32:35]
	v_mfma_f32_16x16x32_bf16 v[20:23], v[148:151], v[180:183], v[20:23]
	v_mfma_f32_16x16x32_bf16 v[16:19], v[156:159], v[180:183], v[16:19]
	v_mfma_f32_16x16x32_bf16 v[4:7], v[148:151], v[206:209], v[4:7]
	v_mfma_f32_16x16x32_bf16 v[0:3], v[156:159], v[206:209], v[0:3]
	s_setprio 0
	s_barrier
	s_add_i32 s76, s76, 2
	s_add_u32 s20, s20, 0x100
	s_addc_u32 s21, s21, 0
	s_add_u32 s74, s74, 0x100
	s_addc_u32 s75, s75, 0
	s_cmp_gt_u32 s76, 13
	s_cbranch_scc0 .LBB0_705
	s_and_b64 vcc, exec, s[14:15]
	s_cbranch_vccz .LBB0_708
	s_barrier

; #define PG8_STAGE(bufoff, gbase, voff) do { _Pragma("unroll") for (int _i = 0; _i < 2; ++_i) \
;         __builtin_amdgcn_global_load_lds((const unsigned*)((const char*)(gbase) + (voff)[_i]), (PG8_LAS unsigned*)(lds + (bufoff) + ldsw + _i * 8192), 16, 0, 0); } while (0)
; #define PG8_LDA(dst, b, h) do { _Pragma("unroll") for (int m = 0; m < 4; ++m) _Pragma("unroll") for (int k = 0; k < 2; ++k) dst[m][k] = *(const PG8_LAS bf16x8*)(lds + PG8_SA(b, h) + aoff + m * 2048 + k * 1024); } while (0)
; #define PG8_LDB(dst, b, h) do { _Pragma("unroll") for (int n = 0; n < 2; ++n) _Pragma("unroll") for (int k = 0; k < 2; ++k) dst[n][k] = *(const PG8_LAS bf16x8*)(lds + PG8_SB(b, h) + boff + n * 2048 + k * 1024); } while (0)
; #define PG8_MMA(ai, bj, At, Bt) do { __builtin_amdgcn_s_setprio(1); _Pragma("unroll") for (int m = 0; m < 4; ++m) _Pragma("unroll") for (int n = 0; n < 2; ++n) _Pragma("unroll") for (int k = 0; k < 2; ++k) \
;         acc[ai][bj][m][n] = __builtin_amdgcn_mfma_f32_16x16x32_bf16(Bt[n][k], At[m][k], acc[ai][bj][m][n], 0, 0, 0); __builtin_amdgcn_s_setprio(0); } while (0)
; #define PG8_WAIT_V(n) asm volatile("s_waitcnt vmcnt(" #n ")" ::: "memory")
; template <class Epi, class Sched, bool ALIGN_EPI = false, bool SP2 = false>
; __device__ __forceinline__ void gemm_phase(PG8_LAS unsigned char* lds, const Gemm g, const Sched& S, const Epi& E) {
;     ...
;         const char* nA = has_next ? (const char*)g.A + (size_t)nxt.pm * tstep : cA; const char* nB = has_next ? (const char*)g.Bt + (size_t)nxt.pn * tstep : cB;
;         for (int t = 0; t < nt; t += 2) {
;             const bool last = (t == nt - 2);
;             const char* a1 = cA + (size_t)(t + 1) * kstep;
;             const char* a2 = last ? nA : cA + (size_t)(t + 2) * kstep; const char* b2 = last ? nB : cB + (size_t)(t + 2) * kstep;
;             const char* a3 = a2 + kstep; const char* b3 = b2 + kstep;
;             if (last && has_next) S.a_ready(nxt);
;             if constexpr (SP2) {
;             PG8_LDB(B0, 0, 0); PG8_LDB(B1, 0, 1); PG8_SCHED; PG8_LDA(At, 0, 0); PG8_STAGE(PG8_SA(1, 1), a1 + hstep, voffA);
;             PG8_WAIT_V(8); PG8_WAIT_L(0); PG8_BAR; PG8_MMA(0, 0, At, B0); PG8_MMA(0, 1, At, B1); PG8_BAR; PG8_SCHED;
;             PG8_LDA(At, 0, 1); PG8_STAGE(PG8_SB(0, 0), b2, voffB); PG8_STAGE(PG8_SB(0, 1), b2 + hstep, voffB); PG8_STAGE(PG8_SA(0, 0), a2, voffA);
.LBB0_809:
	s_ashr_i32 s15, s14, 31
	s_lshl_b64 s[16:17], s[14:15], 19
	s_add_u32 s16, s36, s16
	s_addc_u32 s17, s37, s17
	s_and_b64 s[18:19], s[4:5], exec
	s_cselect_b32 s15, s17, s21
	s_cselect_b32 s65, s16, s20
	s_ashr_i32 s13, s12, 31
	s_lshl_b64 s[18:19], s[12:13], 19
	s_add_u32 s18, s50, s18
	s_addc_u32 s19, s51, s19
	s_and_b64 s[44:45], s[4:5], exec
	s_cselect_b32 s13, s19, s39
	s_cselect_b32 s66, s18, s38
	s_add_u32 s20, s20, 0x40080
	s_addc_u32 s21, s21, 0
	s_add_u32 s67, s38, 0x100
	s_addc_u32 s68, s39, 0
	s_mov_b32 s69, -2
	ds_read_b128 v[154:157], v150
	ds_read_b128 v[158:161], v150 offset:1024
	ds_read_b128 v[162:165], v150 offset:2048
	ds_read_b128 v[166:169], v150 offset:3072
	ds_read_b128 v[170:173], v151
	ds_read_b128 v[174:177], v151 offset:1024
	ds_read_b128 v[178:181], v151 offset:2048
	ds_read_b128 v[182:185], v151 offset:3072
	s_add_u32 s38, s20, 0xfffc0080
	s_addc_u32 s39, s21, -1
	s_cmp_eq_u32 s69, 12
	s_cselect_b32 s45, s15, s39
	s_cselect_b32 s44, s65, s38
	s_cselect_b32 s39, s13, s68
	s_cselect_b32 s38, s66, s67
	v_lshl_add_u64 v[144:145], s[20:21], 0, v[136:137]
	s_add_i32 m0, s35, 0xc000
	ds_read_b128 v[186:189], v152
	ds_read_b128 v[190:193], v152 offset:1024
	ds_read_b128 v[198:201], v152 offset:2048
	ds_read_b128 v[202:205], v152 offset:3072
	ds_read_b128 v[206:209], v152 offset:4096
	ds_read_b128 v[210:213], v152 offset:5120
	ds_read_b128 v[214:217], v152 offset:6144
	ds_read_b128 v[218:221], v152 offset:7168
	global_load_lds_dwordx4 v[144:145], off
	v_lshl_add_u64 v[144:145], s[20:21], 0, v[138:139]
	s_add_i32 m0, s35, 0xe000
	s_nop 0
	global_load_lds_dwordx4 v[144:145], off
	s_waitcnt vmcnt(8)
	s_waitcnt lgkmcnt(0)
	s_barrier
	s_setprio 1
	s_waitcnt lgkmcnt(0)
	v_mfma_f32_16x16x32_bf16 v[124:127], v[154:157], v[186:189], 0
	v_mfma_f32_16x16x32_bf16 v[116:119], v[162:165], v[186:189], 0
	v_mfma_f32_16x16x32_bf16 v[108:111], v[154:157], v[198:201], 0
	v_mfma_f32_16x16x32_bf16 v[100:103], v[162:165], v[198:201], 0
	v_mfma_f32_16x16x32_bf16 v[92:95], v[154:157], v[206:209], 0
	v_mfma_f32_16x16x32_bf16 v[84:87], v[162:165], v[206:209], 0
	v_mfma_f32_16x16x32_bf16 v[76:79], v[154:157], v[214:217], 0
	v_mfma_f32_16x16x32_bf16 v[68:71], v[162:165], v[214:217], 0
	v_mfma_f32_16x16x32_bf16 v[124:127], v[158:161], v[190:193], v[124:127]
	v_mfma_f32_16x16x32_bf16 v[116:119], v[166:169], v[190:193], v[116:119]
	v_mfma_f32_16x16x32_bf16 v[108:111], v[158:161], v[202:205], v[108:111]
	v_mfma_f32_16x16x32_bf16 v[100:103], v[166:169], v[202:205], v[100:103]
	v_mfma_f32_16x16x32_bf16 v[92:95], v[158:161], v[210:213], v[92:95]
	v_mfma_f32_16x16x32_bf16 v[84:87], v[166:169], v[210:213], v[84:87]
	v_mfma_f32_16x16x32_bf16 v[76:79], v[158:161], v[218:221], v[76:79]
	v_mfma_f32_16x16x32_bf16 v[68:71], v[166:169], v[218:221], v[68:71]
	v_mfma_f32_16x16x32_bf16 v[120:123], v[170:173], v[186:189], 0
	v_mfma_f32_16x16x32_bf16 v[112:115], v[178:181], v[186:189], 0
	v_mfma_f32_16x16x32_bf16 v[104:107], v[170:173], v[198:201], 0
	v_mfma_f32_16x16x32_bf16 v[96:99], v[178:181], v[198:201], 0
	v_mfma_f32_16x16x32_bf16 v[88:91], v[170:173], v[206:209], 0
	v_mfma_f32_16x16x32_bf16 v[80:83], v[178:181], v[206:209], 0
	v_mfma_f32_16x16x32_bf16 v[72:75], v[170:173], v[214:217], 0
	v_mfma_f32_16x16x32_bf16 v[64:67], v[178:181], v[214:217], 0
	v_mfma_f32_16x16x32_bf16 v[120:123], v[174:177], v[190:193], v[120:123]
	v_mfma_f32_16x16x32_bf16 v[112:115], v[182:185], v[190:193], v[112:115]
	v_mfma_f32_16x16x32_bf16 v[104:107], v[174:177], v[202:205], v[104:107]
	v_mfma_f32_16x16x32_bf16 v[96:99], v[182:185], v[202:205], v[96:99]
	v_mfma_f32_16x16x32_bf16 v[88:91], v[174:177], v[210:213], v[88:91]
	v_mfma_f32_16x16x32_bf16 v[80:83], v[182:185], v[210:213], v[80:83]
	v_mfma_f32_16x16x32_bf16 v[72:75], v[174:177], v[218:221], v[72:75]
	v_mfma_f32_16x16x32_bf16 v[64:67], v[182:185], v[218:221], v[64:67]
	s_setprio 0
	s_barrier
	s_add_i32 s70, s60, s52
	v_lshl_add_u64 v[144:145], s[38:39], 0, v[132:133]
	s_mov_b32 m0, s70
	ds_read_b128 v[186:189], v152 offset:16384
	ds_read_b128 v[190:193], v152 offset:17408
	ds_read_b128 v[198:201], v152 offset:18432
	ds_read_b128 v[202:205], v152 offset:19456
	ds_read_b128 v[206:209], v152 offset:20480
	ds_read_b128 v[210:213], v152 offset:21504
	ds_read_b128 v[214:217], v152 offset:22528
	ds_read_b128 v[218:221], v152 offset:23552
	global_load_lds_dwordx4 v[144:145], off
	s_add_i32 m0, s70, 0x2000
	s_add_u32 s70, s38, 0x40000
	v_lshl_add_u64 v[194:195], s[38:39], 0, v[128:129]
	s_addc_u32 s71, s39, 0
	s_add_i32 s72, s61, s52
	global_load_lds_dwordx4 v[194:195], off
	v_lshl_add_u64 v[222:223], s[70:71], 0, v[132:133]
	s_mov_b32 m0, s72
	v_lshl_add_u64 v[224:225], s[44:45], 0, v[130:131]
	global_load_lds_dwordx4 v[222:223], off
	v_lshl_add_u64 v[222:223], s[70:71], 0, v[128:129]
	s_add_i32 m0, s72, 0x2000
	s_nop 0
	global_load_lds_dwordx4 v[222:223], off
	v_lshl_add_u64 v[222:223], s[44:45], 0, v[134:135]
	s_mov_b32 m0, s35
	s_nop 0
	global_load_lds_dwordx4 v[222:223], off
	s_mov_b32 m0, s54
	s_nop 0
	global_load_lds_dwordx4 v[224:225], off
	s_waitcnt vmcnt(8)
	s_waitcnt lgkmcnt(0)
	s_barrier
; #define PG8_STAGE(bufoff, gbase, voff) do { _Pragma("unroll") for (int _i = 0; _i < 2; ++_i) \
;         __builtin_amdgcn_global_load_lds((const unsigned*)((const char*)(gbase) + (voff)[_i]), (PG8_LAS unsigned*)(lds + (bufoff) + ldsw + _i * 8192), 16, 0, 0); } while (0)
; #define PG8_LDA(dst, b, h) do { _Pragma("unroll") for (int m = 0; m < 4; ++m) _Pragma("unroll") for (int k = 0; k < 2; ++k) dst[m][k] = *(const PG8_LAS bf16x8*)(lds + PG8_SA(b, h) + aoff + m * 2048 + k * 1024); } while (0)
; #define PG8_LDB(dst, b, h) do { _Pragma("unroll") for (int n = 0; n < 2; ++n) _Pragma("unroll") for (int k = 0; k < 2; ++k) dst[n][k] = *(const PG8_LAS bf16x8*)(lds + PG8_SB(b, h) + boff + n * 2048 + k * 1024); } while (0)
; #define PG8_MMA(ai, bj, At, Bt) do { __builtin_amdgcn_s_setprio(1); _Pragma("unroll") for (int m = 0; m < 4; ++m) _Pragma("unroll") for (int n = 0; n < 2; ++n) _Pragma("unroll") for (int k = 0; k < 2; ++k) \
;         acc[ai][bj][m][n] = __builtin_amdgcn_mfma_f32_16x16x32_bf16(Bt[n][k], At[m][k], acc[ai][bj][m][n], 0, 0, 0); __builtin_amdgcn_s_setprio(0); } while (0)
; #define PG8_WAIT_V(n) asm volatile("s_waitcnt vmcnt(" #n ")" ::: "memory")
; #define PG8_WAIT_L(n) asm volatile("s_waitcnt lgkmcnt(" #n ")" ::: "memory")
; #define PG8_BAR __builtin_amdgcn_s_barrier()
; #define PG8_SCHED __builtin_amdgcn_sched_barrier(0)
; template <class Epi, class Sched, bool ALIGN_EPI = false, bool SP2 = false>
; __device__ __forceinline__ void gemm_phase(PG8_LAS unsigned char* lds, const Gemm g, const Sched& S, const Epi& E) {
;     ...
;             PG8_WAIT_V(8); PG8_WAIT_L(0); PG8_BAR; PG8_MMA(1, 0, At, B0); PG8_MMA(1, 1, At, B1); PG8_BAR; PG8_SCHED;
;             PG8_LDB(B0, 1, 0); PG8_LDB(B1, 1, 1); PG8_SCHED; PG8_LDA(At, 1, 0); PG8_STAGE(PG8_SA(0, 1), a2 + hstep, voffA);
;             PG8_WAIT_V(8); PG8_WAIT_L(0); PG8_BAR; PG8_MMA(0, 0, At, B0); PG8_MMA(0, 1, At, B1); PG8_BAR; PG8_SCHED;
	s_setprio 1
	s_waitcnt lgkmcnt(0)
	v_mfma_f32_16x16x32_bf16 v[60:63], v[154:157], v[186:189], 0
	v_mfma_f32_16x16x32_bf16 v[52:55], v[162:165], v[186:189], 0
	v_mfma_f32_16x16x32_bf16 v[44:47], v[154:157], v[198:201], 0
	v_mfma_f32_16x16x32_bf16 v[36:39], v[162:165], v[198:201], 0
	v_mfma_f32_16x16x32_bf16 v[28:31], v[154:157], v[206:209], 0
	v_mfma_f32_16x16x32_bf16 v[20:23], v[162:165], v[206:209], 0
	v_mfma_f32_16x16x32_bf16 v[12:15], v[154:157], v[214:217], 0
	v_mfma_f32_16x16x32_bf16 v[4:7], v[162:165], v[214:217], 0
	v_mfma_f32_16x16x32_bf16 v[60:63], v[158:161], v[190:193], v[60:63]
	v_mfma_f32_16x16x32_bf16 v[52:55], v[166:169], v[190:193], v[52:55]
	v_mfma_f32_16x16x32_bf16 v[44:47], v[158:161], v[202:205], v[44:47]
	v_mfma_f32_16x16x32_bf16 v[36:39], v[166:169], v[202:205], v[36:39]
	v_mfma_f32_16x16x32_bf16 v[28:31], v[158:161], v[210:213], v[28:31]
	v_mfma_f32_16x16x32_bf16 v[20:23], v[166:169], v[210:213], v[20:23]
	v_mfma_f32_16x16x32_bf16 v[12:15], v[158:161], v[218:221], v[12:15]
	v_mfma_f32_16x16x32_bf16 v[4:7], v[166:169], v[218:221], v[4:7]
	v_mfma_f32_16x16x32_bf16 v[56:59], v[170:173], v[186:189], 0
	v_mfma_f32_16x16x32_bf16 v[48:51], v[178:181], v[186:189], 0
	v_mfma_f32_16x16x32_bf16 v[40:43], v[170:173], v[198:201], 0
	v_mfma_f32_16x16x32_bf16 v[32:35], v[178:181], v[198:201], 0
	v_mfma_f32_16x16x32_bf16 v[24:27], v[170:173], v[206:209], 0
	v_mfma_f32_16x16x32_bf16 v[16:19], v[178:181], v[206:209], 0
	v_mfma_f32_16x16x32_bf16 v[8:11], v[170:173], v[214:217], 0
	v_mfma_f32_16x16x32_bf16 v[0:3], v[178:181], v[214:217], 0
	v_mfma_f32_16x16x32_bf16 v[56:59], v[174:177], v[190:193], v[56:59]
	v_mfma_f32_16x16x32_bf16 v[48:51], v[182:185], v[190:193], v[48:51]
	v_mfma_f32_16x16x32_bf16 v[40:43], v[174:177], v[202:205], v[40:43]
	v_mfma_f32_16x16x32_bf16 v[32:35], v[182:185], v[202:205], v[32:35]
	v_mfma_f32_16x16x32_bf16 v[24:27], v[174:177], v[210:213], v[24:27]
	v_mfma_f32_16x16x32_bf16 v[16:19], v[182:185], v[210:213], v[16:19]
	v_mfma_f32_16x16x32_bf16 v[8:11], v[174:177], v[218:221], v[8:11]
	v_mfma_f32_16x16x32_bf16 v[0:3], v[182:185], v[218:221], v[0:3]
	s_setprio 0
	s_barrier
	s_add_i32 s70, 0, 0x18000
	v_add_u32_e32 v153, s70, v147
	s_add_i32 s71, 0, 0x1c000
	ds_read_b128 v[154:157], v153
	ds_read_b128 v[158:161], v153 offset:1024
	ds_read_b128 v[162:165], v153 offset:2048
	ds_read_b128 v[166:169], v153 offset:3072
	v_add_u32_e32 v153, s71, v147
	ds_read_b128 v[170:173], v153
	ds_read_b128 v[174:177], v153 offset:1024
	ds_read_b128 v[178:181], v153 offset:2048
	ds_read_b128 v[182:185], v153 offset:3072
	s_add_u32 s44, s44, 0x40000
	s_addc_u32 s45, s45, 0
	s_mov_b32 m0, s55
	v_lshl_add_u64 v[226:227], s[44:45], 0, v[134:135]
	ds_read_b128 v[186:189], v152 offset:32768
	ds_read_b128 v[190:193], v152 offset:33792
	ds_read_b128 v[198:201], v152 offset:34816
	ds_read_b128 v[202:205], v152 offset:35840
	ds_read_b128 v[206:209], v152 offset:36864
	ds_read_b128 v[210:213], v152 offset:37888
	ds_read_b128 v[214:217], v152 offset:38912
	ds_read_b128 v[218:221], v152 offset:39936
	global_load_lds_dwordx4 v[226:227], off
	v_lshl_add_u64 v[226:227], s[44:45], 0, v[130:131]
	s_mov_b32 m0, s56
	s_nop 0
	global_load_lds_dwordx4 v[226:227], off
	s_waitcnt vmcnt(8)
	s_waitcnt lgkmcnt(0)
	s_barrier
	s_setprio 1
	s_waitcnt lgkmcnt(0)
	v_mfma_f32_16x16x32_bf16 v[124:127], v[154:157], v[186:189], v[124:127]
	v_mfma_f32_16x16x32_bf16 v[116:119], v[162:165], v[186:189], v[116:119]
	v_mfma_f32_16x16x32_bf16 v[108:111], v[154:157], v[198:201], v[108:111]
	v_mfma_f32_16x16x32_bf16 v[100:103], v[162:165], v[198:201], v[100:103]
	v_mfma_f32_16x16x32_bf16 v[92:95], v[154:157], v[206:209], v[92:95]
	v_mfma_f32_16x16x32_bf16 v[84:87], v[162:165], v[206:209], v[84:87]
	v_mfma_f32_16x16x32_bf16 v[76:79], v[154:157], v[214:217], v[76:79]
	v_mfma_f32_16x16x32_bf16 v[68:71], v[162:165], v[214:217], v[68:71]
	v_mfma_f32_16x16x32_bf16 v[124:127], v[158:161], v[190:193], v[124:127]
	v_mfma_f32_16x16x32_bf16 v[116:119], v[166:169], v[190:193], v[116:119]
	v_mfma_f32_16x16x32_bf16 v[108:111], v[158:161], v[202:205], v[108:111]
	v_mfma_f32_16x16x32_bf16 v[100:103], v[166:169], v[202:205], v[100:103]
	v_mfma_f32_16x16x32_bf16 v[92:95], v[158:161], v[210:213], v[92:95]
	v_mfma_f32_16x16x32_bf16 v[84:87], v[166:169], v[210:213], v[84:87]
	v_mfma_f32_16x16x32_bf16 v[76:79], v[158:161], v[218:221], v[76:79]
	v_mfma_f32_16x16x32_bf16 v[68:71], v[166:169], v[218:221], v[68:71]
	v_mfma_f32_16x16x32_bf16 v[120:123], v[170:173], v[186:189], v[120:123]
	v_mfma_f32_16x16x32_bf16 v[112:115], v[178:181], v[186:189], v[112:115]
	v_mfma_f32_16x16x32_bf16 v[104:107], v[170:173], v[198:201], v[104:107]
	v_mfma_f32_16x16x32_bf16 v[96:99], v[178:181], v[198:201], v[96:99]
	v_mfma_f32_16x16x32_bf16 v[88:91], v[170:173], v[206:209], v[88:91]
	v_mfma_f32_16x16x32_bf16 v[80:83], v[178:181], v[206:209], v[80:83]
	v_mfma_f32_16x16x32_bf16 v[72:75], v[170:173], v[214:217], v[72:75]
	v_mfma_f32_16x16x32_bf16 v[64:67], v[178:181], v[214:217], v[64:67]
	v_mfma_f32_16x16x32_bf16 v[120:123], v[174:177], v[190:193], v[120:123]
	v_mfma_f32_16x16x32_bf16 v[112:115], v[182:185], v[190:193], v[112:115]
	v_mfma_f32_16x16x32_bf16 v[104:107], v[174:177], v[202:205], v[104:107]
	v_mfma_f32_16x16x32_bf16 v[96:99], v[182:185], v[202:205], v[96:99]
	v_mfma_f32_16x16x32_bf16 v[88:91], v[174:177], v[210:213], v[88:91]
	v_mfma_f32_16x16x32_bf16 v[80:83], v[182:185], v[210:213], v[80:83]
	v_mfma_f32_16x16x32_bf16 v[72:75], v[174:177], v[218:221], v[72:75]
	v_mfma_f32_16x16x32_bf16 v[64:67], v[182:185], v[218:221], v[64:67]
	s_setprio 0
	s_barrier
; #define PG8_STAGE(bufoff, gbase, voff) do { _Pragma("unroll") for (int _i = 0; _i < 2; ++_i) \
;         __builtin_amdgcn_global_load_lds((const unsigned*)((const char*)(gbase) + (voff)[_i]), (PG8_LAS unsigned*)(lds + (bufoff) + ldsw + _i * 8192), 16, 0, 0); } while (0)
; #define PG8_LDA(dst, b, h) do { _Pragma("unroll") for (int m = 0; m < 4; ++m) _Pragma("unroll") for (int k = 0; k < 2; ++k) dst[m][k] = *(const PG8_LAS bf16x8*)(lds + PG8_SA(b, h) + aoff + m * 2048 + k * 1024); } while (0)
; #define PG8_LDB(dst, b, h) do { _Pragma("unroll") for (int n = 0; n < 2; ++n) _Pragma("unroll") for (int k = 0; k < 2; ++k) dst[n][k] = *(const PG8_LAS bf16x8*)(lds + PG8_SB(b, h) + boff + n * 2048 + k * 1024); } while (0)
; #define PG8_MMA(ai, bj, At, Bt) do { __builtin_amdgcn_s_setprio(1); _Pragma("unroll") for (int m = 0; m < 4; ++m) _Pragma("unroll") for (int n = 0; n < 2; ++n) _Pragma("unroll") for (int k = 0; k < 2; ++k) \
;         acc[ai][bj][m][n] = __builtin_amdgcn_mfma_f32_16x16x32_bf16(Bt[n][k], At[m][k], acc[ai][bj][m][n], 0, 0, 0); __builtin_amdgcn_s_setprio(0); } while (0)
; #define PG8_WAIT_V(n) asm volatile("s_waitcnt vmcnt(" #n ")" ::: "memory")
; template <class Epi, class Sched, bool ALIGN_EPI = false, bool SP2 = false>
; __device__ __forceinline__ void gemm_phase(PG8_LAS unsigned char* lds, const Gemm g, const Sched& S, const Epi& E) {
;     ...
;             PG8_LDB(B0, 0, 0); PG8_LDB(B1, 0, 1); PG8_SCHED; PG8_LDA(At, 0, 0); PG8_STAGE(PG8_SA(1, 1), a1 + hstep, voffA);
;             PG8_WAIT_V(8); PG8_WAIT_L(0); PG8_BAR; PG8_MMA(0, 0, At, B0); PG8_MMA(0, 1, At, B1); PG8_BAR; PG8_SCHED;
;             PG8_LDA(At, 0, 1); PG8_STAGE(PG8_SB(0, 0), b2, voffB); PG8_STAGE(PG8_SB(0, 1), b2 + hstep, voffB); PG8_STAGE(PG8_SA(0, 0), a2, voffA);
;             PG8_WAIT_V(8); PG8_WAIT_L(0); PG8_BAR; PG8_MMA(1, 0, At, B0); PG8_MMA(1, 1, At, B1); PG8_BAR; PG8_SCHED;
;             PG8_LDB(B0, 1, 0); PG8_LDB(B1, 1, 1); PG8_SCHED; PG8_LDA(At, 1, 0); PG8_STAGE(PG8_SA(0, 1), a2 + hstep, voffA);
;             PG8_WAIT_V(8); PG8_WAIT_L(0); PG8_BAR; PG8_MMA(0, 0, At, B0); PG8_MMA(0, 1, At, B1); PG8_BAR; PG8_SCHED;
;             PG8_LDA(At, 1, 1); PG8_STAGE(PG8_SB(1, 0), b3, voffB); PG8_STAGE(PG8_SB(1, 1), b3 + hstep, voffB); PG8_STAGE(PG8_SA(1, 0), a3, voffA);
;             PG8_WAIT_V(8); PG8_WAIT_L(0); PG8_BAR; PG8_MMA(1, 0, At, B0); PG8_MMA(1, 1, At, B1); PG8_BAR; PG8_SCHED;
	s_add_i32 s44, s70, s52
	v_lshl_add_u64 v[144:145], v[144:145], 0, s[8:9]
	s_mov_b32 m0, s44
	ds_read_b128 v[186:189], v152 offset:49152
	ds_read_b128 v[190:193], v152 offset:50176
	ds_read_b128 v[198:201], v152 offset:51200
	ds_read_b128 v[202:205], v152 offset:52224
	ds_read_b128 v[206:209], v152 offset:53248
	ds_read_b128 v[210:213], v152 offset:54272
	ds_read_b128 v[214:217], v152 offset:55296
	ds_read_b128 v[218:221], v152 offset:56320
	global_load_lds_dwordx4 v[144:145], off
	s_add_i32 m0, s44, 0x2000
	s_add_u32 s38, s38, 0x40080
	v_lshl_add_u64 v[144:145], v[194:195], 0, s[8:9]
	s_addc_u32 s39, s39, 0
	s_add_i32 s44, s71, s52
	global_load_lds_dwordx4 v[144:145], off
	v_lshl_add_u64 v[144:145], s[38:39], 0, v[132:133]
	s_mov_b32 m0, s44
	s_nop 0
	global_load_lds_dwordx4 v[144:145], off
	v_lshl_add_u64 v[144:145], s[38:39], 0, v[128:129]
	s_add_i32 m0, s44, 0x2000
	s_nop 0
	global_load_lds_dwordx4 v[144:145], off
	v_lshl_add_u64 v[144:145], v[222:223], 0, s[8:9]
	s_mov_b32 m0, s58
	s_nop 0
	global_load_lds_dwordx4 v[144:145], off
	v_lshl_add_u64 v[144:145], v[224:225], 0, s[8:9]
	s_mov_b32 m0, s59
	s_nop 0
	global_load_lds_dwordx4 v[144:145], off
	s_waitcnt vmcnt(8)
	s_waitcnt lgkmcnt(0)
	s_barrier
	s_setprio 1
	s_waitcnt lgkmcnt(0)
	v_mfma_f32_16x16x32_bf16 v[60:63], v[154:157], v[186:189], v[60:63]
	v_mfma_f32_16x16x32_bf16 v[52:55], v[162:165], v[186:189], v[52:55]
	v_mfma_f32_16x16x32_bf16 v[44:47], v[154:157], v[198:201], v[44:47]
	v_mfma_f32_16x16x32_bf16 v[36:39], v[162:165], v[198:201], v[36:39]
	v_mfma_f32_16x16x32_bf16 v[28:31], v[154:157], v[206:209], v[28:31]
	v_mfma_f32_16x16x32_bf16 v[20:23], v[162:165], v[206:209], v[20:23]
	v_mfma_f32_16x16x32_bf16 v[12:15], v[154:157], v[214:217], v[12:15]
	v_mfma_f32_16x16x32_bf16 v[4:7], v[162:165], v[214:217], v[4:7]
	v_mfma_f32_16x16x32_bf16 v[60:63], v[158:161], v[190:193], v[60:63]
	v_mfma_f32_16x16x32_bf16 v[52:55], v[166:169], v[190:193], v[52:55]
	v_mfma_f32_16x16x32_bf16 v[44:47], v[158:161], v[202:205], v[44:47]
	v_mfma_f32_16x16x32_bf16 v[36:39], v[166:169], v[202:205], v[36:39]
	v_mfma_f32_16x16x32_bf16 v[28:31], v[158:161], v[210:213], v[28:31]
	v_mfma_f32_16x16x32_bf16 v[20:23], v[166:169], v[210:213], v[20:23]
	v_mfma_f32_16x16x32_bf16 v[12:15], v[158:161], v[218:221], v[12:15]
	v_mfma_f32_16x16x32_bf16 v[4:7], v[166:169], v[218:221], v[4:7]
	v_mfma_f32_16x16x32_bf16 v[56:59], v[170:173], v[186:189], v[56:59]
	v_mfma_f32_16x16x32_bf16 v[48:51], v[178:181], v[186:189], v[48:51]
	v_mfma_f32_16x16x32_bf16 v[40:43], v[170:173], v[198:201], v[40:43]
	v_mfma_f32_16x16x32_bf16 v[32:35], v[178:181], v[198:201], v[32:35]
	v_mfma_f32_16x16x32_bf16 v[24:27], v[170:173], v[206:209], v[24:27]
	v_mfma_f32_16x16x32_bf16 v[16:19], v[178:181], v[206:209], v[16:19]
	v_mfma_f32_16x16x32_bf16 v[8:11], v[170:173], v[214:217], v[8:11]
	v_mfma_f32_16x16x32_bf16 v[0:3], v[178:181], v[214:217], v[0:3]
	v_mfma_f32_16x16x32_bf16 v[56:59], v[174:177], v[190:193], v[56:59]
	v_mfma_f32_16x16x32_bf16 v[48:51], v[182:185], v[190:193], v[48:51]
	v_mfma_f32_16x16x32_bf16 v[40:43], v[174:177], v[202:205], v[40:43]
	v_mfma_f32_16x16x32_bf16 v[32:35], v[182:185], v[202:205], v[32:35]
	v_mfma_f32_16x16x32_bf16 v[24:27], v[174:177], v[210:213], v[24:27]
	v_mfma_f32_16x16x32_bf16 v[16:19], v[182:185], v[210:213], v[16:19]
	v_mfma_f32_16x16x32_bf16 v[8:11], v[174:177], v[218:221], v[8:11]
	v_mfma_f32_16x16x32_bf16 v[0:3], v[182:185], v[218:221], v[0:3]
	s_setprio 0
	s_barrier
	s_add_i32 s69, s69, 2
	s_add_u32 s20, s20, 0x100
	s_addc_u32 s21, s21, 0
	s_add_u32 s67, s67, 0x100
	s_addc_u32 s68, s68, 0
	s_cmp_gt_u32 s69, 13
.LBB0_810:
	ds_read_b128 v[154:157], v150
	ds_read_b128 v[158:161], v150 offset:1024
	ds_read_b128 v[162:165], v150 offset:2048
	ds_read_b128 v[166:169], v150 offset:3072
	ds_read_b128 v[170:173], v151
	ds_read_b128 v[174:177], v151 offset:1024
	ds_read_b128 v[178:181], v151 offset:2048
	ds_read_b128 v[182:185], v151 offset:3072
	s_add_u32 s38, s20, 0xfffc0080
	s_addc_u32 s39, s21, -1
	s_cmp_eq_u32 s69, 12
	s_cselect_b32 s45, s15, s39
	s_cselect_b32 s44, s65, s38
	s_cselect_b32 s39, s13, s68
	s_cselect_b32 s38, s66, s67
	v_lshl_add_u64 v[144:145], s[20:21], 0, v[136:137]
	s_add_i32 m0, s35, 0xc000
	ds_read_b128 v[186:189], v152
	ds_read_b128 v[190:193], v152 offset:1024
	ds_read_b128 v[198:201], v152 offset:2048
	ds_read_b128 v[202:205], v152 offset:3072
	ds_read_b128 v[206:209], v152 offset:4096
	ds_read_b128 v[210:213], v152 offset:5120
	ds_read_b128 v[214:217], v152 offset:6144
	ds_read_b128 v[218:221], v152 offset:7168
	global_load_lds_dwordx4 v[144:145], off
	v_lshl_add_u64 v[144:145], s[20:21], 0, v[138:139]
	s_add_i32 m0, s35, 0xe000
	s_nop 0
	global_load_lds_dwordx4 v[144:145], off
	s_waitcnt vmcnt(8)
	s_waitcnt lgkmcnt(0)
	s_barrier
; #define PG8_STAGE(bufoff, gbase, voff) do { _Pragma("unroll") for (int _i = 0; _i < 2; ++_i) \
;         __builtin_amdgcn_global_load_lds((const unsigned*)((const char*)(gbase) + (voff)[_i]), (PG8_LAS unsigned*)(lds + (bufoff) + ldsw + _i * 8192), 16, 0, 0); } while (0)
; #define PG8_LDA(dst, b, h) do { _Pragma("unroll") for (int m = 0; m < 4; ++m) _Pragma("unroll") for (int k = 0; k < 2; ++k) dst[m][k] = *(const PG8_LAS bf16x8*)(lds + PG8_SA(b, h) + aoff + m * 2048 + k * 1024); } while (0)
; #define PG8_MMA(ai, bj, At, Bt) do { __builtin_amdgcn_s_setprio(1); _Pragma("unroll") for (int m = 0; m < 4; ++m) _Pragma("unroll") for (int n = 0; n < 2; ++n) _Pragma("unroll") for (int k = 0; k < 2; ++k) \
;         acc[ai][bj][m][n] = __builtin_amdgcn_mfma_f32_16x16x32_bf16(Bt[n][k], At[m][k], acc[ai][bj][m][n], 0, 0, 0); __builtin_amdgcn_s_setprio(0); } while (0)
; #define PG8_WAIT_V(n) asm volatile("s_waitcnt vmcnt(" #n ")" ::: "memory")
; #define PG8_WAIT_L(n) asm volatile("s_waitcnt lgkmcnt(" #n ")" ::: "memory")
; #define PG8_BAR __builtin_amdgcn_s_barrier()
; #define PG8_SCHED __builtin_amdgcn_sched_barrier(0)
; template <class Epi, class Sched, bool ALIGN_EPI = false, bool SP2 = false>
; __device__ __forceinline__ void gemm_phase(PG8_LAS unsigned char* lds, const Gemm g, const Sched& S, const Epi& E) {
;     ...
;             PG8_WAIT_V(8); PG8_WAIT_L(0); PG8_BAR; PG8_MMA(0, 0, At, B0); PG8_MMA(0, 1, At, B1); PG8_BAR; PG8_SCHED;
;             PG8_LDA(At, 0, 1); PG8_STAGE(PG8_SB(0, 0), b2, voffB); PG8_STAGE(PG8_SB(0, 1), b2 + hstep, voffB); PG8_STAGE(PG8_SA(0, 0), a2, voffA);
;             PG8_WAIT_V(8); PG8_WAIT_L(0); PG8_BAR; PG8_MMA(1, 0, At, B0); PG8_MMA(1, 1, At, B1); PG8_BAR; PG8_SCHED;
	s_setprio 1
	s_waitcnt lgkmcnt(0)
	v_mfma_f32_16x16x32_bf16 v[124:127], v[154:157], v[186:189], v[124:127]
	v_mfma_f32_16x16x32_bf16 v[116:119], v[162:165], v[186:189], v[116:119]
	v_mfma_f32_16x16x32_bf16 v[108:111], v[154:157], v[198:201], v[108:111]
	v_mfma_f32_16x16x32_bf16 v[100:103], v[162:165], v[198:201], v[100:103]
	v_mfma_f32_16x16x32_bf16 v[92:95], v[154:157], v[206:209], v[92:95]
	v_mfma_f32_16x16x32_bf16 v[84:87], v[162:165], v[206:209], v[84:87]
	v_mfma_f32_16x16x32_bf16 v[76:79], v[154:157], v[214:217], v[76:79]
	v_mfma_f32_16x16x32_bf16 v[68:71], v[162:165], v[214:217], v[68:71]
	v_mfma_f32_16x16x32_bf16 v[124:127], v[158:161], v[190:193], v[124:127]
	v_mfma_f32_16x16x32_bf16 v[116:119], v[166:169], v[190:193], v[116:119]
	v_mfma_f32_16x16x32_bf16 v[108:111], v[158:161], v[202:205], v[108:111]
	v_mfma_f32_16x16x32_bf16 v[100:103], v[166:169], v[202:205], v[100:103]
	v_mfma_f32_16x16x32_bf16 v[92:95], v[158:161], v[210:213], v[92:95]
	v_mfma_f32_16x16x32_bf16 v[84:87], v[166:169], v[210:213], v[84:87]
	v_mfma_f32_16x16x32_bf16 v[76:79], v[158:161], v[218:221], v[76:79]
	v_mfma_f32_16x16x32_bf16 v[68:71], v[166:169], v[218:221], v[68:71]
	v_mfma_f32_16x16x32_bf16 v[120:123], v[170:173], v[186:189], v[120:123]
	v_mfma_f32_16x16x32_bf16 v[112:115], v[178:181], v[186:189], v[112:115]
	v_mfma_f32_16x16x32_bf16 v[104:107], v[170:173], v[198:201], v[104:107]
	v_mfma_f32_16x16x32_bf16 v[96:99], v[178:181], v[198:201], v[96:99]
	v_mfma_f32_16x16x32_bf16 v[88:91], v[170:173], v[206:209], v[88:91]
	v_mfma_f32_16x16x32_bf16 v[80:83], v[178:181], v[206:209], v[80:83]
	v_mfma_f32_16x16x32_bf16 v[72:75], v[170:173], v[214:217], v[72:75]
	v_mfma_f32_16x16x32_bf16 v[64:67], v[178:181], v[214:217], v[64:67]
	v_mfma_f32_16x16x32_bf16 v[120:123], v[174:177], v[190:193], v[120:123]
	v_mfma_f32_16x16x32_bf16 v[112:115], v[182:185], v[190:193], v[112:115]
	v_mfma_f32_16x16x32_bf16 v[104:107], v[174:177], v[202:205], v[104:107]
	v_mfma_f32_16x16x32_bf16 v[96:99], v[182:185], v[202:205], v[96:99]
	v_mfma_f32_16x16x32_bf16 v[88:91], v[174:177], v[210:213], v[88:91]
	v_mfma_f32_16x16x32_bf16 v[80:83], v[182:185], v[210:213], v[80:83]
	v_mfma_f32_16x16x32_bf16 v[72:75], v[174:177], v[218:221], v[72:75]
	v_mfma_f32_16x16x32_bf16 v[64:67], v[182:185], v[218:221], v[64:67]
	s_setprio 0
	s_barrier
	s_add_i32 s70, s60, s52
	v_lshl_add_u64 v[144:145], s[38:39], 0, v[132:133]
	s_mov_b32 m0, s70
	ds_read_b128 v[186:189], v152 offset:16384
	ds_read_b128 v[190:193], v152 offset:17408
	ds_read_b128 v[198:201], v152 offset:18432
	ds_read_b128 v[202:205], v152 offset:19456
	ds_read_b128 v[206:209], v152 offset:20480
	ds_read_b128 v[210:213], v152 offset:21504
	ds_read_b128 v[214:217], v152 offset:22528
	ds_read_b128 v[218:221], v152 offset:23552
	global_load_lds_dwordx4 v[144:145], off
	s_add_i32 m0, s70, 0x2000
	s_add_u32 s70, s38, 0x40000
	v_lshl_add_u64 v[194:195], s[38:39], 0, v[128:129]
	s_addc_u32 s71, s39, 0
	s_add_i32 s72, s61, s52
	global_load_lds_dwordx4 v[194:195], off
	v_lshl_add_u64 v[222:223], s[70:71], 0, v[132:133]
	s_mov_b32 m0, s72
	v_lshl_add_u64 v[224:225], s[44:45], 0, v[130:131]
	global_load_lds_dwordx4 v[222:223], off
	v_lshl_add_u64 v[222:223], s[70:71], 0, v[128:129]
	s_add_i32 m0, s72, 0x2000
	s_nop 0
	global_load_lds_dwordx4 v[222:223], off
	v_lshl_add_u64 v[222:223], s[44:45], 0, v[134:135]
	s_mov_b32 m0, s35
	s_nop 0
	global_load_lds_dwordx4 v[222:223], off
	s_mov_b32 m0, s54
	s_nop 0
	global_load_lds_dwordx4 v[224:225], off
	s_waitcnt vmcnt(8)
	s_waitcnt lgkmcnt(0)
	s_barrier
	s_setprio 1
	s_waitcnt lgkmcnt(0)
	v_mfma_f32_16x16x32_bf16 v[60:63], v[154:157], v[186:189], v[60:63]
	v_mfma_f32_16x16x32_bf16 v[52:55], v[162:165], v[186:189], v[52:55]
	v_mfma_f32_16x16x32_bf16 v[44:47], v[154:157], v[198:201], v[44:47]
	v_mfma_f32_16x16x32_bf16 v[36:39], v[162:165], v[198:201], v[36:39]
	v_mfma_f32_16x16x32_bf16 v[28:31], v[154:157], v[206:209], v[28:31]
	v_mfma_f32_16x16x32_bf16 v[20:23], v[162:165], v[206:209], v[20:23]
	v_mfma_f32_16x16x32_bf16 v[12:15], v[154:157], v[214:217], v[12:15]
	v_mfma_f32_16x16x32_bf16 v[4:7], v[162:165], v[214:217], v[4:7]
	v_mfma_f32_16x16x32_bf16 v[60:63], v[158:161], v[190:193], v[60:63]
	v_mfma_f32_16x16x32_bf16 v[52:55], v[166:169], v[190:193], v[52:55]
	v_mfma_f32_16x16x32_bf16 v[44:47], v[158:161], v[202:205], v[44:47]
	v_mfma_f32_16x16x32_bf16 v[36:39], v[166:169], v[202:205], v[36:39]
	v_mfma_f32_16x16x32_bf16 v[28:31], v[158:161], v[210:213], v[28:31]
	v_mfma_f32_16x16x32_bf16 v[20:23], v[166:169], v[210:213], v[20:23]
	v_mfma_f32_16x16x32_bf16 v[12:15], v[158:161], v[218:221], v[12:15]
	v_mfma_f32_16x16x32_bf16 v[4:7], v[166:169], v[218:221], v[4:7]
	v_mfma_f32_16x16x32_bf16 v[56:59], v[170:173], v[186:189], v[56:59]
	v_mfma_f32_16x16x32_bf16 v[48:51], v[178:181], v[186:189], v[48:51]
	v_mfma_f32_16x16x32_bf16 v[40:43], v[170:173], v[198:201], v[40:43]
	v_mfma_f32_16x16x32_bf16 v[32:35], v[178:181], v[198:201], v[32:35]
	v_mfma_f32_16x16x32_bf16 v[24:27], v[170:173], v[206:209], v[24:27]
	v_mfma_f32_16x16x32_bf16 v[16:19], v[178:181], v[206:209], v[16:19]
	v_mfma_f32_16x16x32_bf16 v[8:11], v[170:173], v[214:217], v[8:11]
	v_mfma_f32_16x16x32_bf16 v[0:3], v[178:181], v[214:217], v[0:3]
	v_mfma_f32_16x16x32_bf16 v[56:59], v[174:177], v[190:193], v[56:59]
	v_mfma_f32_16x16x32_bf16 v[48:51], v[182:185], v[190:193], v[48:51]
	v_mfma_f32_16x16x32_bf16 v[40:43], v[174:177], v[202:205], v[40:43]
	v_mfma_f32_16x16x32_bf16 v[32:35], v[182:185], v[202:205], v[32:35]
	v_mfma_f32_16x16x32_bf16 v[24:27], v[174:177], v[210:213], v[24:27]
	v_mfma_f32_16x16x32_bf16 v[16:19], v[182:185], v[210:213], v[16:19]
	v_mfma_f32_16x16x32_bf16 v[8:11], v[174:177], v[218:221], v[8:11]
	v_mfma_f32_16x16x32_bf16 v[0:3], v[182:185], v[218:221], v[0:3]
	s_setprio 0
	s_barrier
; #define PG8_STAGE(bufoff, gbase, voff) do { _Pragma("unroll") for (int _i = 0; _i < 2; ++_i) \
;         __builtin_amdgcn_global_load_lds((const unsigned*)((const char*)(gbase) + (voff)[_i]), (PG8_LAS unsigned*)(lds + (bufoff) + ldsw + _i * 8192), 16, 0, 0); } while (0)
; #define PG8_LDA(dst, b, h) do { _Pragma("unroll") for (int m = 0; m < 4; ++m) _Pragma("unroll") for (int k = 0; k < 2; ++k) dst[m][k] = *(const PG8_LAS bf16x8*)(lds + PG8_SA(b, h) + aoff + m * 2048 + k * 1024); } while (0)
; #define PG8_LDB(dst, b, h) do { _Pragma("unroll") for (int n = 0; n < 2; ++n) _Pragma("unroll") for (int k = 0; k < 2; ++k) dst[n][k] = *(const PG8_LAS bf16x8*)(lds + PG8_SB(b, h) + boff + n * 2048 + k * 1024); } while (0)
; #define PG8_MMA(ai, bj, At, Bt) do { __builtin_amdgcn_s_setprio(1); _Pragma("unroll") for (int m = 0; m < 4; ++m) _Pragma("unroll") for (int n = 0; n < 2; ++n) _Pragma("unroll") for (int k = 0; k < 2; ++k) \
;         acc[ai][bj][m][n] = __builtin_amdgcn_mfma_f32_16x16x32_bf16(Bt[n][k], At[m][k], acc[ai][bj][m][n], 0, 0, 0); __builtin_amdgcn_s_setprio(0); } while (0)
; #define PG8_WAIT_V(n) asm volatile("s_waitcnt vmcnt(" #n ")" ::: "memory")
; #define PG8_WAIT_L(n) asm volatile("s_waitcnt lgkmcnt(" #n ")" ::: "memory")
; #define PG8_BAR __builtin_amdgcn_s_barrier()
; #define PG8_SCHED __builtin_amdgcn_sched_barrier(0)
; template <class Epi, class Sched, bool ALIGN_EPI = false, bool SP2 = false>
; __device__ __forceinline__ void gemm_phase(PG8_LAS unsigned char* lds, const Gemm g, const Sched& S, const Epi& E) {
;     ...
;             PG8_LDB(B0, 1, 0); PG8_LDB(B1, 1, 1); PG8_SCHED; PG8_LDA(At, 1, 0); PG8_STAGE(PG8_SA(0, 1), a2 + hstep, voffA);
;             PG8_WAIT_V(8); PG8_WAIT_L(0); PG8_BAR; PG8_MMA(0, 0, At, B0); PG8_MMA(0, 1, At, B1); PG8_BAR; PG8_SCHED;
	s_add_i32 s70, 0, 0x18000
	v_add_u32_e32 v153, s70, v147
	s_add_i32 s71, 0, 0x1c000
	ds_read_b128 v[154:157], v153
	ds_read_b128 v[158:161], v153 offset:1024
	ds_read_b128 v[162:165], v153 offset:2048
	ds_read_b128 v[166:169], v153 offset:3072
	v_add_u32_e32 v153, s71, v147
	ds_read_b128 v[170:173], v153
	ds_read_b128 v[174:177], v153 offset:1024
	ds_read_b128 v[178:181], v153 offset:2048
	ds_read_b128 v[182:185], v153 offset:3072
	s_add_u32 s44, s44, 0x40000
	s_addc_u32 s45, s45, 0
	s_mov_b32 m0, s55
	v_lshl_add_u64 v[226:227], s[44:45], 0, v[134:135]
	ds_read_b128 v[186:189], v152 offset:32768
	ds_read_b128 v[190:193], v152 offset:33792
	ds_read_b128 v[198:201], v152 offset:34816
	ds_read_b128 v[202:205], v152 offset:35840
	ds_read_b128 v[206:209], v152 offset:36864
	ds_read_b128 v[210:213], v152 offset:37888
	ds_read_b128 v[214:217], v152 offset:38912
	ds_read_b128 v[218:221], v152 offset:39936
	global_load_lds_dwordx4 v[226:227], off
	v_lshl_add_u64 v[226:227], s[44:45], 0, v[130:131]
	s_mov_b32 m0, s56
	s_nop 0
	global_load_lds_dwordx4 v[226:227], off
	s_waitcnt vmcnt(8)
	s_waitcnt lgkmcnt(0)
	s_barrier
	s_setprio 1
	s_waitcnt lgkmcnt(0)
	v_mfma_f32_16x16x32_bf16 v[124:127], v[154:157], v[186:189], v[124:127]
	v_mfma_f32_16x16x32_bf16 v[116:119], v[162:165], v[186:189], v[116:119]
	v_mfma_f32_16x16x32_bf16 v[108:111], v[154:157], v[198:201], v[108:111]
	v_mfma_f32_16x16x32_bf16 v[100:103], v[162:165], v[198:201], v[100:103]
	v_mfma_f32_16x16x32_bf16 v[92:95], v[154:157], v[206:209], v[92:95]
	v_mfma_f32_16x16x32_bf16 v[84:87], v[162:165], v[206:209], v[84:87]
	v_mfma_f32_16x16x32_bf16 v[76:79], v[154:157], v[214:217], v[76:79]
	v_mfma_f32_16x16x32_bf16 v[68:71], v[162:165], v[214:217], v[68:71]
	v_mfma_f32_16x16x32_bf16 v[124:127], v[158:161], v[190:193], v[124:127]
	v_mfma_f32_16x16x32_bf16 v[116:119], v[166:169], v[190:193], v[116:119]
	v_mfma_f32_16x16x32_bf16 v[108:111], v[158:161], v[202:205], v[108:111]
	v_mfma_f32_16x16x32_bf16 v[100:103], v[166:169], v[202:205], v[100:103]
	v_mfma_f32_16x16x32_bf16 v[92:95], v[158:161], v[210:213], v[92:95]
	v_mfma_f32_16x16x32_bf16 v[84:87], v[166:169], v[210:213], v[84:87]
	v_mfma_f32_16x16x32_bf16 v[76:79], v[158:161], v[218:221], v[76:79]
	v_mfma_f32_16x16x32_bf16 v[68:71], v[166:169], v[218:221], v[68:71]
	v_mfma_f32_16x16x32_bf16 v[120:123], v[170:173], v[186:189], v[120:123]
	v_mfma_f32_16x16x32_bf16 v[112:115], v[178:181], v[186:189], v[112:115]
	v_mfma_f32_16x16x32_bf16 v[104:107], v[170:173], v[198:201], v[104:107]
	v_mfma_f32_16x16x32_bf16 v[96:99], v[178:181], v[198:201], v[96:99]
	v_mfma_f32_16x16x32_bf16 v[88:91], v[170:173], v[206:209], v[88:91]
	v_mfma_f32_16x16x32_bf16 v[80:83], v[178:181], v[206:209], v[80:83]
	v_mfma_f32_16x16x32_bf16 v[72:75], v[170:173], v[214:217], v[72:75]
	v_mfma_f32_16x16x32_bf16 v[64:67], v[178:181], v[214:217], v[64:67]
	v_mfma_f32_16x16x32_bf16 v[120:123], v[174:177], v[190:193], v[120:123]
	v_mfma_f32_16x16x32_bf16 v[112:115], v[182:185], v[190:193], v[112:115]
	v_mfma_f32_16x16x32_bf16 v[104:107], v[174:177], v[202:205], v[104:107]
	v_mfma_f32_16x16x32_bf16 v[96:99], v[182:185], v[202:205], v[96:99]
	v_mfma_f32_16x16x32_bf16 v[88:91], v[174:177], v[210:213], v[88:91]
	v_mfma_f32_16x16x32_bf16 v[80:83], v[182:185], v[210:213], v[80:83]
	v_mfma_f32_16x16x32_bf16 v[72:75], v[174:177], v[218:221], v[72:75]
	v_mfma_f32_16x16x32_bf16 v[64:67], v[182:185], v[218:221], v[64:67]
	s_setprio 0
	s_barrier
; #define PG8_STAGE(bufoff, gbase, voff) do { _Pragma("unroll") for (int _i = 0; _i < 2; ++_i) \
;         __builtin_amdgcn_global_load_lds((const unsigned*)((const char*)(gbase) + (voff)[_i]), (PG8_LAS unsigned*)(lds + (bufoff) + ldsw + _i * 8192), 16, 0, 0); } while (0)
; #define PG8_LDA(dst, b, h) do { _Pragma("unroll") for (int m = 0; m < 4; ++m) _Pragma("unroll") for (int k = 0; k < 2; ++k) dst[m][k] = *(const PG8_LAS bf16x8*)(lds + PG8_SA(b, h) + aoff + m * 2048 + k * 1024); } while (0)
; #define PG8_MMA(ai, bj, At, Bt) do { __builtin_amdgcn_s_setprio(1); _Pragma("unroll") for (int m = 0; m < 4; ++m) _Pragma("unroll") for (int n = 0; n < 2; ++n) _Pragma("unroll") for (int k = 0; k < 2; ++k) \
;         acc[ai][bj][m][n] = __builtin_amdgcn_mfma_f32_16x16x32_bf16(Bt[n][k], At[m][k], acc[ai][bj][m][n], 0, 0, 0); __builtin_amdgcn_s_setprio(0); } while (0)
; #define PG8_WAIT_V(n) asm volatile("s_waitcnt vmcnt(" #n ")" ::: "memory")
; #define PG8_WAIT_L(n) asm volatile("s_waitcnt lgkmcnt(" #n ")" ::: "memory")
; #define PG8_BAR __builtin_amdgcn_s_barrier()
; #define PG8_SCHED __builtin_amdgcn_sched_barrier(0)
; template <class Epi, class Sched, bool ALIGN_EPI = false, bool SP2 = false>
; __device__ __forceinline__ void gemm_phase(PG8_LAS unsigned char* lds, const Gemm g, const Sched& S, const Epi& E) {
;     ...
;             PG8_LDA(At, 1, 1); PG8_STAGE(PG8_SB(1, 0), b3, voffB); PG8_STAGE(PG8_SB(1, 1), b3 + hstep, voffB); PG8_STAGE(PG8_SA(1, 0), a3, voffA);
;             PG8_WAIT_V(8); PG8_WAIT_L(0); PG8_BAR; PG8_MMA(1, 0, At, B0); PG8_MMA(1, 1, At, B1); PG8_BAR; PG8_SCHED;
;     ...
;         if constexpr (ALIGN_EPI) { if (wr == 0) PG8_BAR; }
	s_add_i32 s44, s70, s52
	v_lshl_add_u64 v[144:145], v[144:145], 0, s[8:9]
	s_mov_b32 m0, s44
	ds_read_b128 v[186:189], v152 offset:49152
	ds_read_b128 v[190:193], v152 offset:50176
	ds_read_b128 v[198:201], v152 offset:51200
	ds_read_b128 v[202:205], v152 offset:52224
	ds_read_b128 v[206:209], v152 offset:53248
	ds_read_b128 v[210:213], v152 offset:54272
	ds_read_b128 v[214:217], v152 offset:55296
	ds_read_b128 v[218:221], v152 offset:56320
	global_load_lds_dwordx4 v[144:145], off
	s_add_i32 m0, s44, 0x2000
	s_add_u32 s38, s38, 0x40080
	v_lshl_add_u64 v[144:145], v[194:195], 0, s[8:9]
	s_addc_u32 s39, s39, 0
	s_add_i32 s44, s71, s52
	global_load_lds_dwordx4 v[144:145], off
	v_lshl_add_u64 v[144:145], s[38:39], 0, v[132:133]
	s_mov_b32 m0, s44
	s_nop 0
	global_load_lds_dwordx4 v[144:145], off
	v_lshl_add_u64 v[144:145], s[38:39], 0, v[128:129]
	s_add_i32 m0, s44, 0x2000
	s_nop 0
	global_load_lds_dwordx4 v[144:145], off
	v_lshl_add_u64 v[144:145], v[222:223], 0, s[8:9]
	s_mov_b32 m0, s58
	s_nop 0
	global_load_lds_dwordx4 v[144:145], off
	v_lshl_add_u64 v[144:145], v[224:225], 0, s[8:9]
	s_mov_b32 m0, s59
	s_nop 0
	global_load_lds_dwordx4 v[144:145], off
	s_waitcnt vmcnt(8)
	s_waitcnt lgkmcnt(0)
	s_barrier
	s_setprio 1
	s_waitcnt lgkmcnt(0)
	v_mfma_f32_16x16x32_bf16 v[60:63], v[154:157], v[186:189], v[60:63]
	v_mfma_f32_16x16x32_bf16 v[52:55], v[162:165], v[186:189], v[52:55]
	v_mfma_f32_16x16x32_bf16 v[44:47], v[154:157], v[198:201], v[44:47]
	v_mfma_f32_16x16x32_bf16 v[36:39], v[162:165], v[198:201], v[36:39]
	v_mfma_f32_16x16x32_bf16 v[28:31], v[154:157], v[206:209], v[28:31]
	v_mfma_f32_16x16x32_bf16 v[20:23], v[162:165], v[206:209], v[20:23]
	v_mfma_f32_16x16x32_bf16 v[12:15], v[154:157], v[214:217], v[12:15]
	v_mfma_f32_16x16x32_bf16 v[4:7], v[162:165], v[214:217], v[4:7]
	v_mfma_f32_16x16x32_bf16 v[60:63], v[158:161], v[190:193], v[60:63]
	v_mfma_f32_16x16x32_bf16 v[52:55], v[166:169], v[190:193], v[52:55]
	v_mfma_f32_16x16x32_bf16 v[44:47], v[158:161], v[202:205], v[44:47]
	v_mfma_f32_16x16x32_bf16 v[36:39], v[166:169], v[202:205], v[36:39]
	v_mfma_f32_16x16x32_bf16 v[28:31], v[158:161], v[210:213], v[28:31]
	v_mfma_f32_16x16x32_bf16 v[20:23], v[166:169], v[210:213], v[20:23]
	v_mfma_f32_16x16x32_bf16 v[12:15], v[158:161], v[218:221], v[12:15]
	v_mfma_f32_16x16x32_bf16 v[4:7], v[166:169], v[218:221], v[4:7]
	v_mfma_f32_16x16x32_bf16 v[56:59], v[170:173], v[186:189], v[56:59]
	v_mfma_f32_16x16x32_bf16 v[48:51], v[178:181], v[186:189], v[48:51]
	v_mfma_f32_16x16x32_bf16 v[40:43], v[170:173], v[198:201], v[40:43]
	v_mfma_f32_16x16x32_bf16 v[32:35], v[178:181], v[198:201], v[32:35]
	v_mfma_f32_16x16x32_bf16 v[24:27], v[170:173], v[206:209], v[24:27]
	v_mfma_f32_16x16x32_bf16 v[16:19], v[178:181], v[206:209], v[16:19]
	v_mfma_f32_16x16x32_bf16 v[8:11], v[170:173], v[214:217], v[8:11]
	v_mfma_f32_16x16x32_bf16 v[0:3], v[178:181], v[214:217], v[0:3]
	v_mfma_f32_16x16x32_bf16 v[56:59], v[174:177], v[190:193], v[56:59]
	v_mfma_f32_16x16x32_bf16 v[48:51], v[182:185], v[190:193], v[48:51]
	v_mfma_f32_16x16x32_bf16 v[40:43], v[174:177], v[202:205], v[40:43]
	v_mfma_f32_16x16x32_bf16 v[32:35], v[182:185], v[202:205], v[32:35]
	v_mfma_f32_16x16x32_bf16 v[24:27], v[174:177], v[210:213], v[24:27]
	v_mfma_f32_16x16x32_bf16 v[16:19], v[182:185], v[210:213], v[16:19]
	v_mfma_f32_16x16x32_bf16 v[8:11], v[174:177], v[218:221], v[8:11]
	v_mfma_f32_16x16x32_bf16 v[0:3], v[182:185], v[218:221], v[0:3]
	s_setprio 0
	s_barrier
	s_add_i32 s69, s69, 2
	s_add_u32 s20, s20, 0x100
	s_addc_u32 s21, s21, 0
	s_add_u32 s67, s67, 0x100
	s_addc_u32 s68, s68, 0
	s_cmp_gt_u32 s69, 13
	s_cbranch_scc0 .LBB0_810
	s_and_b64 vcc, exec, s[10:11]
	s_cbranch_vccz .LBB0_813
	s_barrier

; #define PG8_STAGE(bufoff, gbase, voff) do { _Pragma("unroll") for (int _i = 0; _i < 2; ++_i) \
;         __builtin_amdgcn_global_load_lds((const unsigned*)((const char*)(gbase) + (voff)[_i]), (PG8_LAS unsigned*)(lds + (bufoff) + ldsw + _i * 8192), 16, 0, 0); } while (0)
; #define PG8_LDA(dst, b, h) do { _Pragma("unroll") for (int m = 0; m < 4; ++m) _Pragma("unroll") for (int k = 0; k < 2; ++k) dst[m][k] = *(const PG8_LAS bf16x8*)(lds + PG8_SA(b, h) + aoff + m * 2048 + k * 1024); } while (0)
; #define PG8_LDB(dst, b, h) do { _Pragma("unroll") for (int n = 0; n < 2; ++n) _Pragma("unroll") for (int k = 0; k < 2; ++k) dst[n][k] = *(const PG8_LAS bf16x8*)(lds + PG8_SB(b, h) + boff + n * 2048 + k * 1024); } while (0)
; #define PG8_MMA(ai, bj, At, Bt) do { __builtin_amdgcn_s_setprio(1); _Pragma("unroll") for (int m = 0; m < 4; ++m) _Pragma("unroll") for (int n = 0; n < 2; ++n) _Pragma("unroll") for (int k = 0; k < 2; ++k) \
;         acc[ai][bj][m][n] = __builtin_amdgcn_mfma_f32_16x16x32_bf16(Bt[n][k], At[m][k], acc[ai][bj][m][n], 0, 0, 0); __builtin_amdgcn_s_setprio(0); } while (0)
; #define PG8_WAIT_V(n) asm volatile("s_waitcnt vmcnt(" #n ")" ::: "memory")
; #define PG8_WAIT_L(n) asm volatile("s_waitcnt lgkmcnt(" #n ")" ::: "memory")
; #define PG8_BAR __builtin_amdgcn_s_barrier()
; #define PG8_SCHED __builtin_amdgcn_sched_barrier(0)
; template <class Epi, class Sched, bool ALIGN_EPI = false, bool SP2 = false>
; __device__ __forceinline__ void gemm_phase(PG8_LAS unsigned char* lds, const Gemm g, const Sched& S, const Epi& E) {
;     ...
;             const char* a1 = cA + (size_t)(t + 1) * kstep;
;             const char* a2 = last ? nA : cA + (size_t)(t + 2) * kstep; const char* b2 = last ? nB : cB + (size_t)(t + 2) * kstep;
;             const char* a3 = a2 + kstep; const char* b3 = b2 + kstep;
;             if (last && has_next) S.a_ready(nxt);
;             if constexpr (SP2) {
;             PG8_LDB(B0, 0, 0); PG8_LDB(B1, 0, 1); PG8_SCHED; PG8_LDA(At, 0, 0); PG8_STAGE(PG8_SA(1, 1), a1 + hstep, voffA);
;             PG8_WAIT_V(8); PG8_WAIT_L(0); PG8_BAR; PG8_MMA(0, 0, At, B0); PG8_MMA(0, 1, At, B1); PG8_BAR; PG8_SCHED;
;             PG8_LDA(At, 0, 1); PG8_STAGE(PG8_SB(0, 0), b2, voffB); PG8_STAGE(PG8_SB(0, 1), b2 + hstep, voffB); PG8_STAGE(PG8_SA(0, 0), a2, voffA);
.LBB0_894:
	s_add_u32 s20, s20, 0xb0080
	s_addc_u32 s21, s21, 0
	s_add_u32 s70, s34, 0x100
	s_addc_u32 s71, s35, 0
	s_mov_b32 s72, -2
	s_waitcnt lgkmcnt(0)
	ds_read_b128 v[96:99], v223
	ds_read_b128 v[108:111], v223 offset:1024
	ds_read_b128 v[120:123], v223 offset:2048
	ds_read_b128 v[128:131], v223 offset:3072
	ds_read_b128 v[144:147], v224
	ds_read_b128 v[148:151], v224 offset:1024
	ds_read_b128 v[152:155], v224 offset:2048
	ds_read_b128 v[156:159], v224 offset:3072
	s_add_u32 s34, s20, 0xfff50080
	s_addc_u32 s35, s21, -1
	s_cmp_eq_u32 s72, 40
	s_cselect_b32 s49, s1, s35
	s_cselect_b32 s48, s0, s34
	s_cselect_b32 s35, s47, s71
	s_cselect_b32 s34, s46, s70
	v_lshl_add_u64 v[210:211], s[20:21], 0, v[192:193]
	s_add_i32 m0, s51, 0xc000
	ds_read_b128 v[160:163], v225
	ds_read_b128 v[164:167], v225 offset:1024
	ds_read_b128 v[168:171], v225 offset:2048
	ds_read_b128 v[172:175], v225 offset:3072
	ds_read_b128 v[176:179], v225 offset:4096
	ds_read_b128 v[180:183], v225 offset:5120
	ds_read_b128 v[202:205], v225 offset:6144
	ds_read_b128 v[206:209], v225 offset:7168
	global_load_lds_dwordx4 v[210:211], off
	v_lshl_add_u64 v[210:211], s[20:21], 0, v[194:195]
	s_add_i32 m0, s51, 0xe000
	s_nop 0
	global_load_lds_dwordx4 v[210:211], off
	s_waitcnt vmcnt(8)
	s_waitcnt lgkmcnt(0)
	s_barrier
	s_setprio 1
	s_waitcnt lgkmcnt(0)
	v_mfma_f32_16x16x32_bf16 v[140:143], v[96:99], v[160:163], 0
	v_mfma_f32_16x16x32_bf16 v[136:139], v[120:123], v[160:163], 0
	v_mfma_f32_16x16x32_bf16 v[116:119], v[96:99], v[168:171], 0
	v_mfma_f32_16x16x32_bf16 v[112:115], v[120:123], v[168:171], 0
	v_mfma_f32_16x16x32_bf16 v[92:95], v[96:99], v[176:179], 0
	v_mfma_f32_16x16x32_bf16 v[88:91], v[120:123], v[176:179], 0
	v_mfma_f32_16x16x32_bf16 v[76:79], v[96:99], v[202:205], 0
	v_mfma_f32_16x16x32_bf16 v[72:75], v[120:123], v[202:205], 0
	v_mfma_f32_16x16x32_bf16 v[140:143], v[108:111], v[164:167], v[140:143]
	v_mfma_f32_16x16x32_bf16 v[136:139], v[128:131], v[164:167], v[136:139]
	v_mfma_f32_16x16x32_bf16 v[116:119], v[108:111], v[172:175], v[116:119]
	v_mfma_f32_16x16x32_bf16 v[112:115], v[128:131], v[172:175], v[112:115]
	v_mfma_f32_16x16x32_bf16 v[92:95], v[108:111], v[180:183], v[92:95]
	v_mfma_f32_16x16x32_bf16 v[88:91], v[128:131], v[180:183], v[88:91]
	v_mfma_f32_16x16x32_bf16 v[76:79], v[108:111], v[206:209], v[76:79]
	v_mfma_f32_16x16x32_bf16 v[72:75], v[128:131], v[206:209], v[72:75]
	v_mfma_f32_16x16x32_bf16 v[132:135], v[144:147], v[160:163], 0
	v_mfma_f32_16x16x32_bf16 v[124:127], v[152:155], v[160:163], 0
	v_mfma_f32_16x16x32_bf16 v[104:107], v[144:147], v[168:171], 0
	v_mfma_f32_16x16x32_bf16 v[100:103], v[152:155], v[168:171], 0
	v_mfma_f32_16x16x32_bf16 v[84:87], v[144:147], v[176:179], 0
	v_mfma_f32_16x16x32_bf16 v[80:83], v[152:155], v[176:179], 0
	v_mfma_f32_16x16x32_bf16 v[68:71], v[144:147], v[202:205], 0
	v_mfma_f32_16x16x32_bf16 v[64:67], v[152:155], v[202:205], 0
	v_mfma_f32_16x16x32_bf16 v[132:135], v[148:151], v[164:167], v[132:135]
	v_mfma_f32_16x16x32_bf16 v[124:127], v[156:159], v[164:167], v[124:127]
	v_mfma_f32_16x16x32_bf16 v[104:107], v[148:151], v[172:175], v[104:107]
	v_mfma_f32_16x16x32_bf16 v[100:103], v[156:159], v[172:175], v[100:103]
	v_mfma_f32_16x16x32_bf16 v[84:87], v[148:151], v[180:183], v[84:87]
	v_mfma_f32_16x16x32_bf16 v[80:83], v[156:159], v[180:183], v[80:83]
	v_mfma_f32_16x16x32_bf16 v[68:71], v[148:151], v[206:209], v[68:71]
	v_mfma_f32_16x16x32_bf16 v[64:67], v[156:159], v[206:209], v[64:67]
	s_setprio 0
	s_barrier
	s_add_i32 s73, s64, s50
	v_lshl_add_u64 v[210:211], s[34:35], 0, v[186:187]
	s_mov_b32 m0, s73
	ds_read_b128 v[160:163], v225 offset:16384
	ds_read_b128 v[164:167], v225 offset:17408
	ds_read_b128 v[168:171], v225 offset:18432
	ds_read_b128 v[172:175], v225 offset:19456
	ds_read_b128 v[176:179], v225 offset:20480
	ds_read_b128 v[180:183], v225 offset:21504
	ds_read_b128 v[202:205], v225 offset:22528
	ds_read_b128 v[206:209], v225 offset:23552
	global_load_lds_dwordx4 v[210:211], off
	s_add_i32 m0, s73, 0x2000
	s_add_u32 s74, s34, 0xb0000
	v_lshl_add_u64 v[212:213], s[34:35], 0, v[190:191]
	s_addc_u32 s75, s35, 0
	s_add_i32 s73, s65, s50
	global_load_lds_dwordx4 v[212:213], off
	v_lshl_add_u64 v[214:215], s[74:75], 0, v[186:187]
	s_mov_b32 m0, s73
	v_lshl_add_u64 v[216:217], s[48:49], 0, v[188:189]
	global_load_lds_dwordx4 v[214:215], off
	v_lshl_add_u64 v[214:215], s[74:75], 0, v[190:191]
	s_add_i32 m0, s73, 0x2000
	s_nop 0
	global_load_lds_dwordx4 v[214:215], off
	v_lshl_add_u64 v[214:215], s[48:49], 0, v[184:185]
	s_mov_b32 m0, s51
	s_nop 0
	global_load_lds_dwordx4 v[214:215], off
	s_mov_b32 m0, s52
	s_nop 0
	global_load_lds_dwordx4 v[216:217], off
	s_waitcnt vmcnt(8)
	s_waitcnt lgkmcnt(0)
	s_barrier
; #define PG8_STAGE(bufoff, gbase, voff) do { _Pragma("unroll") for (int _i = 0; _i < 2; ++_i) \
;         __builtin_amdgcn_global_load_lds((const unsigned*)((const char*)(gbase) + (voff)[_i]), (PG8_LAS unsigned*)(lds + (bufoff) + ldsw + _i * 8192), 16, 0, 0); } while (0)
; #define PG8_LDA(dst, b, h) do { _Pragma("unroll") for (int m = 0; m < 4; ++m) _Pragma("unroll") for (int k = 0; k < 2; ++k) dst[m][k] = *(const PG8_LAS bf16x8*)(lds + PG8_SA(b, h) + aoff + m * 2048 + k * 1024); } while (0)
; #define PG8_LDB(dst, b, h) do { _Pragma("unroll") for (int n = 0; n < 2; ++n) _Pragma("unroll") for (int k = 0; k < 2; ++k) dst[n][k] = *(const PG8_LAS bf16x8*)(lds + PG8_SB(b, h) + boff + n * 2048 + k * 1024); } while (0)
; #define PG8_MMA(ai, bj, At, Bt) do { __builtin_amdgcn_s_setprio(1); _Pragma("unroll") for (int m = 0; m < 4; ++m) _Pragma("unroll") for (int n = 0; n < 2; ++n) _Pragma("unroll") for (int k = 0; k < 2; ++k) \
;         acc[ai][bj][m][n] = __builtin_amdgcn_mfma_f32_16x16x32_bf16(Bt[n][k], At[m][k], acc[ai][bj][m][n], 0, 0, 0); __builtin_amdgcn_s_setprio(0); } while (0)
; #define PG8_WAIT_V(n) asm volatile("s_waitcnt vmcnt(" #n ")" ::: "memory")
; #define PG8_WAIT_L(n) asm volatile("s_waitcnt lgkmcnt(" #n ")" ::: "memory")
; #define PG8_BAR __builtin_amdgcn_s_barrier()
; #define PG8_SCHED __builtin_amdgcn_sched_barrier(0)
; template <class Epi, class Sched, bool ALIGN_EPI = false, bool SP2 = false>
; __device__ __forceinline__ void gemm_phase(PG8_LAS unsigned char* lds, const Gemm g, const Sched& S, const Epi& E) {
;     ...
;             PG8_WAIT_V(8); PG8_WAIT_L(0); PG8_BAR; PG8_MMA(1, 0, At, B0); PG8_MMA(1, 1, At, B1); PG8_BAR; PG8_SCHED;
;             PG8_LDB(B0, 1, 0); PG8_LDB(B1, 1, 1); PG8_SCHED; PG8_LDA(At, 1, 0); PG8_STAGE(PG8_SA(0, 1), a2 + hstep, voffA);
;             PG8_WAIT_V(8); PG8_WAIT_L(0); PG8_BAR; PG8_MMA(0, 0, At, B0); PG8_MMA(0, 1, At, B1); PG8_BAR; PG8_SCHED;
	s_setprio 1
	s_waitcnt lgkmcnt(0)
	v_mfma_f32_16x16x32_bf16 v[60:63], v[96:99], v[160:163], 0
	v_mfma_f32_16x16x32_bf16 v[56:59], v[120:123], v[160:163], 0
	v_mfma_f32_16x16x32_bf16 v[44:47], v[96:99], v[168:171], 0
	v_mfma_f32_16x16x32_bf16 v[40:43], v[120:123], v[168:171], 0
	v_mfma_f32_16x16x32_bf16 v[28:31], v[96:99], v[176:179], 0
	v_mfma_f32_16x16x32_bf16 v[24:27], v[120:123], v[176:179], 0
	v_mfma_f32_16x16x32_bf16 v[12:15], v[96:99], v[202:205], 0
	v_mfma_f32_16x16x32_bf16 v[8:11], v[120:123], v[202:205], 0
	v_mfma_f32_16x16x32_bf16 v[60:63], v[108:111], v[164:167], v[60:63]
	v_mfma_f32_16x16x32_bf16 v[56:59], v[128:131], v[164:167], v[56:59]
	v_mfma_f32_16x16x32_bf16 v[44:47], v[108:111], v[172:175], v[44:47]
	v_mfma_f32_16x16x32_bf16 v[40:43], v[128:131], v[172:175], v[40:43]
	v_mfma_f32_16x16x32_bf16 v[28:31], v[108:111], v[180:183], v[28:31]
	v_mfma_f32_16x16x32_bf16 v[24:27], v[128:131], v[180:183], v[24:27]
	v_mfma_f32_16x16x32_bf16 v[12:15], v[108:111], v[206:209], v[12:15]
	v_mfma_f32_16x16x32_bf16 v[8:11], v[128:131], v[206:209], v[8:11]
	v_mfma_f32_16x16x32_bf16 v[52:55], v[144:147], v[160:163], 0
	v_mfma_f32_16x16x32_bf16 v[48:51], v[152:155], v[160:163], 0
	v_mfma_f32_16x16x32_bf16 v[36:39], v[144:147], v[168:171], 0
	v_mfma_f32_16x16x32_bf16 v[32:35], v[152:155], v[168:171], 0
	v_mfma_f32_16x16x32_bf16 v[20:23], v[144:147], v[176:179], 0
	v_mfma_f32_16x16x32_bf16 v[16:19], v[152:155], v[176:179], 0
	v_mfma_f32_16x16x32_bf16 v[4:7], v[144:147], v[202:205], 0
	v_mfma_f32_16x16x32_bf16 v[0:3], v[152:155], v[202:205], 0
	v_mfma_f32_16x16x32_bf16 v[52:55], v[148:151], v[164:167], v[52:55]
	v_mfma_f32_16x16x32_bf16 v[48:51], v[156:159], v[164:167], v[48:51]
	v_mfma_f32_16x16x32_bf16 v[36:39], v[148:151], v[172:175], v[36:39]
	v_mfma_f32_16x16x32_bf16 v[32:35], v[156:159], v[172:175], v[32:35]
	v_mfma_f32_16x16x32_bf16 v[20:23], v[148:151], v[180:183], v[20:23]
	v_mfma_f32_16x16x32_bf16 v[16:19], v[156:159], v[180:183], v[16:19]
	v_mfma_f32_16x16x32_bf16 v[4:7], v[148:151], v[206:209], v[4:7]
	v_mfma_f32_16x16x32_bf16 v[0:3], v[156:159], v[206:209], v[0:3]
	s_setprio 0
	s_barrier
	s_add_i32 s73, 0, 0x18000
	s_add_i32 s74, 0, 0x1c000
	v_add_u32_e32 v128, s73, v221
	v_add_u32_e32 v156, s74, v221
	ds_read_b128 v[96:99], v128
	ds_read_b128 v[108:111], v128 offset:1024
	ds_read_b128 v[120:123], v128 offset:2048
	ds_read_b128 v[128:131], v128 offset:3072
	ds_read_b128 v[144:147], v156
	ds_read_b128 v[148:151], v156 offset:1024
	ds_read_b128 v[152:155], v156 offset:2048
	ds_read_b128 v[156:159], v156 offset:3072
	s_add_u32 s48, s48, 0xb0000
	s_addc_u32 s49, s49, 0
	s_mov_b32 m0, s53
	v_lshl_add_u64 v[218:219], s[48:49], 0, v[184:185]
	ds_read_b128 v[160:163], v225 offset:32768
	ds_read_b128 v[164:167], v225 offset:33792
	ds_read_b128 v[168:171], v225 offset:34816
	ds_read_b128 v[172:175], v225 offset:35840
	ds_read_b128 v[176:179], v225 offset:36864
	ds_read_b128 v[180:183], v225 offset:37888
	ds_read_b128 v[202:205], v225 offset:38912
	ds_read_b128 v[206:209], v225 offset:39936
	global_load_lds_dwordx4 v[218:219], off
	v_lshl_add_u64 v[218:219], s[48:49], 0, v[188:189]
	s_mov_b32 m0, s54
	s_nop 0
	global_load_lds_dwordx4 v[218:219], off
	s_waitcnt vmcnt(8)
	s_waitcnt lgkmcnt(0)
	s_barrier
	s_setprio 1
	s_waitcnt lgkmcnt(0)
	v_mfma_f32_16x16x32_bf16 v[140:143], v[96:99], v[160:163], v[140:143]
	v_mfma_f32_16x16x32_bf16 v[136:139], v[120:123], v[160:163], v[136:139]
	v_mfma_f32_16x16x32_bf16 v[116:119], v[96:99], v[168:171], v[116:119]
	v_mfma_f32_16x16x32_bf16 v[112:115], v[120:123], v[168:171], v[112:115]
	v_mfma_f32_16x16x32_bf16 v[92:95], v[96:99], v[176:179], v[92:95]
	v_mfma_f32_16x16x32_bf16 v[88:91], v[120:123], v[176:179], v[88:91]
	v_mfma_f32_16x16x32_bf16 v[76:79], v[96:99], v[202:205], v[76:79]
	v_mfma_f32_16x16x32_bf16 v[72:75], v[120:123], v[202:205], v[72:75]
	v_mfma_f32_16x16x32_bf16 v[140:143], v[108:111], v[164:167], v[140:143]
	v_mfma_f32_16x16x32_bf16 v[136:139], v[128:131], v[164:167], v[136:139]
	v_mfma_f32_16x16x32_bf16 v[116:119], v[108:111], v[172:175], v[116:119]
	v_mfma_f32_16x16x32_bf16 v[112:115], v[128:131], v[172:175], v[112:115]
	v_mfma_f32_16x16x32_bf16 v[92:95], v[108:111], v[180:183], v[92:95]
	v_mfma_f32_16x16x32_bf16 v[88:91], v[128:131], v[180:183], v[88:91]
	v_mfma_f32_16x16x32_bf16 v[76:79], v[108:111], v[206:209], v[76:79]
	v_mfma_f32_16x16x32_bf16 v[72:75], v[128:131], v[206:209], v[72:75]
	v_mfma_f32_16x16x32_bf16 v[132:135], v[144:147], v[160:163], v[132:135]
	v_mfma_f32_16x16x32_bf16 v[124:127], v[152:155], v[160:163], v[124:127]
	v_mfma_f32_16x16x32_bf16 v[104:107], v[144:147], v[168:171], v[104:107]
	v_mfma_f32_16x16x32_bf16 v[100:103], v[152:155], v[168:171], v[100:103]
	v_mfma_f32_16x16x32_bf16 v[84:87], v[144:147], v[176:179], v[84:87]
	v_mfma_f32_16x16x32_bf16 v[80:83], v[152:155], v[176:179], v[80:83]
	v_mfma_f32_16x16x32_bf16 v[68:71], v[144:147], v[202:205], v[68:71]
	v_mfma_f32_16x16x32_bf16 v[64:67], v[152:155], v[202:205], v[64:67]
	v_mfma_f32_16x16x32_bf16 v[132:135], v[148:151], v[164:167], v[132:135]
	v_mfma_f32_16x16x32_bf16 v[124:127], v[156:159], v[164:167], v[124:127]
	v_mfma_f32_16x16x32_bf16 v[104:107], v[148:151], v[172:175], v[104:107]
	v_mfma_f32_16x16x32_bf16 v[100:103], v[156:159], v[172:175], v[100:103]
	v_mfma_f32_16x16x32_bf16 v[84:87], v[148:151], v[180:183], v[84:87]
	v_mfma_f32_16x16x32_bf16 v[80:83], v[156:159], v[180:183], v[80:83]
	v_mfma_f32_16x16x32_bf16 v[68:71], v[148:151], v[206:209], v[68:71]
	v_mfma_f32_16x16x32_bf16 v[64:67], v[156:159], v[206:209], v[64:67]
	s_setprio 0
	s_barrier
; #define PG8_STAGE(bufoff, gbase, voff) do { _Pragma("unroll") for (int _i = 0; _i < 2; ++_i) \
;         __builtin_amdgcn_global_load_lds((const unsigned*)((const char*)(gbase) + (voff)[_i]), (PG8_LAS unsigned*)(lds + (bufoff) + ldsw + _i * 8192), 16, 0, 0); } while (0)
; #define PG8_LDA(dst, b, h) do { _Pragma("unroll") for (int m = 0; m < 4; ++m) _Pragma("unroll") for (int k = 0; k < 2; ++k) dst[m][k] = *(const PG8_LAS bf16x8*)(lds + PG8_SA(b, h) + aoff + m * 2048 + k * 1024); } while (0)
; #define PG8_LDB(dst, b, h) do { _Pragma("unroll") for (int n = 0; n < 2; ++n) _Pragma("unroll") for (int k = 0; k < 2; ++k) dst[n][k] = *(const PG8_LAS bf16x8*)(lds + PG8_SB(b, h) + boff + n * 2048 + k * 1024); } while (0)
; #define PG8_MMA(ai, bj, At, Bt) do { __builtin_amdgcn_s_setprio(1); _Pragma("unroll") for (int m = 0; m < 4; ++m) _Pragma("unroll") for (int n = 0; n < 2; ++n) _Pragma("unroll") for (int k = 0; k < 2; ++k) \
;         acc[ai][bj][m][n] = __builtin_amdgcn_mfma_f32_16x16x32_bf16(Bt[n][k], At[m][k], acc[ai][bj][m][n], 0, 0, 0); __builtin_amdgcn_s_setprio(0); } while (0)
; #define PG8_WAIT_V(n) asm volatile("s_waitcnt vmcnt(" #n ")" ::: "memory")
; template <class Epi, class Sched, bool ALIGN_EPI = false, bool SP2 = false>
; __device__ __forceinline__ void gemm_phase(PG8_LAS unsigned char* lds, const Gemm g, const Sched& S, const Epi& E) {
;     ...
;             PG8_LDB(B0, 0, 0); PG8_LDB(B1, 0, 1); PG8_SCHED; PG8_LDA(At, 0, 0); PG8_STAGE(PG8_SA(1, 1), a1 + hstep, voffA);
;             PG8_WAIT_V(8); PG8_WAIT_L(0); PG8_BAR; PG8_MMA(0, 0, At, B0); PG8_MMA(0, 1, At, B1); PG8_BAR; PG8_SCHED;
;             PG8_LDA(At, 0, 1); PG8_STAGE(PG8_SB(0, 0), b2, voffB); PG8_STAGE(PG8_SB(0, 1), b2 + hstep, voffB); PG8_STAGE(PG8_SA(0, 0), a2, voffA);
;             PG8_WAIT_V(8); PG8_WAIT_L(0); PG8_BAR; PG8_MMA(1, 0, At, B0); PG8_MMA(1, 1, At, B1); PG8_BAR; PG8_SCHED;
;             PG8_LDB(B0, 1, 0); PG8_LDB(B1, 1, 1); PG8_SCHED; PG8_LDA(At, 1, 0); PG8_STAGE(PG8_SA(0, 1), a2 + hstep, voffA);
;             PG8_WAIT_V(8); PG8_WAIT_L(0); PG8_BAR; PG8_MMA(0, 0, At, B0); PG8_MMA(0, 1, At, B1); PG8_BAR; PG8_SCHED;
;             PG8_LDA(At, 1, 1); PG8_STAGE(PG8_SB(1, 0), b3, voffB); PG8_STAGE(PG8_SB(1, 1), b3 + hstep, voffB); PG8_STAGE(PG8_SA(1, 0), a3, voffA);
;             PG8_WAIT_V(8); PG8_WAIT_L(0); PG8_BAR; PG8_MMA(1, 0, At, B0); PG8_MMA(1, 1, At, B1); PG8_BAR; PG8_SCHED;
	s_add_i32 s48, s73, s50
	v_lshl_add_u64 v[210:211], v[210:211], 0, s[12:13]
	s_mov_b32 m0, s48
	ds_read_b128 v[160:163], v225 offset:49152
	ds_read_b128 v[164:167], v225 offset:50176
	ds_read_b128 v[168:171], v225 offset:51200
	ds_read_b128 v[172:175], v225 offset:52224
	ds_read_b128 v[176:179], v225 offset:53248
	ds_read_b128 v[180:183], v225 offset:54272
	ds_read_b128 v[202:205], v225 offset:55296
	ds_read_b128 v[206:209], v225 offset:56320
	global_load_lds_dwordx4 v[210:211], off
	s_add_i32 m0, s48, 0x2000
	s_add_u32 s34, s34, 0xb0080
	v_lshl_add_u64 v[210:211], v[212:213], 0, s[12:13]
	s_addc_u32 s35, s35, 0
	s_add_i32 s48, s74, s50
	global_load_lds_dwordx4 v[210:211], off
	v_lshl_add_u64 v[210:211], s[34:35], 0, v[186:187]
	s_mov_b32 m0, s48
	s_nop 0
	global_load_lds_dwordx4 v[210:211], off
	v_lshl_add_u64 v[210:211], s[34:35], 0, v[190:191]
	s_add_i32 m0, s48, 0x2000
	s_nop 0
	global_load_lds_dwordx4 v[210:211], off
	v_lshl_add_u64 v[210:211], v[214:215], 0, s[12:13]
	s_mov_b32 m0, s59
	s_nop 0
	global_load_lds_dwordx4 v[210:211], off
	v_lshl_add_u64 v[210:211], v[216:217], 0, s[12:13]
	s_mov_b32 m0, s60
	s_nop 0
	global_load_lds_dwordx4 v[210:211], off
	s_waitcnt vmcnt(8)
	s_waitcnt lgkmcnt(0)
	s_barrier
	s_setprio 1
	s_waitcnt lgkmcnt(0)
	v_mfma_f32_16x16x32_bf16 v[60:63], v[96:99], v[160:163], v[60:63]
	v_mfma_f32_16x16x32_bf16 v[56:59], v[120:123], v[160:163], v[56:59]
	v_mfma_f32_16x16x32_bf16 v[44:47], v[96:99], v[168:171], v[44:47]
	v_mfma_f32_16x16x32_bf16 v[40:43], v[120:123], v[168:171], v[40:43]
	v_mfma_f32_16x16x32_bf16 v[28:31], v[96:99], v[176:179], v[28:31]
	v_mfma_f32_16x16x32_bf16 v[24:27], v[120:123], v[176:179], v[24:27]
	v_mfma_f32_16x16x32_bf16 v[12:15], v[96:99], v[202:205], v[12:15]
	v_mfma_f32_16x16x32_bf16 v[8:11], v[120:123], v[202:205], v[8:11]
	v_mfma_f32_16x16x32_bf16 v[60:63], v[108:111], v[164:167], v[60:63]
	v_mfma_f32_16x16x32_bf16 v[56:59], v[128:131], v[164:167], v[56:59]
	v_mfma_f32_16x16x32_bf16 v[44:47], v[108:111], v[172:175], v[44:47]
	v_mfma_f32_16x16x32_bf16 v[40:43], v[128:131], v[172:175], v[40:43]
	v_mfma_f32_16x16x32_bf16 v[28:31], v[108:111], v[180:183], v[28:31]
	v_mfma_f32_16x16x32_bf16 v[24:27], v[128:131], v[180:183], v[24:27]
	v_mfma_f32_16x16x32_bf16 v[12:15], v[108:111], v[206:209], v[12:15]
	v_mfma_f32_16x16x32_bf16 v[8:11], v[128:131], v[206:209], v[8:11]
	v_mfma_f32_16x16x32_bf16 v[52:55], v[144:147], v[160:163], v[52:55]
	v_mfma_f32_16x16x32_bf16 v[48:51], v[152:155], v[160:163], v[48:51]
	v_mfma_f32_16x16x32_bf16 v[36:39], v[144:147], v[168:171], v[36:39]
	v_mfma_f32_16x16x32_bf16 v[32:35], v[152:155], v[168:171], v[32:35]
	v_mfma_f32_16x16x32_bf16 v[20:23], v[144:147], v[176:179], v[20:23]
	v_mfma_f32_16x16x32_bf16 v[16:19], v[152:155], v[176:179], v[16:19]
	v_mfma_f32_16x16x32_bf16 v[4:7], v[144:147], v[202:205], v[4:7]
	v_mfma_f32_16x16x32_bf16 v[0:3], v[152:155], v[202:205], v[0:3]
	v_mfma_f32_16x16x32_bf16 v[52:55], v[148:151], v[164:167], v[52:55]
	v_mfma_f32_16x16x32_bf16 v[48:51], v[156:159], v[164:167], v[48:51]
	v_mfma_f32_16x16x32_bf16 v[36:39], v[148:151], v[172:175], v[36:39]
	v_mfma_f32_16x16x32_bf16 v[32:35], v[156:159], v[172:175], v[32:35]
	v_mfma_f32_16x16x32_bf16 v[20:23], v[148:151], v[180:183], v[20:23]
	v_mfma_f32_16x16x32_bf16 v[16:19], v[156:159], v[180:183], v[16:19]
	v_mfma_f32_16x16x32_bf16 v[4:7], v[148:151], v[206:209], v[4:7]
	v_mfma_f32_16x16x32_bf16 v[0:3], v[156:159], v[206:209], v[0:3]
	s_setprio 0
	s_barrier
	s_add_i32 s72, s72, 2
	s_add_u32 s20, s20, 0x100
	s_addc_u32 s21, s21, 0
	s_add_u32 s70, s70, 0x100
	s_addc_u32 s71, s71, 0
	s_cmp_gt_u32 s72, 41
.LBB0_895:
	ds_read_b128 v[96:99], v223
	ds_read_b128 v[108:111], v223 offset:1024
	ds_read_b128 v[120:123], v223 offset:2048
	ds_read_b128 v[128:131], v223 offset:3072
	ds_read_b128 v[144:147], v224
	ds_read_b128 v[148:151], v224 offset:1024
	ds_read_b128 v[152:155], v224 offset:2048
	ds_read_b128 v[156:159], v224 offset:3072
	s_add_u32 s34, s20, 0xfff50080
	s_addc_u32 s35, s21, -1
	s_cmp_eq_u32 s72, 40
	s_cselect_b32 s49, s1, s35
	s_cselect_b32 s48, s0, s34
	s_cselect_b32 s35, s47, s71
	s_cselect_b32 s34, s46, s70
	v_lshl_add_u64 v[210:211], s[20:21], 0, v[192:193]
	s_add_i32 m0, s51, 0xc000
	ds_read_b128 v[160:163], v225
	ds_read_b128 v[164:167], v225 offset:1024
	ds_read_b128 v[168:171], v225 offset:2048
	ds_read_b128 v[172:175], v225 offset:3072
	ds_read_b128 v[176:179], v225 offset:4096
	ds_read_b128 v[180:183], v225 offset:5120
	ds_read_b128 v[202:205], v225 offset:6144
	ds_read_b128 v[206:209], v225 offset:7168
	global_load_lds_dwordx4 v[210:211], off
	v_lshl_add_u64 v[210:211], s[20:21], 0, v[194:195]
	s_add_i32 m0, s51, 0xe000
	s_nop 0
	global_load_lds_dwordx4 v[210:211], off
	s_waitcnt vmcnt(8)
	s_waitcnt lgkmcnt(0)
	s_barrier
; #define PG8_STAGE(bufoff, gbase, voff) do { _Pragma("unroll") for (int _i = 0; _i < 2; ++_i) \
;         __builtin_amdgcn_global_load_lds((const unsigned*)((const char*)(gbase) + (voff)[_i]), (PG8_LAS unsigned*)(lds + (bufoff) + ldsw + _i * 8192), 16, 0, 0); } while (0)
; #define PG8_LDA(dst, b, h) do { _Pragma("unroll") for (int m = 0; m < 4; ++m) _Pragma("unroll") for (int k = 0; k < 2; ++k) dst[m][k] = *(const PG8_LAS bf16x8*)(lds + PG8_SA(b, h) + aoff + m * 2048 + k * 1024); } while (0)
; #define PG8_MMA(ai, bj, At, Bt) do { __builtin_amdgcn_s_setprio(1); _Pragma("unroll") for (int m = 0; m < 4; ++m) _Pragma("unroll") for (int n = 0; n < 2; ++n) _Pragma("unroll") for (int k = 0; k < 2; ++k) \
;         acc[ai][bj][m][n] = __builtin_amdgcn_mfma_f32_16x16x32_bf16(Bt[n][k], At[m][k], acc[ai][bj][m][n], 0, 0, 0); __builtin_amdgcn_s_setprio(0); } while (0)
; #define PG8_WAIT_V(n) asm volatile("s_waitcnt vmcnt(" #n ")" ::: "memory")
; #define PG8_WAIT_L(n) asm volatile("s_waitcnt lgkmcnt(" #n ")" ::: "memory")
; #define PG8_BAR __builtin_amdgcn_s_barrier()
; #define PG8_SCHED __builtin_amdgcn_sched_barrier(0)
; template <class Epi, class Sched, bool ALIGN_EPI = false, bool SP2 = false>
; __device__ __forceinline__ void gemm_phase(PG8_LAS unsigned char* lds, const Gemm g, const Sched& S, const Epi& E) {
;     ...
;             PG8_WAIT_V(8); PG8_WAIT_L(0); PG8_BAR; PG8_MMA(0, 0, At, B0); PG8_MMA(0, 1, At, B1); PG8_BAR; PG8_SCHED;
;             PG8_LDA(At, 0, 1); PG8_STAGE(PG8_SB(0, 0), b2, voffB); PG8_STAGE(PG8_SB(0, 1), b2 + hstep, voffB); PG8_STAGE(PG8_SA(0, 0), a2, voffA);
;             PG8_WAIT_V(8); PG8_WAIT_L(0); PG8_BAR; PG8_MMA(1, 0, At, B0); PG8_MMA(1, 1, At, B1); PG8_BAR; PG8_SCHED;
	s_setprio 1
	s_waitcnt lgkmcnt(0)
	v_mfma_f32_16x16x32_bf16 v[140:143], v[96:99], v[160:163], v[140:143]
	v_mfma_f32_16x16x32_bf16 v[136:139], v[120:123], v[160:163], v[136:139]
	v_mfma_f32_16x16x32_bf16 v[116:119], v[96:99], v[168:171], v[116:119]
	v_mfma_f32_16x16x32_bf16 v[112:115], v[120:123], v[168:171], v[112:115]
	v_mfma_f32_16x16x32_bf16 v[92:95], v[96:99], v[176:179], v[92:95]
	v_mfma_f32_16x16x32_bf16 v[88:91], v[120:123], v[176:179], v[88:91]
	v_mfma_f32_16x16x32_bf16 v[76:79], v[96:99], v[202:205], v[76:79]
	v_mfma_f32_16x16x32_bf16 v[72:75], v[120:123], v[202:205], v[72:75]
	v_mfma_f32_16x16x32_bf16 v[140:143], v[108:111], v[164:167], v[140:143]
	v_mfma_f32_16x16x32_bf16 v[136:139], v[128:131], v[164:167], v[136:139]
	v_mfma_f32_16x16x32_bf16 v[116:119], v[108:111], v[172:175], v[116:119]
	v_mfma_f32_16x16x32_bf16 v[112:115], v[128:131], v[172:175], v[112:115]
	v_mfma_f32_16x16x32_bf16 v[92:95], v[108:111], v[180:183], v[92:95]
	v_mfma_f32_16x16x32_bf16 v[88:91], v[128:131], v[180:183], v[88:91]
	v_mfma_f32_16x16x32_bf16 v[76:79], v[108:111], v[206:209], v[76:79]
	v_mfma_f32_16x16x32_bf16 v[72:75], v[128:131], v[206:209], v[72:75]
	v_mfma_f32_16x16x32_bf16 v[132:135], v[144:147], v[160:163], v[132:135]
	v_mfma_f32_16x16x32_bf16 v[124:127], v[152:155], v[160:163], v[124:127]
	v_mfma_f32_16x16x32_bf16 v[104:107], v[144:147], v[168:171], v[104:107]
	v_mfma_f32_16x16x32_bf16 v[100:103], v[152:155], v[168:171], v[100:103]
	v_mfma_f32_16x16x32_bf16 v[84:87], v[144:147], v[176:179], v[84:87]
	v_mfma_f32_16x16x32_bf16 v[80:83], v[152:155], v[176:179], v[80:83]
	v_mfma_f32_16x16x32_bf16 v[68:71], v[144:147], v[202:205], v[68:71]
	v_mfma_f32_16x16x32_bf16 v[64:67], v[152:155], v[202:205], v[64:67]
	v_mfma_f32_16x16x32_bf16 v[132:135], v[148:151], v[164:167], v[132:135]
	v_mfma_f32_16x16x32_bf16 v[124:127], v[156:159], v[164:167], v[124:127]
	v_mfma_f32_16x16x32_bf16 v[104:107], v[148:151], v[172:175], v[104:107]
	v_mfma_f32_16x16x32_bf16 v[100:103], v[156:159], v[172:175], v[100:103]
	v_mfma_f32_16x16x32_bf16 v[84:87], v[148:151], v[180:183], v[84:87]
	v_mfma_f32_16x16x32_bf16 v[80:83], v[156:159], v[180:183], v[80:83]
	v_mfma_f32_16x16x32_bf16 v[68:71], v[148:151], v[206:209], v[68:71]
	v_mfma_f32_16x16x32_bf16 v[64:67], v[156:159], v[206:209], v[64:67]
	s_setprio 0
	s_barrier
	s_add_i32 s73, s64, s50
	v_lshl_add_u64 v[210:211], s[34:35], 0, v[186:187]
	s_mov_b32 m0, s73
	ds_read_b128 v[160:163], v225 offset:16384
	ds_read_b128 v[164:167], v225 offset:17408
	ds_read_b128 v[168:171], v225 offset:18432
	ds_read_b128 v[172:175], v225 offset:19456
	ds_read_b128 v[176:179], v225 offset:20480
	ds_read_b128 v[180:183], v225 offset:21504
	ds_read_b128 v[202:205], v225 offset:22528
	ds_read_b128 v[206:209], v225 offset:23552
	global_load_lds_dwordx4 v[210:211], off
	s_add_i32 m0, s73, 0x2000
	s_add_u32 s74, s34, 0xb0000
	v_lshl_add_u64 v[212:213], s[34:35], 0, v[190:191]
	s_addc_u32 s75, s35, 0
	s_add_i32 s73, s65, s50
	global_load_lds_dwordx4 v[212:213], off
	v_lshl_add_u64 v[214:215], s[74:75], 0, v[186:187]
	s_mov_b32 m0, s73
	v_lshl_add_u64 v[216:217], s[48:49], 0, v[188:189]
	global_load_lds_dwordx4 v[214:215], off
	v_lshl_add_u64 v[214:215], s[74:75], 0, v[190:191]
	s_add_i32 m0, s73, 0x2000
	s_nop 0
	global_load_lds_dwordx4 v[214:215], off
	v_lshl_add_u64 v[214:215], s[48:49], 0, v[184:185]
	s_mov_b32 m0, s51
	s_nop 0
	global_load_lds_dwordx4 v[214:215], off
	s_mov_b32 m0, s52
	s_nop 0
	global_load_lds_dwordx4 v[216:217], off
	s_waitcnt vmcnt(8)
	s_waitcnt lgkmcnt(0)
	s_barrier
	s_setprio 1
	s_waitcnt lgkmcnt(0)
	v_mfma_f32_16x16x32_bf16 v[60:63], v[96:99], v[160:163], v[60:63]
	v_mfma_f32_16x16x32_bf16 v[56:59], v[120:123], v[160:163], v[56:59]
	v_mfma_f32_16x16x32_bf16 v[44:47], v[96:99], v[168:171], v[44:47]
	v_mfma_f32_16x16x32_bf16 v[40:43], v[120:123], v[168:171], v[40:43]
	v_mfma_f32_16x16x32_bf16 v[28:31], v[96:99], v[176:179], v[28:31]
	v_mfma_f32_16x16x32_bf16 v[24:27], v[120:123], v[176:179], v[24:27]
	v_mfma_f32_16x16x32_bf16 v[12:15], v[96:99], v[202:205], v[12:15]
	v_mfma_f32_16x16x32_bf16 v[8:11], v[120:123], v[202:205], v[8:11]
	v_mfma_f32_16x16x32_bf16 v[60:63], v[108:111], v[164:167], v[60:63]
	v_mfma_f32_16x16x32_bf16 v[56:59], v[128:131], v[164:167], v[56:59]
	v_mfma_f32_16x16x32_bf16 v[44:47], v[108:111], v[172:175], v[44:47]
	v_mfma_f32_16x16x32_bf16 v[40:43], v[128:131], v[172:175], v[40:43]
	v_mfma_f32_16x16x32_bf16 v[28:31], v[108:111], v[180:183], v[28:31]
	v_mfma_f32_16x16x32_bf16 v[24:27], v[128:131], v[180:183], v[24:27]
	v_mfma_f32_16x16x32_bf16 v[12:15], v[108:111], v[206:209], v[12:15]
	v_mfma_f32_16x16x32_bf16 v[8:11], v[128:131], v[206:209], v[8:11]
	v_mfma_f32_16x16x32_bf16 v[52:55], v[144:147], v[160:163], v[52:55]
	v_mfma_f32_16x16x32_bf16 v[48:51], v[152:155], v[160:163], v[48:51]
	v_mfma_f32_16x16x32_bf16 v[36:39], v[144:147], v[168:171], v[36:39]
	v_mfma_f32_16x16x32_bf16 v[32:35], v[152:155], v[168:171], v[32:35]
	v_mfma_f32_16x16x32_bf16 v[20:23], v[144:147], v[176:179], v[20:23]
	v_mfma_f32_16x16x32_bf16 v[16:19], v[152:155], v[176:179], v[16:19]
	v_mfma_f32_16x16x32_bf16 v[4:7], v[144:147], v[202:205], v[4:7]
	v_mfma_f32_16x16x32_bf16 v[0:3], v[152:155], v[202:205], v[0:3]
	v_mfma_f32_16x16x32_bf16 v[52:55], v[148:151], v[164:167], v[52:55]
	v_mfma_f32_16x16x32_bf16 v[48:51], v[156:159], v[164:167], v[48:51]
	v_mfma_f32_16x16x32_bf16 v[36:39], v[148:151], v[172:175], v[36:39]
	v_mfma_f32_16x16x32_bf16 v[32:35], v[156:159], v[172:175], v[32:35]
	v_mfma_f32_16x16x32_bf16 v[20:23], v[148:151], v[180:183], v[20:23]
	v_mfma_f32_16x16x32_bf16 v[16:19], v[156:159], v[180:183], v[16:19]
	v_mfma_f32_16x16x32_bf16 v[4:7], v[148:151], v[206:209], v[4:7]
	v_mfma_f32_16x16x32_bf16 v[0:3], v[156:159], v[206:209], v[0:3]
	s_setprio 0
	s_barrier
; #define PG8_STAGE(bufoff, gbase, voff) do { _Pragma("unroll") for (int _i = 0; _i < 2; ++_i) \
;         __builtin_amdgcn_global_load_lds((const unsigned*)((const char*)(gbase) + (voff)[_i]), (PG8_LAS unsigned*)(lds + (bufoff) + ldsw + _i * 8192), 16, 0, 0); } while (0)
; #define PG8_LDA(dst, b, h) do { _Pragma("unroll") for (int m = 0; m < 4; ++m) _Pragma("unroll") for (int k = 0; k < 2; ++k) dst[m][k] = *(const PG8_LAS bf16x8*)(lds + PG8_SA(b, h) + aoff + m * 2048 + k * 1024); } while (0)
; #define PG8_LDB(dst, b, h) do { _Pragma("unroll") for (int n = 0; n < 2; ++n) _Pragma("unroll") for (int k = 0; k < 2; ++k) dst[n][k] = *(const PG8_LAS bf16x8*)(lds + PG8_SB(b, h) + boff + n * 2048 + k * 1024); } while (0)
; #define PG8_MMA(ai, bj, At, Bt) do { __builtin_amdgcn_s_setprio(1); _Pragma("unroll") for (int m = 0; m < 4; ++m) _Pragma("unroll") for (int n = 0; n < 2; ++n) _Pragma("unroll") for (int k = 0; k < 2; ++k) \
;         acc[ai][bj][m][n] = __builtin_amdgcn_mfma_f32_16x16x32_bf16(Bt[n][k], At[m][k], acc[ai][bj][m][n], 0, 0, 0); __builtin_amdgcn_s_setprio(0); } while (0)
; #define PG8_WAIT_V(n) asm volatile("s_waitcnt vmcnt(" #n ")" ::: "memory")
; #define PG8_WAIT_L(n) asm volatile("s_waitcnt lgkmcnt(" #n ")" ::: "memory")
; #define PG8_BAR __builtin_amdgcn_s_barrier()
; #define PG8_SCHED __builtin_amdgcn_sched_barrier(0)
; template <class Epi, class Sched, bool ALIGN_EPI = false, bool SP2 = false>
; __device__ __forceinline__ void gemm_phase(PG8_LAS unsigned char* lds, const Gemm g, const Sched& S, const Epi& E) {
;     ...
;             PG8_LDB(B0, 1, 0); PG8_LDB(B1, 1, 1); PG8_SCHED; PG8_LDA(At, 1, 0); PG8_STAGE(PG8_SA(0, 1), a2 + hstep, voffA);
;             PG8_WAIT_V(8); PG8_WAIT_L(0); PG8_BAR; PG8_MMA(0, 0, At, B0); PG8_MMA(0, 1, At, B1); PG8_BAR; PG8_SCHED;
	s_add_i32 s73, 0, 0x18000
	s_add_i32 s74, 0, 0x1c000
	v_add_u32_e32 v128, s73, v221
	v_add_u32_e32 v156, s74, v221
	ds_read_b128 v[96:99], v128
	ds_read_b128 v[108:111], v128 offset:1024
	ds_read_b128 v[120:123], v128 offset:2048
	ds_read_b128 v[128:131], v128 offset:3072
	ds_read_b128 v[144:147], v156
	ds_read_b128 v[148:151], v156 offset:1024
	ds_read_b128 v[152:155], v156 offset:2048
	ds_read_b128 v[156:159], v156 offset:3072
	s_add_u32 s48, s48, 0xb0000
	s_addc_u32 s49, s49, 0
	s_mov_b32 m0, s53
	v_lshl_add_u64 v[218:219], s[48:49], 0, v[184:185]
	ds_read_b128 v[160:163], v225 offset:32768
	ds_read_b128 v[164:167], v225 offset:33792
	ds_read_b128 v[168:171], v225 offset:34816
	ds_read_b128 v[172:175], v225 offset:35840
	ds_read_b128 v[176:179], v225 offset:36864
	ds_read_b128 v[180:183], v225 offset:37888
	ds_read_b128 v[202:205], v225 offset:38912
	ds_read_b128 v[206:209], v225 offset:39936
	global_load_lds_dwordx4 v[218:219], off
	v_lshl_add_u64 v[218:219], s[48:49], 0, v[188:189]
	s_mov_b32 m0, s54
	s_nop 0
	global_load_lds_dwordx4 v[218:219], off
	s_waitcnt vmcnt(8)
	s_waitcnt lgkmcnt(0)
	s_barrier
	s_setprio 1
	s_waitcnt lgkmcnt(0)
	v_mfma_f32_16x16x32_bf16 v[140:143], v[96:99], v[160:163], v[140:143]
	v_mfma_f32_16x16x32_bf16 v[136:139], v[120:123], v[160:163], v[136:139]
	v_mfma_f32_16x16x32_bf16 v[116:119], v[96:99], v[168:171], v[116:119]
	v_mfma_f32_16x16x32_bf16 v[112:115], v[120:123], v[168:171], v[112:115]
	v_mfma_f32_16x16x32_bf16 v[92:95], v[96:99], v[176:179], v[92:95]
	v_mfma_f32_16x16x32_bf16 v[88:91], v[120:123], v[176:179], v[88:91]
	v_mfma_f32_16x16x32_bf16 v[76:79], v[96:99], v[202:205], v[76:79]
	v_mfma_f32_16x16x32_bf16 v[72:75], v[120:123], v[202:205], v[72:75]
	v_mfma_f32_16x16x32_bf16 v[140:143], v[108:111], v[164:167], v[140:143]
	v_mfma_f32_16x16x32_bf16 v[136:139], v[128:131], v[164:167], v[136:139]
	v_mfma_f32_16x16x32_bf16 v[116:119], v[108:111], v[172:175], v[116:119]
	v_mfma_f32_16x16x32_bf16 v[112:115], v[128:131], v[172:175], v[112:115]
	v_mfma_f32_16x16x32_bf16 v[92:95], v[108:111], v[180:183], v[92:95]
	v_mfma_f32_16x16x32_bf16 v[88:91], v[128:131], v[180:183], v[88:91]
	v_mfma_f32_16x16x32_bf16 v[76:79], v[108:111], v[206:209], v[76:79]
	v_mfma_f32_16x16x32_bf16 v[72:75], v[128:131], v[206:209], v[72:75]
	v_mfma_f32_16x16x32_bf16 v[132:135], v[144:147], v[160:163], v[132:135]
	v_mfma_f32_16x16x32_bf16 v[124:127], v[152:155], v[160:163], v[124:127]
	v_mfma_f32_16x16x32_bf16 v[104:107], v[144:147], v[168:171], v[104:107]
	v_mfma_f32_16x16x32_bf16 v[100:103], v[152:155], v[168:171], v[100:103]
	v_mfma_f32_16x16x32_bf16 v[84:87], v[144:147], v[176:179], v[84:87]
	v_mfma_f32_16x16x32_bf16 v[80:83], v[152:155], v[176:179], v[80:83]
	v_mfma_f32_16x16x32_bf16 v[68:71], v[144:147], v[202:205], v[68:71]
	v_mfma_f32_16x16x32_bf16 v[64:67], v[152:155], v[202:205], v[64:67]
	v_mfma_f32_16x16x32_bf16 v[132:135], v[148:151], v[164:167], v[132:135]
	v_mfma_f32_16x16x32_bf16 v[124:127], v[156:159], v[164:167], v[124:127]
	v_mfma_f32_16x16x32_bf16 v[104:107], v[148:151], v[172:175], v[104:107]
	v_mfma_f32_16x16x32_bf16 v[100:103], v[156:159], v[172:175], v[100:103]
	v_mfma_f32_16x16x32_bf16 v[84:87], v[148:151], v[180:183], v[84:87]
	v_mfma_f32_16x16x32_bf16 v[80:83], v[156:159], v[180:183], v[80:83]
	v_mfma_f32_16x16x32_bf16 v[68:71], v[148:151], v[206:209], v[68:71]
	v_mfma_f32_16x16x32_bf16 v[64:67], v[156:159], v[206:209], v[64:67]
	s_setprio 0
	s_barrier
; #define PG8_STAGE(bufoff, gbase, voff) do { _Pragma("unroll") for (int _i = 0; _i < 2; ++_i) \
;         __builtin_amdgcn_global_load_lds((const unsigned*)((const char*)(gbase) + (voff)[_i]), (PG8_LAS unsigned*)(lds + (bufoff) + ldsw + _i * 8192), 16, 0, 0); } while (0)
; #define PG8_LDA(dst, b, h) do { _Pragma("unroll") for (int m = 0; m < 4; ++m) _Pragma("unroll") for (int k = 0; k < 2; ++k) dst[m][k] = *(const PG8_LAS bf16x8*)(lds + PG8_SA(b, h) + aoff + m * 2048 + k * 1024); } while (0)
; #define PG8_MMA(ai, bj, At, Bt) do { __builtin_amdgcn_s_setprio(1); _Pragma("unroll") for (int m = 0; m < 4; ++m) _Pragma("unroll") for (int n = 0; n < 2; ++n) _Pragma("unroll") for (int k = 0; k < 2; ++k) \
;         acc[ai][bj][m][n] = __builtin_amdgcn_mfma_f32_16x16x32_bf16(Bt[n][k], At[m][k], acc[ai][bj][m][n], 0, 0, 0); __builtin_amdgcn_s_setprio(0); } while (0)
; #define PG8_WAIT_V(n) asm volatile("s_waitcnt vmcnt(" #n ")" ::: "memory")
; #define PG8_WAIT_L(n) asm volatile("s_waitcnt lgkmcnt(" #n ")" ::: "memory")
; #define PG8_BAR __builtin_amdgcn_s_barrier()
; #define PG8_SCHED __builtin_amdgcn_sched_barrier(0)
; template <class Epi, class Sched, bool ALIGN_EPI = false, bool SP2 = false>
; __device__ __forceinline__ void gemm_phase(PG8_LAS unsigned char* lds, const Gemm g, const Sched& S, const Epi& E) {
;     ...
;             PG8_LDA(At, 1, 1); PG8_STAGE(PG8_SB(1, 0), b3, voffB); PG8_STAGE(PG8_SB(1, 1), b3 + hstep, voffB); PG8_STAGE(PG8_SA(1, 0), a3, voffA);
;             PG8_WAIT_V(8); PG8_WAIT_L(0); PG8_BAR; PG8_MMA(1, 0, At, B0); PG8_MMA(1, 1, At, B1); PG8_BAR; PG8_SCHED;
;     ...
;         if constexpr (ALIGN_EPI) { if (wr == 0) PG8_BAR; }
	s_add_i32 s48, s73, s50
	v_lshl_add_u64 v[210:211], v[210:211], 0, s[12:13]
	s_mov_b32 m0, s48
	ds_read_b128 v[160:163], v225 offset:49152
	ds_read_b128 v[164:167], v225 offset:50176
	ds_read_b128 v[168:171], v225 offset:51200
	ds_read_b128 v[172:175], v225 offset:52224
	ds_read_b128 v[176:179], v225 offset:53248
	ds_read_b128 v[180:183], v225 offset:54272
	ds_read_b128 v[202:205], v225 offset:55296
	ds_read_b128 v[206:209], v225 offset:56320
	global_load_lds_dwordx4 v[210:211], off
	s_add_i32 m0, s48, 0x2000
	s_add_u32 s34, s34, 0xb0080
	v_lshl_add_u64 v[210:211], v[212:213], 0, s[12:13]
	s_addc_u32 s35, s35, 0
	s_add_i32 s48, s74, s50
	global_load_lds_dwordx4 v[210:211], off
	v_lshl_add_u64 v[210:211], s[34:35], 0, v[186:187]
	s_mov_b32 m0, s48
	s_nop 0
	global_load_lds_dwordx4 v[210:211], off
	v_lshl_add_u64 v[210:211], s[34:35], 0, v[190:191]
	s_add_i32 m0, s48, 0x2000
	s_nop 0
	global_load_lds_dwordx4 v[210:211], off
	v_lshl_add_u64 v[210:211], v[214:215], 0, s[12:13]
	s_mov_b32 m0, s59
	s_nop 0
	global_load_lds_dwordx4 v[210:211], off
	v_lshl_add_u64 v[210:211], v[216:217], 0, s[12:13]
	s_mov_b32 m0, s60
	s_nop 0
	global_load_lds_dwordx4 v[210:211], off
	s_waitcnt vmcnt(8)
	s_waitcnt lgkmcnt(0)
	s_barrier
	s_setprio 1
	s_waitcnt lgkmcnt(0)
	v_mfma_f32_16x16x32_bf16 v[60:63], v[96:99], v[160:163], v[60:63]
	v_mfma_f32_16x16x32_bf16 v[56:59], v[120:123], v[160:163], v[56:59]
	v_mfma_f32_16x16x32_bf16 v[44:47], v[96:99], v[168:171], v[44:47]
	v_mfma_f32_16x16x32_bf16 v[40:43], v[120:123], v[168:171], v[40:43]
	v_mfma_f32_16x16x32_bf16 v[28:31], v[96:99], v[176:179], v[28:31]
	v_mfma_f32_16x16x32_bf16 v[24:27], v[120:123], v[176:179], v[24:27]
	v_mfma_f32_16x16x32_bf16 v[12:15], v[96:99], v[202:205], v[12:15]
	v_mfma_f32_16x16x32_bf16 v[8:11], v[120:123], v[202:205], v[8:11]
	v_mfma_f32_16x16x32_bf16 v[60:63], v[108:111], v[164:167], v[60:63]
	v_mfma_f32_16x16x32_bf16 v[56:59], v[128:131], v[164:167], v[56:59]
	v_mfma_f32_16x16x32_bf16 v[44:47], v[108:111], v[172:175], v[44:47]
	v_mfma_f32_16x16x32_bf16 v[40:43], v[128:131], v[172:175], v[40:43]
	v_mfma_f32_16x16x32_bf16 v[28:31], v[108:111], v[180:183], v[28:31]
	v_mfma_f32_16x16x32_bf16 v[24:27], v[128:131], v[180:183], v[24:27]
	v_mfma_f32_16x16x32_bf16 v[12:15], v[108:111], v[206:209], v[12:15]
	v_mfma_f32_16x16x32_bf16 v[8:11], v[128:131], v[206:209], v[8:11]
	v_mfma_f32_16x16x32_bf16 v[52:55], v[144:147], v[160:163], v[52:55]
	v_mfma_f32_16x16x32_bf16 v[48:51], v[152:155], v[160:163], v[48:51]
	v_mfma_f32_16x16x32_bf16 v[36:39], v[144:147], v[168:171], v[36:39]
	v_mfma_f32_16x16x32_bf16 v[32:35], v[152:155], v[168:171], v[32:35]
	v_mfma_f32_16x16x32_bf16 v[20:23], v[144:147], v[176:179], v[20:23]
	v_mfma_f32_16x16x32_bf16 v[16:19], v[152:155], v[176:179], v[16:19]
	v_mfma_f32_16x16x32_bf16 v[4:7], v[144:147], v[202:205], v[4:7]
	v_mfma_f32_16x16x32_bf16 v[0:3], v[152:155], v[202:205], v[0:3]
	v_mfma_f32_16x16x32_bf16 v[52:55], v[148:151], v[164:167], v[52:55]
	v_mfma_f32_16x16x32_bf16 v[48:51], v[156:159], v[164:167], v[48:51]
	v_mfma_f32_16x16x32_bf16 v[36:39], v[148:151], v[172:175], v[36:39]
	v_mfma_f32_16x16x32_bf16 v[32:35], v[156:159], v[172:175], v[32:35]
	v_mfma_f32_16x16x32_bf16 v[20:23], v[148:151], v[180:183], v[20:23]
	v_mfma_f32_16x16x32_bf16 v[16:19], v[156:159], v[180:183], v[16:19]
	v_mfma_f32_16x16x32_bf16 v[4:7], v[148:151], v[206:209], v[4:7]
	v_mfma_f32_16x16x32_bf16 v[0:3], v[156:159], v[206:209], v[0:3]
	s_setprio 0
	s_barrier
	s_add_i32 s72, s72, 2
	s_add_u32 s20, s20, 0x100
	s_addc_u32 s21, s21, 0
	s_add_u32 s70, s70, 0x100
	s_addc_u32 s71, s71, 0
	s_cmp_gt_u32 s72, 41
	s_cbranch_scc0 .LBB0_895
	s_and_b64 vcc, exec, s[14:15]
	s_cbranch_vccz .LBB0_898
	s_barrier

; #define PG8_STAGE(bufoff, gbase, voff) do { _Pragma("unroll") for (int _i = 0; _i < 2; ++_i) \
;         __builtin_amdgcn_global_load_lds((const unsigned*)((const char*)(gbase) + (voff)[_i]), (PG8_LAS unsigned*)(lds + (bufoff) + ldsw + _i * 8192), 16, 0, 0); } while (0)
; #define PG8_LDA(dst, b, h) do { _Pragma("unroll") for (int m = 0; m < 4; ++m) _Pragma("unroll") for (int k = 0; k < 2; ++k) dst[m][k] = *(const PG8_LAS bf16x8*)(lds + PG8_SA(b, h) + aoff + m * 2048 + k * 1024); } while (0)
; #define PG8_LDB(dst, b, h) do { _Pragma("unroll") for (int n = 0; n < 2; ++n) _Pragma("unroll") for (int k = 0; k < 2; ++k) dst[n][k] = *(const PG8_LAS bf16x8*)(lds + PG8_SB(b, h) + boff + n * 2048 + k * 1024); } while (0)
; #define PG8_MMA(ai, bj, At, Bt) do { __builtin_amdgcn_s_setprio(1); _Pragma("unroll") for (int m = 0; m < 4; ++m) _Pragma("unroll") for (int n = 0; n < 2; ++n) _Pragma("unroll") for (int k = 0; k < 2; ++k) \
;         acc[ai][bj][m][n] = __builtin_amdgcn_mfma_f32_16x16x32_bf16(Bt[n][k], At[m][k], acc[ai][bj][m][n], 0, 0, 0); __builtin_amdgcn_s_setprio(0); } while (0)
; #define PG8_WAIT_V(n) asm volatile("s_waitcnt vmcnt(" #n ")" ::: "memory")
; template <class Epi, class Sched, bool ALIGN_EPI = false, bool SP2 = false>
; __device__ __forceinline__ void gemm_phase(PG8_LAS unsigned char* lds, const Gemm g, const Sched& S, const Epi& E) {
;     ...
;         const char* nA = has_next ? (const char*)g.A + (size_t)nxt.pm * tstep : cA; const char* nB = has_next ? (const char*)g.Bt + (size_t)nxt.pn * tstep : cB;
;         for (int t = 0; t < nt; t += 2) {
;             const bool last = (t == nt - 2);
;             const char* a1 = cA + (size_t)(t + 1) * kstep;
;             const char* a2 = last ? nA : cA + (size_t)(t + 2) * kstep; const char* b2 = last ? nB : cB + (size_t)(t + 2) * kstep;
;             const char* a3 = a2 + kstep; const char* b3 = b2 + kstep;
;             if (last && has_next) S.a_ready(nxt);
;             if constexpr (SP2) {
;             PG8_LDB(B0, 0, 0); PG8_LDB(B1, 0, 1); PG8_SCHED; PG8_LDA(At, 0, 0); PG8_STAGE(PG8_SA(1, 1), a1 + hstep, voffA);
;             PG8_WAIT_V(8); PG8_WAIT_L(0); PG8_BAR; PG8_MMA(0, 0, At, B0); PG8_MMA(0, 1, At, B1); PG8_BAR; PG8_SCHED;
;             PG8_LDA(At, 0, 1); PG8_STAGE(PG8_SB(0, 0), b2, voffB); PG8_STAGE(PG8_SB(0, 1), b2 + hstep, voffB); PG8_STAGE(PG8_SA(0, 0), a2, voffA);
.LBB0_1199:
	s_ashr_i32 s57, s56, 31
	s_lshl_b64 s[58:59], s[56:57], 19
	s_add_u32 s58, s36, s58
	s_addc_u32 s59, s37, s59
	s_and_b64 s[60:61], s[8:9], exec
	s_cselect_b32 s1, s59, s21
	s_cselect_b32 s57, s58, s20
	s_ashr_i32 s55, s54, 31
	s_lshl_b64 s[60:61], s[54:55], 19
	s_add_u32 s60, s68, s60
	s_addc_u32 s61, s69, s61
	s_and_b64 s[62:63], s[8:9], exec
	s_cselect_b32 s55, s61, s35
	s_cselect_b32 s85, s60, s34
	s_add_u32 s20, s20, 0x40080
	s_addc_u32 s21, s21, 0
	s_add_u32 s86, s34, 0x100
	s_addc_u32 s87, s35, 0
	s_mov_b32 s88, -2
	s_waitcnt lgkmcnt(0)
	ds_read_b128 v[140:143], v163
	ds_read_b128 v[168:171], v163 offset:1024
	ds_read_b128 v[172:175], v163 offset:2048
	ds_read_b128 v[176:179], v163 offset:3072
	ds_read_b128 v[180:183], v164
	ds_read_b128 v[184:187], v164 offset:1024
	ds_read_b128 v[188:191], v164 offset:2048
	ds_read_b128 v[192:195], v164 offset:3072
	s_add_u32 s34, s20, 0xfffc0080
	s_addc_u32 s35, s21, -1
	s_cmp_eq_u32 s88, 12
	s_cselect_b32 s63, s1, s35
	s_cselect_b32 s62, s57, s34
	s_cselect_b32 s35, s55, s87
	s_cselect_b32 s34, s85, s86
	v_lshl_add_u64 v[230:231], s[20:21], 0, v[132:133]
	s_add_i32 m0, s71, 0xc000
	ds_read_b128 v[198:201], v165
	ds_read_b128 v[202:205], v165 offset:1024
	ds_read_b128 v[206:209], v165 offset:2048
	ds_read_b128 v[210:213], v165 offset:3072
	ds_read_b128 v[214:217], v165 offset:4096
	ds_read_b128 v[218:221], v165 offset:5120
	ds_read_b128 v[222:225], v165 offset:6144
	ds_read_b128 v[226:229], v165 offset:7168
	global_load_lds_dwordx4 v[230:231], off
	v_lshl_add_u64 v[230:231], s[20:21], 0, v[134:135]
	s_add_i32 m0, s71, 0xe000
	s_nop 0
	global_load_lds_dwordx4 v[230:231], off
	s_waitcnt vmcnt(8)
	s_waitcnt lgkmcnt(0)
	s_barrier
	s_setprio 1
	s_waitcnt lgkmcnt(0)
	v_mfma_f32_16x16x32_bf16 v[124:127], v[140:143], v[198:201], 0
	v_mfma_f32_16x16x32_bf16 v[120:123], v[172:175], v[198:201], 0
	v_mfma_f32_16x16x32_bf16 v[108:111], v[140:143], v[206:209], 0
	v_mfma_f32_16x16x32_bf16 v[104:107], v[172:175], v[206:209], 0
	v_mfma_f32_16x16x32_bf16 v[92:95], v[140:143], v[214:217], 0
	v_mfma_f32_16x16x32_bf16 v[88:91], v[172:175], v[214:217], 0
	v_mfma_f32_16x16x32_bf16 v[76:79], v[140:143], v[222:225], 0
	v_mfma_f32_16x16x32_bf16 v[72:75], v[172:175], v[222:225], 0
	v_mfma_f32_16x16x32_bf16 v[124:127], v[168:171], v[202:205], v[124:127]
	v_mfma_f32_16x16x32_bf16 v[120:123], v[176:179], v[202:205], v[120:123]
	v_mfma_f32_16x16x32_bf16 v[108:111], v[168:171], v[210:213], v[108:111]
	v_mfma_f32_16x16x32_bf16 v[104:107], v[176:179], v[210:213], v[104:107]
	v_mfma_f32_16x16x32_bf16 v[92:95], v[168:171], v[218:221], v[92:95]
	v_mfma_f32_16x16x32_bf16 v[88:91], v[176:179], v[218:221], v[88:91]
	v_mfma_f32_16x16x32_bf16 v[76:79], v[168:171], v[226:229], v[76:79]
	v_mfma_f32_16x16x32_bf16 v[72:75], v[176:179], v[226:229], v[72:75]
	v_mfma_f32_16x16x32_bf16 v[116:119], v[180:183], v[198:201], 0
	v_mfma_f32_16x16x32_bf16 v[112:115], v[188:191], v[198:201], 0
	v_mfma_f32_16x16x32_bf16 v[100:103], v[180:183], v[206:209], 0
	v_mfma_f32_16x16x32_bf16 v[96:99], v[188:191], v[206:209], 0
	v_mfma_f32_16x16x32_bf16 v[84:87], v[180:183], v[214:217], 0
	v_mfma_f32_16x16x32_bf16 v[80:83], v[188:191], v[214:217], 0
	v_mfma_f32_16x16x32_bf16 v[68:71], v[180:183], v[222:225], 0
	v_mfma_f32_16x16x32_bf16 v[64:67], v[188:191], v[222:225], 0
	v_mfma_f32_16x16x32_bf16 v[116:119], v[184:187], v[202:205], v[116:119]
	v_mfma_f32_16x16x32_bf16 v[112:115], v[192:195], v[202:205], v[112:115]
	v_mfma_f32_16x16x32_bf16 v[100:103], v[184:187], v[210:213], v[100:103]
	v_mfma_f32_16x16x32_bf16 v[96:99], v[192:195], v[210:213], v[96:99]
	v_mfma_f32_16x16x32_bf16 v[84:87], v[184:187], v[218:221], v[84:87]
	v_mfma_f32_16x16x32_bf16 v[80:83], v[192:195], v[218:221], v[80:83]
	v_mfma_f32_16x16x32_bf16 v[68:71], v[184:187], v[226:229], v[68:71]
	v_mfma_f32_16x16x32_bf16 v[64:67], v[192:195], v[226:229], v[64:67]
	s_setprio 0
	s_barrier
	s_add_i32 s89, s77, s70
	v_lshl_add_u64 v[230:231], s[34:35], 0, v[146:147]
	s_mov_b32 m0, s89
	ds_read_b128 v[198:201], v165 offset:16384
	ds_read_b128 v[202:205], v165 offset:17408
	ds_read_b128 v[206:209], v165 offset:18432
	ds_read_b128 v[210:213], v165 offset:19456
	ds_read_b128 v[214:217], v165 offset:20480
	ds_read_b128 v[218:221], v165 offset:21504
	ds_read_b128 v[222:225], v165 offset:22528
	ds_read_b128 v[226:229], v165 offset:23552
	global_load_lds_dwordx4 v[230:231], off
	s_add_i32 m0, s89, 0x2000
	s_add_u32 s90, s34, 0x40000
	v_lshl_add_u64 v[232:233], s[34:35], 0, v[150:151]
	s_addc_u32 s91, s35, 0
	s_add_i32 s89, s78, s70
	global_load_lds_dwordx4 v[232:233], off
	v_lshl_add_u64 v[234:235], s[90:91], 0, v[146:147]
	s_mov_b32 m0, s89
	v_lshl_add_u64 v[236:237], s[62:63], 0, v[148:149]
	global_load_lds_dwordx4 v[234:235], off
	v_lshl_add_u64 v[234:235], s[90:91], 0, v[150:151]
	s_add_i32 m0, s89, 0x2000
	s_nop 0
	global_load_lds_dwordx4 v[234:235], off
	v_lshl_add_u64 v[234:235], s[62:63], 0, v[144:145]
	s_mov_b32 m0, s71
	s_nop 0
	global_load_lds_dwordx4 v[234:235], off
	s_mov_b32 m0, s72
	s_nop 0
	global_load_lds_dwordx4 v[236:237], off
	s_waitcnt vmcnt(8)
	s_waitcnt lgkmcnt(0)
	s_barrier
; #define PG8_STAGE(bufoff, gbase, voff) do { _Pragma("unroll") for (int _i = 0; _i < 2; ++_i) \
;         __builtin_amdgcn_global_load_lds((const unsigned*)((const char*)(gbase) + (voff)[_i]), (PG8_LAS unsigned*)(lds + (bufoff) + ldsw + _i * 8192), 16, 0, 0); } while (0)
; #define PG8_LDA(dst, b, h) do { _Pragma("unroll") for (int m = 0; m < 4; ++m) _Pragma("unroll") for (int k = 0; k < 2; ++k) dst[m][k] = *(const PG8_LAS bf16x8*)(lds + PG8_SA(b, h) + aoff + m * 2048 + k * 1024); } while (0)
; #define PG8_LDB(dst, b, h) do { _Pragma("unroll") for (int n = 0; n < 2; ++n) _Pragma("unroll") for (int k = 0; k < 2; ++k) dst[n][k] = *(const PG8_LAS bf16x8*)(lds + PG8_SB(b, h) + boff + n * 2048 + k * 1024); } while (0)
; #define PG8_MMA(ai, bj, At, Bt) do { __builtin_amdgcn_s_setprio(1); _Pragma("unroll") for (int m = 0; m < 4; ++m) _Pragma("unroll") for (int n = 0; n < 2; ++n) _Pragma("unroll") for (int k = 0; k < 2; ++k) \
;         acc[ai][bj][m][n] = __builtin_amdgcn_mfma_f32_16x16x32_bf16(Bt[n][k], At[m][k], acc[ai][bj][m][n], 0, 0, 0); __builtin_amdgcn_s_setprio(0); } while (0)
; #define PG8_WAIT_V(n) asm volatile("s_waitcnt vmcnt(" #n ")" ::: "memory")
; #define PG8_WAIT_L(n) asm volatile("s_waitcnt lgkmcnt(" #n ")" ::: "memory")
; #define PG8_BAR __builtin_amdgcn_s_barrier()
; #define PG8_SCHED __builtin_amdgcn_sched_barrier(0)
; template <class Epi, class Sched, bool ALIGN_EPI = false, bool SP2 = false>
; __device__ __forceinline__ void gemm_phase(PG8_LAS unsigned char* lds, const Gemm g, const Sched& S, const Epi& E) {
;     ...
;             PG8_WAIT_V(8); PG8_WAIT_L(0); PG8_BAR; PG8_MMA(1, 0, At, B0); PG8_MMA(1, 1, At, B1); PG8_BAR; PG8_SCHED;
;             PG8_LDB(B0, 1, 0); PG8_LDB(B1, 1, 1); PG8_SCHED; PG8_LDA(At, 1, 0); PG8_STAGE(PG8_SA(0, 1), a2 + hstep, voffA);
;             PG8_WAIT_V(8); PG8_WAIT_L(0); PG8_BAR; PG8_MMA(0, 0, At, B0); PG8_MMA(0, 1, At, B1); PG8_BAR; PG8_SCHED;
	s_setprio 1
	s_waitcnt lgkmcnt(0)
	v_mfma_f32_16x16x32_bf16 v[60:63], v[140:143], v[198:201], 0
	v_mfma_f32_16x16x32_bf16 v[56:59], v[172:175], v[198:201], 0
	v_mfma_f32_16x16x32_bf16 v[48:51], v[140:143], v[206:209], 0
	v_mfma_f32_16x16x32_bf16 v[40:43], v[172:175], v[206:209], 0
	v_mfma_f32_16x16x32_bf16 v[32:35], v[140:143], v[214:217], 0
	v_mfma_f32_16x16x32_bf16 v[24:27], v[172:175], v[214:217], 0
	v_mfma_f32_16x16x32_bf16 v[16:19], v[140:143], v[222:225], 0
	v_mfma_f32_16x16x32_bf16 v[8:11], v[172:175], v[222:225], 0
	v_mfma_f32_16x16x32_bf16 v[60:63], v[168:171], v[202:205], v[60:63]
	v_mfma_f32_16x16x32_bf16 v[56:59], v[176:179], v[202:205], v[56:59]
	v_mfma_f32_16x16x32_bf16 v[48:51], v[168:171], v[210:213], v[48:51]
	v_mfma_f32_16x16x32_bf16 v[40:43], v[176:179], v[210:213], v[40:43]
	v_mfma_f32_16x16x32_bf16 v[32:35], v[168:171], v[218:221], v[32:35]
	v_mfma_f32_16x16x32_bf16 v[24:27], v[176:179], v[218:221], v[24:27]
	v_mfma_f32_16x16x32_bf16 v[16:19], v[168:171], v[226:229], v[16:19]
	v_mfma_f32_16x16x32_bf16 v[8:11], v[176:179], v[226:229], v[8:11]
	v_mfma_f32_16x16x32_bf16 v[52:55], v[180:183], v[198:201], 0
	v_mfma_f32_16x16x32_bf16 v[44:47], v[188:191], v[198:201], 0
	v_mfma_f32_16x16x32_bf16 v[36:39], v[180:183], v[206:209], 0
	v_mfma_f32_16x16x32_bf16 v[28:31], v[188:191], v[206:209], 0
	v_mfma_f32_16x16x32_bf16 v[20:23], v[180:183], v[214:217], 0
	v_mfma_f32_16x16x32_bf16 v[12:15], v[188:191], v[214:217], 0
	v_mfma_f32_16x16x32_bf16 v[4:7], v[180:183], v[222:225], 0
	v_mfma_f32_16x16x32_bf16 v[0:3], v[188:191], v[222:225], 0
	v_mfma_f32_16x16x32_bf16 v[52:55], v[184:187], v[202:205], v[52:55]
	v_mfma_f32_16x16x32_bf16 v[44:47], v[192:195], v[202:205], v[44:47]
	v_mfma_f32_16x16x32_bf16 v[36:39], v[184:187], v[210:213], v[36:39]
	v_mfma_f32_16x16x32_bf16 v[28:31], v[192:195], v[210:213], v[28:31]
	v_mfma_f32_16x16x32_bf16 v[20:23], v[184:187], v[218:221], v[20:23]
	v_mfma_f32_16x16x32_bf16 v[12:15], v[192:195], v[218:221], v[12:15]
	v_mfma_f32_16x16x32_bf16 v[4:7], v[184:187], v[226:229], v[4:7]
	v_mfma_f32_16x16x32_bf16 v[0:3], v[192:195], v[226:229], v[0:3]
	s_setprio 0
	s_barrier
	s_add_i32 s89, 0, 0x18000
	v_add_u32_e32 v128, s89, v161
	s_add_i32 s90, 0, 0x1c000
	ds_read_b128 v[140:143], v128
	ds_read_b128 v[168:171], v128 offset:1024
	ds_read_b128 v[172:175], v128 offset:2048
	ds_read_b128 v[176:179], v128 offset:3072
	v_add_u32_e32 v128, s90, v161
	ds_read_b128 v[180:183], v128
	ds_read_b128 v[184:187], v128 offset:1024
	ds_read_b128 v[188:191], v128 offset:2048
	ds_read_b128 v[192:195], v128 offset:3072
	s_add_u32 s62, s62, 0x40000
	s_addc_u32 s63, s63, 0
	s_mov_b32 m0, s73
	v_lshl_add_u64 v[238:239], s[62:63], 0, v[144:145]
	ds_read_b128 v[198:201], v165 offset:32768
	ds_read_b128 v[202:205], v165 offset:33792
	ds_read_b128 v[206:209], v165 offset:34816
	ds_read_b128 v[210:213], v165 offset:35840
	ds_read_b128 v[214:217], v165 offset:36864
	ds_read_b128 v[218:221], v165 offset:37888
	ds_read_b128 v[222:225], v165 offset:38912
	ds_read_b128 v[226:229], v165 offset:39936
	global_load_lds_dwordx4 v[238:239], off
	v_lshl_add_u64 v[238:239], s[62:63], 0, v[148:149]
	s_mov_b32 m0, s74
	s_nop 0
	global_load_lds_dwordx4 v[238:239], off
	s_waitcnt vmcnt(8)
	s_waitcnt lgkmcnt(0)
	s_barrier
	s_setprio 1
	s_waitcnt lgkmcnt(0)
	v_mfma_f32_16x16x32_bf16 v[124:127], v[140:143], v[198:201], v[124:127]
	v_mfma_f32_16x16x32_bf16 v[120:123], v[172:175], v[198:201], v[120:123]
	v_mfma_f32_16x16x32_bf16 v[108:111], v[140:143], v[206:209], v[108:111]
	v_mfma_f32_16x16x32_bf16 v[104:107], v[172:175], v[206:209], v[104:107]
	v_mfma_f32_16x16x32_bf16 v[92:95], v[140:143], v[214:217], v[92:95]
	v_mfma_f32_16x16x32_bf16 v[88:91], v[172:175], v[214:217], v[88:91]
	v_mfma_f32_16x16x32_bf16 v[76:79], v[140:143], v[222:225], v[76:79]
	v_mfma_f32_16x16x32_bf16 v[72:75], v[172:175], v[222:225], v[72:75]
	v_mfma_f32_16x16x32_bf16 v[124:127], v[168:171], v[202:205], v[124:127]
	v_mfma_f32_16x16x32_bf16 v[120:123], v[176:179], v[202:205], v[120:123]
	v_mfma_f32_16x16x32_bf16 v[108:111], v[168:171], v[210:213], v[108:111]
	v_mfma_f32_16x16x32_bf16 v[104:107], v[176:179], v[210:213], v[104:107]
	v_mfma_f32_16x16x32_bf16 v[92:95], v[168:171], v[218:221], v[92:95]
	v_mfma_f32_16x16x32_bf16 v[88:91], v[176:179], v[218:221], v[88:91]
	v_mfma_f32_16x16x32_bf16 v[76:79], v[168:171], v[226:229], v[76:79]
	v_mfma_f32_16x16x32_bf16 v[72:75], v[176:179], v[226:229], v[72:75]
	v_mfma_f32_16x16x32_bf16 v[116:119], v[180:183], v[198:201], v[116:119]
	v_mfma_f32_16x16x32_bf16 v[112:115], v[188:191], v[198:201], v[112:115]
	v_mfma_f32_16x16x32_bf16 v[100:103], v[180:183], v[206:209], v[100:103]
	v_mfma_f32_16x16x32_bf16 v[96:99], v[188:191], v[206:209], v[96:99]
	v_mfma_f32_16x16x32_bf16 v[84:87], v[180:183], v[214:217], v[84:87]
	v_mfma_f32_16x16x32_bf16 v[80:83], v[188:191], v[214:217], v[80:83]
	v_mfma_f32_16x16x32_bf16 v[68:71], v[180:183], v[222:225], v[68:71]
	v_mfma_f32_16x16x32_bf16 v[64:67], v[188:191], v[222:225], v[64:67]
	v_mfma_f32_16x16x32_bf16 v[116:119], v[184:187], v[202:205], v[116:119]
	v_mfma_f32_16x16x32_bf16 v[112:115], v[192:195], v[202:205], v[112:115]
	v_mfma_f32_16x16x32_bf16 v[100:103], v[184:187], v[210:213], v[100:103]
	v_mfma_f32_16x16x32_bf16 v[96:99], v[192:195], v[210:213], v[96:99]
	v_mfma_f32_16x16x32_bf16 v[84:87], v[184:187], v[218:221], v[84:87]
	v_mfma_f32_16x16x32_bf16 v[80:83], v[192:195], v[218:221], v[80:83]
	v_mfma_f32_16x16x32_bf16 v[68:71], v[184:187], v[226:229], v[68:71]
	v_mfma_f32_16x16x32_bf16 v[64:67], v[192:195], v[226:229], v[64:67]
	s_setprio 0
	s_barrier
; #define PG8_STAGE(bufoff, gbase, voff) do { _Pragma("unroll") for (int _i = 0; _i < 2; ++_i) \
;         __builtin_amdgcn_global_load_lds((const unsigned*)((const char*)(gbase) + (voff)[_i]), (PG8_LAS unsigned*)(lds + (bufoff) + ldsw + _i * 8192), 16, 0, 0); } while (0)
; #define PG8_LDA(dst, b, h) do { _Pragma("unroll") for (int m = 0; m < 4; ++m) _Pragma("unroll") for (int k = 0; k < 2; ++k) dst[m][k] = *(const PG8_LAS bf16x8*)(lds + PG8_SA(b, h) + aoff + m * 2048 + k * 1024); } while (0)
; #define PG8_LDB(dst, b, h) do { _Pragma("unroll") for (int n = 0; n < 2; ++n) _Pragma("unroll") for (int k = 0; k < 2; ++k) dst[n][k] = *(const PG8_LAS bf16x8*)(lds + PG8_SB(b, h) + boff + n * 2048 + k * 1024); } while (0)
; #define PG8_MMA(ai, bj, At, Bt) do { __builtin_amdgcn_s_setprio(1); _Pragma("unroll") for (int m = 0; m < 4; ++m) _Pragma("unroll") for (int n = 0; n < 2; ++n) _Pragma("unroll") for (int k = 0; k < 2; ++k) \
;         acc[ai][bj][m][n] = __builtin_amdgcn_mfma_f32_16x16x32_bf16(Bt[n][k], At[m][k], acc[ai][bj][m][n], 0, 0, 0); __builtin_amdgcn_s_setprio(0); } while (0)
; #define PG8_WAIT_V(n) asm volatile("s_waitcnt vmcnt(" #n ")" ::: "memory")
; template <class Epi, class Sched, bool ALIGN_EPI = false, bool SP2 = false>
; __device__ __forceinline__ void gemm_phase(PG8_LAS unsigned char* lds, const Gemm g, const Sched& S, const Epi& E) {
;     ...
;             PG8_LDB(B0, 0, 0); PG8_LDB(B1, 0, 1); PG8_SCHED; PG8_LDA(At, 0, 0); PG8_STAGE(PG8_SA(1, 1), a1 + hstep, voffA);
;             PG8_WAIT_V(8); PG8_WAIT_L(0); PG8_BAR; PG8_MMA(0, 0, At, B0); PG8_MMA(0, 1, At, B1); PG8_BAR; PG8_SCHED;
;             PG8_LDA(At, 0, 1); PG8_STAGE(PG8_SB(0, 0), b2, voffB); PG8_STAGE(PG8_SB(0, 1), b2 + hstep, voffB); PG8_STAGE(PG8_SA(0, 0), a2, voffA);
;             PG8_WAIT_V(8); PG8_WAIT_L(0); PG8_BAR; PG8_MMA(1, 0, At, B0); PG8_MMA(1, 1, At, B1); PG8_BAR; PG8_SCHED;
;             PG8_LDB(B0, 1, 0); PG8_LDB(B1, 1, 1); PG8_SCHED; PG8_LDA(At, 1, 0); PG8_STAGE(PG8_SA(0, 1), a2 + hstep, voffA);
;             PG8_WAIT_V(8); PG8_WAIT_L(0); PG8_BAR; PG8_MMA(0, 0, At, B0); PG8_MMA(0, 1, At, B1); PG8_BAR; PG8_SCHED;
;             PG8_LDA(At, 1, 1); PG8_STAGE(PG8_SB(1, 0), b3, voffB); PG8_STAGE(PG8_SB(1, 1), b3 + hstep, voffB); PG8_STAGE(PG8_SA(1, 0), a3, voffA);
;             PG8_WAIT_V(8); PG8_WAIT_L(0); PG8_BAR; PG8_MMA(1, 0, At, B0); PG8_MMA(1, 1, At, B1); PG8_BAR; PG8_SCHED;
	s_add_i32 s62, s89, s70
	v_lshl_add_u64 v[230:231], v[230:231], 0, s[18:19]
	s_mov_b32 m0, s62
	ds_read_b128 v[198:201], v165 offset:49152
	ds_read_b128 v[202:205], v165 offset:50176
	ds_read_b128 v[206:209], v165 offset:51200
	ds_read_b128 v[210:213], v165 offset:52224
	ds_read_b128 v[214:217], v165 offset:53248
	ds_read_b128 v[218:221], v165 offset:54272
	ds_read_b128 v[222:225], v165 offset:55296
	ds_read_b128 v[226:229], v165 offset:56320
	global_load_lds_dwordx4 v[230:231], off
	s_add_i32 m0, s62, 0x2000
	s_add_u32 s34, s34, 0x40080
	v_lshl_add_u64 v[230:231], v[232:233], 0, s[18:19]
	s_addc_u32 s35, s35, 0
	s_add_i32 s62, s90, s70
	global_load_lds_dwordx4 v[230:231], off
	v_lshl_add_u64 v[230:231], s[34:35], 0, v[146:147]
	s_mov_b32 m0, s62
	s_nop 0
	global_load_lds_dwordx4 v[230:231], off
	v_lshl_add_u64 v[230:231], s[34:35], 0, v[150:151]
	s_add_i32 m0, s62, 0x2000
	s_nop 0
	global_load_lds_dwordx4 v[230:231], off
	v_lshl_add_u64 v[230:231], v[234:235], 0, s[18:19]
	s_mov_b32 m0, s75
	s_nop 0
	global_load_lds_dwordx4 v[230:231], off
	v_lshl_add_u64 v[230:231], v[236:237], 0, s[18:19]
	s_mov_b32 m0, s76
	s_nop 0
	global_load_lds_dwordx4 v[230:231], off
	s_waitcnt vmcnt(8)
	s_waitcnt lgkmcnt(0)
	s_barrier
	s_setprio 1
	s_waitcnt lgkmcnt(0)
	v_mfma_f32_16x16x32_bf16 v[60:63], v[140:143], v[198:201], v[60:63]
	v_mfma_f32_16x16x32_bf16 v[56:59], v[172:175], v[198:201], v[56:59]
	v_mfma_f32_16x16x32_bf16 v[48:51], v[140:143], v[206:209], v[48:51]
	v_mfma_f32_16x16x32_bf16 v[40:43], v[172:175], v[206:209], v[40:43]
	v_mfma_f32_16x16x32_bf16 v[32:35], v[140:143], v[214:217], v[32:35]
	v_mfma_f32_16x16x32_bf16 v[24:27], v[172:175], v[214:217], v[24:27]
	v_mfma_f32_16x16x32_bf16 v[16:19], v[140:143], v[222:225], v[16:19]
	v_mfma_f32_16x16x32_bf16 v[8:11], v[172:175], v[222:225], v[8:11]
	v_mfma_f32_16x16x32_bf16 v[60:63], v[168:171], v[202:205], v[60:63]
	v_mfma_f32_16x16x32_bf16 v[56:59], v[176:179], v[202:205], v[56:59]
	v_mfma_f32_16x16x32_bf16 v[48:51], v[168:171], v[210:213], v[48:51]
	v_mfma_f32_16x16x32_bf16 v[40:43], v[176:179], v[210:213], v[40:43]
	v_mfma_f32_16x16x32_bf16 v[32:35], v[168:171], v[218:221], v[32:35]
	v_mfma_f32_16x16x32_bf16 v[24:27], v[176:179], v[218:221], v[24:27]
	v_mfma_f32_16x16x32_bf16 v[16:19], v[168:171], v[226:229], v[16:19]
	v_mfma_f32_16x16x32_bf16 v[8:11], v[176:179], v[226:229], v[8:11]
	v_mfma_f32_16x16x32_bf16 v[52:55], v[180:183], v[198:201], v[52:55]
	v_mfma_f32_16x16x32_bf16 v[44:47], v[188:191], v[198:201], v[44:47]
	v_mfma_f32_16x16x32_bf16 v[36:39], v[180:183], v[206:209], v[36:39]
	v_mfma_f32_16x16x32_bf16 v[28:31], v[188:191], v[206:209], v[28:31]
	v_mfma_f32_16x16x32_bf16 v[20:23], v[180:183], v[214:217], v[20:23]
	v_mfma_f32_16x16x32_bf16 v[12:15], v[188:191], v[214:217], v[12:15]
	v_mfma_f32_16x16x32_bf16 v[4:7], v[180:183], v[222:225], v[4:7]
	v_mfma_f32_16x16x32_bf16 v[0:3], v[188:191], v[222:225], v[0:3]
	v_mfma_f32_16x16x32_bf16 v[52:55], v[184:187], v[202:205], v[52:55]
	v_mfma_f32_16x16x32_bf16 v[44:47], v[192:195], v[202:205], v[44:47]
	v_mfma_f32_16x16x32_bf16 v[36:39], v[184:187], v[210:213], v[36:39]
	v_mfma_f32_16x16x32_bf16 v[28:31], v[192:195], v[210:213], v[28:31]
	v_mfma_f32_16x16x32_bf16 v[20:23], v[184:187], v[218:221], v[20:23]
	v_mfma_f32_16x16x32_bf16 v[12:15], v[192:195], v[218:221], v[12:15]
	v_mfma_f32_16x16x32_bf16 v[4:7], v[184:187], v[226:229], v[4:7]
	v_mfma_f32_16x16x32_bf16 v[0:3], v[192:195], v[226:229], v[0:3]
	s_setprio 0
	s_barrier
	s_add_i32 s88, s88, 2
	s_add_u32 s20, s20, 0x100
	s_addc_u32 s21, s21, 0
	s_add_u32 s86, s86, 0x100
	s_addc_u32 s87, s87, 0
	s_cmp_gt_u32 s88, 13
.LBB0_1200:
	ds_read_b128 v[140:143], v163
	ds_read_b128 v[168:171], v163 offset:1024
	ds_read_b128 v[172:175], v163 offset:2048
	ds_read_b128 v[176:179], v163 offset:3072
	ds_read_b128 v[180:183], v164
	ds_read_b128 v[184:187], v164 offset:1024
	ds_read_b128 v[188:191], v164 offset:2048
	ds_read_b128 v[192:195], v164 offset:3072
	s_add_u32 s34, s20, 0xfffc0080
	s_addc_u32 s35, s21, -1
	s_cmp_eq_u32 s88, 12
	s_cselect_b32 s63, s1, s35
	s_cselect_b32 s62, s57, s34
	s_cselect_b32 s35, s55, s87
	s_cselect_b32 s34, s85, s86
	v_lshl_add_u64 v[230:231], s[20:21], 0, v[132:133]
	s_add_i32 m0, s71, 0xc000
	ds_read_b128 v[198:201], v165
	ds_read_b128 v[202:205], v165 offset:1024
	ds_read_b128 v[206:209], v165 offset:2048
	ds_read_b128 v[210:213], v165 offset:3072
	ds_read_b128 v[214:217], v165 offset:4096
	ds_read_b128 v[218:221], v165 offset:5120
	ds_read_b128 v[222:225], v165 offset:6144
	ds_read_b128 v[226:229], v165 offset:7168
	global_load_lds_dwordx4 v[230:231], off
	v_lshl_add_u64 v[230:231], s[20:21], 0, v[134:135]
	s_add_i32 m0, s71, 0xe000
	s_nop 0
	global_load_lds_dwordx4 v[230:231], off
	s_waitcnt vmcnt(8)
	s_waitcnt lgkmcnt(0)
	s_barrier
; #define PG8_STAGE(bufoff, gbase, voff) do { _Pragma("unroll") for (int _i = 0; _i < 2; ++_i) \
;         __builtin_amdgcn_global_load_lds((const unsigned*)((const char*)(gbase) + (voff)[_i]), (PG8_LAS unsigned*)(lds + (bufoff) + ldsw + _i * 8192), 16, 0, 0); } while (0)
; #define PG8_LDA(dst, b, h) do { _Pragma("unroll") for (int m = 0; m < 4; ++m) _Pragma("unroll") for (int k = 0; k < 2; ++k) dst[m][k] = *(const PG8_LAS bf16x8*)(lds + PG8_SA(b, h) + aoff + m * 2048 + k * 1024); } while (0)
; #define PG8_MMA(ai, bj, At, Bt) do { __builtin_amdgcn_s_setprio(1); _Pragma("unroll") for (int m = 0; m < 4; ++m) _Pragma("unroll") for (int n = 0; n < 2; ++n) _Pragma("unroll") for (int k = 0; k < 2; ++k) \
;         acc[ai][bj][m][n] = __builtin_amdgcn_mfma_f32_16x16x32_bf16(Bt[n][k], At[m][k], acc[ai][bj][m][n], 0, 0, 0); __builtin_amdgcn_s_setprio(0); } while (0)
; #define PG8_WAIT_V(n) asm volatile("s_waitcnt vmcnt(" #n ")" ::: "memory")
; #define PG8_WAIT_L(n) asm volatile("s_waitcnt lgkmcnt(" #n ")" ::: "memory")
; #define PG8_BAR __builtin_amdgcn_s_barrier()
; #define PG8_SCHED __builtin_amdgcn_sched_barrier(0)
; template <class Epi, class Sched, bool ALIGN_EPI = false, bool SP2 = false>
; __device__ __forceinline__ void gemm_phase(PG8_LAS unsigned char* lds, const Gemm g, const Sched& S, const Epi& E) {
;     ...
;             PG8_WAIT_V(8); PG8_WAIT_L(0); PG8_BAR; PG8_MMA(0, 0, At, B0); PG8_MMA(0, 1, At, B1); PG8_BAR; PG8_SCHED;
;             PG8_LDA(At, 0, 1); PG8_STAGE(PG8_SB(0, 0), b2, voffB); PG8_STAGE(PG8_SB(0, 1), b2 + hstep, voffB); PG8_STAGE(PG8_SA(0, 0), a2, voffA);
;             PG8_WAIT_V(8); PG8_WAIT_L(0); PG8_BAR; PG8_MMA(1, 0, At, B0); PG8_MMA(1, 1, At, B1); PG8_BAR; PG8_SCHED;
	s_setprio 1
	s_waitcnt lgkmcnt(0)
	v_mfma_f32_16x16x32_bf16 v[124:127], v[140:143], v[198:201], v[124:127]
	v_mfma_f32_16x16x32_bf16 v[120:123], v[172:175], v[198:201], v[120:123]
	v_mfma_f32_16x16x32_bf16 v[108:111], v[140:143], v[206:209], v[108:111]
	v_mfma_f32_16x16x32_bf16 v[104:107], v[172:175], v[206:209], v[104:107]
	v_mfma_f32_16x16x32_bf16 v[92:95], v[140:143], v[214:217], v[92:95]
	v_mfma_f32_16x16x32_bf16 v[88:91], v[172:175], v[214:217], v[88:91]
	v_mfma_f32_16x16x32_bf16 v[76:79], v[140:143], v[222:225], v[76:79]
	v_mfma_f32_16x16x32_bf16 v[72:75], v[172:175], v[222:225], v[72:75]
	v_mfma_f32_16x16x32_bf16 v[124:127], v[168:171], v[202:205], v[124:127]
	v_mfma_f32_16x16x32_bf16 v[120:123], v[176:179], v[202:205], v[120:123]
	v_mfma_f32_16x16x32_bf16 v[108:111], v[168:171], v[210:213], v[108:111]
	v_mfma_f32_16x16x32_bf16 v[104:107], v[176:179], v[210:213], v[104:107]
	v_mfma_f32_16x16x32_bf16 v[92:95], v[168:171], v[218:221], v[92:95]
	v_mfma_f32_16x16x32_bf16 v[88:91], v[176:179], v[218:221], v[88:91]
	v_mfma_f32_16x16x32_bf16 v[76:79], v[168:171], v[226:229], v[76:79]
	v_mfma_f32_16x16x32_bf16 v[72:75], v[176:179], v[226:229], v[72:75]
	v_mfma_f32_16x16x32_bf16 v[116:119], v[180:183], v[198:201], v[116:119]
	v_mfma_f32_16x16x32_bf16 v[112:115], v[188:191], v[198:201], v[112:115]
	v_mfma_f32_16x16x32_bf16 v[100:103], v[180:183], v[206:209], v[100:103]
	v_mfma_f32_16x16x32_bf16 v[96:99], v[188:191], v[206:209], v[96:99]
	v_mfma_f32_16x16x32_bf16 v[84:87], v[180:183], v[214:217], v[84:87]
	v_mfma_f32_16x16x32_bf16 v[80:83], v[188:191], v[214:217], v[80:83]
	v_mfma_f32_16x16x32_bf16 v[68:71], v[180:183], v[222:225], v[68:71]
	v_mfma_f32_16x16x32_bf16 v[64:67], v[188:191], v[222:225], v[64:67]
	v_mfma_f32_16x16x32_bf16 v[116:119], v[184:187], v[202:205], v[116:119]
	v_mfma_f32_16x16x32_bf16 v[112:115], v[192:195], v[202:205], v[112:115]
	v_mfma_f32_16x16x32_bf16 v[100:103], v[184:187], v[210:213], v[100:103]
	v_mfma_f32_16x16x32_bf16 v[96:99], v[192:195], v[210:213], v[96:99]
	v_mfma_f32_16x16x32_bf16 v[84:87], v[184:187], v[218:221], v[84:87]
	v_mfma_f32_16x16x32_bf16 v[80:83], v[192:195], v[218:221], v[80:83]
	v_mfma_f32_16x16x32_bf16 v[68:71], v[184:187], v[226:229], v[68:71]
	v_mfma_f32_16x16x32_bf16 v[64:67], v[192:195], v[226:229], v[64:67]
	s_setprio 0
	s_barrier
	s_add_i32 s89, s77, s70
	v_lshl_add_u64 v[230:231], s[34:35], 0, v[146:147]
	s_mov_b32 m0, s89
	ds_read_b128 v[198:201], v165 offset:16384
	ds_read_b128 v[202:205], v165 offset:17408
	ds_read_b128 v[206:209], v165 offset:18432
	ds_read_b128 v[210:213], v165 offset:19456
	ds_read_b128 v[214:217], v165 offset:20480
	ds_read_b128 v[218:221], v165 offset:21504
	ds_read_b128 v[222:225], v165 offset:22528
	ds_read_b128 v[226:229], v165 offset:23552
	global_load_lds_dwordx4 v[230:231], off
	s_add_i32 m0, s89, 0x2000
	s_add_u32 s90, s34, 0x40000
	v_lshl_add_u64 v[232:233], s[34:35], 0, v[150:151]
	s_addc_u32 s91, s35, 0
	s_add_i32 s89, s78, s70
	global_load_lds_dwordx4 v[232:233], off
	v_lshl_add_u64 v[234:235], s[90:91], 0, v[146:147]
	s_mov_b32 m0, s89
	v_lshl_add_u64 v[236:237], s[62:63], 0, v[148:149]
	global_load_lds_dwordx4 v[234:235], off
	v_lshl_add_u64 v[234:235], s[90:91], 0, v[150:151]
	s_add_i32 m0, s89, 0x2000
	s_nop 0
	global_load_lds_dwordx4 v[234:235], off
	v_lshl_add_u64 v[234:235], s[62:63], 0, v[144:145]
	s_mov_b32 m0, s71
	s_nop 0
	global_load_lds_dwordx4 v[234:235], off
	s_mov_b32 m0, s72
	s_nop 0
	global_load_lds_dwordx4 v[236:237], off
	s_waitcnt vmcnt(8)
	s_waitcnt lgkmcnt(0)
	s_barrier
	s_setprio 1
	s_waitcnt lgkmcnt(0)
	v_mfma_f32_16x16x32_bf16 v[60:63], v[140:143], v[198:201], v[60:63]
	v_mfma_f32_16x16x32_bf16 v[56:59], v[172:175], v[198:201], v[56:59]
	v_mfma_f32_16x16x32_bf16 v[48:51], v[140:143], v[206:209], v[48:51]
	v_mfma_f32_16x16x32_bf16 v[40:43], v[172:175], v[206:209], v[40:43]
	v_mfma_f32_16x16x32_bf16 v[32:35], v[140:143], v[214:217], v[32:35]
	v_mfma_f32_16x16x32_bf16 v[24:27], v[172:175], v[214:217], v[24:27]
	v_mfma_f32_16x16x32_bf16 v[16:19], v[140:143], v[222:225], v[16:19]
	v_mfma_f32_16x16x32_bf16 v[8:11], v[172:175], v[222:225], v[8:11]
	v_mfma_f32_16x16x32_bf16 v[60:63], v[168:171], v[202:205], v[60:63]
	v_mfma_f32_16x16x32_bf16 v[56:59], v[176:179], v[202:205], v[56:59]
	v_mfma_f32_16x16x32_bf16 v[48:51], v[168:171], v[210:213], v[48:51]
	v_mfma_f32_16x16x32_bf16 v[40:43], v[176:179], v[210:213], v[40:43]
	v_mfma_f32_16x16x32_bf16 v[32:35], v[168:171], v[218:221], v[32:35]
	v_mfma_f32_16x16x32_bf16 v[24:27], v[176:179], v[218:221], v[24:27]
	v_mfma_f32_16x16x32_bf16 v[16:19], v[168:171], v[226:229], v[16:19]
	v_mfma_f32_16x16x32_bf16 v[8:11], v[176:179], v[226:229], v[8:11]
	v_mfma_f32_16x16x32_bf16 v[52:55], v[180:183], v[198:201], v[52:55]
	v_mfma_f32_16x16x32_bf16 v[44:47], v[188:191], v[198:201], v[44:47]
	v_mfma_f32_16x16x32_bf16 v[36:39], v[180:183], v[206:209], v[36:39]
	v_mfma_f32_16x16x32_bf16 v[28:31], v[188:191], v[206:209], v[28:31]
	v_mfma_f32_16x16x32_bf16 v[20:23], v[180:183], v[214:217], v[20:23]
	v_mfma_f32_16x16x32_bf16 v[12:15], v[188:191], v[214:217], v[12:15]
	v_mfma_f32_16x16x32_bf16 v[4:7], v[180:183], v[222:225], v[4:7]
	v_mfma_f32_16x16x32_bf16 v[0:3], v[188:191], v[222:225], v[0:3]
	v_mfma_f32_16x16x32_bf16 v[52:55], v[184:187], v[202:205], v[52:55]
	v_mfma_f32_16x16x32_bf16 v[44:47], v[192:195], v[202:205], v[44:47]
	v_mfma_f32_16x16x32_bf16 v[36:39], v[184:187], v[210:213], v[36:39]
	v_mfma_f32_16x16x32_bf16 v[28:31], v[192:195], v[210:213], v[28:31]
	v_mfma_f32_16x16x32_bf16 v[20:23], v[184:187], v[218:221], v[20:23]
	v_mfma_f32_16x16x32_bf16 v[12:15], v[192:195], v[218:221], v[12:15]
	v_mfma_f32_16x16x32_bf16 v[4:7], v[184:187], v[226:229], v[4:7]
	v_mfma_f32_16x16x32_bf16 v[0:3], v[192:195], v[226:229], v[0:3]
	s_setprio 0
	s_barrier
; #define PG8_STAGE(bufoff, gbase, voff) do { _Pragma("unroll") for (int _i = 0; _i < 2; ++_i) \
;         __builtin_amdgcn_global_load_lds((const unsigned*)((const char*)(gbase) + (voff)[_i]), (PG8_LAS unsigned*)(lds + (bufoff) + ldsw + _i * 8192), 16, 0, 0); } while (0)
; #define PG8_LDA(dst, b, h) do { _Pragma("unroll") for (int m = 0; m < 4; ++m) _Pragma("unroll") for (int k = 0; k < 2; ++k) dst[m][k] = *(const PG8_LAS bf16x8*)(lds + PG8_SA(b, h) + aoff + m * 2048 + k * 1024); } while (0)
; #define PG8_LDB(dst, b, h) do { _Pragma("unroll") for (int n = 0; n < 2; ++n) _Pragma("unroll") for (int k = 0; k < 2; ++k) dst[n][k] = *(const PG8_LAS bf16x8*)(lds + PG8_SB(b, h) + boff + n * 2048 + k * 1024); } while (0)
; #define PG8_MMA(ai, bj, At, Bt) do { __builtin_amdgcn_s_setprio(1); _Pragma("unroll") for (int m = 0; m < 4; ++m) _Pragma("unroll") for (int n = 0; n < 2; ++n) _Pragma("unroll") for (int k = 0; k < 2; ++k) \
;         acc[ai][bj][m][n] = __builtin_amdgcn_mfma_f32_16x16x32_bf16(Bt[n][k], At[m][k], acc[ai][bj][m][n], 0, 0, 0); __builtin_amdgcn_s_setprio(0); } while (0)
; #define PG8_WAIT_V(n) asm volatile("s_waitcnt vmcnt(" #n ")" ::: "memory")
; #define PG8_WAIT_L(n) asm volatile("s_waitcnt lgkmcnt(" #n ")" ::: "memory")
; #define PG8_BAR __builtin_amdgcn_s_barrier()
; #define PG8_SCHED __builtin_amdgcn_sched_barrier(0)
; template <class Epi, class Sched, bool ALIGN_EPI = false, bool SP2 = false>
; __device__ __forceinline__ void gemm_phase(PG8_LAS unsigned char* lds, const Gemm g, const Sched& S, const Epi& E) {
;     ...
;             PG8_LDB(B0, 1, 0); PG8_LDB(B1, 1, 1); PG8_SCHED; PG8_LDA(At, 1, 0); PG8_STAGE(PG8_SA(0, 1), a2 + hstep, voffA);
;             PG8_WAIT_V(8); PG8_WAIT_L(0); PG8_BAR; PG8_MMA(0, 0, At, B0); PG8_MMA(0, 1, At, B1); PG8_BAR; PG8_SCHED;
	s_add_i32 s89, 0, 0x18000
	v_add_u32_e32 v128, s89, v161
	s_add_i32 s90, 0, 0x1c000
	ds_read_b128 v[140:143], v128
	ds_read_b128 v[168:171], v128 offset:1024
	ds_read_b128 v[172:175], v128 offset:2048
	ds_read_b128 v[176:179], v128 offset:3072
	v_add_u32_e32 v128, s90, v161
	ds_read_b128 v[180:183], v128
	ds_read_b128 v[184:187], v128 offset:1024
	ds_read_b128 v[188:191], v128 offset:2048
	ds_read_b128 v[192:195], v128 offset:3072
	s_add_u32 s62, s62, 0x40000
	s_addc_u32 s63, s63, 0
	s_mov_b32 m0, s73
	v_lshl_add_u64 v[238:239], s[62:63], 0, v[144:145]
	ds_read_b128 v[198:201], v165 offset:32768
	ds_read_b128 v[202:205], v165 offset:33792
	ds_read_b128 v[206:209], v165 offset:34816
	ds_read_b128 v[210:213], v165 offset:35840
	ds_read_b128 v[214:217], v165 offset:36864
	ds_read_b128 v[218:221], v165 offset:37888
	ds_read_b128 v[222:225], v165 offset:38912
	ds_read_b128 v[226:229], v165 offset:39936
	global_load_lds_dwordx4 v[238:239], off
	v_lshl_add_u64 v[238:239], s[62:63], 0, v[148:149]
	s_mov_b32 m0, s74
	s_nop 0
	global_load_lds_dwordx4 v[238:239], off
	s_waitcnt vmcnt(8)
	s_waitcnt lgkmcnt(0)
	s_barrier
	s_setprio 1
	s_waitcnt lgkmcnt(0)
	v_mfma_f32_16x16x32_bf16 v[124:127], v[140:143], v[198:201], v[124:127]
	v_mfma_f32_16x16x32_bf16 v[120:123], v[172:175], v[198:201], v[120:123]
	v_mfma_f32_16x16x32_bf16 v[108:111], v[140:143], v[206:209], v[108:111]
	v_mfma_f32_16x16x32_bf16 v[104:107], v[172:175], v[206:209], v[104:107]
	v_mfma_f32_16x16x32_bf16 v[92:95], v[140:143], v[214:217], v[92:95]
	v_mfma_f32_16x16x32_bf16 v[88:91], v[172:175], v[214:217], v[88:91]
	v_mfma_f32_16x16x32_bf16 v[76:79], v[140:143], v[222:225], v[76:79]
	v_mfma_f32_16x16x32_bf16 v[72:75], v[172:175], v[222:225], v[72:75]
	v_mfma_f32_16x16x32_bf16 v[124:127], v[168:171], v[202:205], v[124:127]
	v_mfma_f32_16x16x32_bf16 v[120:123], v[176:179], v[202:205], v[120:123]
	v_mfma_f32_16x16x32_bf16 v[108:111], v[168:171], v[210:213], v[108:111]
	v_mfma_f32_16x16x32_bf16 v[104:107], v[176:179], v[210:213], v[104:107]
	v_mfma_f32_16x16x32_bf16 v[92:95], v[168:171], v[218:221], v[92:95]
	v_mfma_f32_16x16x32_bf16 v[88:91], v[176:179], v[218:221], v[88:91]
	v_mfma_f32_16x16x32_bf16 v[76:79], v[168:171], v[226:229], v[76:79]
	v_mfma_f32_16x16x32_bf16 v[72:75], v[176:179], v[226:229], v[72:75]
	v_mfma_f32_16x16x32_bf16 v[116:119], v[180:183], v[198:201], v[116:119]
	v_mfma_f32_16x16x32_bf16 v[112:115], v[188:191], v[198:201], v[112:115]
	v_mfma_f32_16x16x32_bf16 v[100:103], v[180:183], v[206:209], v[100:103]
	v_mfma_f32_16x16x32_bf16 v[96:99], v[188:191], v[206:209], v[96:99]
	v_mfma_f32_16x16x32_bf16 v[84:87], v[180:183], v[214:217], v[84:87]
	v_mfma_f32_16x16x32_bf16 v[80:83], v[188:191], v[214:217], v[80:83]
	v_mfma_f32_16x16x32_bf16 v[68:71], v[180:183], v[222:225], v[68:71]
	v_mfma_f32_16x16x32_bf16 v[64:67], v[188:191], v[222:225], v[64:67]
	v_mfma_f32_16x16x32_bf16 v[116:119], v[184:187], v[202:205], v[116:119]
	v_mfma_f32_16x16x32_bf16 v[112:115], v[192:195], v[202:205], v[112:115]
	v_mfma_f32_16x16x32_bf16 v[100:103], v[184:187], v[210:213], v[100:103]
	v_mfma_f32_16x16x32_bf16 v[96:99], v[192:195], v[210:213], v[96:99]
	v_mfma_f32_16x16x32_bf16 v[84:87], v[184:187], v[218:221], v[84:87]
	v_mfma_f32_16x16x32_bf16 v[80:83], v[192:195], v[218:221], v[80:83]
	v_mfma_f32_16x16x32_bf16 v[68:71], v[184:187], v[226:229], v[68:71]
	v_mfma_f32_16x16x32_bf16 v[64:67], v[192:195], v[226:229], v[64:67]
	s_setprio 0
	s_barrier
; #define PG8_STAGE(bufoff, gbase, voff) do { _Pragma("unroll") for (int _i = 0; _i < 2; ++_i) \
;         __builtin_amdgcn_global_load_lds((const unsigned*)((const char*)(gbase) + (voff)[_i]), (PG8_LAS unsigned*)(lds + (bufoff) + ldsw + _i * 8192), 16, 0, 0); } while (0)
; #define PG8_LDA(dst, b, h) do { _Pragma("unroll") for (int m = 0; m < 4; ++m) _Pragma("unroll") for (int k = 0; k < 2; ++k) dst[m][k] = *(const PG8_LAS bf16x8*)(lds + PG8_SA(b, h) + aoff + m * 2048 + k * 1024); } while (0)
; #define PG8_MMA(ai, bj, At, Bt) do { __builtin_amdgcn_s_setprio(1); _Pragma("unroll") for (int m = 0; m < 4; ++m) _Pragma("unroll") for (int n = 0; n < 2; ++n) _Pragma("unroll") for (int k = 0; k < 2; ++k) \
;         acc[ai][bj][m][n] = __builtin_amdgcn_mfma_f32_16x16x32_bf16(Bt[n][k], At[m][k], acc[ai][bj][m][n], 0, 0, 0); __builtin_amdgcn_s_setprio(0); } while (0)
; #define PG8_WAIT_V(n) asm volatile("s_waitcnt vmcnt(" #n ")" ::: "memory")
; #define PG8_WAIT_L(n) asm volatile("s_waitcnt lgkmcnt(" #n ")" ::: "memory")
; #define PG8_BAR __builtin_amdgcn_s_barrier()
; #define PG8_SCHED __builtin_amdgcn_sched_barrier(0)
; template <class Epi, class Sched, bool ALIGN_EPI = false, bool SP2 = false>
; __device__ __forceinline__ void gemm_phase(PG8_LAS unsigned char* lds, const Gemm g, const Sched& S, const Epi& E) {
;     ...
;             PG8_LDA(At, 1, 1); PG8_STAGE(PG8_SB(1, 0), b3, voffB); PG8_STAGE(PG8_SB(1, 1), b3 + hstep, voffB); PG8_STAGE(PG8_SA(1, 0), a3, voffA);
;             PG8_WAIT_V(8); PG8_WAIT_L(0); PG8_BAR; PG8_MMA(1, 0, At, B0); PG8_MMA(1, 1, At, B1); PG8_BAR; PG8_SCHED;
;     ...
;         if constexpr (ALIGN_EPI) { if (wr == 0) PG8_BAR; }
	s_add_i32 s62, s89, s70
	v_lshl_add_u64 v[230:231], v[230:231], 0, s[18:19]
	s_mov_b32 m0, s62
	ds_read_b128 v[198:201], v165 offset:49152
	ds_read_b128 v[202:205], v165 offset:50176
	ds_read_b128 v[206:209], v165 offset:51200
	ds_read_b128 v[210:213], v165 offset:52224
	ds_read_b128 v[214:217], v165 offset:53248
	ds_read_b128 v[218:221], v165 offset:54272
	ds_read_b128 v[222:225], v165 offset:55296
	ds_read_b128 v[226:229], v165 offset:56320
	global_load_lds_dwordx4 v[230:231], off
	s_add_i32 m0, s62, 0x2000
	s_add_u32 s34, s34, 0x40080
	v_lshl_add_u64 v[230:231], v[232:233], 0, s[18:19]
	s_addc_u32 s35, s35, 0
	s_add_i32 s62, s90, s70
	global_load_lds_dwordx4 v[230:231], off
	v_lshl_add_u64 v[230:231], s[34:35], 0, v[146:147]
	s_mov_b32 m0, s62
	s_nop 0
	global_load_lds_dwordx4 v[230:231], off
	v_lshl_add_u64 v[230:231], s[34:35], 0, v[150:151]
	s_add_i32 m0, s62, 0x2000
	s_nop 0
	global_load_lds_dwordx4 v[230:231], off
	v_lshl_add_u64 v[230:231], v[234:235], 0, s[18:19]
	s_mov_b32 m0, s75
	s_nop 0
	global_load_lds_dwordx4 v[230:231], off
	v_lshl_add_u64 v[230:231], v[236:237], 0, s[18:19]
	s_mov_b32 m0, s76
	s_nop 0
	global_load_lds_dwordx4 v[230:231], off
	s_waitcnt vmcnt(8)
	s_waitcnt lgkmcnt(0)
	s_barrier
	s_setprio 1
	s_waitcnt lgkmcnt(0)
	v_mfma_f32_16x16x32_bf16 v[60:63], v[140:143], v[198:201], v[60:63]
	v_mfma_f32_16x16x32_bf16 v[56:59], v[172:175], v[198:201], v[56:59]
	v_mfma_f32_16x16x32_bf16 v[48:51], v[140:143], v[206:209], v[48:51]
	v_mfma_f32_16x16x32_bf16 v[40:43], v[172:175], v[206:209], v[40:43]
	v_mfma_f32_16x16x32_bf16 v[32:35], v[140:143], v[214:217], v[32:35]
	v_mfma_f32_16x16x32_bf16 v[24:27], v[172:175], v[214:217], v[24:27]
	v_mfma_f32_16x16x32_bf16 v[16:19], v[140:143], v[222:225], v[16:19]
	v_mfma_f32_16x16x32_bf16 v[8:11], v[172:175], v[222:225], v[8:11]
	v_mfma_f32_16x16x32_bf16 v[60:63], v[168:171], v[202:205], v[60:63]
	v_mfma_f32_16x16x32_bf16 v[56:59], v[176:179], v[202:205], v[56:59]
	v_mfma_f32_16x16x32_bf16 v[48:51], v[168:171], v[210:213], v[48:51]
	v_mfma_f32_16x16x32_bf16 v[40:43], v[176:179], v[210:213], v[40:43]
	v_mfma_f32_16x16x32_bf16 v[32:35], v[168:171], v[218:221], v[32:35]
	v_mfma_f32_16x16x32_bf16 v[24:27], v[176:179], v[218:221], v[24:27]
	v_mfma_f32_16x16x32_bf16 v[16:19], v[168:171], v[226:229], v[16:19]
	v_mfma_f32_16x16x32_bf16 v[8:11], v[176:179], v[226:229], v[8:11]
	v_mfma_f32_16x16x32_bf16 v[52:55], v[180:183], v[198:201], v[52:55]
	v_mfma_f32_16x16x32_bf16 v[44:47], v[188:191], v[198:201], v[44:47]
	v_mfma_f32_16x16x32_bf16 v[36:39], v[180:183], v[206:209], v[36:39]
	v_mfma_f32_16x16x32_bf16 v[28:31], v[188:191], v[206:209], v[28:31]
	v_mfma_f32_16x16x32_bf16 v[20:23], v[180:183], v[214:217], v[20:23]
	v_mfma_f32_16x16x32_bf16 v[12:15], v[188:191], v[214:217], v[12:15]
	v_mfma_f32_16x16x32_bf16 v[4:7], v[180:183], v[222:225], v[4:7]
	v_mfma_f32_16x16x32_bf16 v[0:3], v[188:191], v[222:225], v[0:3]
	v_mfma_f32_16x16x32_bf16 v[52:55], v[184:187], v[202:205], v[52:55]
	v_mfma_f32_16x16x32_bf16 v[44:47], v[192:195], v[202:205], v[44:47]
	v_mfma_f32_16x16x32_bf16 v[36:39], v[184:187], v[210:213], v[36:39]
	v_mfma_f32_16x16x32_bf16 v[28:31], v[192:195], v[210:213], v[28:31]
	v_mfma_f32_16x16x32_bf16 v[20:23], v[184:187], v[218:221], v[20:23]
	v_mfma_f32_16x16x32_bf16 v[12:15], v[192:195], v[218:221], v[12:15]
	v_mfma_f32_16x16x32_bf16 v[4:7], v[184:187], v[226:229], v[4:7]
	v_mfma_f32_16x16x32_bf16 v[0:3], v[192:195], v[226:229], v[0:3]
	s_setprio 0
	s_barrier
	s_add_i32 s88, s88, 2
	s_add_u32 s20, s20, 0x100
	s_addc_u32 s21, s21, 0
	s_add_u32 s86, s86, 0x100
	s_addc_u32 s87, s87, 0
	s_cmp_gt_u32 s88, 13
	s_cbranch_scc0 .LBB0_1200
	s_and_b64 vcc, exec, s[38:39]
	s_cbranch_vccz .LBB0_1203
	s_barrier

; #define PG8_STAGE(bufoff, gbase, voff) do { _Pragma("unroll") for (int _i = 0; _i < 2; ++_i) \
;         __builtin_amdgcn_global_load_lds((const unsigned*)((const char*)(gbase) + (voff)[_i]), (PG8_LAS unsigned*)(lds + (bufoff) + ldsw + _i * 8192), 16, 0, 0); } while (0)
; #define PG8_LDA(dst, b, h) do { _Pragma("unroll") for (int m = 0; m < 4; ++m) _Pragma("unroll") for (int k = 0; k < 2; ++k) dst[m][k] = *(const PG8_LAS bf16x8*)(lds + PG8_SA(b, h) + aoff + m * 2048 + k * 1024); } while (0)
; #define PG8_LDB(dst, b, h) do { _Pragma("unroll") for (int n = 0; n < 2; ++n) _Pragma("unroll") for (int k = 0; k < 2; ++k) dst[n][k] = *(const PG8_LAS bf16x8*)(lds + PG8_SB(b, h) + boff + n * 2048 + k * 1024); } while (0)
; #define PG8_MMA(ai, bj, At, Bt) do { __builtin_amdgcn_s_setprio(1); _Pragma("unroll") for (int m = 0; m < 4; ++m) _Pragma("unroll") for (int n = 0; n < 2; ++n) _Pragma("unroll") for (int k = 0; k < 2; ++k) \
;         acc[ai][bj][m][n] = __builtin_amdgcn_mfma_f32_16x16x32_bf16(Bt[n][k], At[m][k], acc[ai][bj][m][n], 0, 0, 0); __builtin_amdgcn_s_setprio(0); } while (0)
; #define PG8_WAIT_V(n) asm volatile("s_waitcnt vmcnt(" #n ")" ::: "memory")
; template <class Epi, class Sched, bool ALIGN_EPI = false, bool SP2 = false>
; __device__ __forceinline__ void gemm_phase(PG8_LAS unsigned char* lds, const Gemm g, const Sched& S, const Epi& E) {
;     ...
;         const char* nA = has_next ? (const char*)g.A + (size_t)nxt.pm * tstep : cA; const char* nB = has_next ? (const char*)g.Bt + (size_t)nxt.pn * tstep : cB;
;         for (int t = 0; t < nt; t += 2) {
;             const bool last = (t == nt - 2);
;             const char* a1 = cA + (size_t)(t + 1) * kstep;
;             const char* a2 = last ? nA : cA + (size_t)(t + 2) * kstep; const char* b2 = last ? nB : cB + (size_t)(t + 2) * kstep;
;             const char* a3 = a2 + kstep; const char* b3 = b2 + kstep;
;             if (last && has_next) S.a_ready(nxt);
;             if constexpr (SP2) {
;             PG8_LDB(B0, 0, 0); PG8_LDB(B1, 0, 1); PG8_SCHED; PG8_LDA(At, 0, 0); PG8_STAGE(PG8_SA(1, 1), a1 + hstep, voffA);
;             PG8_WAIT_V(8); PG8_WAIT_L(0); PG8_BAR; PG8_MMA(0, 0, At, B0); PG8_MMA(0, 1, At, B1); PG8_BAR; PG8_SCHED;
;             PG8_LDA(At, 0, 1); PG8_STAGE(PG8_SB(0, 0), b2, voffB); PG8_STAGE(PG8_SB(0, 1), b2 + hstep, voffB); PG8_STAGE(PG8_SA(0, 0), a2, voffA);
.LBB0_1445:
	s_ashr_i32 s15, s14, 31
	s_lshl_b64 s[16:17], s[14:15], 19
	s_add_u32 s16, s49, s16
	s_addc_u32 s17, s50, s17
	s_and_b64 s[18:19], s[4:5], exec
	s_cselect_b32 s15, s17, s21
	s_cselect_b32 s65, s16, s20
	s_ashr_i32 s13, s12, 31
	s_lshl_b64 s[18:19], s[12:13], 19
	s_add_u32 s18, s36, s18
	s_addc_u32 s19, s37, s19
	s_and_b64 s[44:45], s[4:5], exec
	s_cselect_b32 s13, s19, s39
	s_cselect_b32 s66, s18, s38
	s_add_u32 s20, s20, 0x40080
	s_addc_u32 s21, s21, 0
	s_add_u32 s67, s38, 0x100
	s_addc_u32 s68, s39, 0
	s_mov_b32 s69, -2
	ds_read_b128 v[128:131], v153
	ds_read_b128 v[132:135], v153 offset:1024
	ds_read_b128 v[136:139], v153 offset:2048
	ds_read_b128 v[140:143], v153 offset:3072
	ds_read_b128 v[172:175], v155
	ds_read_b128 v[176:179], v155 offset:1024
	ds_read_b128 v[180:183], v155 offset:2048
	ds_read_b128 v[184:187], v155 offset:3072
	s_add_u32 s38, s20, 0xfffc0080
	s_addc_u32 s39, s21, -1
	s_cmp_eq_u32 s69, 12
	s_cselect_b32 s45, s15, s39
	s_cselect_b32 s44, s65, s38
	s_cselect_b32 s39, s13, s68
	s_cselect_b32 s38, s66, s67
	v_lshl_add_u64 v[222:223], s[20:21], 0, v[162:163]
	s_add_i32 m0, s35, 0xc000
	ds_read_b128 v[188:191], v157
	ds_read_b128 v[192:195], v157 offset:1024
	ds_read_b128 v[198:201], v157 offset:2048
	ds_read_b128 v[202:205], v157 offset:3072
	ds_read_b128 v[206:209], v157 offset:4096
	ds_read_b128 v[210:213], v157 offset:5120
	ds_read_b128 v[214:217], v157 offset:6144
	ds_read_b128 v[218:221], v157 offset:7168
	global_load_lds_dwordx4 v[222:223], off
	v_lshl_add_u64 v[222:223], s[20:21], 0, v[164:165]
	s_add_i32 m0, s35, 0xe000
	s_nop 0
	global_load_lds_dwordx4 v[222:223], off
	s_waitcnt vmcnt(8)
	s_waitcnt lgkmcnt(0)
	s_barrier
	s_setprio 1
	s_waitcnt lgkmcnt(0)
	v_mfma_f32_16x16x32_bf16 v[124:127], v[128:131], v[188:191], 0
	v_mfma_f32_16x16x32_bf16 v[120:123], v[136:139], v[188:191], 0
	v_mfma_f32_16x16x32_bf16 v[108:111], v[128:131], v[198:201], 0
	v_mfma_f32_16x16x32_bf16 v[104:107], v[136:139], v[198:201], 0
	v_mfma_f32_16x16x32_bf16 v[96:99], v[128:131], v[206:209], 0
	v_mfma_f32_16x16x32_bf16 v[88:91], v[136:139], v[206:209], 0
	v_mfma_f32_16x16x32_bf16 v[80:83], v[128:131], v[214:217], 0
	v_mfma_f32_16x16x32_bf16 v[72:75], v[136:139], v[214:217], 0
	v_mfma_f32_16x16x32_bf16 v[124:127], v[132:135], v[192:195], v[124:127]
	v_mfma_f32_16x16x32_bf16 v[120:123], v[140:143], v[192:195], v[120:123]
	v_mfma_f32_16x16x32_bf16 v[108:111], v[132:135], v[202:205], v[108:111]
	v_mfma_f32_16x16x32_bf16 v[104:107], v[140:143], v[202:205], v[104:107]
	v_mfma_f32_16x16x32_bf16 v[96:99], v[132:135], v[210:213], v[96:99]
	v_mfma_f32_16x16x32_bf16 v[88:91], v[140:143], v[210:213], v[88:91]
	v_mfma_f32_16x16x32_bf16 v[80:83], v[132:135], v[218:221], v[80:83]
	v_mfma_f32_16x16x32_bf16 v[72:75], v[140:143], v[218:221], v[72:75]
	v_mfma_f32_16x16x32_bf16 v[116:119], v[172:175], v[188:191], 0
	v_mfma_f32_16x16x32_bf16 v[112:115], v[180:183], v[188:191], 0
	v_mfma_f32_16x16x32_bf16 v[100:103], v[172:175], v[198:201], 0
	v_mfma_f32_16x16x32_bf16 v[92:95], v[180:183], v[198:201], 0
	v_mfma_f32_16x16x32_bf16 v[84:87], v[172:175], v[206:209], 0
	v_mfma_f32_16x16x32_bf16 v[76:79], v[180:183], v[206:209], 0
	v_mfma_f32_16x16x32_bf16 v[68:71], v[172:175], v[214:217], 0
	v_mfma_f32_16x16x32_bf16 v[64:67], v[180:183], v[214:217], 0
	v_mfma_f32_16x16x32_bf16 v[116:119], v[176:179], v[192:195], v[116:119]
	v_mfma_f32_16x16x32_bf16 v[112:115], v[184:187], v[192:195], v[112:115]
	v_mfma_f32_16x16x32_bf16 v[100:103], v[176:179], v[202:205], v[100:103]
	v_mfma_f32_16x16x32_bf16 v[92:95], v[184:187], v[202:205], v[92:95]
	v_mfma_f32_16x16x32_bf16 v[84:87], v[176:179], v[210:213], v[84:87]
	v_mfma_f32_16x16x32_bf16 v[76:79], v[184:187], v[210:213], v[76:79]
	v_mfma_f32_16x16x32_bf16 v[68:71], v[176:179], v[218:221], v[68:71]
	v_mfma_f32_16x16x32_bf16 v[64:67], v[184:187], v[218:221], v[64:67]
	s_setprio 0
	s_barrier
	s_add_i32 s70, s60, s51
	v_lshl_add_u64 v[222:223], s[38:39], 0, v[146:147]
	s_mov_b32 m0, s70
	ds_read_b128 v[188:191], v157 offset:16384
	ds_read_b128 v[192:195], v157 offset:17408
	ds_read_b128 v[198:201], v157 offset:18432
	ds_read_b128 v[202:205], v157 offset:19456
	ds_read_b128 v[206:209], v157 offset:20480
	ds_read_b128 v[210:213], v157 offset:21504
	ds_read_b128 v[214:217], v157 offset:22528
	ds_read_b128 v[218:221], v157 offset:23552
	global_load_lds_dwordx4 v[222:223], off
	s_add_i32 m0, s70, 0x2000
	s_add_u32 s70, s38, 0x40000
	v_lshl_add_u64 v[224:225], s[38:39], 0, v[150:151]
	s_addc_u32 s71, s39, 0
	s_add_i32 s72, s61, s51
	global_load_lds_dwordx4 v[224:225], off
	v_lshl_add_u64 v[226:227], s[70:71], 0, v[146:147]
	s_mov_b32 m0, s72
	v_lshl_add_u64 v[228:229], s[44:45], 0, v[148:149]
	global_load_lds_dwordx4 v[226:227], off
	v_lshl_add_u64 v[226:227], s[70:71], 0, v[150:151]
	s_add_i32 m0, s72, 0x2000
	s_nop 0
	global_load_lds_dwordx4 v[226:227], off
	v_lshl_add_u64 v[226:227], s[44:45], 0, v[144:145]
	s_mov_b32 m0, s35
	s_nop 0
	global_load_lds_dwordx4 v[226:227], off
	s_mov_b32 m0, s52
	s_nop 0
	global_load_lds_dwordx4 v[228:229], off
	s_waitcnt vmcnt(8)
	s_waitcnt lgkmcnt(0)
	s_barrier
; #define PG8_STAGE(bufoff, gbase, voff) do { _Pragma("unroll") for (int _i = 0; _i < 2; ++_i) \
;         __builtin_amdgcn_global_load_lds((const unsigned*)((const char*)(gbase) + (voff)[_i]), (PG8_LAS unsigned*)(lds + (bufoff) + ldsw + _i * 8192), 16, 0, 0); } while (0)
; #define PG8_LDA(dst, b, h) do { _Pragma("unroll") for (int m = 0; m < 4; ++m) _Pragma("unroll") for (int k = 0; k < 2; ++k) dst[m][k] = *(const PG8_LAS bf16x8*)(lds + PG8_SA(b, h) + aoff + m * 2048 + k * 1024); } while (0)
; #define PG8_LDB(dst, b, h) do { _Pragma("unroll") for (int n = 0; n < 2; ++n) _Pragma("unroll") for (int k = 0; k < 2; ++k) dst[n][k] = *(const PG8_LAS bf16x8*)(lds + PG8_SB(b, h) + boff + n * 2048 + k * 1024); } while (0)
; #define PG8_MMA(ai, bj, At, Bt) do { __builtin_amdgcn_s_setprio(1); _Pragma("unroll") for (int m = 0; m < 4; ++m) _Pragma("unroll") for (int n = 0; n < 2; ++n) _Pragma("unroll") for (int k = 0; k < 2; ++k) \
;         acc[ai][bj][m][n] = __builtin_amdgcn_mfma_f32_16x16x32_bf16(Bt[n][k], At[m][k], acc[ai][bj][m][n], 0, 0, 0); __builtin_amdgcn_s_setprio(0); } while (0)
; #define PG8_WAIT_V(n) asm volatile("s_waitcnt vmcnt(" #n ")" ::: "memory")
; #define PG8_WAIT_L(n) asm volatile("s_waitcnt lgkmcnt(" #n ")" ::: "memory")
; #define PG8_BAR __builtin_amdgcn_s_barrier()
; #define PG8_SCHED __builtin_amdgcn_sched_barrier(0)
; template <class Epi, class Sched, bool ALIGN_EPI = false, bool SP2 = false>
; __device__ __forceinline__ void gemm_phase(PG8_LAS unsigned char* lds, const Gemm g, const Sched& S, const Epi& E) {
;     ...
;             PG8_WAIT_V(8); PG8_WAIT_L(0); PG8_BAR; PG8_MMA(1, 0, At, B0); PG8_MMA(1, 1, At, B1); PG8_BAR; PG8_SCHED;
;             PG8_LDB(B0, 1, 0); PG8_LDB(B1, 1, 1); PG8_SCHED; PG8_LDA(At, 1, 0); PG8_STAGE(PG8_SA(0, 1), a2 + hstep, voffA);
;             PG8_WAIT_V(8); PG8_WAIT_L(0); PG8_BAR; PG8_MMA(0, 0, At, B0); PG8_MMA(0, 1, At, B1); PG8_BAR; PG8_SCHED;
	s_setprio 1
	s_waitcnt lgkmcnt(0)
	v_mfma_f32_16x16x32_bf16 v[60:63], v[128:131], v[188:191], 0
	v_mfma_f32_16x16x32_bf16 v[56:59], v[136:139], v[188:191], 0
	v_mfma_f32_16x16x32_bf16 v[48:51], v[128:131], v[198:201], 0
	v_mfma_f32_16x16x32_bf16 v[40:43], v[136:139], v[198:201], 0
	v_mfma_f32_16x16x32_bf16 v[32:35], v[128:131], v[206:209], 0
	v_mfma_f32_16x16x32_bf16 v[24:27], v[136:139], v[206:209], 0
	v_mfma_f32_16x16x32_bf16 v[16:19], v[128:131], v[214:217], 0
	v_mfma_f32_16x16x32_bf16 v[8:11], v[136:139], v[214:217], 0
	v_mfma_f32_16x16x32_bf16 v[60:63], v[132:135], v[192:195], v[60:63]
	v_mfma_f32_16x16x32_bf16 v[56:59], v[140:143], v[192:195], v[56:59]
	v_mfma_f32_16x16x32_bf16 v[48:51], v[132:135], v[202:205], v[48:51]
	v_mfma_f32_16x16x32_bf16 v[40:43], v[140:143], v[202:205], v[40:43]
	v_mfma_f32_16x16x32_bf16 v[32:35], v[132:135], v[210:213], v[32:35]
	v_mfma_f32_16x16x32_bf16 v[24:27], v[140:143], v[210:213], v[24:27]
	v_mfma_f32_16x16x32_bf16 v[16:19], v[132:135], v[218:221], v[16:19]
	v_mfma_f32_16x16x32_bf16 v[8:11], v[140:143], v[218:221], v[8:11]
	v_mfma_f32_16x16x32_bf16 v[52:55], v[172:175], v[188:191], 0
	v_mfma_f32_16x16x32_bf16 v[44:47], v[180:183], v[188:191], 0
	v_mfma_f32_16x16x32_bf16 v[36:39], v[172:175], v[198:201], 0
	v_mfma_f32_16x16x32_bf16 v[28:31], v[180:183], v[198:201], 0
	v_mfma_f32_16x16x32_bf16 v[20:23], v[172:175], v[206:209], 0
	v_mfma_f32_16x16x32_bf16 v[12:15], v[180:183], v[206:209], 0
	v_mfma_f32_16x16x32_bf16 v[4:7], v[172:175], v[214:217], 0
	v_mfma_f32_16x16x32_bf16 v[0:3], v[180:183], v[214:217], 0
	v_mfma_f32_16x16x32_bf16 v[52:55], v[176:179], v[192:195], v[52:55]
	v_mfma_f32_16x16x32_bf16 v[44:47], v[184:187], v[192:195], v[44:47]
	v_mfma_f32_16x16x32_bf16 v[36:39], v[176:179], v[202:205], v[36:39]
	v_mfma_f32_16x16x32_bf16 v[28:31], v[184:187], v[202:205], v[28:31]
	v_mfma_f32_16x16x32_bf16 v[20:23], v[176:179], v[210:213], v[20:23]
	v_mfma_f32_16x16x32_bf16 v[12:15], v[184:187], v[210:213], v[12:15]
	v_mfma_f32_16x16x32_bf16 v[4:7], v[176:179], v[218:221], v[4:7]
	v_mfma_f32_16x16x32_bf16 v[0:3], v[184:187], v[218:221], v[0:3]
	s_setprio 0
	s_barrier
	s_add_i32 s70, 0, 0x18000
	s_add_i32 s71, 0, 0x1c000
	v_add_u32_e32 v140, s70, v170
	v_add_u32_e32 v159, s71, v170
	ds_read_b128 v[128:131], v140
	ds_read_b128 v[132:135], v140 offset:1024
	ds_read_b128 v[136:139], v140 offset:2048
	ds_read_b128 v[140:143], v140 offset:3072
	ds_read_b128 v[172:175], v159
	ds_read_b128 v[176:179], v159 offset:1024
	ds_read_b128 v[180:183], v159 offset:2048
	ds_read_b128 v[184:187], v159 offset:3072
	s_add_u32 s44, s44, 0x40000
	s_addc_u32 s45, s45, 0
	s_mov_b32 m0, s53
	v_lshl_add_u64 v[230:231], s[44:45], 0, v[144:145]
	ds_read_b128 v[188:191], v157 offset:32768
	ds_read_b128 v[192:195], v157 offset:33792
	ds_read_b128 v[198:201], v157 offset:34816
	ds_read_b128 v[202:205], v157 offset:35840
	ds_read_b128 v[206:209], v157 offset:36864
	ds_read_b128 v[210:213], v157 offset:37888
	ds_read_b128 v[214:217], v157 offset:38912
	ds_read_b128 v[218:221], v157 offset:39936
	global_load_lds_dwordx4 v[230:231], off
	v_lshl_add_u64 v[230:231], s[44:45], 0, v[148:149]
	s_mov_b32 m0, s54
	s_nop 0
	global_load_lds_dwordx4 v[230:231], off
	s_waitcnt vmcnt(8)
	s_waitcnt lgkmcnt(0)
	s_barrier
	s_setprio 1
	s_waitcnt lgkmcnt(0)
	v_mfma_f32_16x16x32_bf16 v[124:127], v[128:131], v[188:191], v[124:127]
	v_mfma_f32_16x16x32_bf16 v[120:123], v[136:139], v[188:191], v[120:123]
	v_mfma_f32_16x16x32_bf16 v[108:111], v[128:131], v[198:201], v[108:111]
	v_mfma_f32_16x16x32_bf16 v[104:107], v[136:139], v[198:201], v[104:107]
	v_mfma_f32_16x16x32_bf16 v[96:99], v[128:131], v[206:209], v[96:99]
	v_mfma_f32_16x16x32_bf16 v[88:91], v[136:139], v[206:209], v[88:91]
	v_mfma_f32_16x16x32_bf16 v[80:83], v[128:131], v[214:217], v[80:83]
	v_mfma_f32_16x16x32_bf16 v[72:75], v[136:139], v[214:217], v[72:75]
	v_mfma_f32_16x16x32_bf16 v[124:127], v[132:135], v[192:195], v[124:127]
	v_mfma_f32_16x16x32_bf16 v[120:123], v[140:143], v[192:195], v[120:123]
	v_mfma_f32_16x16x32_bf16 v[108:111], v[132:135], v[202:205], v[108:111]
	v_mfma_f32_16x16x32_bf16 v[104:107], v[140:143], v[202:205], v[104:107]
	v_mfma_f32_16x16x32_bf16 v[96:99], v[132:135], v[210:213], v[96:99]
	v_mfma_f32_16x16x32_bf16 v[88:91], v[140:143], v[210:213], v[88:91]
	v_mfma_f32_16x16x32_bf16 v[80:83], v[132:135], v[218:221], v[80:83]
	v_mfma_f32_16x16x32_bf16 v[72:75], v[140:143], v[218:221], v[72:75]
	v_mfma_f32_16x16x32_bf16 v[116:119], v[172:175], v[188:191], v[116:119]
	v_mfma_f32_16x16x32_bf16 v[112:115], v[180:183], v[188:191], v[112:115]
	v_mfma_f32_16x16x32_bf16 v[100:103], v[172:175], v[198:201], v[100:103]
	v_mfma_f32_16x16x32_bf16 v[92:95], v[180:183], v[198:201], v[92:95]
	v_mfma_f32_16x16x32_bf16 v[84:87], v[172:175], v[206:209], v[84:87]
	v_mfma_f32_16x16x32_bf16 v[76:79], v[180:183], v[206:209], v[76:79]
	v_mfma_f32_16x16x32_bf16 v[68:71], v[172:175], v[214:217], v[68:71]
	v_mfma_f32_16x16x32_bf16 v[64:67], v[180:183], v[214:217], v[64:67]
	v_mfma_f32_16x16x32_bf16 v[116:119], v[176:179], v[192:195], v[116:119]
	v_mfma_f32_16x16x32_bf16 v[112:115], v[184:187], v[192:195], v[112:115]
	v_mfma_f32_16x16x32_bf16 v[100:103], v[176:179], v[202:205], v[100:103]
	v_mfma_f32_16x16x32_bf16 v[92:95], v[184:187], v[202:205], v[92:95]
	v_mfma_f32_16x16x32_bf16 v[84:87], v[176:179], v[210:213], v[84:87]
	v_mfma_f32_16x16x32_bf16 v[76:79], v[184:187], v[210:213], v[76:79]
	v_mfma_f32_16x16x32_bf16 v[68:71], v[176:179], v[218:221], v[68:71]
	v_mfma_f32_16x16x32_bf16 v[64:67], v[184:187], v[218:221], v[64:67]
	s_setprio 0
	s_barrier
; #define PG8_STAGE(bufoff, gbase, voff) do { _Pragma("unroll") for (int _i = 0; _i < 2; ++_i) \
;         __builtin_amdgcn_global_load_lds((const unsigned*)((const char*)(gbase) + (voff)[_i]), (PG8_LAS unsigned*)(lds + (bufoff) + ldsw + _i * 8192), 16, 0, 0); } while (0)
; #define PG8_LDA(dst, b, h) do { _Pragma("unroll") for (int m = 0; m < 4; ++m) _Pragma("unroll") for (int k = 0; k < 2; ++k) dst[m][k] = *(const PG8_LAS bf16x8*)(lds + PG8_SA(b, h) + aoff + m * 2048 + k * 1024); } while (0)
; #define PG8_LDB(dst, b, h) do { _Pragma("unroll") for (int n = 0; n < 2; ++n) _Pragma("unroll") for (int k = 0; k < 2; ++k) dst[n][k] = *(const PG8_LAS bf16x8*)(lds + PG8_SB(b, h) + boff + n * 2048 + k * 1024); } while (0)
; #define PG8_MMA(ai, bj, At, Bt) do { __builtin_amdgcn_s_setprio(1); _Pragma("unroll") for (int m = 0; m < 4; ++m) _Pragma("unroll") for (int n = 0; n < 2; ++n) _Pragma("unroll") for (int k = 0; k < 2; ++k) \
;         acc[ai][bj][m][n] = __builtin_amdgcn_mfma_f32_16x16x32_bf16(Bt[n][k], At[m][k], acc[ai][bj][m][n], 0, 0, 0); __builtin_amdgcn_s_setprio(0); } while (0)
; #define PG8_WAIT_V(n) asm volatile("s_waitcnt vmcnt(" #n ")" ::: "memory")
; template <class Epi, class Sched, bool ALIGN_EPI = false, bool SP2 = false>
; __device__ __forceinline__ void gemm_phase(PG8_LAS unsigned char* lds, const Gemm g, const Sched& S, const Epi& E) {
;     ...
;             PG8_LDB(B0, 0, 0); PG8_LDB(B1, 0, 1); PG8_SCHED; PG8_LDA(At, 0, 0); PG8_STAGE(PG8_SA(1, 1), a1 + hstep, voffA);
;             PG8_WAIT_V(8); PG8_WAIT_L(0); PG8_BAR; PG8_MMA(0, 0, At, B0); PG8_MMA(0, 1, At, B1); PG8_BAR; PG8_SCHED;
;             PG8_LDA(At, 0, 1); PG8_STAGE(PG8_SB(0, 0), b2, voffB); PG8_STAGE(PG8_SB(0, 1), b2 + hstep, voffB); PG8_STAGE(PG8_SA(0, 0), a2, voffA);
;             PG8_WAIT_V(8); PG8_WAIT_L(0); PG8_BAR; PG8_MMA(1, 0, At, B0); PG8_MMA(1, 1, At, B1); PG8_BAR; PG8_SCHED;
;             PG8_LDB(B0, 1, 0); PG8_LDB(B1, 1, 1); PG8_SCHED; PG8_LDA(At, 1, 0); PG8_STAGE(PG8_SA(0, 1), a2 + hstep, voffA);
;             PG8_WAIT_V(8); PG8_WAIT_L(0); PG8_BAR; PG8_MMA(0, 0, At, B0); PG8_MMA(0, 1, At, B1); PG8_BAR; PG8_SCHED;
;             PG8_LDA(At, 1, 1); PG8_STAGE(PG8_SB(1, 0), b3, voffB); PG8_STAGE(PG8_SB(1, 1), b3 + hstep, voffB); PG8_STAGE(PG8_SA(1, 0), a3, voffA);
;             PG8_WAIT_V(8); PG8_WAIT_L(0); PG8_BAR; PG8_MMA(1, 0, At, B0); PG8_MMA(1, 1, At, B1); PG8_BAR; PG8_SCHED;
	s_add_i32 s44, s70, s51
	v_lshl_add_u64 v[222:223], v[222:223], 0, s[6:7]
	s_mov_b32 m0, s44
	ds_read_b128 v[188:191], v157 offset:49152
	ds_read_b128 v[192:195], v157 offset:50176
	ds_read_b128 v[198:201], v157 offset:51200
	ds_read_b128 v[202:205], v157 offset:52224
	ds_read_b128 v[206:209], v157 offset:53248
	ds_read_b128 v[210:213], v157 offset:54272
	ds_read_b128 v[214:217], v157 offset:55296
	ds_read_b128 v[218:221], v157 offset:56320
	global_load_lds_dwordx4 v[222:223], off
	s_add_i32 m0, s44, 0x2000
	s_add_u32 s38, s38, 0x40080
	v_lshl_add_u64 v[222:223], v[224:225], 0, s[6:7]
	s_addc_u32 s39, s39, 0
	s_add_i32 s44, s71, s51
	global_load_lds_dwordx4 v[222:223], off
	v_lshl_add_u64 v[222:223], s[38:39], 0, v[146:147]
	s_mov_b32 m0, s44
	s_nop 0
	global_load_lds_dwordx4 v[222:223], off
	v_lshl_add_u64 v[222:223], s[38:39], 0, v[150:151]
	s_add_i32 m0, s44, 0x2000
	s_nop 0
	global_load_lds_dwordx4 v[222:223], off
	v_lshl_add_u64 v[222:223], v[226:227], 0, s[6:7]
	s_mov_b32 m0, s58
	s_nop 0
	global_load_lds_dwordx4 v[222:223], off
	v_lshl_add_u64 v[222:223], v[228:229], 0, s[6:7]
	s_mov_b32 m0, s59
	s_nop 0
	global_load_lds_dwordx4 v[222:223], off
	s_waitcnt vmcnt(8)
	s_waitcnt lgkmcnt(0)
	s_barrier
	s_setprio 1
	s_waitcnt lgkmcnt(0)
	v_mfma_f32_16x16x32_bf16 v[60:63], v[128:131], v[188:191], v[60:63]
	v_mfma_f32_16x16x32_bf16 v[56:59], v[136:139], v[188:191], v[56:59]
	v_mfma_f32_16x16x32_bf16 v[48:51], v[128:131], v[198:201], v[48:51]
	v_mfma_f32_16x16x32_bf16 v[40:43], v[136:139], v[198:201], v[40:43]
	v_mfma_f32_16x16x32_bf16 v[32:35], v[128:131], v[206:209], v[32:35]
	v_mfma_f32_16x16x32_bf16 v[24:27], v[136:139], v[206:209], v[24:27]
	v_mfma_f32_16x16x32_bf16 v[16:19], v[128:131], v[214:217], v[16:19]
	v_mfma_f32_16x16x32_bf16 v[8:11], v[136:139], v[214:217], v[8:11]
	v_mfma_f32_16x16x32_bf16 v[60:63], v[132:135], v[192:195], v[60:63]
	v_mfma_f32_16x16x32_bf16 v[56:59], v[140:143], v[192:195], v[56:59]
	v_mfma_f32_16x16x32_bf16 v[48:51], v[132:135], v[202:205], v[48:51]
	v_mfma_f32_16x16x32_bf16 v[40:43], v[140:143], v[202:205], v[40:43]
	v_mfma_f32_16x16x32_bf16 v[32:35], v[132:135], v[210:213], v[32:35]
	v_mfma_f32_16x16x32_bf16 v[24:27], v[140:143], v[210:213], v[24:27]
	v_mfma_f32_16x16x32_bf16 v[16:19], v[132:135], v[218:221], v[16:19]
	v_mfma_f32_16x16x32_bf16 v[8:11], v[140:143], v[218:221], v[8:11]
	v_mfma_f32_16x16x32_bf16 v[52:55], v[172:175], v[188:191], v[52:55]
	v_mfma_f32_16x16x32_bf16 v[44:47], v[180:183], v[188:191], v[44:47]
	v_mfma_f32_16x16x32_bf16 v[36:39], v[172:175], v[198:201], v[36:39]
	v_mfma_f32_16x16x32_bf16 v[28:31], v[180:183], v[198:201], v[28:31]
	v_mfma_f32_16x16x32_bf16 v[20:23], v[172:175], v[206:209], v[20:23]
	v_mfma_f32_16x16x32_bf16 v[12:15], v[180:183], v[206:209], v[12:15]
	v_mfma_f32_16x16x32_bf16 v[4:7], v[172:175], v[214:217], v[4:7]
	v_mfma_f32_16x16x32_bf16 v[0:3], v[180:183], v[214:217], v[0:3]
	v_mfma_f32_16x16x32_bf16 v[52:55], v[176:179], v[192:195], v[52:55]
	v_mfma_f32_16x16x32_bf16 v[44:47], v[184:187], v[192:195], v[44:47]
	v_mfma_f32_16x16x32_bf16 v[36:39], v[176:179], v[202:205], v[36:39]
	v_mfma_f32_16x16x32_bf16 v[28:31], v[184:187], v[202:205], v[28:31]
	v_mfma_f32_16x16x32_bf16 v[20:23], v[176:179], v[210:213], v[20:23]
	v_mfma_f32_16x16x32_bf16 v[12:15], v[184:187], v[210:213], v[12:15]
	v_mfma_f32_16x16x32_bf16 v[4:7], v[176:179], v[218:221], v[4:7]
	v_mfma_f32_16x16x32_bf16 v[0:3], v[184:187], v[218:221], v[0:3]
	s_setprio 0
	s_barrier
	s_add_i32 s69, s69, 2
	s_add_u32 s20, s20, 0x100
	s_addc_u32 s21, s21, 0
	s_add_u32 s67, s67, 0x100
	s_addc_u32 s68, s68, 0
	s_cmp_gt_u32 s69, 13
.LBB0_1446:
	ds_read_b128 v[128:131], v153
	ds_read_b128 v[132:135], v153 offset:1024
	ds_read_b128 v[136:139], v153 offset:2048
	ds_read_b128 v[140:143], v153 offset:3072
	ds_read_b128 v[172:175], v155
	ds_read_b128 v[176:179], v155 offset:1024
	ds_read_b128 v[180:183], v155 offset:2048
	ds_read_b128 v[184:187], v155 offset:3072
	s_add_u32 s38, s20, 0xfffc0080
	s_addc_u32 s39, s21, -1
	s_cmp_eq_u32 s69, 12
	s_cselect_b32 s45, s15, s39
	s_cselect_b32 s44, s65, s38
	s_cselect_b32 s39, s13, s68
	s_cselect_b32 s38, s66, s67
	v_lshl_add_u64 v[222:223], s[20:21], 0, v[162:163]
	s_add_i32 m0, s35, 0xc000
	ds_read_b128 v[188:191], v157
	ds_read_b128 v[192:195], v157 offset:1024
	ds_read_b128 v[198:201], v157 offset:2048
	ds_read_b128 v[202:205], v157 offset:3072
	ds_read_b128 v[206:209], v157 offset:4096
	ds_read_b128 v[210:213], v157 offset:5120
	ds_read_b128 v[214:217], v157 offset:6144
	ds_read_b128 v[218:221], v157 offset:7168
	global_load_lds_dwordx4 v[222:223], off
	v_lshl_add_u64 v[222:223], s[20:21], 0, v[164:165]
	s_add_i32 m0, s35, 0xe000
	s_nop 0
	global_load_lds_dwordx4 v[222:223], off
	s_waitcnt vmcnt(8)
	s_waitcnt lgkmcnt(0)
	s_barrier
; #define PG8_STAGE(bufoff, gbase, voff) do { _Pragma("unroll") for (int _i = 0; _i < 2; ++_i) \
;         __builtin_amdgcn_global_load_lds((const unsigned*)((const char*)(gbase) + (voff)[_i]), (PG8_LAS unsigned*)(lds + (bufoff) + ldsw + _i * 8192), 16, 0, 0); } while (0)
; #define PG8_LDA(dst, b, h) do { _Pragma("unroll") for (int m = 0; m < 4; ++m) _Pragma("unroll") for (int k = 0; k < 2; ++k) dst[m][k] = *(const PG8_LAS bf16x8*)(lds + PG8_SA(b, h) + aoff + m * 2048 + k * 1024); } while (0)
; #define PG8_MMA(ai, bj, At, Bt) do { __builtin_amdgcn_s_setprio(1); _Pragma("unroll") for (int m = 0; m < 4; ++m) _Pragma("unroll") for (int n = 0; n < 2; ++n) _Pragma("unroll") for (int k = 0; k < 2; ++k) \
;         acc[ai][bj][m][n] = __builtin_amdgcn_mfma_f32_16x16x32_bf16(Bt[n][k], At[m][k], acc[ai][bj][m][n], 0, 0, 0); __builtin_amdgcn_s_setprio(0); } while (0)
; #define PG8_WAIT_V(n) asm volatile("s_waitcnt vmcnt(" #n ")" ::: "memory")
; #define PG8_WAIT_L(n) asm volatile("s_waitcnt lgkmcnt(" #n ")" ::: "memory")
; #define PG8_BAR __builtin_amdgcn_s_barrier()
; #define PG8_SCHED __builtin_amdgcn_sched_barrier(0)
; template <class Epi, class Sched, bool ALIGN_EPI = false, bool SP2 = false>
; __device__ __forceinline__ void gemm_phase(PG8_LAS unsigned char* lds, const Gemm g, const Sched& S, const Epi& E) {
;     ...
;             PG8_WAIT_V(8); PG8_WAIT_L(0); PG8_BAR; PG8_MMA(0, 0, At, B0); PG8_MMA(0, 1, At, B1); PG8_BAR; PG8_SCHED;
;             PG8_LDA(At, 0, 1); PG8_STAGE(PG8_SB(0, 0), b2, voffB); PG8_STAGE(PG8_SB(0, 1), b2 + hstep, voffB); PG8_STAGE(PG8_SA(0, 0), a2, voffA);
;             PG8_WAIT_V(8); PG8_WAIT_L(0); PG8_BAR; PG8_MMA(1, 0, At, B0); PG8_MMA(1, 1, At, B1); PG8_BAR; PG8_SCHED;
	s_setprio 1
	s_waitcnt lgkmcnt(0)
	v_mfma_f32_16x16x32_bf16 v[124:127], v[128:131], v[188:191], v[124:127]
	v_mfma_f32_16x16x32_bf16 v[120:123], v[136:139], v[188:191], v[120:123]
	v_mfma_f32_16x16x32_bf16 v[108:111], v[128:131], v[198:201], v[108:111]
	v_mfma_f32_16x16x32_bf16 v[104:107], v[136:139], v[198:201], v[104:107]
	v_mfma_f32_16x16x32_bf16 v[96:99], v[128:131], v[206:209], v[96:99]
	v_mfma_f32_16x16x32_bf16 v[88:91], v[136:139], v[206:209], v[88:91]
	v_mfma_f32_16x16x32_bf16 v[80:83], v[128:131], v[214:217], v[80:83]
	v_mfma_f32_16x16x32_bf16 v[72:75], v[136:139], v[214:217], v[72:75]
	v_mfma_f32_16x16x32_bf16 v[124:127], v[132:135], v[192:195], v[124:127]
	v_mfma_f32_16x16x32_bf16 v[120:123], v[140:143], v[192:195], v[120:123]
	v_mfma_f32_16x16x32_bf16 v[108:111], v[132:135], v[202:205], v[108:111]
	v_mfma_f32_16x16x32_bf16 v[104:107], v[140:143], v[202:205], v[104:107]
	v_mfma_f32_16x16x32_bf16 v[96:99], v[132:135], v[210:213], v[96:99]
	v_mfma_f32_16x16x32_bf16 v[88:91], v[140:143], v[210:213], v[88:91]
	v_mfma_f32_16x16x32_bf16 v[80:83], v[132:135], v[218:221], v[80:83]
	v_mfma_f32_16x16x32_bf16 v[72:75], v[140:143], v[218:221], v[72:75]
	v_mfma_f32_16x16x32_bf16 v[116:119], v[172:175], v[188:191], v[116:119]
	v_mfma_f32_16x16x32_bf16 v[112:115], v[180:183], v[188:191], v[112:115]
	v_mfma_f32_16x16x32_bf16 v[100:103], v[172:175], v[198:201], v[100:103]
	v_mfma_f32_16x16x32_bf16 v[92:95], v[180:183], v[198:201], v[92:95]
	v_mfma_f32_16x16x32_bf16 v[84:87], v[172:175], v[206:209], v[84:87]
	v_mfma_f32_16x16x32_bf16 v[76:79], v[180:183], v[206:209], v[76:79]
	v_mfma_f32_16x16x32_bf16 v[68:71], v[172:175], v[214:217], v[68:71]
	v_mfma_f32_16x16x32_bf16 v[64:67], v[180:183], v[214:217], v[64:67]
	v_mfma_f32_16x16x32_bf16 v[116:119], v[176:179], v[192:195], v[116:119]
	v_mfma_f32_16x16x32_bf16 v[112:115], v[184:187], v[192:195], v[112:115]
	v_mfma_f32_16x16x32_bf16 v[100:103], v[176:179], v[202:205], v[100:103]
	v_mfma_f32_16x16x32_bf16 v[92:95], v[184:187], v[202:205], v[92:95]
	v_mfma_f32_16x16x32_bf16 v[84:87], v[176:179], v[210:213], v[84:87]
	v_mfma_f32_16x16x32_bf16 v[76:79], v[184:187], v[210:213], v[76:79]
	v_mfma_f32_16x16x32_bf16 v[68:71], v[176:179], v[218:221], v[68:71]
	v_mfma_f32_16x16x32_bf16 v[64:67], v[184:187], v[218:221], v[64:67]
	s_setprio 0
	s_barrier
	s_add_i32 s70, s60, s51
	v_lshl_add_u64 v[222:223], s[38:39], 0, v[146:147]
	s_mov_b32 m0, s70
	ds_read_b128 v[188:191], v157 offset:16384
	ds_read_b128 v[192:195], v157 offset:17408
	ds_read_b128 v[198:201], v157 offset:18432
	ds_read_b128 v[202:205], v157 offset:19456
	ds_read_b128 v[206:209], v157 offset:20480
	ds_read_b128 v[210:213], v157 offset:21504
	ds_read_b128 v[214:217], v157 offset:22528
	ds_read_b128 v[218:221], v157 offset:23552
	global_load_lds_dwordx4 v[222:223], off
	s_add_i32 m0, s70, 0x2000
	s_add_u32 s70, s38, 0x40000
	v_lshl_add_u64 v[224:225], s[38:39], 0, v[150:151]
	s_addc_u32 s71, s39, 0
	s_add_i32 s72, s61, s51
	global_load_lds_dwordx4 v[224:225], off
	v_lshl_add_u64 v[226:227], s[70:71], 0, v[146:147]
	s_mov_b32 m0, s72
	v_lshl_add_u64 v[228:229], s[44:45], 0, v[148:149]
	global_load_lds_dwordx4 v[226:227], off
	v_lshl_add_u64 v[226:227], s[70:71], 0, v[150:151]
	s_add_i32 m0, s72, 0x2000
	s_nop 0
	global_load_lds_dwordx4 v[226:227], off
	v_lshl_add_u64 v[226:227], s[44:45], 0, v[144:145]
	s_mov_b32 m0, s35
	s_nop 0
	global_load_lds_dwordx4 v[226:227], off
	s_mov_b32 m0, s52
	s_nop 0
	global_load_lds_dwordx4 v[228:229], off
	s_waitcnt vmcnt(8)
	s_waitcnt lgkmcnt(0)
	s_barrier
	s_setprio 1
	s_waitcnt lgkmcnt(0)
	v_mfma_f32_16x16x32_bf16 v[60:63], v[128:131], v[188:191], v[60:63]
	v_mfma_f32_16x16x32_bf16 v[56:59], v[136:139], v[188:191], v[56:59]
	v_mfma_f32_16x16x32_bf16 v[48:51], v[128:131], v[198:201], v[48:51]
	v_mfma_f32_16x16x32_bf16 v[40:43], v[136:139], v[198:201], v[40:43]
	v_mfma_f32_16x16x32_bf16 v[32:35], v[128:131], v[206:209], v[32:35]
	v_mfma_f32_16x16x32_bf16 v[24:27], v[136:139], v[206:209], v[24:27]
	v_mfma_f32_16x16x32_bf16 v[16:19], v[128:131], v[214:217], v[16:19]
	v_mfma_f32_16x16x32_bf16 v[8:11], v[136:139], v[214:217], v[8:11]
	v_mfma_f32_16x16x32_bf16 v[60:63], v[132:135], v[192:195], v[60:63]
	v_mfma_f32_16x16x32_bf16 v[56:59], v[140:143], v[192:195], v[56:59]
	v_mfma_f32_16x16x32_bf16 v[48:51], v[132:135], v[202:205], v[48:51]
	v_mfma_f32_16x16x32_bf16 v[40:43], v[140:143], v[202:205], v[40:43]
	v_mfma_f32_16x16x32_bf16 v[32:35], v[132:135], v[210:213], v[32:35]
	v_mfma_f32_16x16x32_bf16 v[24:27], v[140:143], v[210:213], v[24:27]
	v_mfma_f32_16x16x32_bf16 v[16:19], v[132:135], v[218:221], v[16:19]
	v_mfma_f32_16x16x32_bf16 v[8:11], v[140:143], v[218:221], v[8:11]
	v_mfma_f32_16x16x32_bf16 v[52:55], v[172:175], v[188:191], v[52:55]
	v_mfma_f32_16x16x32_bf16 v[44:47], v[180:183], v[188:191], v[44:47]
	v_mfma_f32_16x16x32_bf16 v[36:39], v[172:175], v[198:201], v[36:39]
	v_mfma_f32_16x16x32_bf16 v[28:31], v[180:183], v[198:201], v[28:31]
	v_mfma_f32_16x16x32_bf16 v[20:23], v[172:175], v[206:209], v[20:23]
	v_mfma_f32_16x16x32_bf16 v[12:15], v[180:183], v[206:209], v[12:15]
	v_mfma_f32_16x16x32_bf16 v[4:7], v[172:175], v[214:217], v[4:7]
	v_mfma_f32_16x16x32_bf16 v[0:3], v[180:183], v[214:217], v[0:3]
	v_mfma_f32_16x16x32_bf16 v[52:55], v[176:179], v[192:195], v[52:55]
	v_mfma_f32_16x16x32_bf16 v[44:47], v[184:187], v[192:195], v[44:47]
	v_mfma_f32_16x16x32_bf16 v[36:39], v[176:179], v[202:205], v[36:39]
	v_mfma_f32_16x16x32_bf16 v[28:31], v[184:187], v[202:205], v[28:31]
	v_mfma_f32_16x16x32_bf16 v[20:23], v[176:179], v[210:213], v[20:23]
	v_mfma_f32_16x16x32_bf16 v[12:15], v[184:187], v[210:213], v[12:15]
	v_mfma_f32_16x16x32_bf16 v[4:7], v[176:179], v[218:221], v[4:7]
	v_mfma_f32_16x16x32_bf16 v[0:3], v[184:187], v[218:221], v[0:3]
	s_setprio 0
	s_barrier
; #define PG8_STAGE(bufoff, gbase, voff) do { _Pragma("unroll") for (int _i = 0; _i < 2; ++_i) \
;         __builtin_amdgcn_global_load_lds((const unsigned*)((const char*)(gbase) + (voff)[_i]), (PG8_LAS unsigned*)(lds + (bufoff) + ldsw + _i * 8192), 16, 0, 0); } while (0)
; #define PG8_LDA(dst, b, h) do { _Pragma("unroll") for (int m = 0; m < 4; ++m) _Pragma("unroll") for (int k = 0; k < 2; ++k) dst[m][k] = *(const PG8_LAS bf16x8*)(lds + PG8_SA(b, h) + aoff + m * 2048 + k * 1024); } while (0)
; #define PG8_LDB(dst, b, h) do { _Pragma("unroll") for (int n = 0; n < 2; ++n) _Pragma("unroll") for (int k = 0; k < 2; ++k) dst[n][k] = *(const PG8_LAS bf16x8*)(lds + PG8_SB(b, h) + boff + n * 2048 + k * 1024); } while (0)
; #define PG8_MMA(ai, bj, At, Bt) do { __builtin_amdgcn_s_setprio(1); _Pragma("unroll") for (int m = 0; m < 4; ++m) _Pragma("unroll") for (int n = 0; n < 2; ++n) _Pragma("unroll") for (int k = 0; k < 2; ++k) \
;         acc[ai][bj][m][n] = __builtin_amdgcn_mfma_f32_16x16x32_bf16(Bt[n][k], At[m][k], acc[ai][bj][m][n], 0, 0, 0); __builtin_amdgcn_s_setprio(0); } while (0)
; #define PG8_WAIT_V(n) asm volatile("s_waitcnt vmcnt(" #n ")" ::: "memory")
; #define PG8_WAIT_L(n) asm volatile("s_waitcnt lgkmcnt(" #n ")" ::: "memory")
; #define PG8_BAR __builtin_amdgcn_s_barrier()
; #define PG8_SCHED __builtin_amdgcn_sched_barrier(0)
; template <class Epi, class Sched, bool ALIGN_EPI = false, bool SP2 = false>
; __device__ __forceinline__ void gemm_phase(PG8_LAS unsigned char* lds, const Gemm g, const Sched& S, const Epi& E) {
;     ...
;             PG8_LDB(B0, 1, 0); PG8_LDB(B1, 1, 1); PG8_SCHED; PG8_LDA(At, 1, 0); PG8_STAGE(PG8_SA(0, 1), a2 + hstep, voffA);
;             PG8_WAIT_V(8); PG8_WAIT_L(0); PG8_BAR; PG8_MMA(0, 0, At, B0); PG8_MMA(0, 1, At, B1); PG8_BAR; PG8_SCHED;
	s_add_i32 s70, 0, 0x18000
	s_add_i32 s71, 0, 0x1c000
	v_add_u32_e32 v140, s70, v170
	v_add_u32_e32 v159, s71, v170
	ds_read_b128 v[128:131], v140
	ds_read_b128 v[132:135], v140 offset:1024
	ds_read_b128 v[136:139], v140 offset:2048
	ds_read_b128 v[140:143], v140 offset:3072
	ds_read_b128 v[172:175], v159
	ds_read_b128 v[176:179], v159 offset:1024
	ds_read_b128 v[180:183], v159 offset:2048
	ds_read_b128 v[184:187], v159 offset:3072
	s_add_u32 s44, s44, 0x40000
	s_addc_u32 s45, s45, 0
	s_mov_b32 m0, s53
	v_lshl_add_u64 v[230:231], s[44:45], 0, v[144:145]
	ds_read_b128 v[188:191], v157 offset:32768
	ds_read_b128 v[192:195], v157 offset:33792
	ds_read_b128 v[198:201], v157 offset:34816
	ds_read_b128 v[202:205], v157 offset:35840
	ds_read_b128 v[206:209], v157 offset:36864
	ds_read_b128 v[210:213], v157 offset:37888
	ds_read_b128 v[214:217], v157 offset:38912
	ds_read_b128 v[218:221], v157 offset:39936
	global_load_lds_dwordx4 v[230:231], off
	v_lshl_add_u64 v[230:231], s[44:45], 0, v[148:149]
	s_mov_b32 m0, s54
	s_nop 0
	global_load_lds_dwordx4 v[230:231], off
	s_waitcnt vmcnt(8)
	s_waitcnt lgkmcnt(0)
	s_barrier
	s_setprio 1
	s_waitcnt lgkmcnt(0)
	v_mfma_f32_16x16x32_bf16 v[124:127], v[128:131], v[188:191], v[124:127]
	v_mfma_f32_16x16x32_bf16 v[120:123], v[136:139], v[188:191], v[120:123]
	v_mfma_f32_16x16x32_bf16 v[108:111], v[128:131], v[198:201], v[108:111]
	v_mfma_f32_16x16x32_bf16 v[104:107], v[136:139], v[198:201], v[104:107]
	v_mfma_f32_16x16x32_bf16 v[96:99], v[128:131], v[206:209], v[96:99]
	v_mfma_f32_16x16x32_bf16 v[88:91], v[136:139], v[206:209], v[88:91]
	v_mfma_f32_16x16x32_bf16 v[80:83], v[128:131], v[214:217], v[80:83]
	v_mfma_f32_16x16x32_bf16 v[72:75], v[136:139], v[214:217], v[72:75]
	v_mfma_f32_16x16x32_bf16 v[124:127], v[132:135], v[192:195], v[124:127]
	v_mfma_f32_16x16x32_bf16 v[120:123], v[140:143], v[192:195], v[120:123]
	v_mfma_f32_16x16x32_bf16 v[108:111], v[132:135], v[202:205], v[108:111]
	v_mfma_f32_16x16x32_bf16 v[104:107], v[140:143], v[202:205], v[104:107]
	v_mfma_f32_16x16x32_bf16 v[96:99], v[132:135], v[210:213], v[96:99]
	v_mfma_f32_16x16x32_bf16 v[88:91], v[140:143], v[210:213], v[88:91]
	v_mfma_f32_16x16x32_bf16 v[80:83], v[132:135], v[218:221], v[80:83]
	v_mfma_f32_16x16x32_bf16 v[72:75], v[140:143], v[218:221], v[72:75]
	v_mfma_f32_16x16x32_bf16 v[116:119], v[172:175], v[188:191], v[116:119]
	v_mfma_f32_16x16x32_bf16 v[112:115], v[180:183], v[188:191], v[112:115]
	v_mfma_f32_16x16x32_bf16 v[100:103], v[172:175], v[198:201], v[100:103]
	v_mfma_f32_16x16x32_bf16 v[92:95], v[180:183], v[198:201], v[92:95]
	v_mfma_f32_16x16x32_bf16 v[84:87], v[172:175], v[206:209], v[84:87]
	v_mfma_f32_16x16x32_bf16 v[76:79], v[180:183], v[206:209], v[76:79]
	v_mfma_f32_16x16x32_bf16 v[68:71], v[172:175], v[214:217], v[68:71]
	v_mfma_f32_16x16x32_bf16 v[64:67], v[180:183], v[214:217], v[64:67]
	v_mfma_f32_16x16x32_bf16 v[116:119], v[176:179], v[192:195], v[116:119]
	v_mfma_f32_16x16x32_bf16 v[112:115], v[184:187], v[192:195], v[112:115]
	v_mfma_f32_16x16x32_bf16 v[100:103], v[176:179], v[202:205], v[100:103]
	v_mfma_f32_16x16x32_bf16 v[92:95], v[184:187], v[202:205], v[92:95]
	v_mfma_f32_16x16x32_bf16 v[84:87], v[176:179], v[210:213], v[84:87]
	v_mfma_f32_16x16x32_bf16 v[76:79], v[184:187], v[210:213], v[76:79]
	v_mfma_f32_16x16x32_bf16 v[68:71], v[176:179], v[218:221], v[68:71]
	v_mfma_f32_16x16x32_bf16 v[64:67], v[184:187], v[218:221], v[64:67]
	s_setprio 0
	s_barrier
; #define PG8_STAGE(bufoff, gbase, voff) do { _Pragma("unroll") for (int _i = 0; _i < 2; ++_i) \
;         __builtin_amdgcn_global_load_lds((const unsigned*)((const char*)(gbase) + (voff)[_i]), (PG8_LAS unsigned*)(lds + (bufoff) + ldsw + _i * 8192), 16, 0, 0); } while (0)
; #define PG8_LDA(dst, b, h) do { _Pragma("unroll") for (int m = 0; m < 4; ++m) _Pragma("unroll") for (int k = 0; k < 2; ++k) dst[m][k] = *(const PG8_LAS bf16x8*)(lds + PG8_SA(b, h) + aoff + m * 2048 + k * 1024); } while (0)
; #define PG8_MMA(ai, bj, At, Bt) do { __builtin_amdgcn_s_setprio(1); _Pragma("unroll") for (int m = 0; m < 4; ++m) _Pragma("unroll") for (int n = 0; n < 2; ++n) _Pragma("unroll") for (int k = 0; k < 2; ++k) \
;         acc[ai][bj][m][n] = __builtin_amdgcn_mfma_f32_16x16x32_bf16(Bt[n][k], At[m][k], acc[ai][bj][m][n], 0, 0, 0); __builtin_amdgcn_s_setprio(0); } while (0)
; #define PG8_WAIT_V(n) asm volatile("s_waitcnt vmcnt(" #n ")" ::: "memory")
; #define PG8_WAIT_L(n) asm volatile("s_waitcnt lgkmcnt(" #n ")" ::: "memory")
; #define PG8_BAR __builtin_amdgcn_s_barrier()
; #define PG8_SCHED __builtin_amdgcn_sched_barrier(0)
; template <class Epi, class Sched, bool ALIGN_EPI = false, bool SP2 = false>
; __device__ __forceinline__ void gemm_phase(PG8_LAS unsigned char* lds, const Gemm g, const Sched& S, const Epi& E) {
;     ...
;             PG8_LDA(At, 1, 1); PG8_STAGE(PG8_SB(1, 0), b3, voffB); PG8_STAGE(PG8_SB(1, 1), b3 + hstep, voffB); PG8_STAGE(PG8_SA(1, 0), a3, voffA);
;             PG8_WAIT_V(8); PG8_WAIT_L(0); PG8_BAR; PG8_MMA(1, 0, At, B0); PG8_MMA(1, 1, At, B1); PG8_BAR; PG8_SCHED;
;     ...
;         if constexpr (ALIGN_EPI) { if (wr == 0) PG8_BAR; }
	s_add_i32 s44, s70, s51
	v_lshl_add_u64 v[222:223], v[222:223], 0, s[6:7]
	s_mov_b32 m0, s44
	ds_read_b128 v[188:191], v157 offset:49152
	ds_read_b128 v[192:195], v157 offset:50176
	ds_read_b128 v[198:201], v157 offset:51200
	ds_read_b128 v[202:205], v157 offset:52224
	ds_read_b128 v[206:209], v157 offset:53248
	ds_read_b128 v[210:213], v157 offset:54272
	ds_read_b128 v[214:217], v157 offset:55296
	ds_read_b128 v[218:221], v157 offset:56320
	global_load_lds_dwordx4 v[222:223], off
	s_add_i32 m0, s44, 0x2000
	s_add_u32 s38, s38, 0x40080
	v_lshl_add_u64 v[222:223], v[224:225], 0, s[6:7]
	s_addc_u32 s39, s39, 0
	s_add_i32 s44, s71, s51
	global_load_lds_dwordx4 v[222:223], off
	v_lshl_add_u64 v[222:223], s[38:39], 0, v[146:147]
	s_mov_b32 m0, s44
	s_nop 0
	global_load_lds_dwordx4 v[222:223], off
	v_lshl_add_u64 v[222:223], s[38:39], 0, v[150:151]
	s_add_i32 m0, s44, 0x2000
	s_nop 0
	global_load_lds_dwordx4 v[222:223], off
	v_lshl_add_u64 v[222:223], v[226:227], 0, s[6:7]
	s_mov_b32 m0, s58
	s_nop 0
	global_load_lds_dwordx4 v[222:223], off
	v_lshl_add_u64 v[222:223], v[228:229], 0, s[6:7]
	s_mov_b32 m0, s59
	s_nop 0
	global_load_lds_dwordx4 v[222:223], off
	s_waitcnt vmcnt(8)
	s_waitcnt lgkmcnt(0)
	s_barrier
	s_setprio 1
	s_waitcnt lgkmcnt(0)
	v_mfma_f32_16x16x32_bf16 v[60:63], v[128:131], v[188:191], v[60:63]
	v_mfma_f32_16x16x32_bf16 v[56:59], v[136:139], v[188:191], v[56:59]
	v_mfma_f32_16x16x32_bf16 v[48:51], v[128:131], v[198:201], v[48:51]
	v_mfma_f32_16x16x32_bf16 v[40:43], v[136:139], v[198:201], v[40:43]
	v_mfma_f32_16x16x32_bf16 v[32:35], v[128:131], v[206:209], v[32:35]
	v_mfma_f32_16x16x32_bf16 v[24:27], v[136:139], v[206:209], v[24:27]
	v_mfma_f32_16x16x32_bf16 v[16:19], v[128:131], v[214:217], v[16:19]
	v_mfma_f32_16x16x32_bf16 v[8:11], v[136:139], v[214:217], v[8:11]
	v_mfma_f32_16x16x32_bf16 v[60:63], v[132:135], v[192:195], v[60:63]
	v_mfma_f32_16x16x32_bf16 v[56:59], v[140:143], v[192:195], v[56:59]
	v_mfma_f32_16x16x32_bf16 v[48:51], v[132:135], v[202:205], v[48:51]
	v_mfma_f32_16x16x32_bf16 v[40:43], v[140:143], v[202:205], v[40:43]
	v_mfma_f32_16x16x32_bf16 v[32:35], v[132:135], v[210:213], v[32:35]
	v_mfma_f32_16x16x32_bf16 v[24:27], v[140:143], v[210:213], v[24:27]
	v_mfma_f32_16x16x32_bf16 v[16:19], v[132:135], v[218:221], v[16:19]
	v_mfma_f32_16x16x32_bf16 v[8:11], v[140:143], v[218:221], v[8:11]
	v_mfma_f32_16x16x32_bf16 v[52:55], v[172:175], v[188:191], v[52:55]
	v_mfma_f32_16x16x32_bf16 v[44:47], v[180:183], v[188:191], v[44:47]
	v_mfma_f32_16x16x32_bf16 v[36:39], v[172:175], v[198:201], v[36:39]
	v_mfma_f32_16x16x32_bf16 v[28:31], v[180:183], v[198:201], v[28:31]
	v_mfma_f32_16x16x32_bf16 v[20:23], v[172:175], v[206:209], v[20:23]
	v_mfma_f32_16x16x32_bf16 v[12:15], v[180:183], v[206:209], v[12:15]
	v_mfma_f32_16x16x32_bf16 v[4:7], v[172:175], v[214:217], v[4:7]
	v_mfma_f32_16x16x32_bf16 v[0:3], v[180:183], v[214:217], v[0:3]
	v_mfma_f32_16x16x32_bf16 v[52:55], v[176:179], v[192:195], v[52:55]
	v_mfma_f32_16x16x32_bf16 v[44:47], v[184:187], v[192:195], v[44:47]
	v_mfma_f32_16x16x32_bf16 v[36:39], v[176:179], v[202:205], v[36:39]
	v_mfma_f32_16x16x32_bf16 v[28:31], v[184:187], v[202:205], v[28:31]
	v_mfma_f32_16x16x32_bf16 v[20:23], v[176:179], v[210:213], v[20:23]
	v_mfma_f32_16x16x32_bf16 v[12:15], v[184:187], v[210:213], v[12:15]
	v_mfma_f32_16x16x32_bf16 v[4:7], v[176:179], v[218:221], v[4:7]
	v_mfma_f32_16x16x32_bf16 v[0:3], v[184:187], v[218:221], v[0:3]
	s_setprio 0
	s_barrier
	s_add_i32 s69, s69, 2
	s_add_u32 s20, s20, 0x100
	s_addc_u32 s21, s21, 0
	s_add_u32 s67, s67, 0x100
	s_addc_u32 s68, s68, 0
	s_cmp_gt_u32 s69, 13
	s_cbranch_scc0 .LBB0_1446
	s_and_b64 vcc, exec, s[8:9]
	s_cbranch_vccz .LBB0_1449
	s_barrier

; #define PG8_STAGE(bufoff, gbase, voff) do { _Pragma("unroll") for (int _i = 0; _i < 2; ++_i) \
;         __builtin_amdgcn_global_load_lds((const unsigned*)((const char*)(gbase) + (voff)[_i]), (PG8_LAS unsigned*)(lds + (bufoff) + ldsw + _i * 8192), 16, 0, 0); } while (0)
; #define PG8_LDA(dst, b, h) do { _Pragma("unroll") for (int m = 0; m < 4; ++m) _Pragma("unroll") for (int k = 0; k < 2; ++k) dst[m][k] = *(const PG8_LAS bf16x8*)(lds + PG8_SA(b, h) + aoff + m * 2048 + k * 1024); } while (0)
; #define PG8_LDB(dst, b, h) do { _Pragma("unroll") for (int n = 0; n < 2; ++n) _Pragma("unroll") for (int k = 0; k < 2; ++k) dst[n][k] = *(const PG8_LAS bf16x8*)(lds + PG8_SB(b, h) + boff + n * 2048 + k * 1024); } while (0)
; #define PG8_WAIT_V(n) asm volatile("s_waitcnt vmcnt(" #n ")" ::: "memory")
; #define PG8_WAIT_L(n) asm volatile("s_waitcnt lgkmcnt(" #n ")" ::: "memory")
; #define PG8_BAR __builtin_amdgcn_s_barrier()
; #define PG8_SCHED __builtin_amdgcn_sched_barrier(0)
; template <class Epi, class Sched, bool ALIGN_EPI = false, bool SP2 = false>
; __device__ __forceinline__ void gemm_phase(PG8_LAS unsigned char* lds, const Gemm g, const Sched& S, const Epi& E) {
;     ...
;         const bool has_next = S.next(ui + 1, nxt);
;         const char* nA = has_next ? (const char*)g.A + (size_t)nxt.pm * tstep : cA; const char* nB = has_next ? (const char*)g.Bt + (size_t)nxt.pn * tstep : cB;
;         for (int t = 0; t < nt; t += 2) {
;             const bool last = (t == nt - 2);
;             const char* a1 = cA + (size_t)(t + 1) * kstep;
;             const char* a2 = last ? nA : cA + (size_t)(t + 2) * kstep; const char* b2 = last ? nB : cB + (size_t)(t + 2) * kstep;
;             const char* a3 = a2 + kstep; const char* b3 = b2 + kstep;
;             if (last && has_next) S.a_ready(nxt);
;             if constexpr (SP2) {
;             PG8_LDB(B0, 0, 0); PG8_LDB(B1, 0, 1); PG8_SCHED; PG8_LDA(At, 0, 0); PG8_STAGE(PG8_SA(1, 1), a1 + hstep, voffA);
;             PG8_WAIT_V(8); PG8_WAIT_L(0); PG8_BAR; PG8_MMA(0, 0, At, B0); PG8_MMA(0, 1, At, B1); PG8_BAR; PG8_SCHED;
;             PG8_LDA(At, 0, 1); PG8_STAGE(PG8_SB(0, 0), b2, voffB); PG8_STAGE(PG8_SB(0, 1), b2 + hstep, voffB); PG8_STAGE(PG8_SA(0, 0), a2, voffA);
;             PG8_WAIT_V(8); PG8_WAIT_L(0); PG8_BAR; PG8_MMA(1, 0, At, B0); PG8_MMA(1, 1, At, B1); PG8_BAR; PG8_SCHED;
.LBB0_1634:
	s_ashr_i32 s47, s46, 31
	s_lshl_b64 s[48:49], s[46:47], 19
	s_add_u32 s48, s18, s48
	s_addc_u32 s49, s19, s49
	s_and_b64 s[50:51], s[6:7], exec
	s_cselect_b32 s35, s49, s21
	s_cselect_b32 s47, s48, s20
	s_ashr_i32 s45, s44, 31
	s_lshl_b64 s[50:51], s[44:45], 19
	s_add_u32 s50, s3, s50
	s_addc_u32 s51, s33, s51
	s_and_b64 s[56:57], s[6:7], exec
	s_cselect_b32 s45, s51, s55
	s_cselect_b32 s73, s50, s54
	s_add_u32 s20, s20, 0x40080
	s_addc_u32 s21, s21, 0
	s_add_u32 s74, s54, 0x100
	s_addc_u32 s75, s55, 0
	s_mov_b32 s76, -2
	s_waitcnt lgkmcnt(0)
	ds_read_b128 v[96:99], v223
	ds_read_b128 v[108:111], v223 offset:1024
	ds_read_b128 v[120:123], v223 offset:2048
	ds_read_b128 v[128:131], v223 offset:3072
	ds_read_b128 v[144:147], v224
	ds_read_b128 v[148:151], v224 offset:1024
	ds_read_b128 v[152:155], v224 offset:2048
	ds_read_b128 v[156:159], v224 offset:3072
	s_add_u32 s54, s20, 0xfffc0080
	s_addc_u32 s55, s21, -1
	s_cmp_eq_u32 s76, 12
	s_cselect_b32 s57, s35, s55
	s_cselect_b32 s56, s47, s54
	s_cselect_b32 s55, s45, s75
	s_cselect_b32 s54, s73, s74
	v_lshl_add_u64 v[210:211], s[20:21], 0, v[192:193]
	s_add_i32 m0, s53, 0xc000
	ds_read_b128 v[160:163], v225
	ds_read_b128 v[164:167], v225 offset:1024
	ds_read_b128 v[168:171], v225 offset:2048
	ds_read_b128 v[172:175], v225 offset:3072
	ds_read_b128 v[176:179], v225 offset:4096
	ds_read_b128 v[180:183], v225 offset:5120
	ds_read_b128 v[202:205], v225 offset:6144
	ds_read_b128 v[206:209], v225 offset:7168
	global_load_lds_dwordx4 v[210:211], off
	v_lshl_add_u64 v[210:211], s[20:21], 0, v[194:195]
	s_add_i32 m0, s53, 0xe000
	s_nop 0
	global_load_lds_dwordx4 v[210:211], off
	s_waitcnt vmcnt(8)
	s_waitcnt lgkmcnt(0)
	s_barrier
	s_setprio 1
	s_waitcnt lgkmcnt(0)
	v_mfma_f32_16x16x32_bf16 v[140:143], v[96:99], v[160:163], 0
	v_mfma_f32_16x16x32_bf16 v[136:139], v[120:123], v[160:163], 0
	v_mfma_f32_16x16x32_bf16 v[116:119], v[96:99], v[168:171], 0
	v_mfma_f32_16x16x32_bf16 v[112:115], v[120:123], v[168:171], 0
	v_mfma_f32_16x16x32_bf16 v[92:95], v[96:99], v[176:179], 0
	v_mfma_f32_16x16x32_bf16 v[88:91], v[120:123], v[176:179], 0
	v_mfma_f32_16x16x32_bf16 v[76:79], v[96:99], v[202:205], 0
	v_mfma_f32_16x16x32_bf16 v[72:75], v[120:123], v[202:205], 0
	v_mfma_f32_16x16x32_bf16 v[140:143], v[108:111], v[164:167], v[140:143]
	v_mfma_f32_16x16x32_bf16 v[136:139], v[128:131], v[164:167], v[136:139]
	v_mfma_f32_16x16x32_bf16 v[116:119], v[108:111], v[172:175], v[116:119]
	v_mfma_f32_16x16x32_bf16 v[112:115], v[128:131], v[172:175], v[112:115]
	v_mfma_f32_16x16x32_bf16 v[92:95], v[108:111], v[180:183], v[92:95]
	v_mfma_f32_16x16x32_bf16 v[88:91], v[128:131], v[180:183], v[88:91]
	v_mfma_f32_16x16x32_bf16 v[76:79], v[108:111], v[206:209], v[76:79]
	v_mfma_f32_16x16x32_bf16 v[72:75], v[128:131], v[206:209], v[72:75]
	v_mfma_f32_16x16x32_bf16 v[132:135], v[144:147], v[160:163], 0
	v_mfma_f32_16x16x32_bf16 v[124:127], v[152:155], v[160:163], 0
	v_mfma_f32_16x16x32_bf16 v[104:107], v[144:147], v[168:171], 0
	v_mfma_f32_16x16x32_bf16 v[100:103], v[152:155], v[168:171], 0
	v_mfma_f32_16x16x32_bf16 v[84:87], v[144:147], v[176:179], 0
	v_mfma_f32_16x16x32_bf16 v[80:83], v[152:155], v[176:179], 0
	v_mfma_f32_16x16x32_bf16 v[68:71], v[144:147], v[202:205], 0
	v_mfma_f32_16x16x32_bf16 v[64:67], v[152:155], v[202:205], 0
	v_mfma_f32_16x16x32_bf16 v[132:135], v[148:151], v[164:167], v[132:135]
	v_mfma_f32_16x16x32_bf16 v[124:127], v[156:159], v[164:167], v[124:127]
	v_mfma_f32_16x16x32_bf16 v[104:107], v[148:151], v[172:175], v[104:107]
	v_mfma_f32_16x16x32_bf16 v[100:103], v[156:159], v[172:175], v[100:103]
	v_mfma_f32_16x16x32_bf16 v[84:87], v[148:151], v[180:183], v[84:87]
	v_mfma_f32_16x16x32_bf16 v[80:83], v[156:159], v[180:183], v[80:83]
	v_mfma_f32_16x16x32_bf16 v[68:71], v[148:151], v[206:209], v[68:71]
	v_mfma_f32_16x16x32_bf16 v[64:67], v[156:159], v[206:209], v[64:67]
	s_setprio 0
	s_barrier
	s_add_i32 s77, s71, s58
	v_lshl_add_u64 v[210:211], s[54:55], 0, v[186:187]
	s_mov_b32 m0, s77
	ds_read_b128 v[160:163], v225 offset:16384
	ds_read_b128 v[164:167], v225 offset:17408
	ds_read_b128 v[168:171], v225 offset:18432
	ds_read_b128 v[172:175], v225 offset:19456
	ds_read_b128 v[176:179], v225 offset:20480
	ds_read_b128 v[180:183], v225 offset:21504
	ds_read_b128 v[202:205], v225 offset:22528
	ds_read_b128 v[206:209], v225 offset:23552
	global_load_lds_dwordx4 v[210:211], off
	s_add_i32 m0, s77, 0x2000
	s_add_u32 s78, s54, 0x40000
	v_lshl_add_u64 v[212:213], s[54:55], 0, v[190:191]
	s_addc_u32 s79, s55, 0
	s_add_i32 s77, s72, s58
	global_load_lds_dwordx4 v[212:213], off
	v_lshl_add_u64 v[214:215], s[78:79], 0, v[186:187]
	s_mov_b32 m0, s77
	v_lshl_add_u64 v[216:217], s[56:57], 0, v[188:189]
	global_load_lds_dwordx4 v[214:215], off
	v_lshl_add_u64 v[214:215], s[78:79], 0, v[190:191]
	s_add_i32 m0, s77, 0x2000
	s_nop 0
	global_load_lds_dwordx4 v[214:215], off
	v_lshl_add_u64 v[214:215], s[56:57], 0, v[184:185]
	s_mov_b32 m0, s53
	s_nop 0
	global_load_lds_dwordx4 v[214:215], off
	s_mov_b32 m0, s59
	s_nop 0
	global_load_lds_dwordx4 v[216:217], off
	s_waitcnt vmcnt(8)
	s_waitcnt lgkmcnt(0)
	s_barrier
; #define PG8_STAGE(bufoff, gbase, voff) do { _Pragma("unroll") for (int _i = 0; _i < 2; ++_i) \
;         __builtin_amdgcn_global_load_lds((const unsigned*)((const char*)(gbase) + (voff)[_i]), (PG8_LAS unsigned*)(lds + (bufoff) + ldsw + _i * 8192), 16, 0, 0); } while (0)
; #define PG8_LDA(dst, b, h) do { _Pragma("unroll") for (int m = 0; m < 4; ++m) _Pragma("unroll") for (int k = 0; k < 2; ++k) dst[m][k] = *(const PG8_LAS bf16x8*)(lds + PG8_SA(b, h) + aoff + m * 2048 + k * 1024); } while (0)
; #define PG8_LDB(dst, b, h) do { _Pragma("unroll") for (int n = 0; n < 2; ++n) _Pragma("unroll") for (int k = 0; k < 2; ++k) dst[n][k] = *(const PG8_LAS bf16x8*)(lds + PG8_SB(b, h) + boff + n * 2048 + k * 1024); } while (0)
; #define PG8_MMA(ai, bj, At, Bt) do { __builtin_amdgcn_s_setprio(1); _Pragma("unroll") for (int m = 0; m < 4; ++m) _Pragma("unroll") for (int n = 0; n < 2; ++n) _Pragma("unroll") for (int k = 0; k < 2; ++k) \
;         acc[ai][bj][m][n] = __builtin_amdgcn_mfma_f32_16x16x32_bf16(Bt[n][k], At[m][k], acc[ai][bj][m][n], 0, 0, 0); __builtin_amdgcn_s_setprio(0); } while (0)
; #define PG8_WAIT_V(n) asm volatile("s_waitcnt vmcnt(" #n ")" ::: "memory")
; #define PG8_WAIT_L(n) asm volatile("s_waitcnt lgkmcnt(" #n ")" ::: "memory")
; #define PG8_BAR __builtin_amdgcn_s_barrier()
; #define PG8_SCHED __builtin_amdgcn_sched_barrier(0)
; template <class Epi, class Sched, bool ALIGN_EPI = false, bool SP2 = false>
; __device__ __forceinline__ void gemm_phase(PG8_LAS unsigned char* lds, const Gemm g, const Sched& S, const Epi& E) {
;     ...
;             PG8_WAIT_V(8); PG8_WAIT_L(0); PG8_BAR; PG8_MMA(1, 0, At, B0); PG8_MMA(1, 1, At, B1); PG8_BAR; PG8_SCHED;
;             PG8_LDB(B0, 1, 0); PG8_LDB(B1, 1, 1); PG8_SCHED; PG8_LDA(At, 1, 0); PG8_STAGE(PG8_SA(0, 1), a2 + hstep, voffA);
;             PG8_WAIT_V(8); PG8_WAIT_L(0); PG8_BAR; PG8_MMA(0, 0, At, B0); PG8_MMA(0, 1, At, B1); PG8_BAR; PG8_SCHED;
	s_setprio 1
	s_waitcnt lgkmcnt(0)
	v_mfma_f32_16x16x32_bf16 v[60:63], v[96:99], v[160:163], 0
	v_mfma_f32_16x16x32_bf16 v[56:59], v[120:123], v[160:163], 0
	v_mfma_f32_16x16x32_bf16 v[44:47], v[96:99], v[168:171], 0
	v_mfma_f32_16x16x32_bf16 v[40:43], v[120:123], v[168:171], 0
	v_mfma_f32_16x16x32_bf16 v[28:31], v[96:99], v[176:179], 0
	v_mfma_f32_16x16x32_bf16 v[24:27], v[120:123], v[176:179], 0
	v_mfma_f32_16x16x32_bf16 v[12:15], v[96:99], v[202:205], 0
	v_mfma_f32_16x16x32_bf16 v[8:11], v[120:123], v[202:205], 0
	v_mfma_f32_16x16x32_bf16 v[60:63], v[108:111], v[164:167], v[60:63]
	v_mfma_f32_16x16x32_bf16 v[56:59], v[128:131], v[164:167], v[56:59]
	v_mfma_f32_16x16x32_bf16 v[44:47], v[108:111], v[172:175], v[44:47]
	v_mfma_f32_16x16x32_bf16 v[40:43], v[128:131], v[172:175], v[40:43]
	v_mfma_f32_16x16x32_bf16 v[28:31], v[108:111], v[180:183], v[28:31]
	v_mfma_f32_16x16x32_bf16 v[24:27], v[128:131], v[180:183], v[24:27]
	v_mfma_f32_16x16x32_bf16 v[12:15], v[108:111], v[206:209], v[12:15]
	v_mfma_f32_16x16x32_bf16 v[8:11], v[128:131], v[206:209], v[8:11]
	v_mfma_f32_16x16x32_bf16 v[52:55], v[144:147], v[160:163], 0
	v_mfma_f32_16x16x32_bf16 v[48:51], v[152:155], v[160:163], 0
	v_mfma_f32_16x16x32_bf16 v[36:39], v[144:147], v[168:171], 0
	v_mfma_f32_16x16x32_bf16 v[32:35], v[152:155], v[168:171], 0
	v_mfma_f32_16x16x32_bf16 v[20:23], v[144:147], v[176:179], 0
	v_mfma_f32_16x16x32_bf16 v[16:19], v[152:155], v[176:179], 0
	v_mfma_f32_16x16x32_bf16 v[4:7], v[144:147], v[202:205], 0
	v_mfma_f32_16x16x32_bf16 v[0:3], v[152:155], v[202:205], 0
	v_mfma_f32_16x16x32_bf16 v[52:55], v[148:151], v[164:167], v[52:55]
	v_mfma_f32_16x16x32_bf16 v[48:51], v[156:159], v[164:167], v[48:51]
	v_mfma_f32_16x16x32_bf16 v[36:39], v[148:151], v[172:175], v[36:39]
	v_mfma_f32_16x16x32_bf16 v[32:35], v[156:159], v[172:175], v[32:35]
	v_mfma_f32_16x16x32_bf16 v[20:23], v[148:151], v[180:183], v[20:23]
	v_mfma_f32_16x16x32_bf16 v[16:19], v[156:159], v[180:183], v[16:19]
	v_mfma_f32_16x16x32_bf16 v[4:7], v[148:151], v[206:209], v[4:7]
	v_mfma_f32_16x16x32_bf16 v[0:3], v[156:159], v[206:209], v[0:3]
	s_setprio 0
	s_barrier
	s_add_i32 s77, 0, 0x18000
	s_add_i32 s78, 0, 0x1c000
	v_add_u32_e32 v128, s77, v221
	v_add_u32_e32 v156, s78, v221
	ds_read_b128 v[96:99], v128
	ds_read_b128 v[108:111], v128 offset:1024
	ds_read_b128 v[120:123], v128 offset:2048
	ds_read_b128 v[128:131], v128 offset:3072
	ds_read_b128 v[144:147], v156
	ds_read_b128 v[148:151], v156 offset:1024
	ds_read_b128 v[152:155], v156 offset:2048
	ds_read_b128 v[156:159], v156 offset:3072
	s_add_u32 s56, s56, 0x40000
	s_addc_u32 s57, s57, 0
	s_mov_b32 m0, s60
	v_lshl_add_u64 v[218:219], s[56:57], 0, v[184:185]
	ds_read_b128 v[160:163], v225 offset:32768
	ds_read_b128 v[164:167], v225 offset:33792
	ds_read_b128 v[168:171], v225 offset:34816
	ds_read_b128 v[172:175], v225 offset:35840
	ds_read_b128 v[176:179], v225 offset:36864
	ds_read_b128 v[180:183], v225 offset:37888
	ds_read_b128 v[202:205], v225 offset:38912
	ds_read_b128 v[206:209], v225 offset:39936
	global_load_lds_dwordx4 v[218:219], off
	v_lshl_add_u64 v[218:219], s[56:57], 0, v[188:189]
	s_mov_b32 m0, s61
	s_nop 0
	global_load_lds_dwordx4 v[218:219], off
	s_waitcnt vmcnt(8)
	s_waitcnt lgkmcnt(0)
	s_barrier
	s_setprio 1
	s_waitcnt lgkmcnt(0)
	v_mfma_f32_16x16x32_bf16 v[140:143], v[96:99], v[160:163], v[140:143]
	v_mfma_f32_16x16x32_bf16 v[136:139], v[120:123], v[160:163], v[136:139]
	v_mfma_f32_16x16x32_bf16 v[116:119], v[96:99], v[168:171], v[116:119]
	v_mfma_f32_16x16x32_bf16 v[112:115], v[120:123], v[168:171], v[112:115]
	v_mfma_f32_16x16x32_bf16 v[92:95], v[96:99], v[176:179], v[92:95]
	v_mfma_f32_16x16x32_bf16 v[88:91], v[120:123], v[176:179], v[88:91]
	v_mfma_f32_16x16x32_bf16 v[76:79], v[96:99], v[202:205], v[76:79]
	v_mfma_f32_16x16x32_bf16 v[72:75], v[120:123], v[202:205], v[72:75]
	v_mfma_f32_16x16x32_bf16 v[140:143], v[108:111], v[164:167], v[140:143]
	v_mfma_f32_16x16x32_bf16 v[136:139], v[128:131], v[164:167], v[136:139]
	v_mfma_f32_16x16x32_bf16 v[116:119], v[108:111], v[172:175], v[116:119]
	v_mfma_f32_16x16x32_bf16 v[112:115], v[128:131], v[172:175], v[112:115]
	v_mfma_f32_16x16x32_bf16 v[92:95], v[108:111], v[180:183], v[92:95]
	v_mfma_f32_16x16x32_bf16 v[88:91], v[128:131], v[180:183], v[88:91]
	v_mfma_f32_16x16x32_bf16 v[76:79], v[108:111], v[206:209], v[76:79]
	v_mfma_f32_16x16x32_bf16 v[72:75], v[128:131], v[206:209], v[72:75]
	v_mfma_f32_16x16x32_bf16 v[132:135], v[144:147], v[160:163], v[132:135]
	v_mfma_f32_16x16x32_bf16 v[124:127], v[152:155], v[160:163], v[124:127]
	v_mfma_f32_16x16x32_bf16 v[104:107], v[144:147], v[168:171], v[104:107]
	v_mfma_f32_16x16x32_bf16 v[100:103], v[152:155], v[168:171], v[100:103]
	v_mfma_f32_16x16x32_bf16 v[84:87], v[144:147], v[176:179], v[84:87]
	v_mfma_f32_16x16x32_bf16 v[80:83], v[152:155], v[176:179], v[80:83]
	v_mfma_f32_16x16x32_bf16 v[68:71], v[144:147], v[202:205], v[68:71]
	v_mfma_f32_16x16x32_bf16 v[64:67], v[152:155], v[202:205], v[64:67]
	v_mfma_f32_16x16x32_bf16 v[132:135], v[148:151], v[164:167], v[132:135]
	v_mfma_f32_16x16x32_bf16 v[124:127], v[156:159], v[164:167], v[124:127]
	v_mfma_f32_16x16x32_bf16 v[104:107], v[148:151], v[172:175], v[104:107]
	v_mfma_f32_16x16x32_bf16 v[100:103], v[156:159], v[172:175], v[100:103]
	v_mfma_f32_16x16x32_bf16 v[84:87], v[148:151], v[180:183], v[84:87]
	v_mfma_f32_16x16x32_bf16 v[80:83], v[156:159], v[180:183], v[80:83]
	v_mfma_f32_16x16x32_bf16 v[68:71], v[148:151], v[206:209], v[68:71]
	v_mfma_f32_16x16x32_bf16 v[64:67], v[156:159], v[206:209], v[64:67]
	s_setprio 0
	s_barrier
; #define PG8_STAGE(bufoff, gbase, voff) do { _Pragma("unroll") for (int _i = 0; _i < 2; ++_i) \
;         __builtin_amdgcn_global_load_lds((const unsigned*)((const char*)(gbase) + (voff)[_i]), (PG8_LAS unsigned*)(lds + (bufoff) + ldsw + _i * 8192), 16, 0, 0); } while (0)
; #define PG8_LDA(dst, b, h) do { _Pragma("unroll") for (int m = 0; m < 4; ++m) _Pragma("unroll") for (int k = 0; k < 2; ++k) dst[m][k] = *(const PG8_LAS bf16x8*)(lds + PG8_SA(b, h) + aoff + m * 2048 + k * 1024); } while (0)
; #define PG8_MMA(ai, bj, At, Bt) do { __builtin_amdgcn_s_setprio(1); _Pragma("unroll") for (int m = 0; m < 4; ++m) _Pragma("unroll") for (int n = 0; n < 2; ++n) _Pragma("unroll") for (int k = 0; k < 2; ++k) \
;         acc[ai][bj][m][n] = __builtin_amdgcn_mfma_f32_16x16x32_bf16(Bt[n][k], At[m][k], acc[ai][bj][m][n], 0, 0, 0); __builtin_amdgcn_s_setprio(0); } while (0)
; #define PG8_WAIT_V(n) asm volatile("s_waitcnt vmcnt(" #n ")" ::: "memory")
; #define PG8_WAIT_L(n) asm volatile("s_waitcnt lgkmcnt(" #n ")" ::: "memory")
; #define PG8_BAR __builtin_amdgcn_s_barrier()
; #define PG8_SCHED __builtin_amdgcn_sched_barrier(0)
; template <class Epi, class Sched, bool ALIGN_EPI = false, bool SP2 = false>
; __device__ __forceinline__ void gemm_phase(PG8_LAS unsigned char* lds, const Gemm g, const Sched& S, const Epi& E) {
;     ...
;             PG8_LDA(At, 1, 1); PG8_STAGE(PG8_SB(1, 0), b3, voffB); PG8_STAGE(PG8_SB(1, 1), b3 + hstep, voffB); PG8_STAGE(PG8_SA(1, 0), a3, voffA);
;             PG8_WAIT_V(8); PG8_WAIT_L(0); PG8_BAR; PG8_MMA(1, 0, At, B0); PG8_MMA(1, 1, At, B1); PG8_BAR; PG8_SCHED;
	s_add_i32 s56, s77, s58
	v_lshl_add_u64 v[210:211], v[210:211], 0, s[12:13]
	s_mov_b32 m0, s56
	ds_read_b128 v[160:163], v225 offset:49152
	ds_read_b128 v[164:167], v225 offset:50176
	ds_read_b128 v[168:171], v225 offset:51200
	ds_read_b128 v[172:175], v225 offset:52224
	ds_read_b128 v[176:179], v225 offset:53248
	ds_read_b128 v[180:183], v225 offset:54272
	ds_read_b128 v[202:205], v225 offset:55296
	ds_read_b128 v[206:209], v225 offset:56320
	global_load_lds_dwordx4 v[210:211], off
	s_add_i32 m0, s56, 0x2000
	s_add_u32 s54, s54, 0x40080
	v_lshl_add_u64 v[210:211], v[212:213], 0, s[12:13]
	s_addc_u32 s55, s55, 0
	s_add_i32 s56, s78, s58
	global_load_lds_dwordx4 v[210:211], off
	v_lshl_add_u64 v[210:211], s[54:55], 0, v[186:187]
	s_mov_b32 m0, s56
	s_nop 0
	global_load_lds_dwordx4 v[210:211], off
	v_lshl_add_u64 v[210:211], s[54:55], 0, v[190:191]
	s_add_i32 m0, s56, 0x2000
	s_nop 0
	global_load_lds_dwordx4 v[210:211], off
	v_lshl_add_u64 v[210:211], v[214:215], 0, s[12:13]
	s_mov_b32 m0, s66
	s_nop 0
	global_load_lds_dwordx4 v[210:211], off
	v_lshl_add_u64 v[210:211], v[216:217], 0, s[12:13]
	s_mov_b32 m0, s67
	s_nop 0
	global_load_lds_dwordx4 v[210:211], off
	s_waitcnt vmcnt(8)
	s_waitcnt lgkmcnt(0)
	s_barrier
	s_setprio 1
	s_waitcnt lgkmcnt(0)
	v_mfma_f32_16x16x32_bf16 v[60:63], v[96:99], v[160:163], v[60:63]
	v_mfma_f32_16x16x32_bf16 v[56:59], v[120:123], v[160:163], v[56:59]
	v_mfma_f32_16x16x32_bf16 v[44:47], v[96:99], v[168:171], v[44:47]
	v_mfma_f32_16x16x32_bf16 v[40:43], v[120:123], v[168:171], v[40:43]
	v_mfma_f32_16x16x32_bf16 v[28:31], v[96:99], v[176:179], v[28:31]
	v_mfma_f32_16x16x32_bf16 v[24:27], v[120:123], v[176:179], v[24:27]
	v_mfma_f32_16x16x32_bf16 v[12:15], v[96:99], v[202:205], v[12:15]
	v_mfma_f32_16x16x32_bf16 v[8:11], v[120:123], v[202:205], v[8:11]
	v_mfma_f32_16x16x32_bf16 v[60:63], v[108:111], v[164:167], v[60:63]
	v_mfma_f32_16x16x32_bf16 v[56:59], v[128:131], v[164:167], v[56:59]
	v_mfma_f32_16x16x32_bf16 v[44:47], v[108:111], v[172:175], v[44:47]
	v_mfma_f32_16x16x32_bf16 v[40:43], v[128:131], v[172:175], v[40:43]
	v_mfma_f32_16x16x32_bf16 v[28:31], v[108:111], v[180:183], v[28:31]
	v_mfma_f32_16x16x32_bf16 v[24:27], v[128:131], v[180:183], v[24:27]
	v_mfma_f32_16x16x32_bf16 v[12:15], v[108:111], v[206:209], v[12:15]
	v_mfma_f32_16x16x32_bf16 v[8:11], v[128:131], v[206:209], v[8:11]
	v_mfma_f32_16x16x32_bf16 v[52:55], v[144:147], v[160:163], v[52:55]
	v_mfma_f32_16x16x32_bf16 v[48:51], v[152:155], v[160:163], v[48:51]
	v_mfma_f32_16x16x32_bf16 v[36:39], v[144:147], v[168:171], v[36:39]
	v_mfma_f32_16x16x32_bf16 v[32:35], v[152:155], v[168:171], v[32:35]
	v_mfma_f32_16x16x32_bf16 v[20:23], v[144:147], v[176:179], v[20:23]
	v_mfma_f32_16x16x32_bf16 v[16:19], v[152:155], v[176:179], v[16:19]
	v_mfma_f32_16x16x32_bf16 v[4:7], v[144:147], v[202:205], v[4:7]
	v_mfma_f32_16x16x32_bf16 v[0:3], v[152:155], v[202:205], v[0:3]
	v_mfma_f32_16x16x32_bf16 v[52:55], v[148:151], v[164:167], v[52:55]
	v_mfma_f32_16x16x32_bf16 v[48:51], v[156:159], v[164:167], v[48:51]
	v_mfma_f32_16x16x32_bf16 v[36:39], v[148:151], v[172:175], v[36:39]
	v_mfma_f32_16x16x32_bf16 v[32:35], v[156:159], v[172:175], v[32:35]
	v_mfma_f32_16x16x32_bf16 v[20:23], v[148:151], v[180:183], v[20:23]
	v_mfma_f32_16x16x32_bf16 v[16:19], v[156:159], v[180:183], v[16:19]
	v_mfma_f32_16x16x32_bf16 v[4:7], v[148:151], v[206:209], v[4:7]
	v_mfma_f32_16x16x32_bf16 v[0:3], v[156:159], v[206:209], v[0:3]
	s_setprio 0
	s_barrier
	s_add_i32 s76, s76, 2
	s_add_u32 s20, s20, 0x100
	s_addc_u32 s21, s21, 0
	s_add_u32 s74, s74, 0x100
	s_addc_u32 s75, s75, 0
	s_cmp_gt_u32 s76, 13

; #define PG8_STAGE(bufoff, gbase, voff) do { _Pragma("unroll") for (int _i = 0; _i < 2; ++_i) \
;         __builtin_amdgcn_global_load_lds((const unsigned*)((const char*)(gbase) + (voff)[_i]), (PG8_LAS unsigned*)(lds + (bufoff) + ldsw + _i * 8192), 16, 0, 0); } while (0)
; #define PG8_LDA(dst, b, h) do { _Pragma("unroll") for (int m = 0; m < 4; ++m) _Pragma("unroll") for (int k = 0; k < 2; ++k) dst[m][k] = *(const PG8_LAS bf16x8*)(lds + PG8_SA(b, h) + aoff + m * 2048 + k * 1024); } while (0)
; #define PG8_LDB(dst, b, h) do { _Pragma("unroll") for (int n = 0; n < 2; ++n) _Pragma("unroll") for (int k = 0; k < 2; ++k) dst[n][k] = *(const PG8_LAS bf16x8*)(lds + PG8_SB(b, h) + boff + n * 2048 + k * 1024); } while (0)
; #define PG8_WAIT_V(n) asm volatile("s_waitcnt vmcnt(" #n ")" ::: "memory")
; #define PG8_WAIT_L(n) asm volatile("s_waitcnt lgkmcnt(" #n ")" ::: "memory")
; #define PG8_BAR __builtin_amdgcn_s_barrier()
; #define PG8_SCHED __builtin_amdgcn_sched_barrier(0)
; template <class Epi, class Sched, bool ALIGN_EPI = false, bool SP2 = false>
; __device__ __forceinline__ void gemm_phase(PG8_LAS unsigned char* lds, const Gemm g, const Sched& S, const Epi& E) {
;     ...
;         const bool has_next = S.next(ui + 1, nxt);
;         const char* nA = has_next ? (const char*)g.A + (size_t)nxt.pm * tstep : cA; const char* nB = has_next ? (const char*)g.Bt + (size_t)nxt.pn * tstep : cB;
;         for (int t = 0; t < nt; t += 2) {
;             const bool last = (t == nt - 2);
;             const char* a1 = cA + (size_t)(t + 1) * kstep;
;             const char* a2 = last ? nA : cA + (size_t)(t + 2) * kstep; const char* b2 = last ? nB : cB + (size_t)(t + 2) * kstep;
;             const char* a3 = a2 + kstep; const char* b3 = b2 + kstep;
;             if (last && has_next) S.a_ready(nxt);
;             if constexpr (SP2) {
;             PG8_LDB(B0, 0, 0); PG8_LDB(B1, 0, 1); PG8_SCHED; PG8_LDA(At, 0, 0); PG8_STAGE(PG8_SA(1, 1), a1 + hstep, voffA);
;             PG8_WAIT_V(8); PG8_WAIT_L(0); PG8_BAR; PG8_MMA(0, 0, At, B0); PG8_MMA(0, 1, At, B1); PG8_BAR; PG8_SCHED;
;             PG8_LDA(At, 0, 1); PG8_STAGE(PG8_SB(0, 0), b2, voffB); PG8_STAGE(PG8_SB(0, 1), b2 + hstep, voffB); PG8_STAGE(PG8_SA(0, 0), a2, voffA);
;             PG8_WAIT_V(8); PG8_WAIT_L(0); PG8_BAR; PG8_MMA(1, 0, At, B0); PG8_MMA(1, 1, At, B1); PG8_BAR; PG8_SCHED;
.LBB0_1739:
	s_ashr_i32 s15, s14, 31
	s_lshl_b64 s[16:17], s[14:15], 19
	s_add_u32 s16, s36, s16
	s_addc_u32 s17, s37, s17
	s_and_b64 s[18:19], s[4:5], exec
	s_cselect_b32 s15, s17, s21
	s_cselect_b32 s63, s16, s20
	s_ashr_i32 s13, s12, 31
	s_lshl_b64 s[18:19], s[12:13], 19
	s_add_u32 s18, s48, s18
	s_addc_u32 s19, s49, s19
	s_and_b64 s[42:43], s[4:5], exec
	s_cselect_b32 s13, s19, s39
	s_cselect_b32 s64, s18, s38
	s_add_u32 s20, s20, 0x40080
	s_addc_u32 s21, s21, 0
	s_add_u32 s65, s38, 0x100
	s_addc_u32 s66, s39, 0
	s_mov_b32 s67, -2
	ds_read_b128 v[154:157], v150
	ds_read_b128 v[158:161], v150 offset:1024
	ds_read_b128 v[162:165], v150 offset:2048
	ds_read_b128 v[166:169], v150 offset:3072
	ds_read_b128 v[170:173], v151
	ds_read_b128 v[174:177], v151 offset:1024
	ds_read_b128 v[178:181], v151 offset:2048
	ds_read_b128 v[182:185], v151 offset:3072
	s_add_u32 s38, s20, 0xfffc0080
	s_addc_u32 s39, s21, -1
	s_cmp_eq_u32 s67, 12
	s_cselect_b32 s43, s15, s39
	s_cselect_b32 s42, s63, s38
	s_cselect_b32 s39, s13, s66
	s_cselect_b32 s38, s64, s65
	v_lshl_add_u64 v[144:145], s[20:21], 0, v[136:137]
	s_add_i32 m0, s35, 0xc000
	ds_read_b128 v[186:189], v152
	ds_read_b128 v[190:193], v152 offset:1024
	ds_read_b128 v[198:201], v152 offset:2048
	ds_read_b128 v[202:205], v152 offset:3072
	ds_read_b128 v[206:209], v152 offset:4096
	ds_read_b128 v[210:213], v152 offset:5120
	ds_read_b128 v[214:217], v152 offset:6144
	ds_read_b128 v[218:221], v152 offset:7168
	global_load_lds_dwordx4 v[144:145], off
	v_lshl_add_u64 v[144:145], s[20:21], 0, v[138:139]
	s_add_i32 m0, s35, 0xe000
	s_nop 0
	global_load_lds_dwordx4 v[144:145], off
	s_waitcnt vmcnt(8)
	s_waitcnt lgkmcnt(0)
	s_barrier
	s_setprio 1
	s_waitcnt lgkmcnt(0)
	v_mfma_f32_16x16x32_bf16 v[124:127], v[154:157], v[186:189], 0
	v_mfma_f32_16x16x32_bf16 v[116:119], v[162:165], v[186:189], 0
	v_mfma_f32_16x16x32_bf16 v[108:111], v[154:157], v[198:201], 0
	v_mfma_f32_16x16x32_bf16 v[100:103], v[162:165], v[198:201], 0
	v_mfma_f32_16x16x32_bf16 v[92:95], v[154:157], v[206:209], 0
	v_mfma_f32_16x16x32_bf16 v[84:87], v[162:165], v[206:209], 0
	v_mfma_f32_16x16x32_bf16 v[76:79], v[154:157], v[214:217], 0
	v_mfma_f32_16x16x32_bf16 v[68:71], v[162:165], v[214:217], 0
	v_mfma_f32_16x16x32_bf16 v[124:127], v[158:161], v[190:193], v[124:127]
	v_mfma_f32_16x16x32_bf16 v[116:119], v[166:169], v[190:193], v[116:119]
	v_mfma_f32_16x16x32_bf16 v[108:111], v[158:161], v[202:205], v[108:111]
	v_mfma_f32_16x16x32_bf16 v[100:103], v[166:169], v[202:205], v[100:103]
	v_mfma_f32_16x16x32_bf16 v[92:95], v[158:161], v[210:213], v[92:95]
	v_mfma_f32_16x16x32_bf16 v[84:87], v[166:169], v[210:213], v[84:87]
	v_mfma_f32_16x16x32_bf16 v[76:79], v[158:161], v[218:221], v[76:79]
	v_mfma_f32_16x16x32_bf16 v[68:71], v[166:169], v[218:221], v[68:71]
	v_mfma_f32_16x16x32_bf16 v[120:123], v[170:173], v[186:189], 0
	v_mfma_f32_16x16x32_bf16 v[112:115], v[178:181], v[186:189], 0
	v_mfma_f32_16x16x32_bf16 v[104:107], v[170:173], v[198:201], 0
	v_mfma_f32_16x16x32_bf16 v[96:99], v[178:181], v[198:201], 0
	v_mfma_f32_16x16x32_bf16 v[88:91], v[170:173], v[206:209], 0
	v_mfma_f32_16x16x32_bf16 v[80:83], v[178:181], v[206:209], 0
	v_mfma_f32_16x16x32_bf16 v[72:75], v[170:173], v[214:217], 0
	v_mfma_f32_16x16x32_bf16 v[64:67], v[178:181], v[214:217], 0
	v_mfma_f32_16x16x32_bf16 v[120:123], v[174:177], v[190:193], v[120:123]
	v_mfma_f32_16x16x32_bf16 v[112:115], v[182:185], v[190:193], v[112:115]
	v_mfma_f32_16x16x32_bf16 v[104:107], v[174:177], v[202:205], v[104:107]
	v_mfma_f32_16x16x32_bf16 v[96:99], v[182:185], v[202:205], v[96:99]
	v_mfma_f32_16x16x32_bf16 v[88:91], v[174:177], v[210:213], v[88:91]
	v_mfma_f32_16x16x32_bf16 v[80:83], v[182:185], v[210:213], v[80:83]
	v_mfma_f32_16x16x32_bf16 v[72:75], v[174:177], v[218:221], v[72:75]
	v_mfma_f32_16x16x32_bf16 v[64:67], v[182:185], v[218:221], v[64:67]
	s_setprio 0
	s_barrier
	s_add_i32 s68, s58, s50
	v_lshl_add_u64 v[144:145], s[38:39], 0, v[132:133]
	s_mov_b32 m0, s68
	ds_read_b128 v[186:189], v152 offset:16384
	ds_read_b128 v[190:193], v152 offset:17408
	ds_read_b128 v[198:201], v152 offset:18432
	ds_read_b128 v[202:205], v152 offset:19456
	ds_read_b128 v[206:209], v152 offset:20480
	ds_read_b128 v[210:213], v152 offset:21504
	ds_read_b128 v[214:217], v152 offset:22528
	ds_read_b128 v[218:221], v152 offset:23552
	global_load_lds_dwordx4 v[144:145], off
	s_add_i32 m0, s68, 0x2000
	s_add_u32 s68, s38, 0x40000
	v_lshl_add_u64 v[194:195], s[38:39], 0, v[128:129]
	s_addc_u32 s69, s39, 0
	s_add_i32 s70, s59, s50
	global_load_lds_dwordx4 v[194:195], off
	v_lshl_add_u64 v[222:223], s[68:69], 0, v[132:133]
	s_mov_b32 m0, s70
	v_lshl_add_u64 v[224:225], s[42:43], 0, v[130:131]
	global_load_lds_dwordx4 v[222:223], off
	v_lshl_add_u64 v[222:223], s[68:69], 0, v[128:129]
	s_add_i32 m0, s70, 0x2000
	s_nop 0
	global_load_lds_dwordx4 v[222:223], off
	v_lshl_add_u64 v[222:223], s[42:43], 0, v[134:135]
	s_mov_b32 m0, s35
	s_nop 0
	global_load_lds_dwordx4 v[222:223], off
	s_mov_b32 m0, s52
	s_nop 0
	global_load_lds_dwordx4 v[224:225], off
	s_waitcnt vmcnt(8)
	s_waitcnt lgkmcnt(0)
	s_barrier
; #define PG8_STAGE(bufoff, gbase, voff) do { _Pragma("unroll") for (int _i = 0; _i < 2; ++_i) \
;         __builtin_amdgcn_global_load_lds((const unsigned*)((const char*)(gbase) + (voff)[_i]), (PG8_LAS unsigned*)(lds + (bufoff) + ldsw + _i * 8192), 16, 0, 0); } while (0)
; #define PG8_LDA(dst, b, h) do { _Pragma("unroll") for (int m = 0; m < 4; ++m) _Pragma("unroll") for (int k = 0; k < 2; ++k) dst[m][k] = *(const PG8_LAS bf16x8*)(lds + PG8_SA(b, h) + aoff + m * 2048 + k * 1024); } while (0)
; #define PG8_LDB(dst, b, h) do { _Pragma("unroll") for (int n = 0; n < 2; ++n) _Pragma("unroll") for (int k = 0; k < 2; ++k) dst[n][k] = *(const PG8_LAS bf16x8*)(lds + PG8_SB(b, h) + boff + n * 2048 + k * 1024); } while (0)
; #define PG8_MMA(ai, bj, At, Bt) do { __builtin_amdgcn_s_setprio(1); _Pragma("unroll") for (int m = 0; m < 4; ++m) _Pragma("unroll") for (int n = 0; n < 2; ++n) _Pragma("unroll") for (int k = 0; k < 2; ++k) \
;         acc[ai][bj][m][n] = __builtin_amdgcn_mfma_f32_16x16x32_bf16(Bt[n][k], At[m][k], acc[ai][bj][m][n], 0, 0, 0); __builtin_amdgcn_s_setprio(0); } while (0)
; #define PG8_WAIT_V(n) asm volatile("s_waitcnt vmcnt(" #n ")" ::: "memory")
; #define PG8_WAIT_L(n) asm volatile("s_waitcnt lgkmcnt(" #n ")" ::: "memory")
; #define PG8_BAR __builtin_amdgcn_s_barrier()
; #define PG8_SCHED __builtin_amdgcn_sched_barrier(0)
; template <class Epi, class Sched, bool ALIGN_EPI = false, bool SP2 = false>
; __device__ __forceinline__ void gemm_phase(PG8_LAS unsigned char* lds, const Gemm g, const Sched& S, const Epi& E) {
;     ...
;             PG8_WAIT_V(8); PG8_WAIT_L(0); PG8_BAR; PG8_MMA(1, 0, At, B0); PG8_MMA(1, 1, At, B1); PG8_BAR; PG8_SCHED;
;             PG8_LDB(B0, 1, 0); PG8_LDB(B1, 1, 1); PG8_SCHED; PG8_LDA(At, 1, 0); PG8_STAGE(PG8_SA(0, 1), a2 + hstep, voffA);
;             PG8_WAIT_V(8); PG8_WAIT_L(0); PG8_BAR; PG8_MMA(0, 0, At, B0); PG8_MMA(0, 1, At, B1); PG8_BAR; PG8_SCHED;
	s_setprio 1
	s_waitcnt lgkmcnt(0)
	v_mfma_f32_16x16x32_bf16 v[60:63], v[154:157], v[186:189], 0
	v_mfma_f32_16x16x32_bf16 v[52:55], v[162:165], v[186:189], 0
	v_mfma_f32_16x16x32_bf16 v[44:47], v[154:157], v[198:201], 0
	v_mfma_f32_16x16x32_bf16 v[36:39], v[162:165], v[198:201], 0
	v_mfma_f32_16x16x32_bf16 v[28:31], v[154:157], v[206:209], 0
	v_mfma_f32_16x16x32_bf16 v[20:23], v[162:165], v[206:209], 0
	v_mfma_f32_16x16x32_bf16 v[12:15], v[154:157], v[214:217], 0
	v_mfma_f32_16x16x32_bf16 v[4:7], v[162:165], v[214:217], 0
	v_mfma_f32_16x16x32_bf16 v[60:63], v[158:161], v[190:193], v[60:63]
	v_mfma_f32_16x16x32_bf16 v[52:55], v[166:169], v[190:193], v[52:55]
	v_mfma_f32_16x16x32_bf16 v[44:47], v[158:161], v[202:205], v[44:47]
	v_mfma_f32_16x16x32_bf16 v[36:39], v[166:169], v[202:205], v[36:39]
	v_mfma_f32_16x16x32_bf16 v[28:31], v[158:161], v[210:213], v[28:31]
	v_mfma_f32_16x16x32_bf16 v[20:23], v[166:169], v[210:213], v[20:23]
	v_mfma_f32_16x16x32_bf16 v[12:15], v[158:161], v[218:221], v[12:15]
	v_mfma_f32_16x16x32_bf16 v[4:7], v[166:169], v[218:221], v[4:7]
	v_mfma_f32_16x16x32_bf16 v[56:59], v[170:173], v[186:189], 0
	v_mfma_f32_16x16x32_bf16 v[48:51], v[178:181], v[186:189], 0
	v_mfma_f32_16x16x32_bf16 v[40:43], v[170:173], v[198:201], 0
	v_mfma_f32_16x16x32_bf16 v[32:35], v[178:181], v[198:201], 0
	v_mfma_f32_16x16x32_bf16 v[24:27], v[170:173], v[206:209], 0
	v_mfma_f32_16x16x32_bf16 v[16:19], v[178:181], v[206:209], 0
	v_mfma_f32_16x16x32_bf16 v[8:11], v[170:173], v[214:217], 0
	v_mfma_f32_16x16x32_bf16 v[0:3], v[178:181], v[214:217], 0
	v_mfma_f32_16x16x32_bf16 v[56:59], v[174:177], v[190:193], v[56:59]
	v_mfma_f32_16x16x32_bf16 v[48:51], v[182:185], v[190:193], v[48:51]
	v_mfma_f32_16x16x32_bf16 v[40:43], v[174:177], v[202:205], v[40:43]
	v_mfma_f32_16x16x32_bf16 v[32:35], v[182:185], v[202:205], v[32:35]
	v_mfma_f32_16x16x32_bf16 v[24:27], v[174:177], v[210:213], v[24:27]
	v_mfma_f32_16x16x32_bf16 v[16:19], v[182:185], v[210:213], v[16:19]
	v_mfma_f32_16x16x32_bf16 v[8:11], v[174:177], v[218:221], v[8:11]
	v_mfma_f32_16x16x32_bf16 v[0:3], v[182:185], v[218:221], v[0:3]
	s_setprio 0
	s_barrier
	s_add_i32 s68, 0, 0x18000
	v_add_u32_e32 v153, s68, v147
	s_add_i32 s69, 0, 0x1c000
	ds_read_b128 v[154:157], v153
	ds_read_b128 v[158:161], v153 offset:1024
	ds_read_b128 v[162:165], v153 offset:2048
	ds_read_b128 v[166:169], v153 offset:3072
	v_add_u32_e32 v153, s69, v147
	ds_read_b128 v[170:173], v153
	ds_read_b128 v[174:177], v153 offset:1024
	ds_read_b128 v[178:181], v153 offset:2048
	ds_read_b128 v[182:185], v153 offset:3072
	s_add_u32 s42, s42, 0x40000
	s_addc_u32 s43, s43, 0
	s_mov_b32 m0, s53
	v_lshl_add_u64 v[226:227], s[42:43], 0, v[134:135]
	ds_read_b128 v[186:189], v152 offset:32768
	ds_read_b128 v[190:193], v152 offset:33792
	ds_read_b128 v[198:201], v152 offset:34816
	ds_read_b128 v[202:205], v152 offset:35840
	ds_read_b128 v[206:209], v152 offset:36864
	ds_read_b128 v[210:213], v152 offset:37888
	ds_read_b128 v[214:217], v152 offset:38912
	ds_read_b128 v[218:221], v152 offset:39936
	global_load_lds_dwordx4 v[226:227], off
	v_lshl_add_u64 v[226:227], s[42:43], 0, v[130:131]
	s_mov_b32 m0, s54
	s_nop 0
	global_load_lds_dwordx4 v[226:227], off
	s_waitcnt vmcnt(8)
	s_waitcnt lgkmcnt(0)
	s_barrier
	s_setprio 1
	s_waitcnt lgkmcnt(0)
	v_mfma_f32_16x16x32_bf16 v[124:127], v[154:157], v[186:189], v[124:127]
	v_mfma_f32_16x16x32_bf16 v[116:119], v[162:165], v[186:189], v[116:119]
	v_mfma_f32_16x16x32_bf16 v[108:111], v[154:157], v[198:201], v[108:111]
	v_mfma_f32_16x16x32_bf16 v[100:103], v[162:165], v[198:201], v[100:103]
	v_mfma_f32_16x16x32_bf16 v[92:95], v[154:157], v[206:209], v[92:95]
	v_mfma_f32_16x16x32_bf16 v[84:87], v[162:165], v[206:209], v[84:87]
	v_mfma_f32_16x16x32_bf16 v[76:79], v[154:157], v[214:217], v[76:79]
	v_mfma_f32_16x16x32_bf16 v[68:71], v[162:165], v[214:217], v[68:71]
	v_mfma_f32_16x16x32_bf16 v[124:127], v[158:161], v[190:193], v[124:127]
	v_mfma_f32_16x16x32_bf16 v[116:119], v[166:169], v[190:193], v[116:119]
	v_mfma_f32_16x16x32_bf16 v[108:111], v[158:161], v[202:205], v[108:111]
	v_mfma_f32_16x16x32_bf16 v[100:103], v[166:169], v[202:205], v[100:103]
	v_mfma_f32_16x16x32_bf16 v[92:95], v[158:161], v[210:213], v[92:95]
	v_mfma_f32_16x16x32_bf16 v[84:87], v[166:169], v[210:213], v[84:87]
	v_mfma_f32_16x16x32_bf16 v[76:79], v[158:161], v[218:221], v[76:79]
	v_mfma_f32_16x16x32_bf16 v[68:71], v[166:169], v[218:221], v[68:71]
	v_mfma_f32_16x16x32_bf16 v[120:123], v[170:173], v[186:189], v[120:123]
	v_mfma_f32_16x16x32_bf16 v[112:115], v[178:181], v[186:189], v[112:115]
	v_mfma_f32_16x16x32_bf16 v[104:107], v[170:173], v[198:201], v[104:107]
	v_mfma_f32_16x16x32_bf16 v[96:99], v[178:181], v[198:201], v[96:99]
	v_mfma_f32_16x16x32_bf16 v[88:91], v[170:173], v[206:209], v[88:91]
	v_mfma_f32_16x16x32_bf16 v[80:83], v[178:181], v[206:209], v[80:83]
	v_mfma_f32_16x16x32_bf16 v[72:75], v[170:173], v[214:217], v[72:75]
	v_mfma_f32_16x16x32_bf16 v[64:67], v[178:181], v[214:217], v[64:67]
	v_mfma_f32_16x16x32_bf16 v[120:123], v[174:177], v[190:193], v[120:123]
	v_mfma_f32_16x16x32_bf16 v[112:115], v[182:185], v[190:193], v[112:115]
	v_mfma_f32_16x16x32_bf16 v[104:107], v[174:177], v[202:205], v[104:107]
	v_mfma_f32_16x16x32_bf16 v[96:99], v[182:185], v[202:205], v[96:99]
	v_mfma_f32_16x16x32_bf16 v[88:91], v[174:177], v[210:213], v[88:91]
	v_mfma_f32_16x16x32_bf16 v[80:83], v[182:185], v[210:213], v[80:83]
	v_mfma_f32_16x16x32_bf16 v[72:75], v[174:177], v[218:221], v[72:75]
	v_mfma_f32_16x16x32_bf16 v[64:67], v[182:185], v[218:221], v[64:67]
	s_setprio 0
	s_barrier
; #define PG8_STAGE(bufoff, gbase, voff) do { _Pragma("unroll") for (int _i = 0; _i < 2; ++_i) \
;         __builtin_amdgcn_global_load_lds((const unsigned*)((const char*)(gbase) + (voff)[_i]), (PG8_LAS unsigned*)(lds + (bufoff) + ldsw + _i * 8192), 16, 0, 0); } while (0)
; #define PG8_LDA(dst, b, h) do { _Pragma("unroll") for (int m = 0; m < 4; ++m) _Pragma("unroll") for (int k = 0; k < 2; ++k) dst[m][k] = *(const PG8_LAS bf16x8*)(lds + PG8_SA(b, h) + aoff + m * 2048 + k * 1024); } while (0)
; #define PG8_LDB(dst, b, h) do { _Pragma("unroll") for (int n = 0; n < 2; ++n) _Pragma("unroll") for (int k = 0; k < 2; ++k) dst[n][k] = *(const PG8_LAS bf16x8*)(lds + PG8_SB(b, h) + boff + n * 2048 + k * 1024); } while (0)
; #define PG8_MMA(ai, bj, At, Bt) do { __builtin_amdgcn_s_setprio(1); _Pragma("unroll") for (int m = 0; m < 4; ++m) _Pragma("unroll") for (int n = 0; n < 2; ++n) _Pragma("unroll") for (int k = 0; k < 2; ++k) \
;         acc[ai][bj][m][n] = __builtin_amdgcn_mfma_f32_16x16x32_bf16(Bt[n][k], At[m][k], acc[ai][bj][m][n], 0, 0, 0); __builtin_amdgcn_s_setprio(0); } while (0)
; #define PG8_WAIT_V(n) asm volatile("s_waitcnt vmcnt(" #n ")" ::: "memory")
; template <class Epi, class Sched, bool ALIGN_EPI = false, bool SP2 = false>
; __device__ __forceinline__ void gemm_phase(PG8_LAS unsigned char* lds, const Gemm g, const Sched& S, const Epi& E) {
;     ...
;             PG8_LDB(B0, 0, 0); PG8_LDB(B1, 0, 1); PG8_SCHED; PG8_LDA(At, 0, 0); PG8_STAGE(PG8_SA(1, 1), a1 + hstep, voffA);
;             PG8_WAIT_V(8); PG8_WAIT_L(0); PG8_BAR; PG8_MMA(0, 0, At, B0); PG8_MMA(0, 1, At, B1); PG8_BAR; PG8_SCHED;
;             PG8_LDA(At, 0, 1); PG8_STAGE(PG8_SB(0, 0), b2, voffB); PG8_STAGE(PG8_SB(0, 1), b2 + hstep, voffB); PG8_STAGE(PG8_SA(0, 0), a2, voffA);
;             PG8_WAIT_V(8); PG8_WAIT_L(0); PG8_BAR; PG8_MMA(1, 0, At, B0); PG8_MMA(1, 1, At, B1); PG8_BAR; PG8_SCHED;
;             PG8_LDB(B0, 1, 0); PG8_LDB(B1, 1, 1); PG8_SCHED; PG8_LDA(At, 1, 0); PG8_STAGE(PG8_SA(0, 1), a2 + hstep, voffA);
;             PG8_WAIT_V(8); PG8_WAIT_L(0); PG8_BAR; PG8_MMA(0, 0, At, B0); PG8_MMA(0, 1, At, B1); PG8_BAR; PG8_SCHED;
;             PG8_LDA(At, 1, 1); PG8_STAGE(PG8_SB(1, 0), b3, voffB); PG8_STAGE(PG8_SB(1, 1), b3 + hstep, voffB); PG8_STAGE(PG8_SA(1, 0), a3, voffA);
;             PG8_WAIT_V(8); PG8_WAIT_L(0); PG8_BAR; PG8_MMA(1, 0, At, B0); PG8_MMA(1, 1, At, B1); PG8_BAR; PG8_SCHED;
	s_add_i32 s42, s68, s50
	v_lshl_add_u64 v[144:145], v[144:145], 0, s[8:9]
	s_mov_b32 m0, s42
	ds_read_b128 v[186:189], v152 offset:49152
	ds_read_b128 v[190:193], v152 offset:50176
	ds_read_b128 v[198:201], v152 offset:51200
	ds_read_b128 v[202:205], v152 offset:52224
	ds_read_b128 v[206:209], v152 offset:53248
	ds_read_b128 v[210:213], v152 offset:54272
	ds_read_b128 v[214:217], v152 offset:55296
	ds_read_b128 v[218:221], v152 offset:56320
	global_load_lds_dwordx4 v[144:145], off
	s_add_i32 m0, s42, 0x2000
	s_add_u32 s38, s38, 0x40080
	v_lshl_add_u64 v[144:145], v[194:195], 0, s[8:9]
	s_addc_u32 s39, s39, 0
	s_add_i32 s42, s69, s50
	global_load_lds_dwordx4 v[144:145], off
	v_lshl_add_u64 v[144:145], s[38:39], 0, v[132:133]
	s_mov_b32 m0, s42
	s_nop 0
	global_load_lds_dwordx4 v[144:145], off
	v_lshl_add_u64 v[144:145], s[38:39], 0, v[128:129]
	s_add_i32 m0, s42, 0x2000
	s_nop 0
	global_load_lds_dwordx4 v[144:145], off
	v_lshl_add_u64 v[144:145], v[222:223], 0, s[8:9]
	s_mov_b32 m0, s56
	s_nop 0
	global_load_lds_dwordx4 v[144:145], off
	v_lshl_add_u64 v[144:145], v[224:225], 0, s[8:9]
	s_mov_b32 m0, s57
	s_nop 0
	global_load_lds_dwordx4 v[144:145], off
	s_waitcnt vmcnt(8)
	s_waitcnt lgkmcnt(0)
	s_barrier
	s_setprio 1
	s_waitcnt lgkmcnt(0)
	v_mfma_f32_16x16x32_bf16 v[60:63], v[154:157], v[186:189], v[60:63]
	v_mfma_f32_16x16x32_bf16 v[52:55], v[162:165], v[186:189], v[52:55]
	v_mfma_f32_16x16x32_bf16 v[44:47], v[154:157], v[198:201], v[44:47]
	v_mfma_f32_16x16x32_bf16 v[36:39], v[162:165], v[198:201], v[36:39]
	v_mfma_f32_16x16x32_bf16 v[28:31], v[154:157], v[206:209], v[28:31]
	v_mfma_f32_16x16x32_bf16 v[20:23], v[162:165], v[206:209], v[20:23]
	v_mfma_f32_16x16x32_bf16 v[12:15], v[154:157], v[214:217], v[12:15]
	v_mfma_f32_16x16x32_bf16 v[4:7], v[162:165], v[214:217], v[4:7]
	v_mfma_f32_16x16x32_bf16 v[60:63], v[158:161], v[190:193], v[60:63]
	v_mfma_f32_16x16x32_bf16 v[52:55], v[166:169], v[190:193], v[52:55]
	v_mfma_f32_16x16x32_bf16 v[44:47], v[158:161], v[202:205], v[44:47]
	v_mfma_f32_16x16x32_bf16 v[36:39], v[166:169], v[202:205], v[36:39]
	v_mfma_f32_16x16x32_bf16 v[28:31], v[158:161], v[210:213], v[28:31]
	v_mfma_f32_16x16x32_bf16 v[20:23], v[166:169], v[210:213], v[20:23]
	v_mfma_f32_16x16x32_bf16 v[12:15], v[158:161], v[218:221], v[12:15]
	v_mfma_f32_16x16x32_bf16 v[4:7], v[166:169], v[218:221], v[4:7]
	v_mfma_f32_16x16x32_bf16 v[56:59], v[170:173], v[186:189], v[56:59]
	v_mfma_f32_16x16x32_bf16 v[48:51], v[178:181], v[186:189], v[48:51]
	v_mfma_f32_16x16x32_bf16 v[40:43], v[170:173], v[198:201], v[40:43]
	v_mfma_f32_16x16x32_bf16 v[32:35], v[178:181], v[198:201], v[32:35]
	v_mfma_f32_16x16x32_bf16 v[24:27], v[170:173], v[206:209], v[24:27]
	v_mfma_f32_16x16x32_bf16 v[16:19], v[178:181], v[206:209], v[16:19]
	v_mfma_f32_16x16x32_bf16 v[8:11], v[170:173], v[214:217], v[8:11]
	v_mfma_f32_16x16x32_bf16 v[0:3], v[178:181], v[214:217], v[0:3]
	v_mfma_f32_16x16x32_bf16 v[56:59], v[174:177], v[190:193], v[56:59]
	v_mfma_f32_16x16x32_bf16 v[48:51], v[182:185], v[190:193], v[48:51]
	v_mfma_f32_16x16x32_bf16 v[40:43], v[174:177], v[202:205], v[40:43]
	v_mfma_f32_16x16x32_bf16 v[32:35], v[182:185], v[202:205], v[32:35]
	v_mfma_f32_16x16x32_bf16 v[24:27], v[174:177], v[210:213], v[24:27]
	v_mfma_f32_16x16x32_bf16 v[16:19], v[182:185], v[210:213], v[16:19]
	v_mfma_f32_16x16x32_bf16 v[8:11], v[174:177], v[218:221], v[8:11]
	v_mfma_f32_16x16x32_bf16 v[0:3], v[182:185], v[218:221], v[0:3]
	s_setprio 0
	s_barrier
	s_add_i32 s67, s67, 2
	s_add_u32 s20, s20, 0x100
	s_addc_u32 s21, s21, 0
	s_add_u32 s65, s65, 0x100
	s_addc_u32 s66, s66, 0
	s_cmp_gt_u32 s67, 13
.LBB0_1740:
	ds_read_b128 v[154:157], v150
	ds_read_b128 v[158:161], v150 offset:1024
	ds_read_b128 v[162:165], v150 offset:2048
	ds_read_b128 v[166:169], v150 offset:3072
	ds_read_b128 v[170:173], v151
	ds_read_b128 v[174:177], v151 offset:1024
	ds_read_b128 v[178:181], v151 offset:2048
	ds_read_b128 v[182:185], v151 offset:3072
	s_add_u32 s38, s20, 0xfffc0080
	s_addc_u32 s39, s21, -1
	s_cmp_eq_u32 s67, 12
	s_cselect_b32 s43, s15, s39
	s_cselect_b32 s42, s63, s38
	s_cselect_b32 s39, s13, s66
	s_cselect_b32 s38, s64, s65
	v_lshl_add_u64 v[144:145], s[20:21], 0, v[136:137]
	s_add_i32 m0, s35, 0xc000
	ds_read_b128 v[186:189], v152
	ds_read_b128 v[190:193], v152 offset:1024
	ds_read_b128 v[198:201], v152 offset:2048
	ds_read_b128 v[202:205], v152 offset:3072
	ds_read_b128 v[206:209], v152 offset:4096
	ds_read_b128 v[210:213], v152 offset:5120
	ds_read_b128 v[214:217], v152 offset:6144
	ds_read_b128 v[218:221], v152 offset:7168
	global_load_lds_dwordx4 v[144:145], off
	v_lshl_add_u64 v[144:145], s[20:21], 0, v[138:139]
	s_add_i32 m0, s35, 0xe000
	s_nop 0
	global_load_lds_dwordx4 v[144:145], off
	s_waitcnt vmcnt(8)
	s_waitcnt lgkmcnt(0)
	s_barrier
; #define PG8_STAGE(bufoff, gbase, voff) do { _Pragma("unroll") for (int _i = 0; _i < 2; ++_i) \
;         __builtin_amdgcn_global_load_lds((const unsigned*)((const char*)(gbase) + (voff)[_i]), (PG8_LAS unsigned*)(lds + (bufoff) + ldsw + _i * 8192), 16, 0, 0); } while (0)
; #define PG8_LDA(dst, b, h) do { _Pragma("unroll") for (int m = 0; m < 4; ++m) _Pragma("unroll") for (int k = 0; k < 2; ++k) dst[m][k] = *(const PG8_LAS bf16x8*)(lds + PG8_SA(b, h) + aoff + m * 2048 + k * 1024); } while (0)
; #define PG8_MMA(ai, bj, At, Bt) do { __builtin_amdgcn_s_setprio(1); _Pragma("unroll") for (int m = 0; m < 4; ++m) _Pragma("unroll") for (int n = 0; n < 2; ++n) _Pragma("unroll") for (int k = 0; k < 2; ++k) \
;         acc[ai][bj][m][n] = __builtin_amdgcn_mfma_f32_16x16x32_bf16(Bt[n][k], At[m][k], acc[ai][bj][m][n], 0, 0, 0); __builtin_amdgcn_s_setprio(0); } while (0)
; #define PG8_WAIT_V(n) asm volatile("s_waitcnt vmcnt(" #n ")" ::: "memory")
; #define PG8_WAIT_L(n) asm volatile("s_waitcnt lgkmcnt(" #n ")" ::: "memory")
; #define PG8_BAR __builtin_amdgcn_s_barrier()
; #define PG8_SCHED __builtin_amdgcn_sched_barrier(0)
; template <class Epi, class Sched, bool ALIGN_EPI = false, bool SP2 = false>
; __device__ __forceinline__ void gemm_phase(PG8_LAS unsigned char* lds, const Gemm g, const Sched& S, const Epi& E) {
;     ...
;             PG8_WAIT_V(8); PG8_WAIT_L(0); PG8_BAR; PG8_MMA(0, 0, At, B0); PG8_MMA(0, 1, At, B1); PG8_BAR; PG8_SCHED;
;             PG8_LDA(At, 0, 1); PG8_STAGE(PG8_SB(0, 0), b2, voffB); PG8_STAGE(PG8_SB(0, 1), b2 + hstep, voffB); PG8_STAGE(PG8_SA(0, 0), a2, voffA);
;             PG8_WAIT_V(8); PG8_WAIT_L(0); PG8_BAR; PG8_MMA(1, 0, At, B0); PG8_MMA(1, 1, At, B1); PG8_BAR; PG8_SCHED;
	s_setprio 1
	s_waitcnt lgkmcnt(0)
	v_mfma_f32_16x16x32_bf16 v[124:127], v[154:157], v[186:189], v[124:127]
	v_mfma_f32_16x16x32_bf16 v[116:119], v[162:165], v[186:189], v[116:119]
	v_mfma_f32_16x16x32_bf16 v[108:111], v[154:157], v[198:201], v[108:111]
	v_mfma_f32_16x16x32_bf16 v[100:103], v[162:165], v[198:201], v[100:103]
	v_mfma_f32_16x16x32_bf16 v[92:95], v[154:157], v[206:209], v[92:95]
	v_mfma_f32_16x16x32_bf16 v[84:87], v[162:165], v[206:209], v[84:87]
	v_mfma_f32_16x16x32_bf16 v[76:79], v[154:157], v[214:217], v[76:79]
	v_mfma_f32_16x16x32_bf16 v[68:71], v[162:165], v[214:217], v[68:71]
	v_mfma_f32_16x16x32_bf16 v[124:127], v[158:161], v[190:193], v[124:127]
	v_mfma_f32_16x16x32_bf16 v[116:119], v[166:169], v[190:193], v[116:119]
	v_mfma_f32_16x16x32_bf16 v[108:111], v[158:161], v[202:205], v[108:111]
	v_mfma_f32_16x16x32_bf16 v[100:103], v[166:169], v[202:205], v[100:103]
	v_mfma_f32_16x16x32_bf16 v[92:95], v[158:161], v[210:213], v[92:95]
	v_mfma_f32_16x16x32_bf16 v[84:87], v[166:169], v[210:213], v[84:87]
	v_mfma_f32_16x16x32_bf16 v[76:79], v[158:161], v[218:221], v[76:79]
	v_mfma_f32_16x16x32_bf16 v[68:71], v[166:169], v[218:221], v[68:71]
	v_mfma_f32_16x16x32_bf16 v[120:123], v[170:173], v[186:189], v[120:123]
	v_mfma_f32_16x16x32_bf16 v[112:115], v[178:181], v[186:189], v[112:115]
	v_mfma_f32_16x16x32_bf16 v[104:107], v[170:173], v[198:201], v[104:107]
	v_mfma_f32_16x16x32_bf16 v[96:99], v[178:181], v[198:201], v[96:99]
	v_mfma_f32_16x16x32_bf16 v[88:91], v[170:173], v[206:209], v[88:91]
	v_mfma_f32_16x16x32_bf16 v[80:83], v[178:181], v[206:209], v[80:83]
	v_mfma_f32_16x16x32_bf16 v[72:75], v[170:173], v[214:217], v[72:75]
	v_mfma_f32_16x16x32_bf16 v[64:67], v[178:181], v[214:217], v[64:67]
	v_mfma_f32_16x16x32_bf16 v[120:123], v[174:177], v[190:193], v[120:123]
	v_mfma_f32_16x16x32_bf16 v[112:115], v[182:185], v[190:193], v[112:115]
	v_mfma_f32_16x16x32_bf16 v[104:107], v[174:177], v[202:205], v[104:107]
	v_mfma_f32_16x16x32_bf16 v[96:99], v[182:185], v[202:205], v[96:99]
	v_mfma_f32_16x16x32_bf16 v[88:91], v[174:177], v[210:213], v[88:91]
	v_mfma_f32_16x16x32_bf16 v[80:83], v[182:185], v[210:213], v[80:83]
	v_mfma_f32_16x16x32_bf16 v[72:75], v[174:177], v[218:221], v[72:75]
	v_mfma_f32_16x16x32_bf16 v[64:67], v[182:185], v[218:221], v[64:67]
	s_setprio 0
	s_barrier
	s_add_i32 s68, s58, s50
	v_lshl_add_u64 v[144:145], s[38:39], 0, v[132:133]
	s_mov_b32 m0, s68
	ds_read_b128 v[186:189], v152 offset:16384
	ds_read_b128 v[190:193], v152 offset:17408
	ds_read_b128 v[198:201], v152 offset:18432
	ds_read_b128 v[202:205], v152 offset:19456
	ds_read_b128 v[206:209], v152 offset:20480
	ds_read_b128 v[210:213], v152 offset:21504
	ds_read_b128 v[214:217], v152 offset:22528
	ds_read_b128 v[218:221], v152 offset:23552
	global_load_lds_dwordx4 v[144:145], off
	s_add_i32 m0, s68, 0x2000
	s_add_u32 s68, s38, 0x40000
	v_lshl_add_u64 v[194:195], s[38:39], 0, v[128:129]
	s_addc_u32 s69, s39, 0
	s_add_i32 s70, s59, s50
	global_load_lds_dwordx4 v[194:195], off
	v_lshl_add_u64 v[222:223], s[68:69], 0, v[132:133]
	s_mov_b32 m0, s70
	v_lshl_add_u64 v[224:225], s[42:43], 0, v[130:131]
	global_load_lds_dwordx4 v[222:223], off
	v_lshl_add_u64 v[222:223], s[68:69], 0, v[128:129]
	s_add_i32 m0, s70, 0x2000
	s_nop 0
	global_load_lds_dwordx4 v[222:223], off
	v_lshl_add_u64 v[222:223], s[42:43], 0, v[134:135]
	s_mov_b32 m0, s35
	s_nop 0
	global_load_lds_dwordx4 v[222:223], off
	s_mov_b32 m0, s52
	s_nop 0
	global_load_lds_dwordx4 v[224:225], off
	s_waitcnt vmcnt(8)
	s_waitcnt lgkmcnt(0)
	s_barrier
	s_setprio 1
	s_waitcnt lgkmcnt(0)
	v_mfma_f32_16x16x32_bf16 v[60:63], v[154:157], v[186:189], v[60:63]
	v_mfma_f32_16x16x32_bf16 v[52:55], v[162:165], v[186:189], v[52:55]
	v_mfma_f32_16x16x32_bf16 v[44:47], v[154:157], v[198:201], v[44:47]
	v_mfma_f32_16x16x32_bf16 v[36:39], v[162:165], v[198:201], v[36:39]
	v_mfma_f32_16x16x32_bf16 v[28:31], v[154:157], v[206:209], v[28:31]
	v_mfma_f32_16x16x32_bf16 v[20:23], v[162:165], v[206:209], v[20:23]
	v_mfma_f32_16x16x32_bf16 v[12:15], v[154:157], v[214:217], v[12:15]
	v_mfma_f32_16x16x32_bf16 v[4:7], v[162:165], v[214:217], v[4:7]
	v_mfma_f32_16x16x32_bf16 v[60:63], v[158:161], v[190:193], v[60:63]
	v_mfma_f32_16x16x32_bf16 v[52:55], v[166:169], v[190:193], v[52:55]
	v_mfma_f32_16x16x32_bf16 v[44:47], v[158:161], v[202:205], v[44:47]
	v_mfma_f32_16x16x32_bf16 v[36:39], v[166:169], v[202:205], v[36:39]
	v_mfma_f32_16x16x32_bf16 v[28:31], v[158:161], v[210:213], v[28:31]
	v_mfma_f32_16x16x32_bf16 v[20:23], v[166:169], v[210:213], v[20:23]
	v_mfma_f32_16x16x32_bf16 v[12:15], v[158:161], v[218:221], v[12:15]
	v_mfma_f32_16x16x32_bf16 v[4:7], v[166:169], v[218:221], v[4:7]
	v_mfma_f32_16x16x32_bf16 v[56:59], v[170:173], v[186:189], v[56:59]
	v_mfma_f32_16x16x32_bf16 v[48:51], v[178:181], v[186:189], v[48:51]
	v_mfma_f32_16x16x32_bf16 v[40:43], v[170:173], v[198:201], v[40:43]
	v_mfma_f32_16x16x32_bf16 v[32:35], v[178:181], v[198:201], v[32:35]
	v_mfma_f32_16x16x32_bf16 v[24:27], v[170:173], v[206:209], v[24:27]
	v_mfma_f32_16x16x32_bf16 v[16:19], v[178:181], v[206:209], v[16:19]
	v_mfma_f32_16x16x32_bf16 v[8:11], v[170:173], v[214:217], v[8:11]
	v_mfma_f32_16x16x32_bf16 v[0:3], v[178:181], v[214:217], v[0:3]
	v_mfma_f32_16x16x32_bf16 v[56:59], v[174:177], v[190:193], v[56:59]
	v_mfma_f32_16x16x32_bf16 v[48:51], v[182:185], v[190:193], v[48:51]
	v_mfma_f32_16x16x32_bf16 v[40:43], v[174:177], v[202:205], v[40:43]
	v_mfma_f32_16x16x32_bf16 v[32:35], v[182:185], v[202:205], v[32:35]
	v_mfma_f32_16x16x32_bf16 v[24:27], v[174:177], v[210:213], v[24:27]
	v_mfma_f32_16x16x32_bf16 v[16:19], v[182:185], v[210:213], v[16:19]
	v_mfma_f32_16x16x32_bf16 v[8:11], v[174:177], v[218:221], v[8:11]
	v_mfma_f32_16x16x32_bf16 v[0:3], v[182:185], v[218:221], v[0:3]
	s_setprio 0
	s_barrier
; #define PG8_STAGE(bufoff, gbase, voff) do { _Pragma("unroll") for (int _i = 0; _i < 2; ++_i) \
;         __builtin_amdgcn_global_load_lds((const unsigned*)((const char*)(gbase) + (voff)[_i]), (PG8_LAS unsigned*)(lds + (bufoff) + ldsw + _i * 8192), 16, 0, 0); } while (0)
; #define PG8_LDA(dst, b, h) do { _Pragma("unroll") for (int m = 0; m < 4; ++m) _Pragma("unroll") for (int k = 0; k < 2; ++k) dst[m][k] = *(const PG8_LAS bf16x8*)(lds + PG8_SA(b, h) + aoff + m * 2048 + k * 1024); } while (0)
; #define PG8_LDB(dst, b, h) do { _Pragma("unroll") for (int n = 0; n < 2; ++n) _Pragma("unroll") for (int k = 0; k < 2; ++k) dst[n][k] = *(const PG8_LAS bf16x8*)(lds + PG8_SB(b, h) + boff + n * 2048 + k * 1024); } while (0)
; #define PG8_MMA(ai, bj, At, Bt) do { __builtin_amdgcn_s_setprio(1); _Pragma("unroll") for (int m = 0; m < 4; ++m) _Pragma("unroll") for (int n = 0; n < 2; ++n) _Pragma("unroll") for (int k = 0; k < 2; ++k) \
;         acc[ai][bj][m][n] = __builtin_amdgcn_mfma_f32_16x16x32_bf16(Bt[n][k], At[m][k], acc[ai][bj][m][n], 0, 0, 0); __builtin_amdgcn_s_setprio(0); } while (0)
; #define PG8_WAIT_V(n) asm volatile("s_waitcnt vmcnt(" #n ")" ::: "memory")
; #define PG8_WAIT_L(n) asm volatile("s_waitcnt lgkmcnt(" #n ")" ::: "memory")
; #define PG8_BAR __builtin_amdgcn_s_barrier()
; #define PG8_SCHED __builtin_amdgcn_sched_barrier(0)
; template <class Epi, class Sched, bool ALIGN_EPI = false, bool SP2 = false>
; __device__ __forceinline__ void gemm_phase(PG8_LAS unsigned char* lds, const Gemm g, const Sched& S, const Epi& E) {
;     ...
;             PG8_LDB(B0, 1, 0); PG8_LDB(B1, 1, 1); PG8_SCHED; PG8_LDA(At, 1, 0); PG8_STAGE(PG8_SA(0, 1), a2 + hstep, voffA);
;             PG8_WAIT_V(8); PG8_WAIT_L(0); PG8_BAR; PG8_MMA(0, 0, At, B0); PG8_MMA(0, 1, At, B1); PG8_BAR; PG8_SCHED;
	s_add_i32 s68, 0, 0x18000
	v_add_u32_e32 v153, s68, v147
	s_add_i32 s69, 0, 0x1c000
	ds_read_b128 v[154:157], v153
	ds_read_b128 v[158:161], v153 offset:1024
	ds_read_b128 v[162:165], v153 offset:2048
	ds_read_b128 v[166:169], v153 offset:3072
	v_add_u32_e32 v153, s69, v147
	ds_read_b128 v[170:173], v153
	ds_read_b128 v[174:177], v153 offset:1024
	ds_read_b128 v[178:181], v153 offset:2048
	ds_read_b128 v[182:185], v153 offset:3072
	s_add_u32 s42, s42, 0x40000
	s_addc_u32 s43, s43, 0
	s_mov_b32 m0, s53
	v_lshl_add_u64 v[226:227], s[42:43], 0, v[134:135]
	ds_read_b128 v[186:189], v152 offset:32768
	ds_read_b128 v[190:193], v152 offset:33792
	ds_read_b128 v[198:201], v152 offset:34816
	ds_read_b128 v[202:205], v152 offset:35840
	ds_read_b128 v[206:209], v152 offset:36864
	ds_read_b128 v[210:213], v152 offset:37888
	ds_read_b128 v[214:217], v152 offset:38912
	ds_read_b128 v[218:221], v152 offset:39936
	global_load_lds_dwordx4 v[226:227], off
	v_lshl_add_u64 v[226:227], s[42:43], 0, v[130:131]
	s_mov_b32 m0, s54
	s_nop 0
	global_load_lds_dwordx4 v[226:227], off
	s_waitcnt vmcnt(8)
	s_waitcnt lgkmcnt(0)
	s_barrier
	s_setprio 1
	s_waitcnt lgkmcnt(0)
	v_mfma_f32_16x16x32_bf16 v[124:127], v[154:157], v[186:189], v[124:127]
	v_mfma_f32_16x16x32_bf16 v[116:119], v[162:165], v[186:189], v[116:119]
	v_mfma_f32_16x16x32_bf16 v[108:111], v[154:157], v[198:201], v[108:111]
	v_mfma_f32_16x16x32_bf16 v[100:103], v[162:165], v[198:201], v[100:103]
	v_mfma_f32_16x16x32_bf16 v[92:95], v[154:157], v[206:209], v[92:95]
	v_mfma_f32_16x16x32_bf16 v[84:87], v[162:165], v[206:209], v[84:87]
	v_mfma_f32_16x16x32_bf16 v[76:79], v[154:157], v[214:217], v[76:79]
	v_mfma_f32_16x16x32_bf16 v[68:71], v[162:165], v[214:217], v[68:71]
	v_mfma_f32_16x16x32_bf16 v[124:127], v[158:161], v[190:193], v[124:127]
	v_mfma_f32_16x16x32_bf16 v[116:119], v[166:169], v[190:193], v[116:119]
	v_mfma_f32_16x16x32_bf16 v[108:111], v[158:161], v[202:205], v[108:111]
	v_mfma_f32_16x16x32_bf16 v[100:103], v[166:169], v[202:205], v[100:103]
	v_mfma_f32_16x16x32_bf16 v[92:95], v[158:161], v[210:213], v[92:95]
	v_mfma_f32_16x16x32_bf16 v[84:87], v[166:169], v[210:213], v[84:87]
	v_mfma_f32_16x16x32_bf16 v[76:79], v[158:161], v[218:221], v[76:79]
	v_mfma_f32_16x16x32_bf16 v[68:71], v[166:169], v[218:221], v[68:71]
	v_mfma_f32_16x16x32_bf16 v[120:123], v[170:173], v[186:189], v[120:123]
	v_mfma_f32_16x16x32_bf16 v[112:115], v[178:181], v[186:189], v[112:115]
	v_mfma_f32_16x16x32_bf16 v[104:107], v[170:173], v[198:201], v[104:107]
	v_mfma_f32_16x16x32_bf16 v[96:99], v[178:181], v[198:201], v[96:99]
	v_mfma_f32_16x16x32_bf16 v[88:91], v[170:173], v[206:209], v[88:91]
	v_mfma_f32_16x16x32_bf16 v[80:83], v[178:181], v[206:209], v[80:83]
	v_mfma_f32_16x16x32_bf16 v[72:75], v[170:173], v[214:217], v[72:75]
	v_mfma_f32_16x16x32_bf16 v[64:67], v[178:181], v[214:217], v[64:67]
	v_mfma_f32_16x16x32_bf16 v[120:123], v[174:177], v[190:193], v[120:123]
	v_mfma_f32_16x16x32_bf16 v[112:115], v[182:185], v[190:193], v[112:115]
	v_mfma_f32_16x16x32_bf16 v[104:107], v[174:177], v[202:205], v[104:107]
	v_mfma_f32_16x16x32_bf16 v[96:99], v[182:185], v[202:205], v[96:99]
	v_mfma_f32_16x16x32_bf16 v[88:91], v[174:177], v[210:213], v[88:91]
	v_mfma_f32_16x16x32_bf16 v[80:83], v[182:185], v[210:213], v[80:83]
	v_mfma_f32_16x16x32_bf16 v[72:75], v[174:177], v[218:221], v[72:75]
	v_mfma_f32_16x16x32_bf16 v[64:67], v[182:185], v[218:221], v[64:67]
	s_setprio 0
	s_barrier
; #define PG8_STAGE(bufoff, gbase, voff) do { _Pragma("unroll") for (int _i = 0; _i < 2; ++_i) \
;         __builtin_amdgcn_global_load_lds((const unsigned*)((const char*)(gbase) + (voff)[_i]), (PG8_LAS unsigned*)(lds + (bufoff) + ldsw + _i * 8192), 16, 0, 0); } while (0)
; #define PG8_LDA(dst, b, h) do { _Pragma("unroll") for (int m = 0; m < 4; ++m) _Pragma("unroll") for (int k = 0; k < 2; ++k) dst[m][k] = *(const PG8_LAS bf16x8*)(lds + PG8_SA(b, h) + aoff + m * 2048 + k * 1024); } while (0)
; #define PG8_MMA(ai, bj, At, Bt) do { __builtin_amdgcn_s_setprio(1); _Pragma("unroll") for (int m = 0; m < 4; ++m) _Pragma("unroll") for (int n = 0; n < 2; ++n) _Pragma("unroll") for (int k = 0; k < 2; ++k) \
;         acc[ai][bj][m][n] = __builtin_amdgcn_mfma_f32_16x16x32_bf16(Bt[n][k], At[m][k], acc[ai][bj][m][n], 0, 0, 0); __builtin_amdgcn_s_setprio(0); } while (0)
; #define PG8_WAIT_V(n) asm volatile("s_waitcnt vmcnt(" #n ")" ::: "memory")
; #define PG8_WAIT_L(n) asm volatile("s_waitcnt lgkmcnt(" #n ")" ::: "memory")
; #define PG8_BAR __builtin_amdgcn_s_barrier()
; #define PG8_SCHED __builtin_amdgcn_sched_barrier(0)
; template <class Epi, class Sched, bool ALIGN_EPI = false, bool SP2 = false>
; __device__ __forceinline__ void gemm_phase(PG8_LAS unsigned char* lds, const Gemm g, const Sched& S, const Epi& E) {
;     ...
;             PG8_LDA(At, 1, 1); PG8_STAGE(PG8_SB(1, 0), b3, voffB); PG8_STAGE(PG8_SB(1, 1), b3 + hstep, voffB); PG8_STAGE(PG8_SA(1, 0), a3, voffA);
;             PG8_WAIT_V(8); PG8_WAIT_L(0); PG8_BAR; PG8_MMA(1, 0, At, B0); PG8_MMA(1, 1, At, B1); PG8_BAR; PG8_SCHED;
;     ...
;         if constexpr (ALIGN_EPI) { if (wr == 0) PG8_BAR; }
	s_add_i32 s42, s68, s50
	v_lshl_add_u64 v[144:145], v[144:145], 0, s[8:9]
	s_mov_b32 m0, s42
	ds_read_b128 v[186:189], v152 offset:49152
	ds_read_b128 v[190:193], v152 offset:50176
	ds_read_b128 v[198:201], v152 offset:51200
	ds_read_b128 v[202:205], v152 offset:52224
	ds_read_b128 v[206:209], v152 offset:53248
	ds_read_b128 v[210:213], v152 offset:54272
	ds_read_b128 v[214:217], v152 offset:55296
	ds_read_b128 v[218:221], v152 offset:56320
	global_load_lds_dwordx4 v[144:145], off
	s_add_i32 m0, s42, 0x2000
	s_add_u32 s38, s38, 0x40080
	v_lshl_add_u64 v[144:145], v[194:195], 0, s[8:9]
	s_addc_u32 s39, s39, 0
	s_add_i32 s42, s69, s50
	global_load_lds_dwordx4 v[144:145], off
	v_lshl_add_u64 v[144:145], s[38:39], 0, v[132:133]
	s_mov_b32 m0, s42
	s_nop 0
	global_load_lds_dwordx4 v[144:145], off
	v_lshl_add_u64 v[144:145], s[38:39], 0, v[128:129]
	s_add_i32 m0, s42, 0x2000
	s_nop 0
	global_load_lds_dwordx4 v[144:145], off
	v_lshl_add_u64 v[144:145], v[222:223], 0, s[8:9]
	s_mov_b32 m0, s56
	s_nop 0
	global_load_lds_dwordx4 v[144:145], off
	v_lshl_add_u64 v[144:145], v[224:225], 0, s[8:9]
	s_mov_b32 m0, s57
	s_nop 0
	global_load_lds_dwordx4 v[144:145], off
	s_waitcnt vmcnt(8)
	s_waitcnt lgkmcnt(0)
	s_barrier
	s_setprio 1
	s_waitcnt lgkmcnt(0)
	v_mfma_f32_16x16x32_bf16 v[60:63], v[154:157], v[186:189], v[60:63]
	v_mfma_f32_16x16x32_bf16 v[52:55], v[162:165], v[186:189], v[52:55]
	v_mfma_f32_16x16x32_bf16 v[44:47], v[154:157], v[198:201], v[44:47]
	v_mfma_f32_16x16x32_bf16 v[36:39], v[162:165], v[198:201], v[36:39]
	v_mfma_f32_16x16x32_bf16 v[28:31], v[154:157], v[206:209], v[28:31]
	v_mfma_f32_16x16x32_bf16 v[20:23], v[162:165], v[206:209], v[20:23]
	v_mfma_f32_16x16x32_bf16 v[12:15], v[154:157], v[214:217], v[12:15]
	v_mfma_f32_16x16x32_bf16 v[4:7], v[162:165], v[214:217], v[4:7]
	v_mfma_f32_16x16x32_bf16 v[60:63], v[158:161], v[190:193], v[60:63]
	v_mfma_f32_16x16x32_bf16 v[52:55], v[166:169], v[190:193], v[52:55]
	v_mfma_f32_16x16x32_bf16 v[44:47], v[158:161], v[202:205], v[44:47]
	v_mfma_f32_16x16x32_bf16 v[36:39], v[166:169], v[202:205], v[36:39]
	v_mfma_f32_16x16x32_bf16 v[28:31], v[158:161], v[210:213], v[28:31]
	v_mfma_f32_16x16x32_bf16 v[20:23], v[166:169], v[210:213], v[20:23]
	v_mfma_f32_16x16x32_bf16 v[12:15], v[158:161], v[218:221], v[12:15]
	v_mfma_f32_16x16x32_bf16 v[4:7], v[166:169], v[218:221], v[4:7]
	v_mfma_f32_16x16x32_bf16 v[56:59], v[170:173], v[186:189], v[56:59]
	v_mfma_f32_16x16x32_bf16 v[48:51], v[178:181], v[186:189], v[48:51]
	v_mfma_f32_16x16x32_bf16 v[40:43], v[170:173], v[198:201], v[40:43]
	v_mfma_f32_16x16x32_bf16 v[32:35], v[178:181], v[198:201], v[32:35]
	v_mfma_f32_16x16x32_bf16 v[24:27], v[170:173], v[206:209], v[24:27]
	v_mfma_f32_16x16x32_bf16 v[16:19], v[178:181], v[206:209], v[16:19]
	v_mfma_f32_16x16x32_bf16 v[8:11], v[170:173], v[214:217], v[8:11]
	v_mfma_f32_16x16x32_bf16 v[0:3], v[178:181], v[214:217], v[0:3]
	v_mfma_f32_16x16x32_bf16 v[56:59], v[174:177], v[190:193], v[56:59]
	v_mfma_f32_16x16x32_bf16 v[48:51], v[182:185], v[190:193], v[48:51]
	v_mfma_f32_16x16x32_bf16 v[40:43], v[174:177], v[202:205], v[40:43]
	v_mfma_f32_16x16x32_bf16 v[32:35], v[182:185], v[202:205], v[32:35]
	v_mfma_f32_16x16x32_bf16 v[24:27], v[174:177], v[210:213], v[24:27]
	v_mfma_f32_16x16x32_bf16 v[16:19], v[182:185], v[210:213], v[16:19]
	v_mfma_f32_16x16x32_bf16 v[8:11], v[174:177], v[218:221], v[8:11]
	v_mfma_f32_16x16x32_bf16 v[0:3], v[182:185], v[218:221], v[0:3]
	s_setprio 0
	s_barrier
	s_add_i32 s67, s67, 2
	s_add_u32 s20, s20, 0x100
	s_addc_u32 s21, s21, 0
	s_add_u32 s65, s65, 0x100
	s_addc_u32 s66, s66, 0
	s_cmp_gt_u32 s67, 13
	s_cbranch_scc0 .LBB0_1740
	s_and_b64 vcc, exec, s[10:11]
	s_cbranch_vccz .LBB0_1743
	s_barrier

; #define PG8_STAGE(bufoff, gbase, voff) do { _Pragma("unroll") for (int _i = 0; _i < 2; ++_i) \
;         __builtin_amdgcn_global_load_lds((const unsigned*)((const char*)(gbase) + (voff)[_i]), (PG8_LAS unsigned*)(lds + (bufoff) + ldsw + _i * 8192), 16, 0, 0); } while (0)
; #define PG8_LDA(dst, b, h) do { _Pragma("unroll") for (int m = 0; m < 4; ++m) _Pragma("unroll") for (int k = 0; k < 2; ++k) dst[m][k] = *(const PG8_LAS bf16x8*)(lds + PG8_SA(b, h) + aoff + m * 2048 + k * 1024); } while (0)
; #define PG8_LDB(dst, b, h) do { _Pragma("unroll") for (int n = 0; n < 2; ++n) _Pragma("unroll") for (int k = 0; k < 2; ++k) dst[n][k] = *(const PG8_LAS bf16x8*)(lds + PG8_SB(b, h) + boff + n * 2048 + k * 1024); } while (0)
; #define PG8_MMA(ai, bj, At, Bt) do { __builtin_amdgcn_s_setprio(1); _Pragma("unroll") for (int m = 0; m < 4; ++m) _Pragma("unroll") for (int n = 0; n < 2; ++n) _Pragma("unroll") for (int k = 0; k < 2; ++k) \
;         acc[ai][bj][m][n] = __builtin_amdgcn_mfma_f32_16x16x32_bf16(Bt[n][k], At[m][k], acc[ai][bj][m][n], 0, 0, 0); __builtin_amdgcn_s_setprio(0); } while (0)
; #define PG8_WAIT_V(n) asm volatile("s_waitcnt vmcnt(" #n ")" ::: "memory")
; #define PG8_BAR __builtin_amdgcn_s_barrier()
; template <class Epi, class Sched, bool ALIGN_EPI = false, bool SP2 = false>
; __device__ __forceinline__ void gemm_phase(PG8_LAS unsigned char* lds, const Gemm g, const Sched& S, const Epi& E) {
;     ...
;         for (int t = 0; t < nt; t += 2) {
;             const bool last = (t == nt - 2);
;             const char* a1 = cA + (size_t)(t + 1) * kstep;
;             const char* a2 = last ? nA : cA + (size_t)(t + 2) * kstep; const char* b2 = last ? nB : cB + (size_t)(t + 2) * kstep;
;             const char* a3 = a2 + kstep; const char* b3 = b2 + kstep;
;             if (last && has_next) S.a_ready(nxt);
;             if constexpr (SP2) {
;             PG8_LDB(B0, 0, 0); PG8_LDB(B1, 0, 1); PG8_SCHED; PG8_LDA(At, 0, 0); PG8_STAGE(PG8_SA(1, 1), a1 + hstep, voffA);
;             PG8_WAIT_V(8); PG8_WAIT_L(0); PG8_BAR; PG8_MMA(0, 0, At, B0); PG8_MMA(0, 1, At, B1); PG8_BAR; PG8_SCHED;
;             PG8_LDA(At, 0, 1); PG8_STAGE(PG8_SB(0, 0), b2, voffB); PG8_STAGE(PG8_SB(0, 1), b2 + hstep, voffB); PG8_STAGE(PG8_SA(0, 0), a2, voffA);
;             PG8_WAIT_V(8); PG8_WAIT_L(0); PG8_BAR; PG8_MMA(1, 0, At, B0); PG8_MMA(1, 1, At, B1); PG8_BAR; PG8_SCHED;
.LBB0_1824:
	s_add_u32 s20, s20, 0xb0080
	s_addc_u32 s21, s21, 0
	s_add_u32 s68, s34, 0x100
	s_addc_u32 s69, s35, 0
	s_mov_b32 s70, -2
	s_waitcnt lgkmcnt(0)
	ds_read_b128 v[96:99], v222
	ds_read_b128 v[108:111], v222 offset:1024
	ds_read_b128 v[120:123], v222 offset:2048
	ds_read_b128 v[128:131], v222 offset:3072
	ds_read_b128 v[144:147], v223
	ds_read_b128 v[148:151], v223 offset:1024
	ds_read_b128 v[152:155], v223 offset:2048
	ds_read_b128 v[156:159], v223 offset:3072
	s_add_u32 s34, s20, 0xfff50080
	s_addc_u32 s35, s21, -1
	s_cmp_eq_u32 s70, 40
	s_cselect_b32 s47, s1, s35
	s_cselect_b32 s46, s0, s34
	s_cselect_b32 s35, s45, s69
	s_cselect_b32 s34, s44, s68
	v_lshl_add_u64 v[210:211], s[20:21], 0, v[192:193]
	s_add_i32 m0, s49, 0xc000
	ds_read_b128 v[160:163], v224
	ds_read_b128 v[164:167], v224 offset:1024
	ds_read_b128 v[168:171], v224 offset:2048
	ds_read_b128 v[172:175], v224 offset:3072
	ds_read_b128 v[176:179], v224 offset:4096
	ds_read_b128 v[180:183], v224 offset:5120
	ds_read_b128 v[202:205], v224 offset:6144
	ds_read_b128 v[206:209], v224 offset:7168
	global_load_lds_dwordx4 v[210:211], off
	v_lshl_add_u64 v[210:211], s[20:21], 0, v[194:195]
	s_add_i32 m0, s49, 0xe000
	s_nop 0
	global_load_lds_dwordx4 v[210:211], off
	s_waitcnt vmcnt(8)
	s_waitcnt lgkmcnt(0)
	s_barrier
	s_setprio 1
	s_waitcnt lgkmcnt(0)
	v_mfma_f32_16x16x32_bf16 v[140:143], v[96:99], v[160:163], 0
	v_mfma_f32_16x16x32_bf16 v[136:139], v[120:123], v[160:163], 0
	v_mfma_f32_16x16x32_bf16 v[116:119], v[96:99], v[168:171], 0
	v_mfma_f32_16x16x32_bf16 v[112:115], v[120:123], v[168:171], 0
	v_mfma_f32_16x16x32_bf16 v[92:95], v[96:99], v[176:179], 0
	v_mfma_f32_16x16x32_bf16 v[88:91], v[120:123], v[176:179], 0
	v_mfma_f32_16x16x32_bf16 v[76:79], v[96:99], v[202:205], 0
	v_mfma_f32_16x16x32_bf16 v[72:75], v[120:123], v[202:205], 0
	v_mfma_f32_16x16x32_bf16 v[140:143], v[108:111], v[164:167], v[140:143]
	v_mfma_f32_16x16x32_bf16 v[136:139], v[128:131], v[164:167], v[136:139]
	v_mfma_f32_16x16x32_bf16 v[116:119], v[108:111], v[172:175], v[116:119]
	v_mfma_f32_16x16x32_bf16 v[112:115], v[128:131], v[172:175], v[112:115]
	v_mfma_f32_16x16x32_bf16 v[92:95], v[108:111], v[180:183], v[92:95]
	v_mfma_f32_16x16x32_bf16 v[88:91], v[128:131], v[180:183], v[88:91]
	v_mfma_f32_16x16x32_bf16 v[76:79], v[108:111], v[206:209], v[76:79]
	v_mfma_f32_16x16x32_bf16 v[72:75], v[128:131], v[206:209], v[72:75]
	v_mfma_f32_16x16x32_bf16 v[132:135], v[144:147], v[160:163], 0
	v_mfma_f32_16x16x32_bf16 v[124:127], v[152:155], v[160:163], 0
	v_mfma_f32_16x16x32_bf16 v[104:107], v[144:147], v[168:171], 0
	v_mfma_f32_16x16x32_bf16 v[100:103], v[152:155], v[168:171], 0
	v_mfma_f32_16x16x32_bf16 v[84:87], v[144:147], v[176:179], 0
	v_mfma_f32_16x16x32_bf16 v[80:83], v[152:155], v[176:179], 0
	v_mfma_f32_16x16x32_bf16 v[68:71], v[144:147], v[202:205], 0
	v_mfma_f32_16x16x32_bf16 v[64:67], v[152:155], v[202:205], 0
	v_mfma_f32_16x16x32_bf16 v[132:135], v[148:151], v[164:167], v[132:135]
	v_mfma_f32_16x16x32_bf16 v[124:127], v[156:159], v[164:167], v[124:127]
	v_mfma_f32_16x16x32_bf16 v[104:107], v[148:151], v[172:175], v[104:107]
	v_mfma_f32_16x16x32_bf16 v[100:103], v[156:159], v[172:175], v[100:103]
	v_mfma_f32_16x16x32_bf16 v[84:87], v[148:151], v[180:183], v[84:87]
	v_mfma_f32_16x16x32_bf16 v[80:83], v[156:159], v[180:183], v[80:83]
	v_mfma_f32_16x16x32_bf16 v[68:71], v[148:151], v[206:209], v[68:71]
	v_mfma_f32_16x16x32_bf16 v[64:67], v[156:159], v[206:209], v[64:67]
	s_setprio 0
	s_barrier
	s_add_i32 s71, s62, s48
	v_lshl_add_u64 v[210:211], s[34:35], 0, v[186:187]
	s_mov_b32 m0, s71
	ds_read_b128 v[160:163], v224 offset:16384
	ds_read_b128 v[164:167], v224 offset:17408
	ds_read_b128 v[168:171], v224 offset:18432
	ds_read_b128 v[172:175], v224 offset:19456
	ds_read_b128 v[176:179], v224 offset:20480
	ds_read_b128 v[180:183], v224 offset:21504
	ds_read_b128 v[202:205], v224 offset:22528
	ds_read_b128 v[206:209], v224 offset:23552
	global_load_lds_dwordx4 v[210:211], off
	s_add_i32 m0, s71, 0x2000
	s_add_u32 s72, s34, 0xb0000
	v_lshl_add_u64 v[212:213], s[34:35], 0, v[190:191]
	s_addc_u32 s73, s35, 0
	s_add_i32 s71, s63, s48
	global_load_lds_dwordx4 v[212:213], off
	v_lshl_add_u64 v[214:215], s[72:73], 0, v[186:187]
	s_mov_b32 m0, s71
	v_lshl_add_u64 v[216:217], s[46:47], 0, v[188:189]
	global_load_lds_dwordx4 v[214:215], off
	v_lshl_add_u64 v[214:215], s[72:73], 0, v[190:191]
	s_add_i32 m0, s71, 0x2000
	s_nop 0
	global_load_lds_dwordx4 v[214:215], off
	v_lshl_add_u64 v[214:215], s[46:47], 0, v[184:185]
	s_mov_b32 m0, s49
	s_nop 0
	global_load_lds_dwordx4 v[214:215], off
	s_mov_b32 m0, s50
	s_nop 0
	global_load_lds_dwordx4 v[216:217], off
	s_waitcnt vmcnt(8)
	s_waitcnt lgkmcnt(0)
	s_barrier
; #define PG8_STAGE(bufoff, gbase, voff) do { _Pragma("unroll") for (int _i = 0; _i < 2; ++_i) \
;         __builtin_amdgcn_global_load_lds((const unsigned*)((const char*)(gbase) + (voff)[_i]), (PG8_LAS unsigned*)(lds + (bufoff) + ldsw + _i * 8192), 16, 0, 0); } while (0)
; #define PG8_LDA(dst, b, h) do { _Pragma("unroll") for (int m = 0; m < 4; ++m) _Pragma("unroll") for (int k = 0; k < 2; ++k) dst[m][k] = *(const PG8_LAS bf16x8*)(lds + PG8_SA(b, h) + aoff + m * 2048 + k * 1024); } while (0)
; #define PG8_LDB(dst, b, h) do { _Pragma("unroll") for (int n = 0; n < 2; ++n) _Pragma("unroll") for (int k = 0; k < 2; ++k) dst[n][k] = *(const PG8_LAS bf16x8*)(lds + PG8_SB(b, h) + boff + n * 2048 + k * 1024); } while (0)
; #define PG8_MMA(ai, bj, At, Bt) do { __builtin_amdgcn_s_setprio(1); _Pragma("unroll") for (int m = 0; m < 4; ++m) _Pragma("unroll") for (int n = 0; n < 2; ++n) _Pragma("unroll") for (int k = 0; k < 2; ++k) \
;         acc[ai][bj][m][n] = __builtin_amdgcn_mfma_f32_16x16x32_bf16(Bt[n][k], At[m][k], acc[ai][bj][m][n], 0, 0, 0); __builtin_amdgcn_s_setprio(0); } while (0)
; #define PG8_WAIT_V(n) asm volatile("s_waitcnt vmcnt(" #n ")" ::: "memory")
; #define PG8_WAIT_L(n) asm volatile("s_waitcnt lgkmcnt(" #n ")" ::: "memory")
; #define PG8_BAR __builtin_amdgcn_s_barrier()
; #define PG8_SCHED __builtin_amdgcn_sched_barrier(0)
; template <class Epi, class Sched, bool ALIGN_EPI = false, bool SP2 = false>
; __device__ __forceinline__ void gemm_phase(PG8_LAS unsigned char* lds, const Gemm g, const Sched& S, const Epi& E) {
;     ...
;             PG8_WAIT_V(8); PG8_WAIT_L(0); PG8_BAR; PG8_MMA(1, 0, At, B0); PG8_MMA(1, 1, At, B1); PG8_BAR; PG8_SCHED;
;             PG8_LDB(B0, 1, 0); PG8_LDB(B1, 1, 1); PG8_SCHED; PG8_LDA(At, 1, 0); PG8_STAGE(PG8_SA(0, 1), a2 + hstep, voffA);
;             PG8_WAIT_V(8); PG8_WAIT_L(0); PG8_BAR; PG8_MMA(0, 0, At, B0); PG8_MMA(0, 1, At, B1); PG8_BAR; PG8_SCHED;
	s_setprio 1
	s_waitcnt lgkmcnt(0)
	v_mfma_f32_16x16x32_bf16 v[60:63], v[96:99], v[160:163], 0
	v_mfma_f32_16x16x32_bf16 v[56:59], v[120:123], v[160:163], 0
	v_mfma_f32_16x16x32_bf16 v[44:47], v[96:99], v[168:171], 0
	v_mfma_f32_16x16x32_bf16 v[40:43], v[120:123], v[168:171], 0
	v_mfma_f32_16x16x32_bf16 v[28:31], v[96:99], v[176:179], 0
	v_mfma_f32_16x16x32_bf16 v[24:27], v[120:123], v[176:179], 0
	v_mfma_f32_16x16x32_bf16 v[12:15], v[96:99], v[202:205], 0
	v_mfma_f32_16x16x32_bf16 v[8:11], v[120:123], v[202:205], 0
	v_mfma_f32_16x16x32_bf16 v[60:63], v[108:111], v[164:167], v[60:63]
	v_mfma_f32_16x16x32_bf16 v[56:59], v[128:131], v[164:167], v[56:59]
	v_mfma_f32_16x16x32_bf16 v[44:47], v[108:111], v[172:175], v[44:47]
	v_mfma_f32_16x16x32_bf16 v[40:43], v[128:131], v[172:175], v[40:43]
	v_mfma_f32_16x16x32_bf16 v[28:31], v[108:111], v[180:183], v[28:31]
	v_mfma_f32_16x16x32_bf16 v[24:27], v[128:131], v[180:183], v[24:27]
	v_mfma_f32_16x16x32_bf16 v[12:15], v[108:111], v[206:209], v[12:15]
	v_mfma_f32_16x16x32_bf16 v[8:11], v[128:131], v[206:209], v[8:11]
	v_mfma_f32_16x16x32_bf16 v[52:55], v[144:147], v[160:163], 0
	v_mfma_f32_16x16x32_bf16 v[48:51], v[152:155], v[160:163], 0
	v_mfma_f32_16x16x32_bf16 v[36:39], v[144:147], v[168:171], 0
	v_mfma_f32_16x16x32_bf16 v[32:35], v[152:155], v[168:171], 0
	v_mfma_f32_16x16x32_bf16 v[20:23], v[144:147], v[176:179], 0
	v_mfma_f32_16x16x32_bf16 v[16:19], v[152:155], v[176:179], 0
	v_mfma_f32_16x16x32_bf16 v[4:7], v[144:147], v[202:205], 0
	v_mfma_f32_16x16x32_bf16 v[0:3], v[152:155], v[202:205], 0
	v_mfma_f32_16x16x32_bf16 v[52:55], v[148:151], v[164:167], v[52:55]
	v_mfma_f32_16x16x32_bf16 v[48:51], v[156:159], v[164:167], v[48:51]
	v_mfma_f32_16x16x32_bf16 v[36:39], v[148:151], v[172:175], v[36:39]
	v_mfma_f32_16x16x32_bf16 v[32:35], v[156:159], v[172:175], v[32:35]
	v_mfma_f32_16x16x32_bf16 v[20:23], v[148:151], v[180:183], v[20:23]
	v_mfma_f32_16x16x32_bf16 v[16:19], v[156:159], v[180:183], v[16:19]
	v_mfma_f32_16x16x32_bf16 v[4:7], v[148:151], v[206:209], v[4:7]
	v_mfma_f32_16x16x32_bf16 v[0:3], v[156:159], v[206:209], v[0:3]
	s_setprio 0
	s_barrier
	s_add_i32 s71, 0, 0x18000
	s_add_i32 s72, 0, 0x1c000
	v_add_u32_e32 v128, s71, v197
	v_add_u32_e32 v156, s72, v197
	ds_read_b128 v[96:99], v128
	ds_read_b128 v[108:111], v128 offset:1024
	ds_read_b128 v[120:123], v128 offset:2048
	ds_read_b128 v[128:131], v128 offset:3072
	ds_read_b128 v[144:147], v156
	ds_read_b128 v[148:151], v156 offset:1024
	ds_read_b128 v[152:155], v156 offset:2048
	ds_read_b128 v[156:159], v156 offset:3072
	s_add_u32 s46, s46, 0xb0000
	s_addc_u32 s47, s47, 0
	s_mov_b32 m0, s51
	v_lshl_add_u64 v[218:219], s[46:47], 0, v[184:185]
	ds_read_b128 v[160:163], v224 offset:32768
	ds_read_b128 v[164:167], v224 offset:33792
	ds_read_b128 v[168:171], v224 offset:34816
	ds_read_b128 v[172:175], v224 offset:35840
	ds_read_b128 v[176:179], v224 offset:36864
	ds_read_b128 v[180:183], v224 offset:37888
	ds_read_b128 v[202:205], v224 offset:38912
	ds_read_b128 v[206:209], v224 offset:39936
	global_load_lds_dwordx4 v[218:219], off
	v_lshl_add_u64 v[218:219], s[46:47], 0, v[188:189]
	s_mov_b32 m0, s52
	s_nop 0
	global_load_lds_dwordx4 v[218:219], off
	s_waitcnt vmcnt(8)
	s_waitcnt lgkmcnt(0)
	s_barrier
	s_setprio 1
	s_waitcnt lgkmcnt(0)
	v_mfma_f32_16x16x32_bf16 v[140:143], v[96:99], v[160:163], v[140:143]
	v_mfma_f32_16x16x32_bf16 v[136:139], v[120:123], v[160:163], v[136:139]
	v_mfma_f32_16x16x32_bf16 v[116:119], v[96:99], v[168:171], v[116:119]
	v_mfma_f32_16x16x32_bf16 v[112:115], v[120:123], v[168:171], v[112:115]
	v_mfma_f32_16x16x32_bf16 v[92:95], v[96:99], v[176:179], v[92:95]
	v_mfma_f32_16x16x32_bf16 v[88:91], v[120:123], v[176:179], v[88:91]
	v_mfma_f32_16x16x32_bf16 v[76:79], v[96:99], v[202:205], v[76:79]
	v_mfma_f32_16x16x32_bf16 v[72:75], v[120:123], v[202:205], v[72:75]
	v_mfma_f32_16x16x32_bf16 v[140:143], v[108:111], v[164:167], v[140:143]
	v_mfma_f32_16x16x32_bf16 v[136:139], v[128:131], v[164:167], v[136:139]
	v_mfma_f32_16x16x32_bf16 v[116:119], v[108:111], v[172:175], v[116:119]
	v_mfma_f32_16x16x32_bf16 v[112:115], v[128:131], v[172:175], v[112:115]
	v_mfma_f32_16x16x32_bf16 v[92:95], v[108:111], v[180:183], v[92:95]
	v_mfma_f32_16x16x32_bf16 v[88:91], v[128:131], v[180:183], v[88:91]
	v_mfma_f32_16x16x32_bf16 v[76:79], v[108:111], v[206:209], v[76:79]
	v_mfma_f32_16x16x32_bf16 v[72:75], v[128:131], v[206:209], v[72:75]
	v_mfma_f32_16x16x32_bf16 v[132:135], v[144:147], v[160:163], v[132:135]
	v_mfma_f32_16x16x32_bf16 v[124:127], v[152:155], v[160:163], v[124:127]
	v_mfma_f32_16x16x32_bf16 v[104:107], v[144:147], v[168:171], v[104:107]
	v_mfma_f32_16x16x32_bf16 v[100:103], v[152:155], v[168:171], v[100:103]
	v_mfma_f32_16x16x32_bf16 v[84:87], v[144:147], v[176:179], v[84:87]
	v_mfma_f32_16x16x32_bf16 v[80:83], v[152:155], v[176:179], v[80:83]
	v_mfma_f32_16x16x32_bf16 v[68:71], v[144:147], v[202:205], v[68:71]
	v_mfma_f32_16x16x32_bf16 v[64:67], v[152:155], v[202:205], v[64:67]
	v_mfma_f32_16x16x32_bf16 v[132:135], v[148:151], v[164:167], v[132:135]
	v_mfma_f32_16x16x32_bf16 v[124:127], v[156:159], v[164:167], v[124:127]
	v_mfma_f32_16x16x32_bf16 v[104:107], v[148:151], v[172:175], v[104:107]
	v_mfma_f32_16x16x32_bf16 v[100:103], v[156:159], v[172:175], v[100:103]
	v_mfma_f32_16x16x32_bf16 v[84:87], v[148:151], v[180:183], v[84:87]
	v_mfma_f32_16x16x32_bf16 v[80:83], v[156:159], v[180:183], v[80:83]
	v_mfma_f32_16x16x32_bf16 v[68:71], v[148:151], v[206:209], v[68:71]
	v_mfma_f32_16x16x32_bf16 v[64:67], v[156:159], v[206:209], v[64:67]
	s_setprio 0
	s_barrier
; #define PG8_STAGE(bufoff, gbase, voff) do { _Pragma("unroll") for (int _i = 0; _i < 2; ++_i) \
;         __builtin_amdgcn_global_load_lds((const unsigned*)((const char*)(gbase) + (voff)[_i]), (PG8_LAS unsigned*)(lds + (bufoff) + ldsw + _i * 8192), 16, 0, 0); } while (0)
; #define PG8_LDA(dst, b, h) do { _Pragma("unroll") for (int m = 0; m < 4; ++m) _Pragma("unroll") for (int k = 0; k < 2; ++k) dst[m][k] = *(const PG8_LAS bf16x8*)(lds + PG8_SA(b, h) + aoff + m * 2048 + k * 1024); } while (0)
; #define PG8_LDB(dst, b, h) do { _Pragma("unroll") for (int n = 0; n < 2; ++n) _Pragma("unroll") for (int k = 0; k < 2; ++k) dst[n][k] = *(const PG8_LAS bf16x8*)(lds + PG8_SB(b, h) + boff + n * 2048 + k * 1024); } while (0)
; #define PG8_MMA(ai, bj, At, Bt) do { __builtin_amdgcn_s_setprio(1); _Pragma("unroll") for (int m = 0; m < 4; ++m) _Pragma("unroll") for (int n = 0; n < 2; ++n) _Pragma("unroll") for (int k = 0; k < 2; ++k) \
;         acc[ai][bj][m][n] = __builtin_amdgcn_mfma_f32_16x16x32_bf16(Bt[n][k], At[m][k], acc[ai][bj][m][n], 0, 0, 0); __builtin_amdgcn_s_setprio(0); } while (0)
; #define PG8_WAIT_V(n) asm volatile("s_waitcnt vmcnt(" #n ")" ::: "memory")
; template <class Epi, class Sched, bool ALIGN_EPI = false, bool SP2 = false>
; __device__ __forceinline__ void gemm_phase(PG8_LAS unsigned char* lds, const Gemm g, const Sched& S, const Epi& E) {
;     ...
;             PG8_LDB(B0, 0, 0); PG8_LDB(B1, 0, 1); PG8_SCHED; PG8_LDA(At, 0, 0); PG8_STAGE(PG8_SA(1, 1), a1 + hstep, voffA);
;             PG8_WAIT_V(8); PG8_WAIT_L(0); PG8_BAR; PG8_MMA(0, 0, At, B0); PG8_MMA(0, 1, At, B1); PG8_BAR; PG8_SCHED;
;             PG8_LDA(At, 0, 1); PG8_STAGE(PG8_SB(0, 0), b2, voffB); PG8_STAGE(PG8_SB(0, 1), b2 + hstep, voffB); PG8_STAGE(PG8_SA(0, 0), a2, voffA);
;             PG8_WAIT_V(8); PG8_WAIT_L(0); PG8_BAR; PG8_MMA(1, 0, At, B0); PG8_MMA(1, 1, At, B1); PG8_BAR; PG8_SCHED;
;             PG8_LDB(B0, 1, 0); PG8_LDB(B1, 1, 1); PG8_SCHED; PG8_LDA(At, 1, 0); PG8_STAGE(PG8_SA(0, 1), a2 + hstep, voffA);
;             PG8_WAIT_V(8); PG8_WAIT_L(0); PG8_BAR; PG8_MMA(0, 0, At, B0); PG8_MMA(0, 1, At, B1); PG8_BAR; PG8_SCHED;
;             PG8_LDA(At, 1, 1); PG8_STAGE(PG8_SB(1, 0), b3, voffB); PG8_STAGE(PG8_SB(1, 1), b3 + hstep, voffB); PG8_STAGE(PG8_SA(1, 0), a3, voffA);
;             PG8_WAIT_V(8); PG8_WAIT_L(0); PG8_BAR; PG8_MMA(1, 0, At, B0); PG8_MMA(1, 1, At, B1); PG8_BAR; PG8_SCHED;
	s_add_i32 s46, s71, s48
	v_lshl_add_u64 v[210:211], v[210:211], 0, s[12:13]
	s_mov_b32 m0, s46
	ds_read_b128 v[160:163], v224 offset:49152
	ds_read_b128 v[164:167], v224 offset:50176
	ds_read_b128 v[168:171], v224 offset:51200
	ds_read_b128 v[172:175], v224 offset:52224
	ds_read_b128 v[176:179], v224 offset:53248
	ds_read_b128 v[180:183], v224 offset:54272
	ds_read_b128 v[202:205], v224 offset:55296
	ds_read_b128 v[206:209], v224 offset:56320
	global_load_lds_dwordx4 v[210:211], off
	s_add_i32 m0, s46, 0x2000
	s_add_u32 s34, s34, 0xb0080
	v_lshl_add_u64 v[210:211], v[212:213], 0, s[12:13]
	s_addc_u32 s35, s35, 0
	s_add_i32 s46, s72, s48
	global_load_lds_dwordx4 v[210:211], off
	v_lshl_add_u64 v[210:211], s[34:35], 0, v[186:187]
	s_mov_b32 m0, s46
	s_nop 0
	global_load_lds_dwordx4 v[210:211], off
	v_lshl_add_u64 v[210:211], s[34:35], 0, v[190:191]
	s_add_i32 m0, s46, 0x2000
	s_nop 0
	global_load_lds_dwordx4 v[210:211], off
	v_lshl_add_u64 v[210:211], v[214:215], 0, s[12:13]
	s_mov_b32 m0, s57
	s_nop 0
	global_load_lds_dwordx4 v[210:211], off
	v_lshl_add_u64 v[210:211], v[216:217], 0, s[12:13]
	s_mov_b32 m0, s58
	s_nop 0
	global_load_lds_dwordx4 v[210:211], off
	s_waitcnt vmcnt(8)
	s_waitcnt lgkmcnt(0)
	s_barrier
	s_setprio 1
	s_waitcnt lgkmcnt(0)
	v_mfma_f32_16x16x32_bf16 v[60:63], v[96:99], v[160:163], v[60:63]
	v_mfma_f32_16x16x32_bf16 v[56:59], v[120:123], v[160:163], v[56:59]
	v_mfma_f32_16x16x32_bf16 v[44:47], v[96:99], v[168:171], v[44:47]
	v_mfma_f32_16x16x32_bf16 v[40:43], v[120:123], v[168:171], v[40:43]
	v_mfma_f32_16x16x32_bf16 v[28:31], v[96:99], v[176:179], v[28:31]
	v_mfma_f32_16x16x32_bf16 v[24:27], v[120:123], v[176:179], v[24:27]
	v_mfma_f32_16x16x32_bf16 v[12:15], v[96:99], v[202:205], v[12:15]
	v_mfma_f32_16x16x32_bf16 v[8:11], v[120:123], v[202:205], v[8:11]
	v_mfma_f32_16x16x32_bf16 v[60:63], v[108:111], v[164:167], v[60:63]
	v_mfma_f32_16x16x32_bf16 v[56:59], v[128:131], v[164:167], v[56:59]
	v_mfma_f32_16x16x32_bf16 v[44:47], v[108:111], v[172:175], v[44:47]
	v_mfma_f32_16x16x32_bf16 v[40:43], v[128:131], v[172:175], v[40:43]
	v_mfma_f32_16x16x32_bf16 v[28:31], v[108:111], v[180:183], v[28:31]
	v_mfma_f32_16x16x32_bf16 v[24:27], v[128:131], v[180:183], v[24:27]
	v_mfma_f32_16x16x32_bf16 v[12:15], v[108:111], v[206:209], v[12:15]
	v_mfma_f32_16x16x32_bf16 v[8:11], v[128:131], v[206:209], v[8:11]
	v_mfma_f32_16x16x32_bf16 v[52:55], v[144:147], v[160:163], v[52:55]
	v_mfma_f32_16x16x32_bf16 v[48:51], v[152:155], v[160:163], v[48:51]
	v_mfma_f32_16x16x32_bf16 v[36:39], v[144:147], v[168:171], v[36:39]
	v_mfma_f32_16x16x32_bf16 v[32:35], v[152:155], v[168:171], v[32:35]
	v_mfma_f32_16x16x32_bf16 v[20:23], v[144:147], v[176:179], v[20:23]
	v_mfma_f32_16x16x32_bf16 v[16:19], v[152:155], v[176:179], v[16:19]
	v_mfma_f32_16x16x32_bf16 v[4:7], v[144:147], v[202:205], v[4:7]
	v_mfma_f32_16x16x32_bf16 v[0:3], v[152:155], v[202:205], v[0:3]
	v_mfma_f32_16x16x32_bf16 v[52:55], v[148:151], v[164:167], v[52:55]
	v_mfma_f32_16x16x32_bf16 v[48:51], v[156:159], v[164:167], v[48:51]
	v_mfma_f32_16x16x32_bf16 v[36:39], v[148:151], v[172:175], v[36:39]
	v_mfma_f32_16x16x32_bf16 v[32:35], v[156:159], v[172:175], v[32:35]
	v_mfma_f32_16x16x32_bf16 v[20:23], v[148:151], v[180:183], v[20:23]
	v_mfma_f32_16x16x32_bf16 v[16:19], v[156:159], v[180:183], v[16:19]
	v_mfma_f32_16x16x32_bf16 v[4:7], v[148:151], v[206:209], v[4:7]
	v_mfma_f32_16x16x32_bf16 v[0:3], v[156:159], v[206:209], v[0:3]
	s_setprio 0
	s_barrier
	s_add_i32 s70, s70, 2
	s_add_u32 s20, s20, 0x100
	s_addc_u32 s21, s21, 0
	s_add_u32 s68, s68, 0x100
	s_addc_u32 s69, s69, 0
	s_cmp_gt_u32 s70, 41
.LBB0_1825:
	ds_read_b128 v[96:99], v222
	ds_read_b128 v[108:111], v222 offset:1024
	ds_read_b128 v[120:123], v222 offset:2048
	ds_read_b128 v[128:131], v222 offset:3072
	ds_read_b128 v[144:147], v223
	ds_read_b128 v[148:151], v223 offset:1024
	ds_read_b128 v[152:155], v223 offset:2048
	ds_read_b128 v[156:159], v223 offset:3072
	s_add_u32 s34, s20, 0xfff50080
	s_addc_u32 s35, s21, -1
	s_cmp_eq_u32 s70, 40
	s_cselect_b32 s47, s1, s35
	s_cselect_b32 s46, s0, s34
	s_cselect_b32 s35, s45, s69
	s_cselect_b32 s34, s44, s68
	v_lshl_add_u64 v[210:211], s[20:21], 0, v[192:193]
	s_add_i32 m0, s49, 0xc000
	ds_read_b128 v[160:163], v224
	ds_read_b128 v[164:167], v224 offset:1024
	ds_read_b128 v[168:171], v224 offset:2048
	ds_read_b128 v[172:175], v224 offset:3072
	ds_read_b128 v[176:179], v224 offset:4096
	ds_read_b128 v[180:183], v224 offset:5120
	ds_read_b128 v[202:205], v224 offset:6144
	ds_read_b128 v[206:209], v224 offset:7168
	global_load_lds_dwordx4 v[210:211], off
	v_lshl_add_u64 v[210:211], s[20:21], 0, v[194:195]
	s_add_i32 m0, s49, 0xe000
	s_nop 0
	global_load_lds_dwordx4 v[210:211], off
	s_waitcnt vmcnt(8)
	s_waitcnt lgkmcnt(0)
	s_barrier
; #define PG8_STAGE(bufoff, gbase, voff) do { _Pragma("unroll") for (int _i = 0; _i < 2; ++_i) \
;         __builtin_amdgcn_global_load_lds((const unsigned*)((const char*)(gbase) + (voff)[_i]), (PG8_LAS unsigned*)(lds + (bufoff) + ldsw + _i * 8192), 16, 0, 0); } while (0)
; #define PG8_LDA(dst, b, h) do { _Pragma("unroll") for (int m = 0; m < 4; ++m) _Pragma("unroll") for (int k = 0; k < 2; ++k) dst[m][k] = *(const PG8_LAS bf16x8*)(lds + PG8_SA(b, h) + aoff + m * 2048 + k * 1024); } while (0)
; #define PG8_MMA(ai, bj, At, Bt) do { __builtin_amdgcn_s_setprio(1); _Pragma("unroll") for (int m = 0; m < 4; ++m) _Pragma("unroll") for (int n = 0; n < 2; ++n) _Pragma("unroll") for (int k = 0; k < 2; ++k) \
;         acc[ai][bj][m][n] = __builtin_amdgcn_mfma_f32_16x16x32_bf16(Bt[n][k], At[m][k], acc[ai][bj][m][n], 0, 0, 0); __builtin_amdgcn_s_setprio(0); } while (0)
; #define PG8_WAIT_V(n) asm volatile("s_waitcnt vmcnt(" #n ")" ::: "memory")
; #define PG8_WAIT_L(n) asm volatile("s_waitcnt lgkmcnt(" #n ")" ::: "memory")
; #define PG8_BAR __builtin_amdgcn_s_barrier()
; #define PG8_SCHED __builtin_amdgcn_sched_barrier(0)
; template <class Epi, class Sched, bool ALIGN_EPI = false, bool SP2 = false>
; __device__ __forceinline__ void gemm_phase(PG8_LAS unsigned char* lds, const Gemm g, const Sched& S, const Epi& E) {
;     ...
;             PG8_WAIT_V(8); PG8_WAIT_L(0); PG8_BAR; PG8_MMA(0, 0, At, B0); PG8_MMA(0, 1, At, B1); PG8_BAR; PG8_SCHED;
;             PG8_LDA(At, 0, 1); PG8_STAGE(PG8_SB(0, 0), b2, voffB); PG8_STAGE(PG8_SB(0, 1), b2 + hstep, voffB); PG8_STAGE(PG8_SA(0, 0), a2, voffA);
;             PG8_WAIT_V(8); PG8_WAIT_L(0); PG8_BAR; PG8_MMA(1, 0, At, B0); PG8_MMA(1, 1, At, B1); PG8_BAR; PG8_SCHED;
	s_setprio 1
	s_waitcnt lgkmcnt(0)
	v_mfma_f32_16x16x32_bf16 v[140:143], v[96:99], v[160:163], v[140:143]
	v_mfma_f32_16x16x32_bf16 v[136:139], v[120:123], v[160:163], v[136:139]
	v_mfma_f32_16x16x32_bf16 v[116:119], v[96:99], v[168:171], v[116:119]
	v_mfma_f32_16x16x32_bf16 v[112:115], v[120:123], v[168:171], v[112:115]
	v_mfma_f32_16x16x32_bf16 v[92:95], v[96:99], v[176:179], v[92:95]
	v_mfma_f32_16x16x32_bf16 v[88:91], v[120:123], v[176:179], v[88:91]
	v_mfma_f32_16x16x32_bf16 v[76:79], v[96:99], v[202:205], v[76:79]
	v_mfma_f32_16x16x32_bf16 v[72:75], v[120:123], v[202:205], v[72:75]
	v_mfma_f32_16x16x32_bf16 v[140:143], v[108:111], v[164:167], v[140:143]
	v_mfma_f32_16x16x32_bf16 v[136:139], v[128:131], v[164:167], v[136:139]
	v_mfma_f32_16x16x32_bf16 v[116:119], v[108:111], v[172:175], v[116:119]
	v_mfma_f32_16x16x32_bf16 v[112:115], v[128:131], v[172:175], v[112:115]
	v_mfma_f32_16x16x32_bf16 v[92:95], v[108:111], v[180:183], v[92:95]
	v_mfma_f32_16x16x32_bf16 v[88:91], v[128:131], v[180:183], v[88:91]
	v_mfma_f32_16x16x32_bf16 v[76:79], v[108:111], v[206:209], v[76:79]
	v_mfma_f32_16x16x32_bf16 v[72:75], v[128:131], v[206:209], v[72:75]
	v_mfma_f32_16x16x32_bf16 v[132:135], v[144:147], v[160:163], v[132:135]
	v_mfma_f32_16x16x32_bf16 v[124:127], v[152:155], v[160:163], v[124:127]
	v_mfma_f32_16x16x32_bf16 v[104:107], v[144:147], v[168:171], v[104:107]
	v_mfma_f32_16x16x32_bf16 v[100:103], v[152:155], v[168:171], v[100:103]
	v_mfma_f32_16x16x32_bf16 v[84:87], v[144:147], v[176:179], v[84:87]
	v_mfma_f32_16x16x32_bf16 v[80:83], v[152:155], v[176:179], v[80:83]
	v_mfma_f32_16x16x32_bf16 v[68:71], v[144:147], v[202:205], v[68:71]
	v_mfma_f32_16x16x32_bf16 v[64:67], v[152:155], v[202:205], v[64:67]
	v_mfma_f32_16x16x32_bf16 v[132:135], v[148:151], v[164:167], v[132:135]
	v_mfma_f32_16x16x32_bf16 v[124:127], v[156:159], v[164:167], v[124:127]
	v_mfma_f32_16x16x32_bf16 v[104:107], v[148:151], v[172:175], v[104:107]
	v_mfma_f32_16x16x32_bf16 v[100:103], v[156:159], v[172:175], v[100:103]
	v_mfma_f32_16x16x32_bf16 v[84:87], v[148:151], v[180:183], v[84:87]
	v_mfma_f32_16x16x32_bf16 v[80:83], v[156:159], v[180:183], v[80:83]
	v_mfma_f32_16x16x32_bf16 v[68:71], v[148:151], v[206:209], v[68:71]
	v_mfma_f32_16x16x32_bf16 v[64:67], v[156:159], v[206:209], v[64:67]
	s_setprio 0
	s_barrier
	s_add_i32 s71, s62, s48
	v_lshl_add_u64 v[210:211], s[34:35], 0, v[186:187]
	s_mov_b32 m0, s71
	ds_read_b128 v[160:163], v224 offset:16384
	ds_read_b128 v[164:167], v224 offset:17408
	ds_read_b128 v[168:171], v224 offset:18432
	ds_read_b128 v[172:175], v224 offset:19456
	ds_read_b128 v[176:179], v224 offset:20480
	ds_read_b128 v[180:183], v224 offset:21504
	ds_read_b128 v[202:205], v224 offset:22528
	ds_read_b128 v[206:209], v224 offset:23552
	global_load_lds_dwordx4 v[210:211], off
	s_add_i32 m0, s71, 0x2000
	s_add_u32 s72, s34, 0xb0000
	v_lshl_add_u64 v[212:213], s[34:35], 0, v[190:191]
	s_addc_u32 s73, s35, 0
	s_add_i32 s71, s63, s48
	global_load_lds_dwordx4 v[212:213], off
	v_lshl_add_u64 v[214:215], s[72:73], 0, v[186:187]
	s_mov_b32 m0, s71
	v_lshl_add_u64 v[216:217], s[46:47], 0, v[188:189]
	global_load_lds_dwordx4 v[214:215], off
	v_lshl_add_u64 v[214:215], s[72:73], 0, v[190:191]
	s_add_i32 m0, s71, 0x2000
	s_nop 0
	global_load_lds_dwordx4 v[214:215], off
	v_lshl_add_u64 v[214:215], s[46:47], 0, v[184:185]
	s_mov_b32 m0, s49
	s_nop 0
	global_load_lds_dwordx4 v[214:215], off
	s_mov_b32 m0, s50
	s_nop 0
	global_load_lds_dwordx4 v[216:217], off
	s_waitcnt vmcnt(8)
	s_waitcnt lgkmcnt(0)
	s_barrier
	s_setprio 1
	s_waitcnt lgkmcnt(0)
	v_mfma_f32_16x16x32_bf16 v[60:63], v[96:99], v[160:163], v[60:63]
	v_mfma_f32_16x16x32_bf16 v[56:59], v[120:123], v[160:163], v[56:59]
	v_mfma_f32_16x16x32_bf16 v[44:47], v[96:99], v[168:171], v[44:47]
	v_mfma_f32_16x16x32_bf16 v[40:43], v[120:123], v[168:171], v[40:43]
	v_mfma_f32_16x16x32_bf16 v[28:31], v[96:99], v[176:179], v[28:31]
	v_mfma_f32_16x16x32_bf16 v[24:27], v[120:123], v[176:179], v[24:27]
	v_mfma_f32_16x16x32_bf16 v[12:15], v[96:99], v[202:205], v[12:15]
	v_mfma_f32_16x16x32_bf16 v[8:11], v[120:123], v[202:205], v[8:11]
	v_mfma_f32_16x16x32_bf16 v[60:63], v[108:111], v[164:167], v[60:63]
	v_mfma_f32_16x16x32_bf16 v[56:59], v[128:131], v[164:167], v[56:59]
	v_mfma_f32_16x16x32_bf16 v[44:47], v[108:111], v[172:175], v[44:47]
	v_mfma_f32_16x16x32_bf16 v[40:43], v[128:131], v[172:175], v[40:43]
	v_mfma_f32_16x16x32_bf16 v[28:31], v[108:111], v[180:183], v[28:31]
	v_mfma_f32_16x16x32_bf16 v[24:27], v[128:131], v[180:183], v[24:27]
	v_mfma_f32_16x16x32_bf16 v[12:15], v[108:111], v[206:209], v[12:15]
	v_mfma_f32_16x16x32_bf16 v[8:11], v[128:131], v[206:209], v[8:11]
	v_mfma_f32_16x16x32_bf16 v[52:55], v[144:147], v[160:163], v[52:55]
	v_mfma_f32_16x16x32_bf16 v[48:51], v[152:155], v[160:163], v[48:51]
	v_mfma_f32_16x16x32_bf16 v[36:39], v[144:147], v[168:171], v[36:39]
	v_mfma_f32_16x16x32_bf16 v[32:35], v[152:155], v[168:171], v[32:35]
	v_mfma_f32_16x16x32_bf16 v[20:23], v[144:147], v[176:179], v[20:23]
	v_mfma_f32_16x16x32_bf16 v[16:19], v[152:155], v[176:179], v[16:19]
	v_mfma_f32_16x16x32_bf16 v[4:7], v[144:147], v[202:205], v[4:7]
	v_mfma_f32_16x16x32_bf16 v[0:3], v[152:155], v[202:205], v[0:3]
	v_mfma_f32_16x16x32_bf16 v[52:55], v[148:151], v[164:167], v[52:55]
	v_mfma_f32_16x16x32_bf16 v[48:51], v[156:159], v[164:167], v[48:51]
	v_mfma_f32_16x16x32_bf16 v[36:39], v[148:151], v[172:175], v[36:39]
	v_mfma_f32_16x16x32_bf16 v[32:35], v[156:159], v[172:175], v[32:35]
	v_mfma_f32_16x16x32_bf16 v[20:23], v[148:151], v[180:183], v[20:23]
	v_mfma_f32_16x16x32_bf16 v[16:19], v[156:159], v[180:183], v[16:19]
	v_mfma_f32_16x16x32_bf16 v[4:7], v[148:151], v[206:209], v[4:7]
	v_mfma_f32_16x16x32_bf16 v[0:3], v[156:159], v[206:209], v[0:3]
	s_setprio 0
	s_barrier
; #define PG8_STAGE(bufoff, gbase, voff) do { _Pragma("unroll") for (int _i = 0; _i < 2; ++_i) \
;         __builtin_amdgcn_global_load_lds((const unsigned*)((const char*)(gbase) + (voff)[_i]), (PG8_LAS unsigned*)(lds + (bufoff) + ldsw + _i * 8192), 16, 0, 0); } while (0)
; #define PG8_LDA(dst, b, h) do { _Pragma("unroll") for (int m = 0; m < 4; ++m) _Pragma("unroll") for (int k = 0; k < 2; ++k) dst[m][k] = *(const PG8_LAS bf16x8*)(lds + PG8_SA(b, h) + aoff + m * 2048 + k * 1024); } while (0)
; #define PG8_LDB(dst, b, h) do { _Pragma("unroll") for (int n = 0; n < 2; ++n) _Pragma("unroll") for (int k = 0; k < 2; ++k) dst[n][k] = *(const PG8_LAS bf16x8*)(lds + PG8_SB(b, h) + boff + n * 2048 + k * 1024); } while (0)
; #define PG8_MMA(ai, bj, At, Bt) do { __builtin_amdgcn_s_setprio(1); _Pragma("unroll") for (int m = 0; m < 4; ++m) _Pragma("unroll") for (int n = 0; n < 2; ++n) _Pragma("unroll") for (int k = 0; k < 2; ++k) \
;         acc[ai][bj][m][n] = __builtin_amdgcn_mfma_f32_16x16x32_bf16(Bt[n][k], At[m][k], acc[ai][bj][m][n], 0, 0, 0); __builtin_amdgcn_s_setprio(0); } while (0)
; #define PG8_WAIT_V(n) asm volatile("s_waitcnt vmcnt(" #n ")" ::: "memory")
; #define PG8_WAIT_L(n) asm volatile("s_waitcnt lgkmcnt(" #n ")" ::: "memory")
; #define PG8_BAR __builtin_amdgcn_s_barrier()
; #define PG8_SCHED __builtin_amdgcn_sched_barrier(0)
; template <class Epi, class Sched, bool ALIGN_EPI = false, bool SP2 = false>
; __device__ __forceinline__ void gemm_phase(PG8_LAS unsigned char* lds, const Gemm g, const Sched& S, const Epi& E) {
;     ...
;             PG8_LDB(B0, 1, 0); PG8_LDB(B1, 1, 1); PG8_SCHED; PG8_LDA(At, 1, 0); PG8_STAGE(PG8_SA(0, 1), a2 + hstep, voffA);
;             PG8_WAIT_V(8); PG8_WAIT_L(0); PG8_BAR; PG8_MMA(0, 0, At, B0); PG8_MMA(0, 1, At, B1); PG8_BAR; PG8_SCHED;
	s_add_i32 s71, 0, 0x18000
	s_add_i32 s72, 0, 0x1c000
	v_add_u32_e32 v128, s71, v197
	v_add_u32_e32 v156, s72, v197
	ds_read_b128 v[96:99], v128
	ds_read_b128 v[108:111], v128 offset:1024
	ds_read_b128 v[120:123], v128 offset:2048
	ds_read_b128 v[128:131], v128 offset:3072
	ds_read_b128 v[144:147], v156
	ds_read_b128 v[148:151], v156 offset:1024
	ds_read_b128 v[152:155], v156 offset:2048
	ds_read_b128 v[156:159], v156 offset:3072
	s_add_u32 s46, s46, 0xb0000
	s_addc_u32 s47, s47, 0
	s_mov_b32 m0, s51
	v_lshl_add_u64 v[218:219], s[46:47], 0, v[184:185]
	ds_read_b128 v[160:163], v224 offset:32768
	ds_read_b128 v[164:167], v224 offset:33792
	ds_read_b128 v[168:171], v224 offset:34816
	ds_read_b128 v[172:175], v224 offset:35840
	ds_read_b128 v[176:179], v224 offset:36864
	ds_read_b128 v[180:183], v224 offset:37888
	ds_read_b128 v[202:205], v224 offset:38912
	ds_read_b128 v[206:209], v224 offset:39936
	global_load_lds_dwordx4 v[218:219], off
	v_lshl_add_u64 v[218:219], s[46:47], 0, v[188:189]
	s_mov_b32 m0, s52
	s_nop 0
	global_load_lds_dwordx4 v[218:219], off
	s_waitcnt vmcnt(8)
	s_waitcnt lgkmcnt(0)
	s_barrier
	s_setprio 1
	s_waitcnt lgkmcnt(0)
	v_mfma_f32_16x16x32_bf16 v[140:143], v[96:99], v[160:163], v[140:143]
	v_mfma_f32_16x16x32_bf16 v[136:139], v[120:123], v[160:163], v[136:139]
	v_mfma_f32_16x16x32_bf16 v[116:119], v[96:99], v[168:171], v[116:119]
	v_mfma_f32_16x16x32_bf16 v[112:115], v[120:123], v[168:171], v[112:115]
	v_mfma_f32_16x16x32_bf16 v[92:95], v[96:99], v[176:179], v[92:95]
	v_mfma_f32_16x16x32_bf16 v[88:91], v[120:123], v[176:179], v[88:91]
	v_mfma_f32_16x16x32_bf16 v[76:79], v[96:99], v[202:205], v[76:79]
	v_mfma_f32_16x16x32_bf16 v[72:75], v[120:123], v[202:205], v[72:75]
	v_mfma_f32_16x16x32_bf16 v[140:143], v[108:111], v[164:167], v[140:143]
	v_mfma_f32_16x16x32_bf16 v[136:139], v[128:131], v[164:167], v[136:139]
	v_mfma_f32_16x16x32_bf16 v[116:119], v[108:111], v[172:175], v[116:119]
	v_mfma_f32_16x16x32_bf16 v[112:115], v[128:131], v[172:175], v[112:115]
	v_mfma_f32_16x16x32_bf16 v[92:95], v[108:111], v[180:183], v[92:95]
	v_mfma_f32_16x16x32_bf16 v[88:91], v[128:131], v[180:183], v[88:91]
	v_mfma_f32_16x16x32_bf16 v[76:79], v[108:111], v[206:209], v[76:79]
	v_mfma_f32_16x16x32_bf16 v[72:75], v[128:131], v[206:209], v[72:75]
	v_mfma_f32_16x16x32_bf16 v[132:135], v[144:147], v[160:163], v[132:135]
	v_mfma_f32_16x16x32_bf16 v[124:127], v[152:155], v[160:163], v[124:127]
	v_mfma_f32_16x16x32_bf16 v[104:107], v[144:147], v[168:171], v[104:107]
	v_mfma_f32_16x16x32_bf16 v[100:103], v[152:155], v[168:171], v[100:103]
	v_mfma_f32_16x16x32_bf16 v[84:87], v[144:147], v[176:179], v[84:87]
	v_mfma_f32_16x16x32_bf16 v[80:83], v[152:155], v[176:179], v[80:83]
	v_mfma_f32_16x16x32_bf16 v[68:71], v[144:147], v[202:205], v[68:71]
	v_mfma_f32_16x16x32_bf16 v[64:67], v[152:155], v[202:205], v[64:67]
	v_mfma_f32_16x16x32_bf16 v[132:135], v[148:151], v[164:167], v[132:135]
	v_mfma_f32_16x16x32_bf16 v[124:127], v[156:159], v[164:167], v[124:127]
	v_mfma_f32_16x16x32_bf16 v[104:107], v[148:151], v[172:175], v[104:107]
	v_mfma_f32_16x16x32_bf16 v[100:103], v[156:159], v[172:175], v[100:103]
	v_mfma_f32_16x16x32_bf16 v[84:87], v[148:151], v[180:183], v[84:87]
	v_mfma_f32_16x16x32_bf16 v[80:83], v[156:159], v[180:183], v[80:83]
	v_mfma_f32_16x16x32_bf16 v[68:71], v[148:151], v[206:209], v[68:71]
	v_mfma_f32_16x16x32_bf16 v[64:67], v[156:159], v[206:209], v[64:67]
	s_setprio 0
	s_barrier
; #define PG8_STAGE(bufoff, gbase, voff) do { _Pragma("unroll") for (int _i = 0; _i < 2; ++_i) \
;         __builtin_amdgcn_global_load_lds((const unsigned*)((const char*)(gbase) + (voff)[_i]), (PG8_LAS unsigned*)(lds + (bufoff) + ldsw + _i * 8192), 16, 0, 0); } while (0)
; #define PG8_LDA(dst, b, h) do { _Pragma("unroll") for (int m = 0; m < 4; ++m) _Pragma("unroll") for (int k = 0; k < 2; ++k) dst[m][k] = *(const PG8_LAS bf16x8*)(lds + PG8_SA(b, h) + aoff + m * 2048 + k * 1024); } while (0)
; #define PG8_MMA(ai, bj, At, Bt) do { __builtin_amdgcn_s_setprio(1); _Pragma("unroll") for (int m = 0; m < 4; ++m) _Pragma("unroll") for (int n = 0; n < 2; ++n) _Pragma("unroll") for (int k = 0; k < 2; ++k) \
;         acc[ai][bj][m][n] = __builtin_amdgcn_mfma_f32_16x16x32_bf16(Bt[n][k], At[m][k], acc[ai][bj][m][n], 0, 0, 0); __builtin_amdgcn_s_setprio(0); } while (0)
; #define PG8_WAIT_V(n) asm volatile("s_waitcnt vmcnt(" #n ")" ::: "memory")
; #define PG8_WAIT_L(n) asm volatile("s_waitcnt lgkmcnt(" #n ")" ::: "memory")
; #define PG8_BAR __builtin_amdgcn_s_barrier()
; #define PG8_SCHED __builtin_amdgcn_sched_barrier(0)
; template <class Epi, class Sched, bool ALIGN_EPI = false, bool SP2 = false>
; __device__ __forceinline__ void gemm_phase(PG8_LAS unsigned char* lds, const Gemm g, const Sched& S, const Epi& E) {
;     ...
;             PG8_LDA(At, 1, 1); PG8_STAGE(PG8_SB(1, 0), b3, voffB); PG8_STAGE(PG8_SB(1, 1), b3 + hstep, voffB); PG8_STAGE(PG8_SA(1, 0), a3, voffA);
;             PG8_WAIT_V(8); PG8_WAIT_L(0); PG8_BAR; PG8_MMA(1, 0, At, B0); PG8_MMA(1, 1, At, B1); PG8_BAR; PG8_SCHED;
;     ...
;         if constexpr (ALIGN_EPI) { if (wr == 0) PG8_BAR; }
	s_add_i32 s46, s71, s48
	v_lshl_add_u64 v[210:211], v[210:211], 0, s[12:13]
	s_mov_b32 m0, s46
	ds_read_b128 v[160:163], v224 offset:49152
	ds_read_b128 v[164:167], v224 offset:50176
	ds_read_b128 v[168:171], v224 offset:51200
	ds_read_b128 v[172:175], v224 offset:52224
	ds_read_b128 v[176:179], v224 offset:53248
	ds_read_b128 v[180:183], v224 offset:54272
	ds_read_b128 v[202:205], v224 offset:55296
	ds_read_b128 v[206:209], v224 offset:56320
	global_load_lds_dwordx4 v[210:211], off
	s_add_i32 m0, s46, 0x2000
	s_add_u32 s34, s34, 0xb0080
	v_lshl_add_u64 v[210:211], v[212:213], 0, s[12:13]
	s_addc_u32 s35, s35, 0
	s_add_i32 s46, s72, s48
	global_load_lds_dwordx4 v[210:211], off
	v_lshl_add_u64 v[210:211], s[34:35], 0, v[186:187]
	s_mov_b32 m0, s46
	s_nop 0
	global_load_lds_dwordx4 v[210:211], off
	v_lshl_add_u64 v[210:211], s[34:35], 0, v[190:191]
	s_add_i32 m0, s46, 0x2000
	s_nop 0
	global_load_lds_dwordx4 v[210:211], off
	v_lshl_add_u64 v[210:211], v[214:215], 0, s[12:13]
	s_mov_b32 m0, s57
	s_nop 0
	global_load_lds_dwordx4 v[210:211], off
	v_lshl_add_u64 v[210:211], v[216:217], 0, s[12:13]
	s_mov_b32 m0, s58
	s_nop 0
	global_load_lds_dwordx4 v[210:211], off
	s_waitcnt vmcnt(8)
	s_waitcnt lgkmcnt(0)
	s_barrier
	s_setprio 1
	s_waitcnt lgkmcnt(0)
	v_mfma_f32_16x16x32_bf16 v[60:63], v[96:99], v[160:163], v[60:63]
	v_mfma_f32_16x16x32_bf16 v[56:59], v[120:123], v[160:163], v[56:59]
	v_mfma_f32_16x16x32_bf16 v[44:47], v[96:99], v[168:171], v[44:47]
	v_mfma_f32_16x16x32_bf16 v[40:43], v[120:123], v[168:171], v[40:43]
	v_mfma_f32_16x16x32_bf16 v[28:31], v[96:99], v[176:179], v[28:31]
	v_mfma_f32_16x16x32_bf16 v[24:27], v[120:123], v[176:179], v[24:27]
	v_mfma_f32_16x16x32_bf16 v[12:15], v[96:99], v[202:205], v[12:15]
	v_mfma_f32_16x16x32_bf16 v[8:11], v[120:123], v[202:205], v[8:11]
	v_mfma_f32_16x16x32_bf16 v[60:63], v[108:111], v[164:167], v[60:63]
	v_mfma_f32_16x16x32_bf16 v[56:59], v[128:131], v[164:167], v[56:59]
	v_mfma_f32_16x16x32_bf16 v[44:47], v[108:111], v[172:175], v[44:47]
	v_mfma_f32_16x16x32_bf16 v[40:43], v[128:131], v[172:175], v[40:43]
	v_mfma_f32_16x16x32_bf16 v[28:31], v[108:111], v[180:183], v[28:31]
	v_mfma_f32_16x16x32_bf16 v[24:27], v[128:131], v[180:183], v[24:27]
	v_mfma_f32_16x16x32_bf16 v[12:15], v[108:111], v[206:209], v[12:15]
	v_mfma_f32_16x16x32_bf16 v[8:11], v[128:131], v[206:209], v[8:11]
	v_mfma_f32_16x16x32_bf16 v[52:55], v[144:147], v[160:163], v[52:55]
	v_mfma_f32_16x16x32_bf16 v[48:51], v[152:155], v[160:163], v[48:51]
	v_mfma_f32_16x16x32_bf16 v[36:39], v[144:147], v[168:171], v[36:39]
	v_mfma_f32_16x16x32_bf16 v[32:35], v[152:155], v[168:171], v[32:35]
	v_mfma_f32_16x16x32_bf16 v[20:23], v[144:147], v[176:179], v[20:23]
	v_mfma_f32_16x16x32_bf16 v[16:19], v[152:155], v[176:179], v[16:19]
	v_mfma_f32_16x16x32_bf16 v[4:7], v[144:147], v[202:205], v[4:7]
	v_mfma_f32_16x16x32_bf16 v[0:3], v[152:155], v[202:205], v[0:3]
	v_mfma_f32_16x16x32_bf16 v[52:55], v[148:151], v[164:167], v[52:55]
	v_mfma_f32_16x16x32_bf16 v[48:51], v[156:159], v[164:167], v[48:51]
	v_mfma_f32_16x16x32_bf16 v[36:39], v[148:151], v[172:175], v[36:39]
	v_mfma_f32_16x16x32_bf16 v[32:35], v[156:159], v[172:175], v[32:35]
	v_mfma_f32_16x16x32_bf16 v[20:23], v[148:151], v[180:183], v[20:23]
	v_mfma_f32_16x16x32_bf16 v[16:19], v[156:159], v[180:183], v[16:19]
	v_mfma_f32_16x16x32_bf16 v[4:7], v[148:151], v[206:209], v[4:7]
	v_mfma_f32_16x16x32_bf16 v[0:3], v[156:159], v[206:209], v[0:3]
	s_setprio 0
	s_barrier
	s_add_i32 s70, s70, 2
	s_add_u32 s20, s20, 0x100
	s_addc_u32 s21, s21, 0
	s_add_u32 s68, s68, 0x100
	s_addc_u32 s69, s69, 0
	s_cmp_gt_u32 s70, 41
	s_cbranch_scc0 .LBB0_1825
	s_and_b64 vcc, exec, s[14:15]
	s_cbranch_vccz .LBB0_1828
	s_barrier
